# speedup vs baseline: 1.0175x; 1.0044x over previous
; #define STAGE(P, RS, SOFF, OFF, kt) do { const int _so = (SOFF) + (kt) * (BK * 2); \
;     _Pragma("unroll") for (int _i = 0; _i < 2; ++_i) { \
;       __builtin_amdgcn_raw_ptr_buffer_load_lds(RS, (__attribute__((address_space(3))) void*)((P) + wave * 1024 + _i * 8192), 16, OFF[_i], _so, 0, 0); } } while (0)
; #define LDA(dst, b, h) _Pragma("unroll") for (int m = 0; m < 4; ++m) _Pragma("unroll") for (int k = 0; k < 2; ++k) \
;     dst[m][k] = *reinterpret_cast<const bf16x8*>(SA(b, h) + lds_byte(wr * 64 + m * 16 + fr, k * 32 + fq * 8))
; #define LDB(dst, b, h) _Pragma("unroll") for (int n = 0; n < 2; ++n) _Pragma("unroll") for (int k = 0; k < 2; ++k) \
;     dst[n][k] = *reinterpret_cast<const bf16x8*>(SB(b, h) + lds_byte(wc * 32 + n * 16 + fr, k * 32 + fq * 8))
; #define WAIT_V(n) asm volatile("s_waitcnt vmcnt(" #n ")" ::: "memory")
; #define WAIT_L(n) asm volatile("s_waitcnt lgkmcnt(" #n ")" ::: "memory")
; #define BAR __builtin_amdgcn_s_barrier()
; #define SCHED __builtin_amdgcn_sched_barrier(0)
;     ...
;       LDB(B0, 0, 0); SCHED; LDA(At, 0, 0); STAGE(SA(1, 1), rsA, sA1, offA, t + 1);
;       WAIT_L(8); BAR; WAIT_L(0); MMA(0, 0, At, B0); BAR; SCHED;
;       LDB(B1, 0, 1); STAGE(SB(0, 0), rsB, sB0, offB, t + 2);
;       BAR; WAIT_L(0); MMA(0, 1, At, B1); BAR;
;       LDA(At, 0, 1); STAGE(SA(0, 0), rsA, sA0, offA, t + 2);
;       BAR; WAIT_L(0); MMA(1, 0, At, B0); BAR; SCHED;
;       STAGE(SB(0, 1), rsB, sB1, offB, t + 2);
;       WAIT_V(6); BAR; MMA(1, 1, At, B1); BAR;
;       LDB(B0, 1, 0); SCHED; LDA(At, 1, 0); STAGE(SA(0, 1), rsA, sA1, offA, t + 2);
;       WAIT_L(8); BAR; WAIT_L(0); MMA(0, 0, At, B0); BAR; SCHED;
;       LDB(B1, 1, 1); STAGE(SB(1, 0), rsB, sB0, offB, t + 3);
;       BAR; WAIT_L(0); MMA(0, 1, At, B1); BAR;
;       LDA(At, 1, 1); STAGE(SA(1, 0), rsA, sA0, offA, t + 3);
;       BAR; WAIT_L(0); MMA(1, 0, At, B0); BAR; SCHED;
;       STAGE(SB(1, 1), rsB, sB1, offB, t + 3);
;       WAIT_V(6); BAR; MMA(1, 1, At, B1); BAR;
.LBB0_95:
	s_waitcnt vmcnt(6)
	s_barrier
	v_mfma_f32_16x16x32_bf16 v[28:31], v[202:205], v[170:173], v[28:31]
	v_mfma_f32_16x16x32_bf16 v[28:31], v[206:209], v[174:177], v[28:31]
	v_mfma_f32_16x16x32_bf16 v[24:27], v[214:217], v[174:177], v[24:27]
	v_mfma_f32_16x16x32_bf16 v[24:27], v[210:213], v[170:173], v[24:27]
	v_mfma_f32_16x16x32_bf16 v[16:19], v[210:213], v[178:181], v[16:19]
	v_mfma_f32_16x16x32_bf16 v[16:19], v[214:217], v[182:185], v[16:19]
	v_mfma_f32_16x16x32_bf16 v[20:23], v[206:209], v[182:185], v[20:23]
	v_mfma_f32_16x16x32_bf16 v[20:23], v[202:205], v[178:181], v[20:23]
	v_mfma_f32_16x16x32_bf16 v[12:15], v[202:205], v[186:189], v[12:15]
	v_mfma_f32_16x16x32_bf16 v[12:15], v[206:209], v[190:193], v[12:15]
	v_mfma_f32_16x16x32_bf16 v[8:11], v[214:217], v[190:193], v[8:11]
	v_mfma_f32_16x16x32_bf16 v[8:11], v[210:213], v[186:189], v[8:11]
	v_mfma_f32_16x16x32_bf16 v[0:3], v[210:213], v[194:197], v[0:3]
	v_mfma_f32_16x16x32_bf16 v[0:3], v[214:217], v[198:201], v[0:3]
	v_mfma_f32_16x16x32_bf16 v[4:7], v[206:209], v[198:201], v[4:7]
	v_mfma_f32_16x16x32_bf16 v[4:7], v[202:205], v[194:197], v[4:7]
	s_barrier
.Lmy_rot_95:
	ds_read_b128 v[154:157], v149
	ds_read_b128 v[158:161], v150
	ds_read_b128 v[162:165], v151
	ds_read_b128 v[166:169], v152
	s_add_i32 s43, s37, s15
	s_add_i32 s10, s43, 0x80
	s_mov_b32 m0, s30
	ds_read_b128 v[170:173], v131
	ds_read_b128 v[174:177], v131 offset:1024
	ds_read_b128 v[178:181], v134
	ds_read_b128 v[182:185], v134 offset:1024
	ds_read_b128 v[186:189], v133
	ds_read_b128 v[190:193], v133 offset:1024
	ds_read_b128 v[194:197], v132
	ds_read_b128 v[198:201], v132 offset:1024
	buffer_load_dwordx4 v143, s[4:7], s10 offen lds
	s_mov_b32 m0, s31
	s_nop 0
	buffer_load_dwordx4 v144, s[4:7], s10 offen lds
	s_waitcnt lgkmcnt(8)
	s_barrier
	s_waitcnt lgkmcnt(0)
	v_mfma_f32_16x16x32_bf16 v[124:127], v[154:157], v[170:173], v[124:127]
	v_mfma_f32_16x16x32_bf16 v[124:127], v[158:161], v[174:177], v[124:127]
	v_mfma_f32_16x16x32_bf16 v[120:123], v[166:169], v[174:177], v[120:123]
	v_mfma_f32_16x16x32_bf16 v[120:123], v[162:165], v[170:173], v[120:123]
	v_mfma_f32_16x16x32_bf16 v[112:115], v[162:165], v[178:181], v[112:115]
	v_mfma_f32_16x16x32_bf16 v[112:115], v[166:169], v[182:185], v[112:115]
	v_mfma_f32_16x16x32_bf16 v[116:119], v[158:161], v[182:185], v[116:119]
	v_mfma_f32_16x16x32_bf16 v[116:119], v[154:157], v[178:181], v[116:119]
	v_mfma_f32_16x16x32_bf16 v[108:111], v[154:157], v[186:189], v[108:111]
	v_mfma_f32_16x16x32_bf16 v[108:111], v[158:161], v[190:193], v[108:111]
	v_mfma_f32_16x16x32_bf16 v[104:107], v[166:169], v[190:193], v[104:107]
	v_mfma_f32_16x16x32_bf16 v[104:107], v[162:165], v[186:189], v[104:107]
	v_mfma_f32_16x16x32_bf16 v[96:99], v[162:165], v[194:197], v[96:99]
	v_mfma_f32_16x16x32_bf16 v[96:99], v[166:169], v[198:201], v[96:99]
	v_mfma_f32_16x16x32_bf16 v[100:103], v[158:161], v[198:201], v[100:103]
	v_mfma_f32_16x16x32_bf16 v[100:103], v[154:157], v[194:197], v[100:103]
	s_barrier
	s_add_i32 s44, s39, s15
	s_add_i32 s45, s44, 0x100
	s_mov_b32 s10, s6
	s_mov_b32 s11, s7
	s_mov_b32 m0, s1
	ds_read_b128 v[202:205], v145
	ds_read_b128 v[206:209], v146
	ds_read_b128 v[210:213], v147
	ds_read_b128 v[214:217], v148
	buffer_load_dwordx4 v143, s[8:11], s45 offen lds
	s_mov_b32 m0, s3
	s_nop 0
	buffer_load_dwordx4 v144, s[8:11], s45 offen lds
	s_barrier
	s_waitcnt lgkmcnt(0)
	v_mfma_f32_16x16x32_bf16 v[92:95], v[202:205], v[170:173], v[92:95]
	v_mfma_f32_16x16x32_bf16 v[92:95], v[206:209], v[174:177], v[92:95]
	v_mfma_f32_16x16x32_bf16 v[88:91], v[214:217], v[174:177], v[88:91]
	v_mfma_f32_16x16x32_bf16 v[88:91], v[210:213], v[170:173], v[88:91]
	v_mfma_f32_16x16x32_bf16 v[80:83], v[210:213], v[178:181], v[80:83]
	v_mfma_f32_16x16x32_bf16 v[80:83], v[214:217], v[182:185], v[80:83]
	v_mfma_f32_16x16x32_bf16 v[84:87], v[206:209], v[182:185], v[84:87]
	v_mfma_f32_16x16x32_bf16 v[84:87], v[202:205], v[178:181], v[84:87]
	v_mfma_f32_16x16x32_bf16 v[76:79], v[202:205], v[186:189], v[76:79]
	v_mfma_f32_16x16x32_bf16 v[76:79], v[206:209], v[190:193], v[76:79]
	v_mfma_f32_16x16x32_bf16 v[72:75], v[214:217], v[190:193], v[72:75]
	v_mfma_f32_16x16x32_bf16 v[72:75], v[210:213], v[186:189], v[72:75]
	v_mfma_f32_16x16x32_bf16 v[64:67], v[210:213], v[194:197], v[64:67]
	v_mfma_f32_16x16x32_bf16 v[64:67], v[214:217], v[198:201], v[64:67]
	v_mfma_f32_16x16x32_bf16 v[68:71], v[206:209], v[198:201], v[68:71]
	v_mfma_f32_16x16x32_bf16 v[68:71], v[202:205], v[194:197], v[68:71]
	s_barrier
	s_add_i32 s45, s38, s15
	s_add_i32 s46, s45, 0x100
	s_mov_b32 m0, s0
	ds_read_b128 v[170:173], v131 offset:16384
	ds_read_b128 v[174:177], v131 offset:17408
	ds_read_b128 v[178:181], v134 offset:16384
	ds_read_b128 v[182:185], v134 offset:17408
	ds_read_b128 v[186:189], v133 offset:16384
	ds_read_b128 v[190:193], v133 offset:17408
	ds_read_b128 v[194:197], v132 offset:16384
	ds_read_b128 v[198:201], v132 offset:17408
	buffer_load_dwordx4 v143, s[4:7], s46 offen lds
	s_mov_b32 m0, s18
	s_nop 0
	buffer_load_dwordx4 v144, s[4:7], s46 offen lds
	s_barrier
	s_waitcnt lgkmcnt(0)
	v_mfma_f32_16x16x32_bf16 v[60:63], v[154:157], v[170:173], v[60:63]
	v_mfma_f32_16x16x32_bf16 v[60:63], v[158:161], v[174:177], v[60:63]
	v_mfma_f32_16x16x32_bf16 v[56:59], v[166:169], v[174:177], v[56:59]
	v_mfma_f32_16x16x32_bf16 v[56:59], v[162:165], v[170:173], v[56:59]
	v_mfma_f32_16x16x32_bf16 v[48:51], v[162:165], v[178:181], v[48:51]
	v_mfma_f32_16x16x32_bf16 v[48:51], v[166:169], v[182:185], v[48:51]
	v_mfma_f32_16x16x32_bf16 v[52:55], v[158:161], v[182:185], v[52:55]
	v_mfma_f32_16x16x32_bf16 v[52:55], v[154:157], v[178:181], v[52:55]
	v_mfma_f32_16x16x32_bf16 v[44:47], v[154:157], v[186:189], v[44:47]
	v_mfma_f32_16x16x32_bf16 v[44:47], v[158:161], v[190:193], v[44:47]
	v_mfma_f32_16x16x32_bf16 v[40:43], v[166:169], v[190:193], v[40:43]
	v_mfma_f32_16x16x32_bf16 v[40:43], v[162:165], v[186:189], v[40:43]
	v_mfma_f32_16x16x32_bf16 v[32:35], v[162:165], v[194:197], v[32:35]
	v_mfma_f32_16x16x32_bf16 v[32:35], v[166:169], v[198:201], v[32:35]
	v_mfma_f32_16x16x32_bf16 v[36:39], v[158:161], v[198:201], v[36:39]
	v_mfma_f32_16x16x32_bf16 v[36:39], v[154:157], v[194:197], v[36:39]
	s_barrier
; #define STAGE(P, RS, SOFF, OFF, kt) do { const int _so = (SOFF) + (kt) * (BK * 2); \
;     _Pragma("unroll") for (int _i = 0; _i < 2; ++_i) { \
;       __builtin_amdgcn_raw_ptr_buffer_load_lds(RS, (__attribute__((address_space(3))) void*)((P) + wave * 1024 + _i * 8192), 16, OFF[_i], _so, 0, 0); } } while (0)
; #define LDA(dst, b, h) _Pragma("unroll") for (int m = 0; m < 4; ++m) _Pragma("unroll") for (int k = 0; k < 2; ++k) \
;     dst[m][k] = *reinterpret_cast<const bf16x8*>(SA(b, h) + lds_byte(wr * 64 + m * 16 + fr, k * 32 + fq * 8))
; #define LDB(dst, b, h) _Pragma("unroll") for (int n = 0; n < 2; ++n) _Pragma("unroll") for (int k = 0; k < 2; ++k) \
;     dst[n][k] = *reinterpret_cast<const bf16x8*>(SB(b, h) + lds_byte(wc * 32 + n * 16 + fr, k * 32 + fq * 8))
; #define WAIT_V(n) asm volatile("s_waitcnt vmcnt(" #n ")" ::: "memory")
; #define WAIT_L(n) asm volatile("s_waitcnt lgkmcnt(" #n ")" ::: "memory")
; #define BAR __builtin_amdgcn_s_barrier()
; #define SCHED __builtin_amdgcn_sched_barrier(0)
;     ...
;       STAGE(SB(0, 1), rsB, sB1, offB, t + 2);
;       WAIT_V(6); BAR; MMA(1, 1, At, B1); BAR;
;       LDB(B0, 1, 0); SCHED; LDA(At, 1, 0); STAGE(SA(0, 1), rsA, sA1, offA, t + 2);
;       WAIT_L(8); BAR; WAIT_L(0); MMA(0, 0, At, B0); BAR; SCHED;
;       LDB(B1, 1, 1); STAGE(SB(1, 0), rsB, sB0, offB, t + 3);
;       BAR; WAIT_L(0); MMA(0, 1, At, B1); BAR;
;       LDA(At, 1, 1); STAGE(SA(1, 0), rsA, sA0, offA, t + 3);
	s_add_i32 s46, s40, s15
	s_add_i32 s47, s46, 0x100
	s_mov_b32 m0, s19
	s_nop 0
	buffer_load_dwordx4 v143, s[8:11], s47 offen lds
	s_mov_b32 m0, s20
	s_nop 0
	buffer_load_dwordx4 v144, s[8:11], s47 offen lds
	s_waitcnt vmcnt(6)
	s_barrier
	v_mfma_f32_16x16x32_bf16 v[28:31], v[202:205], v[170:173], v[28:31]
	v_mfma_f32_16x16x32_bf16 v[28:31], v[206:209], v[174:177], v[28:31]
	v_mfma_f32_16x16x32_bf16 v[24:27], v[214:217], v[174:177], v[24:27]
	v_mfma_f32_16x16x32_bf16 v[24:27], v[210:213], v[170:173], v[24:27]
	v_mfma_f32_16x16x32_bf16 v[16:19], v[210:213], v[178:181], v[16:19]
	v_mfma_f32_16x16x32_bf16 v[16:19], v[214:217], v[182:185], v[16:19]
	v_mfma_f32_16x16x32_bf16 v[20:23], v[206:209], v[182:185], v[20:23]
	v_mfma_f32_16x16x32_bf16 v[20:23], v[202:205], v[178:181], v[20:23]
	v_mfma_f32_16x16x32_bf16 v[12:15], v[202:205], v[186:189], v[12:15]
	v_mfma_f32_16x16x32_bf16 v[12:15], v[206:209], v[190:193], v[12:15]
	v_mfma_f32_16x16x32_bf16 v[8:11], v[214:217], v[190:193], v[8:11]
	v_mfma_f32_16x16x32_bf16 v[8:11], v[210:213], v[186:189], v[8:11]
	v_mfma_f32_16x16x32_bf16 v[0:3], v[210:213], v[194:197], v[0:3]
	v_mfma_f32_16x16x32_bf16 v[0:3], v[214:217], v[198:201], v[0:3]
	v_mfma_f32_16x16x32_bf16 v[4:7], v[206:209], v[198:201], v[4:7]
	v_mfma_f32_16x16x32_bf16 v[4:7], v[202:205], v[194:197], v[4:7]
	s_barrier
	ds_read_b128 v[154:157], v139
	ds_read_b128 v[158:161], v140
	ds_read_b128 v[162:165], v141
	ds_read_b128 v[166:169], v142
	s_addk_i32 s43, 0x100
	s_mov_b32 m0, s21
	ds_read_b128 v[170:173], v131 offset:32768
	ds_read_b128 v[174:177], v131 offset:33792
	ds_read_b128 v[178:181], v134 offset:32768
	ds_read_b128 v[182:185], v134 offset:33792
	ds_read_b128 v[186:189], v133 offset:32768
	ds_read_b128 v[190:193], v133 offset:33792
	ds_read_b128 v[194:197], v132 offset:32768
	ds_read_b128 v[198:201], v132 offset:33792
	buffer_load_dwordx4 v143, s[4:7], s43 offen lds
	s_mov_b32 m0, s22
	s_nop 0
	buffer_load_dwordx4 v144, s[4:7], s43 offen lds
	s_waitcnt lgkmcnt(8)
	s_barrier
	s_waitcnt lgkmcnt(0)
	v_mfma_f32_16x16x32_bf16 v[124:127], v[154:157], v[170:173], v[124:127]
	v_mfma_f32_16x16x32_bf16 v[124:127], v[158:161], v[174:177], v[124:127]
	v_mfma_f32_16x16x32_bf16 v[120:123], v[166:169], v[174:177], v[120:123]
	v_mfma_f32_16x16x32_bf16 v[120:123], v[162:165], v[170:173], v[120:123]
	v_mfma_f32_16x16x32_bf16 v[112:115], v[162:165], v[178:181], v[112:115]
	v_mfma_f32_16x16x32_bf16 v[112:115], v[166:169], v[182:185], v[112:115]
	v_mfma_f32_16x16x32_bf16 v[116:119], v[158:161], v[182:185], v[116:119]
	v_mfma_f32_16x16x32_bf16 v[116:119], v[154:157], v[178:181], v[116:119]
	v_mfma_f32_16x16x32_bf16 v[108:111], v[154:157], v[186:189], v[108:111]
	v_mfma_f32_16x16x32_bf16 v[108:111], v[158:161], v[190:193], v[108:111]
	v_mfma_f32_16x16x32_bf16 v[104:107], v[166:169], v[190:193], v[104:107]
	v_mfma_f32_16x16x32_bf16 v[104:107], v[162:165], v[186:189], v[104:107]
	v_mfma_f32_16x16x32_bf16 v[96:99], v[162:165], v[194:197], v[96:99]
	v_mfma_f32_16x16x32_bf16 v[96:99], v[166:169], v[198:201], v[96:99]
	v_mfma_f32_16x16x32_bf16 v[100:103], v[158:161], v[198:201], v[100:103]
	v_mfma_f32_16x16x32_bf16 v[100:103], v[154:157], v[194:197], v[100:103]
	s_barrier
	s_addk_i32 s44, 0x180
	s_mov_b32 m0, s23
	ds_read_b128 v[202:205], v135
	ds_read_b128 v[206:209], v136
	ds_read_b128 v[210:213], v137
	ds_read_b128 v[214:217], v138
	buffer_load_dwordx4 v143, s[8:11], s44 offen lds
	s_mov_b32 m0, s24
	s_nop 0
	buffer_load_dwordx4 v144, s[8:11], s44 offen lds
	s_barrier
	s_waitcnt lgkmcnt(0)
	v_mfma_f32_16x16x32_bf16 v[92:95], v[202:205], v[170:173], v[92:95]
	v_mfma_f32_16x16x32_bf16 v[92:95], v[206:209], v[174:177], v[92:95]
	v_mfma_f32_16x16x32_bf16 v[88:91], v[214:217], v[174:177], v[88:91]
	v_mfma_f32_16x16x32_bf16 v[88:91], v[210:213], v[170:173], v[88:91]
	v_mfma_f32_16x16x32_bf16 v[80:83], v[210:213], v[178:181], v[80:83]
	v_mfma_f32_16x16x32_bf16 v[80:83], v[214:217], v[182:185], v[80:83]
	v_mfma_f32_16x16x32_bf16 v[84:87], v[206:209], v[182:185], v[84:87]
	v_mfma_f32_16x16x32_bf16 v[84:87], v[202:205], v[178:181], v[84:87]
	v_mfma_f32_16x16x32_bf16 v[76:79], v[202:205], v[186:189], v[76:79]
	v_mfma_f32_16x16x32_bf16 v[76:79], v[206:209], v[190:193], v[76:79]
	v_mfma_f32_16x16x32_bf16 v[72:75], v[214:217], v[190:193], v[72:75]
	v_mfma_f32_16x16x32_bf16 v[72:75], v[210:213], v[186:189], v[72:75]
	v_mfma_f32_16x16x32_bf16 v[64:67], v[210:213], v[194:197], v[64:67]
	v_mfma_f32_16x16x32_bf16 v[64:67], v[214:217], v[198:201], v[64:67]
	v_mfma_f32_16x16x32_bf16 v[68:71], v[206:209], v[198:201], v[68:71]
	v_mfma_f32_16x16x32_bf16 v[68:71], v[202:205], v[194:197], v[68:71]
	s_barrier
	s_addk_i32 s45, 0x180
	s_mov_b32 m0, s25
	ds_read_b128 v[170:173], v131 offset:49152
	ds_read_b128 v[174:177], v131 offset:50176
	ds_read_b128 v[178:181], v134 offset:49152
	ds_read_b128 v[182:185], v134 offset:50176
	ds_read_b128 v[186:189], v133 offset:49152
	ds_read_b128 v[190:193], v133 offset:50176
	ds_read_b128 v[194:197], v132 offset:49152
	ds_read_b128 v[198:201], v132 offset:50176
	buffer_load_dwordx4 v143, s[4:7], s45 offen lds
	s_mov_b32 m0, s26
	s_nop 0
	buffer_load_dwordx4 v144, s[4:7], s45 offen lds
	s_barrier
; #define STAGE(P, RS, SOFF, OFF, kt) do { const int _so = (SOFF) + (kt) * (BK * 2); \
;     _Pragma("unroll") for (int _i = 0; _i < 2; ++_i) { \
;       __builtin_amdgcn_raw_ptr_buffer_load_lds(RS, (__attribute__((address_space(3))) void*)((P) + wave * 1024 + _i * 8192), 16, OFF[_i], _so, 0, 0); } } while (0)
; #define LDA(dst, b, h) _Pragma("unroll") for (int m = 0; m < 4; ++m) _Pragma("unroll") for (int k = 0; k < 2; ++k) \
;     dst[m][k] = *reinterpret_cast<const bf16x8*>(SA(b, h) + lds_byte(wr * 64 + m * 16 + fr, k * 32 + fq * 8))
; #define LDB(dst, b, h) _Pragma("unroll") for (int n = 0; n < 2; ++n) _Pragma("unroll") for (int k = 0; k < 2; ++k) \
;     dst[n][k] = *reinterpret_cast<const bf16x8*>(SB(b, h) + lds_byte(wc * 32 + n * 16 + fr, k * 32 + fq * 8))
; #define WAIT_V(n) asm volatile("s_waitcnt vmcnt(" #n ")" ::: "memory")
; #define WAIT_L(n) asm volatile("s_waitcnt lgkmcnt(" #n ")" ::: "memory")
; #define BAR __builtin_amdgcn_s_barrier()
; #define SCHED __builtin_amdgcn_sched_barrier(0)
;     ...
;       BAR; WAIT_L(0); MMA(1, 0, At, B0); BAR; SCHED;
;       STAGE(SB(1, 1), rsB, sB1, offB, t + 3);
;       WAIT_V(6); BAR; MMA(1, 1, At, B1); BAR;
;     }
;     { LDB(B0, 0, 0); LDA(At, 0, 0); STAGE(SA(1, 1), rsA, sA1, offA, nt - 1);
;       BAR; WAIT_L(0); MMA(0, 0, At, B0); BAR;
;       LDB(B1, 0, 1); BAR; WAIT_L(0); MMA(0, 1, At, B1); BAR;
;       LDA(At, 0, 1); WAIT_V(4); BAR; WAIT_L(0); MMA(1, 0, At, B0); MMA(1, 1, At, B1); BAR; }
	s_waitcnt lgkmcnt(0)
	v_mfma_f32_16x16x32_bf16 v[60:63], v[154:157], v[170:173], v[60:63]
	v_mfma_f32_16x16x32_bf16 v[60:63], v[158:161], v[174:177], v[60:63]
	v_mfma_f32_16x16x32_bf16 v[56:59], v[166:169], v[174:177], v[56:59]
	v_mfma_f32_16x16x32_bf16 v[56:59], v[162:165], v[170:173], v[56:59]
	v_mfma_f32_16x16x32_bf16 v[48:51], v[162:165], v[178:181], v[48:51]
	v_mfma_f32_16x16x32_bf16 v[48:51], v[166:169], v[182:185], v[48:51]
	v_mfma_f32_16x16x32_bf16 v[52:55], v[158:161], v[182:185], v[52:55]
	v_mfma_f32_16x16x32_bf16 v[52:55], v[154:157], v[178:181], v[52:55]
	v_mfma_f32_16x16x32_bf16 v[44:47], v[154:157], v[186:189], v[44:47]
	v_mfma_f32_16x16x32_bf16 v[44:47], v[158:161], v[190:193], v[44:47]
	v_mfma_f32_16x16x32_bf16 v[40:43], v[166:169], v[190:193], v[40:43]
	v_mfma_f32_16x16x32_bf16 v[40:43], v[162:165], v[186:189], v[40:43]
	v_mfma_f32_16x16x32_bf16 v[32:35], v[162:165], v[194:197], v[32:35]
	v_mfma_f32_16x16x32_bf16 v[32:35], v[166:169], v[198:201], v[32:35]
	v_mfma_f32_16x16x32_bf16 v[36:39], v[158:161], v[198:201], v[36:39]
	v_mfma_f32_16x16x32_bf16 v[36:39], v[154:157], v[194:197], v[36:39]
	s_barrier
	s_addk_i32 s46, 0x180
	s_mov_b32 m0, s27
	s_nop 0
	buffer_load_dwordx4 v143, s[8:11], s46 offen lds
	s_mov_b32 m0, s28
	s_nop 0
	buffer_load_dwordx4 v144, s[8:11], s46 offen lds
	s_add_i32 s14, s14, 2
	s_addk_i32 s15, 0x100
	s_cmp_gt_u32 s14, 27
	s_cbranch_scc0 .LBB0_95
	s_waitcnt vmcnt(6)
	s_barrier
	v_mfma_f32_16x16x32_bf16 v[28:31], v[202:205], v[170:173], v[28:31]
	v_mfma_f32_16x16x32_bf16 v[28:31], v[206:209], v[174:177], v[28:31]
	v_mfma_f32_16x16x32_bf16 v[24:27], v[214:217], v[174:177], v[24:27]
	v_mfma_f32_16x16x32_bf16 v[24:27], v[210:213], v[170:173], v[24:27]
	v_mfma_f32_16x16x32_bf16 v[16:19], v[210:213], v[178:181], v[16:19]
	v_mfma_f32_16x16x32_bf16 v[16:19], v[214:217], v[182:185], v[16:19]
	v_mfma_f32_16x16x32_bf16 v[20:23], v[206:209], v[182:185], v[20:23]
	v_mfma_f32_16x16x32_bf16 v[20:23], v[202:205], v[178:181], v[20:23]
	v_mfma_f32_16x16x32_bf16 v[12:15], v[202:205], v[186:189], v[12:15]
	v_mfma_f32_16x16x32_bf16 v[12:15], v[206:209], v[190:193], v[12:15]
	v_mfma_f32_16x16x32_bf16 v[8:11], v[214:217], v[190:193], v[8:11]
	v_mfma_f32_16x16x32_bf16 v[8:11], v[210:213], v[186:189], v[8:11]
	v_mfma_f32_16x16x32_bf16 v[0:3], v[210:213], v[194:197], v[0:3]
	v_mfma_f32_16x16x32_bf16 v[0:3], v[214:217], v[198:201], v[0:3]
	v_mfma_f32_16x16x32_bf16 v[4:7], v[206:209], v[198:201], v[4:7]
	v_mfma_f32_16x16x32_bf16 v[4:7], v[202:205], v[194:197], v[4:7]
	s_barrier
	s_add_i32 s10, s37, 0xf80
	s_mov_b32 m0, s30
	ds_read_b128 v[154:157], v149
	ds_read_b128 v[158:161], v150
	ds_read_b128 v[162:165], v151
	ds_read_b128 v[150:153], v152
	ds_read_b128 v[166:169], v131
	ds_read_b128 v[170:173], v131 offset:1024
	ds_read_b128 v[174:177], v134
	ds_read_b128 v[178:181], v134 offset:1024
	ds_read_b128 v[182:185], v133
	ds_read_b128 v[186:189], v133 offset:1024
	ds_read_b128 v[190:193], v132
	ds_read_b128 v[194:197], v132 offset:1024
	buffer_load_dwordx4 v143, s[4:7], s10 offen lds
	s_mov_b32 m0, s31
	s_nop 0
	buffer_load_dwordx4 v144, s[4:7], s10 offen lds
	s_barrier
	s_waitcnt lgkmcnt(0)
	v_mfma_f32_16x16x32_bf16 v[124:127], v[154:157], v[166:169], v[124:127]
	v_mfma_f32_16x16x32_bf16 v[124:127], v[158:161], v[170:173], v[124:127]
	v_mfma_f32_16x16x32_bf16 v[120:123], v[150:153], v[170:173], v[120:123]
	v_mfma_f32_16x16x32_bf16 v[120:123], v[162:165], v[166:169], v[120:123]
	v_mfma_f32_16x16x32_bf16 v[112:115], v[162:165], v[174:177], v[112:115]
	v_mfma_f32_16x16x32_bf16 v[112:115], v[150:153], v[178:181], v[112:115]
	v_mfma_f32_16x16x32_bf16 v[116:119], v[158:161], v[178:181], v[116:119]
	v_mfma_f32_16x16x32_bf16 v[116:119], v[154:157], v[174:177], v[116:119]
	v_mfma_f32_16x16x32_bf16 v[108:111], v[154:157], v[182:185], v[108:111]
	v_mfma_f32_16x16x32_bf16 v[108:111], v[158:161], v[186:189], v[108:111]
	v_mfma_f32_16x16x32_bf16 v[104:107], v[150:153], v[186:189], v[104:107]
	v_mfma_f32_16x16x32_bf16 v[104:107], v[162:165], v[182:185], v[104:107]
	v_mfma_f32_16x16x32_bf16 v[96:99], v[162:165], v[190:193], v[96:99]
	v_mfma_f32_16x16x32_bf16 v[96:99], v[150:153], v[194:197], v[96:99]
	v_mfma_f32_16x16x32_bf16 v[100:103], v[158:161], v[194:197], v[100:103]
	v_mfma_f32_16x16x32_bf16 v[100:103], v[154:157], v[190:193], v[100:103]
	s_barrier
	ds_read_b128 v[198:201], v145
	ds_read_b128 v[202:205], v146
	ds_read_b128 v[144:147], v147
	ds_read_b128 v[206:209], v148
	s_barrier
	s_waitcnt lgkmcnt(0)
	v_mfma_f32_16x16x32_bf16 v[92:95], v[198:201], v[166:169], v[92:95]
	v_mfma_f32_16x16x32_bf16 v[84:87], v[198:201], v[174:177], v[84:87]
	v_mfma_f32_16x16x32_bf16 v[76:79], v[198:201], v[182:185], v[76:79]
	v_mfma_f32_16x16x32_bf16 v[68:71], v[198:201], v[190:193], v[68:71]
	v_mfma_f32_16x16x32_bf16 v[88:91], v[144:147], v[166:169], v[88:91]
	v_mfma_f32_16x16x32_bf16 v[80:83], v[144:147], v[174:177], v[80:83]
	v_mfma_f32_16x16x32_bf16 v[72:75], v[144:147], v[182:185], v[72:75]
	v_mfma_f32_16x16x32_bf16 v[64:67], v[144:147], v[190:193], v[64:67]
	v_mfma_f32_16x16x32_bf16 v[92:95], v[202:205], v[170:173], v[92:95]
	v_mfma_f32_16x16x32_bf16 v[84:87], v[202:205], v[178:181], v[84:87]
	v_mfma_f32_16x16x32_bf16 v[76:79], v[202:205], v[186:189], v[76:79]
	v_mfma_f32_16x16x32_bf16 v[68:71], v[202:205], v[194:197], v[68:71]
	v_mfma_f32_16x16x32_bf16 v[166:169], v[206:209], v[170:173], v[88:91]
	v_mfma_f32_16x16x32_bf16 v[170:173], v[206:209], v[178:181], v[80:83]
	v_mfma_f32_16x16x32_bf16 v[174:177], v[206:209], v[186:189], v[72:75]
	v_mfma_f32_16x16x32_bf16 v[178:181], v[206:209], v[194:197], v[64:67]
	s_barrier
; #define LDA(dst, b, h) _Pragma("unroll") for (int m = 0; m < 4; ++m) _Pragma("unroll") for (int k = 0; k < 2; ++k) \
;     dst[m][k] = *reinterpret_cast<const bf16x8*>(SA(b, h) + lds_byte(wr * 64 + m * 16 + fr, k * 32 + fq * 8))
; #define LDB(dst, b, h) _Pragma("unroll") for (int n = 0; n < 2; ++n) _Pragma("unroll") for (int k = 0; k < 2; ++k) \
;     dst[n][k] = *reinterpret_cast<const bf16x8*>(SB(b, h) + lds_byte(wc * 32 + n * 16 + fr, k * 32 + fq * 8))
; #define WAIT_V(n) asm volatile("s_waitcnt vmcnt(" #n ")" ::: "memory")
; #define WAIT_L(n) asm volatile("s_waitcnt lgkmcnt(" #n ")" ::: "memory")
; #define BAR __builtin_amdgcn_s_barrier()
;     ...
;       LDA(At, 0, 1); WAIT_V(4); BAR; WAIT_L(0); MMA(1, 0, At, B0); MMA(1, 1, At, B1); BAR; }
;     { LDB(B0, 1, 0); LDA(At, 1, 0); WAIT_V(2); BAR; WAIT_L(0); MMA(0, 0, At, B0); BAR;
	s_nop 0
	ds_read_b128 v[64:67], v131 offset:16384
	ds_read_b128 v[72:75], v131 offset:17408
	ds_read_b128 v[80:83], v134 offset:16384
	ds_read_b128 v[88:91], v134 offset:17408
	ds_read_b128 v[182:185], v133 offset:16384
	ds_read_b128 v[186:189], v133 offset:17408
	ds_read_b128 v[190:193], v132 offset:16384
	ds_read_b128 v[194:197], v132 offset:17408
	s_waitcnt vmcnt(4)
	s_barrier
	s_waitcnt lgkmcnt(0)
	v_mfma_f32_16x16x32_bf16 v[60:63], v[154:157], v[64:67], v[60:63]
	v_mfma_f32_16x16x32_bf16 v[56:59], v[162:165], v[64:67], v[56:59]
	v_mfma_f32_16x16x32_bf16 v[52:55], v[154:157], v[80:83], v[52:55]
	v_mfma_f32_16x16x32_bf16 v[48:51], v[162:165], v[80:83], v[48:51]
	v_mfma_f32_16x16x32_bf16 v[44:47], v[154:157], v[182:185], v[44:47]
	v_mfma_f32_16x16x32_bf16 v[40:43], v[162:165], v[182:185], v[40:43]
	v_mfma_f32_16x16x32_bf16 v[36:39], v[154:157], v[190:193], v[36:39]
	v_mfma_f32_16x16x32_bf16 v[32:35], v[162:165], v[190:193], v[32:35]
	v_mfma_f32_16x16x32_bf16 v[60:63], v[158:161], v[72:75], v[60:63]
	v_mfma_f32_16x16x32_bf16 v[56:59], v[150:153], v[72:75], v[56:59]
	v_mfma_f32_16x16x32_bf16 v[52:55], v[158:161], v[88:91], v[52:55]
	v_mfma_f32_16x16x32_bf16 v[48:51], v[150:153], v[88:91], v[48:51]
	v_mfma_f32_16x16x32_bf16 v[44:47], v[158:161], v[186:189], v[44:47]
	v_mfma_f32_16x16x32_bf16 v[40:43], v[150:153], v[186:189], v[40:43]
	v_mfma_f32_16x16x32_bf16 v[36:39], v[158:161], v[194:197], v[36:39]
	v_mfma_f32_16x16x32_bf16 v[32:35], v[150:153], v[194:197], v[32:35]
	v_mfma_f32_16x16x32_bf16 v[28:31], v[198:201], v[64:67], v[28:31]
	v_mfma_f32_16x16x32_bf16 v[20:23], v[198:201], v[80:83], v[20:23]
	v_mfma_f32_16x16x32_bf16 v[12:15], v[198:201], v[182:185], v[12:15]
	v_mfma_f32_16x16x32_bf16 v[4:7], v[198:201], v[190:193], v[4:7]
	v_mfma_f32_16x16x32_bf16 v[24:27], v[144:147], v[64:67], v[24:27]
	v_mfma_f32_16x16x32_bf16 v[16:19], v[144:147], v[80:83], v[16:19]
	v_mfma_f32_16x16x32_bf16 v[8:11], v[144:147], v[182:185], v[8:11]
	v_mfma_f32_16x16x32_bf16 v[0:3], v[144:147], v[190:193], v[0:3]
	v_mfma_f32_16x16x32_bf16 v[28:31], v[202:205], v[72:75], v[28:31]
	v_mfma_f32_16x16x32_bf16 v[20:23], v[202:205], v[88:91], v[20:23]
	v_mfma_f32_16x16x32_bf16 v[12:15], v[202:205], v[186:189], v[12:15]
	v_mfma_f32_16x16x32_bf16 v[4:7], v[202:205], v[194:197], v[4:7]
	v_mfma_f32_16x16x32_bf16 v[144:147], v[206:209], v[72:75], v[24:27]
	v_mfma_f32_16x16x32_bf16 v[148:151], v[206:209], v[88:91], v[16:19]
	v_mfma_f32_16x16x32_bf16 v[152:155], v[206:209], v[186:189], v[8:11]
	v_mfma_f32_16x16x32_bf16 v[156:159], v[206:209], v[194:197], v[0:3]
	s_barrier
	s_nop 0
	ds_read_b128 v[0:3], v139
	ds_read_b128 v[8:11], v140
	ds_read_b128 v[16:19], v141
	ds_read_b128 v[140:143], v142
	ds_read_b128 v[24:27], v131 offset:32768
	ds_read_b128 v[160:163], v131 offset:33792
	ds_read_b128 v[182:185], v134 offset:32768
	ds_read_b128 v[186:189], v134 offset:33792
	ds_read_b128 v[190:193], v133 offset:32768
	ds_read_b128 v[194:197], v133 offset:33792
	ds_read_b128 v[198:201], v132 offset:32768
	ds_read_b128 v[202:205], v132 offset:33792
	s_waitcnt vmcnt(2)
	s_barrier
	s_waitcnt lgkmcnt(0)
	v_mfma_f32_16x16x32_bf16 v[64:67], v[0:3], v[24:27], v[124:127]
	v_mfma_f32_16x16x32_bf16 v[72:75], v[16:19], v[24:27], v[120:123]
	v_mfma_f32_16x16x32_bf16 v[80:83], v[0:3], v[182:185], v[116:119]
	v_mfma_f32_16x16x32_bf16 v[88:91], v[16:19], v[182:185], v[112:115]
	v_mfma_f32_16x16x32_bf16 v[108:111], v[0:3], v[190:193], v[108:111]
	v_mfma_f32_16x16x32_bf16 v[116:119], v[16:19], v[190:193], v[104:107]
	v_mfma_f32_16x16x32_bf16 v[100:103], v[0:3], v[198:201], v[100:103]
	v_mfma_f32_16x16x32_bf16 v[124:127], v[16:19], v[198:201], v[96:99]
	v_mfma_f32_16x16x32_bf16 v[120:123], v[8:11], v[160:163], v[64:67]
	v_mfma_f32_16x16x32_bf16 v[112:115], v[140:143], v[160:163], v[72:75]
	v_mfma_f32_16x16x32_bf16 v[104:107], v[8:11], v[186:189], v[80:83]
	v_mfma_f32_16x16x32_bf16 v[96:99], v[140:143], v[186:189], v[88:91]
	v_mfma_f32_16x16x32_bf16 v[88:91], v[8:11], v[194:197], v[108:111]
	v_mfma_f32_16x16x32_bf16 v[80:83], v[140:143], v[194:197], v[116:119]
	v_mfma_f32_16x16x32_bf16 v[72:75], v[8:11], v[202:205], v[100:103]
	v_mfma_f32_16x16x32_bf16 v[64:67], v[140:143], v[202:205], v[124:127]
	s_barrier
; #define LDA(dst, b, h) _Pragma("unroll") for (int m = 0; m < 4; ++m) _Pragma("unroll") for (int k = 0; k < 2; ++k) \
;     dst[m][k] = *reinterpret_cast<const bf16x8*>(SA(b, h) + lds_byte(wr * 64 + m * 16 + fr, k * 32 + fq * 8))
; #define LDB(dst, b, h) _Pragma("unroll") for (int n = 0; n < 2; ++n) _Pragma("unroll") for (int k = 0; k < 2; ++k) \
;     dst[n][k] = *reinterpret_cast<const bf16x8*>(SB(b, h) + lds_byte(wc * 32 + n * 16 + fr, k * 32 + fq * 8))
; #define WAIT_V(n) asm volatile("s_waitcnt vmcnt(" #n ")" ::: "memory")
; #define WAIT_L(n) asm volatile("s_waitcnt lgkmcnt(" #n ")" ::: "memory")
; #define BAR __builtin_amdgcn_s_barrier()
;     ...
;       LDB(B1, 1, 1); WAIT_V(0); BAR; WAIT_L(0); MMA(0, 1, At, B1); BAR;
;       LDA(At, 1, 1); BAR; WAIT_L(0); MMA(1, 0, At, B0); MMA(1, 1, At, B1); BAR; }
;     if (wr == 0) BAR;
	ds_read_b128 v[206:209], v135
	ds_read_b128 v[210:213], v136
	ds_read_b128 v[214:217], v137
	ds_read_b128 v[136:139], v138
	s_waitcnt vmcnt(0)
	s_barrier
	s_waitcnt lgkmcnt(0)
	v_mfma_f32_16x16x32_bf16 v[92:95], v[206:209], v[24:27], v[92:95]
	v_mfma_f32_16x16x32_bf16 v[24:27], v[214:217], v[24:27], v[166:169]
	v_mfma_f32_16x16x32_bf16 v[84:87], v[206:209], v[182:185], v[84:87]
	v_mfma_f32_16x16x32_bf16 v[100:103], v[214:217], v[182:185], v[170:173]
	v_mfma_f32_16x16x32_bf16 v[76:79], v[206:209], v[190:193], v[76:79]
	v_mfma_f32_16x16x32_bf16 v[164:167], v[214:217], v[190:193], v[174:177]
	v_mfma_f32_16x16x32_bf16 v[68:71], v[206:209], v[198:201], v[68:71]
	v_mfma_f32_16x16x32_bf16 v[168:171], v[214:217], v[198:201], v[178:181]
	v_mfma_f32_16x16x32_bf16 v[124:127], v[210:213], v[160:163], v[92:95]
	v_mfma_f32_16x16x32_bf16 v[116:119], v[136:139], v[160:163], v[24:27]
	v_mfma_f32_16x16x32_bf16 v[108:111], v[210:213], v[186:189], v[84:87]
	v_mfma_f32_16x16x32_bf16 v[100:103], v[136:139], v[186:189], v[100:103]
	v_mfma_f32_16x16x32_bf16 v[92:95], v[210:213], v[194:197], v[76:79]
	v_mfma_f32_16x16x32_bf16 v[84:87], v[136:139], v[194:197], v[164:167]
	v_mfma_f32_16x16x32_bf16 v[76:79], v[210:213], v[202:205], v[68:71]
	v_mfma_f32_16x16x32_bf16 v[68:71], v[136:139], v[202:205], v[168:171]
	s_barrier
	ds_read_b128 v[160:163], v131 offset:49152
	ds_read_b128 v[164:167], v131 offset:50176
	ds_read_b128 v[168:171], v134 offset:49152
	ds_read_b128 v[172:175], v134 offset:50176
	ds_read_b128 v[176:179], v133 offset:49152
	ds_read_b128 v[180:183], v133 offset:50176
	ds_read_b128 v[184:187], v132 offset:49152
	ds_read_b128 v[132:135], v132 offset:50176
	s_barrier
	s_waitcnt lgkmcnt(0)
	v_mfma_f32_16x16x32_bf16 v[24:27], v[0:3], v[160:163], v[60:63]
	v_mfma_f32_16x16x32_bf16 v[60:63], v[16:19], v[160:163], v[56:59]
	v_mfma_f32_16x16x32_bf16 v[52:55], v[0:3], v[168:171], v[52:55]
	v_mfma_f32_16x16x32_bf16 v[188:191], v[16:19], v[168:171], v[48:51]
	v_mfma_f32_16x16x32_bf16 v[44:47], v[0:3], v[176:179], v[44:47]
	v_mfma_f32_16x16x32_bf16 v[192:195], v[16:19], v[176:179], v[40:43]
	v_mfma_f32_16x16x32_bf16 v[0:3], v[0:3], v[184:187], v[36:39]
	v_mfma_f32_16x16x32_bf16 v[36:39], v[16:19], v[184:187], v[32:35]
	v_mfma_f32_16x16x32_bf16 v[56:59], v[8:11], v[164:167], v[24:27]
	v_mfma_f32_16x16x32_bf16 v[48:51], v[140:143], v[164:167], v[60:63]
	v_mfma_f32_16x16x32_bf16 v[40:43], v[8:11], v[172:175], v[52:55]
	v_mfma_f32_16x16x32_bf16 v[32:35], v[140:143], v[172:175], v[188:191]
	v_mfma_f32_16x16x32_bf16 v[24:27], v[8:11], v[180:183], v[44:47]
	v_mfma_f32_16x16x32_bf16 v[16:19], v[140:143], v[180:183], v[192:195]
	v_mfma_f32_16x16x32_bf16 v[8:11], v[8:11], v[132:135], v[0:3]
	v_mfma_f32_16x16x32_bf16 v[0:3], v[140:143], v[132:135], v[36:39]
	v_mfma_f32_16x16x32_bf16 v[28:31], v[206:209], v[160:163], v[28:31]
	v_mfma_f32_16x16x32_bf16 v[36:39], v[214:217], v[160:163], v[144:147]
	v_mfma_f32_16x16x32_bf16 v[20:23], v[206:209], v[168:171], v[20:23]
	v_mfma_f32_16x16x32_bf16 v[140:143], v[214:217], v[168:171], v[148:151]
	v_mfma_f32_16x16x32_bf16 v[12:15], v[206:209], v[176:179], v[12:15]
	v_mfma_f32_16x16x32_bf16 v[144:147], v[214:217], v[176:179], v[152:155]
	v_mfma_f32_16x16x32_bf16 v[4:7], v[206:209], v[184:187], v[4:7]
	v_mfma_f32_16x16x32_bf16 v[148:151], v[214:217], v[184:187], v[156:159]
	v_mfma_f32_16x16x32_bf16 v[60:63], v[210:213], v[164:167], v[28:31]
	v_mfma_f32_16x16x32_bf16 v[52:55], v[136:139], v[164:167], v[36:39]
	v_mfma_f32_16x16x32_bf16 v[44:47], v[210:213], v[172:175], v[20:23]
	v_mfma_f32_16x16x32_bf16 v[36:39], v[136:139], v[172:175], v[140:143]
	v_mfma_f32_16x16x32_bf16 v[28:31], v[210:213], v[180:183], v[12:15]
	v_mfma_f32_16x16x32_bf16 v[20:23], v[136:139], v[180:183], v[144:147]
	v_mfma_f32_16x16x32_bf16 v[12:15], v[210:213], v[132:135], v[4:7]
	v_mfma_f32_16x16x32_bf16 v[4:7], v[136:139], v[132:135], v[148:151]
	v_cmp_gt_u32_e32 vcc, s35, v130
	s_barrier
	s_and_saveexec_b64 s[10:11], vcc
	s_cbranch_execz .LBB0_98
	s_barrier

; #define STAGE(P, RS, SOFF, OFF, kt) do { const int _so = (SOFF) + (kt) * (BK * 2); \
;     _Pragma("unroll") for (int _i = 0; _i < 2; ++_i) { \
;       __builtin_amdgcn_raw_ptr_buffer_load_lds(RS, (__attribute__((address_space(3))) void*)((P) + wave * 1024 + _i * 8192), 16, OFF[_i], _so, 0, 0); } } while (0)
; #define LDA(dst, b, h) _Pragma("unroll") for (int m = 0; m < 4; ++m) _Pragma("unroll") for (int k = 0; k < 2; ++k) \
;     dst[m][k] = *reinterpret_cast<const bf16x8*>(SA(b, h) + lds_byte(wr * 64 + m * 16 + fr, k * 32 + fq * 8))
; #define LDB(dst, b, h) _Pragma("unroll") for (int n = 0; n < 2; ++n) _Pragma("unroll") for (int k = 0; k < 2; ++k) \
;     dst[n][k] = *reinterpret_cast<const bf16x8*>(SB(b, h) + lds_byte(wc * 32 + n * 16 + fr, k * 32 + fq * 8))
; #define WAIT_V(n) asm volatile("s_waitcnt vmcnt(" #n ")" ::: "memory")
; #define WAIT_L(n) asm volatile("s_waitcnt lgkmcnt(" #n ")" ::: "memory")
; #define BAR __builtin_amdgcn_s_barrier()
; #define SCHED __builtin_amdgcn_sched_barrier(0)
;     ...
;       LDB(B0, 0, 0); SCHED; LDA(At, 0, 0); STAGE(SA(1, 1), rsA, sA1, offA, t + 1);
;       WAIT_L(8); BAR; WAIT_L(0); MMA(0, 0, At, B0); BAR; SCHED;
;       LDB(B1, 0, 1); STAGE(SB(0, 0), rsB, sB0, offB, t + 2);
;       BAR; WAIT_L(0); MMA(0, 1, At, B1); BAR;
;       LDA(At, 0, 1); STAGE(SA(0, 0), rsA, sA0, offA, t + 2);
;       BAR; WAIT_L(0); MMA(1, 0, At, B0); BAR; SCHED;
;       STAGE(SB(0, 1), rsB, sB1, offB, t + 2);
;       WAIT_V(6); BAR; MMA(1, 1, At, B1); BAR;
;       LDB(B0, 1, 0); SCHED; LDA(At, 1, 0); STAGE(SA(0, 1), rsA, sA1, offA, t + 2);
;       WAIT_L(8); BAR; WAIT_L(0); MMA(0, 0, At, B0); BAR; SCHED;
;       LDB(B1, 1, 1); STAGE(SB(1, 0), rsB, sB0, offB, t + 3);
;       BAR; WAIT_L(0); MMA(0, 1, At, B1); BAR;
;       LDA(At, 1, 1); STAGE(SA(1, 0), rsA, sA0, offA, t + 3);
;       BAR; WAIT_L(0); MMA(1, 0, At, B0); BAR; SCHED;
;       STAGE(SB(1, 1), rsB, sB1, offB, t + 3);
;       WAIT_V(6); BAR; MMA(1, 1, At, B1); BAR;
.LBB0_110:
	s_waitcnt vmcnt(6)
	s_barrier
	v_mfma_f32_16x16x32_bf16 v[28:31], v[204:207], v[172:175], v[28:31]
	v_mfma_f32_16x16x32_bf16 v[28:31], v[208:211], v[176:179], v[28:31]
	v_mfma_f32_16x16x32_bf16 v[24:27], v[216:219], v[176:179], v[24:27]
	v_mfma_f32_16x16x32_bf16 v[24:27], v[212:215], v[172:175], v[24:27]
	v_mfma_f32_16x16x32_bf16 v[16:19], v[212:215], v[180:183], v[16:19]
	v_mfma_f32_16x16x32_bf16 v[16:19], v[216:219], v[184:187], v[16:19]
	v_mfma_f32_16x16x32_bf16 v[20:23], v[208:211], v[184:187], v[20:23]
	v_mfma_f32_16x16x32_bf16 v[20:23], v[204:207], v[180:183], v[20:23]
	v_mfma_f32_16x16x32_bf16 v[12:15], v[204:207], v[188:191], v[12:15]
	v_mfma_f32_16x16x32_bf16 v[12:15], v[208:211], v[192:195], v[12:15]
	v_mfma_f32_16x16x32_bf16 v[8:11], v[216:219], v[192:195], v[8:11]
	v_mfma_f32_16x16x32_bf16 v[8:11], v[212:215], v[188:191], v[8:11]
	v_mfma_f32_16x16x32_bf16 v[0:3], v[212:215], v[196:199], v[0:3]
	v_mfma_f32_16x16x32_bf16 v[0:3], v[216:219], v[200:203], v[0:3]
	v_mfma_f32_16x16x32_bf16 v[4:7], v[208:211], v[200:203], v[4:7]
	v_mfma_f32_16x16x32_bf16 v[4:7], v[204:207], v[196:199], v[4:7]
	s_barrier
.Lmy_rot_110:
	ds_read_b128 v[156:159], v151
	ds_read_b128 v[160:163], v152
	ds_read_b128 v[164:167], v153
	ds_read_b128 v[168:171], v154
	s_add_i32 s44, s38, s17
	s_add_i32 s10, s44, 0x80
	s_mov_b32 m0, s31
	ds_read_b128 v[172:175], v131
	ds_read_b128 v[176:179], v131 offset:1024
	ds_read_b128 v[180:183], v138
	ds_read_b128 v[184:187], v138 offset:1024
	ds_read_b128 v[188:191], v137
	ds_read_b128 v[192:195], v137 offset:1024
	ds_read_b128 v[196:199], v135
	ds_read_b128 v[200:203], v135 offset:1024
	buffer_load_dwordx4 v128, s[4:7], s10 offen lds
	s_mov_b32 m0, s33
	s_nop 0
	buffer_load_dwordx4 v132, s[4:7], s10 offen lds
	s_waitcnt lgkmcnt(8)
	s_barrier
	s_waitcnt lgkmcnt(0)
	v_mfma_f32_16x16x32_bf16 v[124:127], v[156:159], v[172:175], v[124:127]
	v_mfma_f32_16x16x32_bf16 v[124:127], v[160:163], v[176:179], v[124:127]
	v_mfma_f32_16x16x32_bf16 v[120:123], v[168:171], v[176:179], v[120:123]
	v_mfma_f32_16x16x32_bf16 v[120:123], v[164:167], v[172:175], v[120:123]
	v_mfma_f32_16x16x32_bf16 v[112:115], v[164:167], v[180:183], v[112:115]
	v_mfma_f32_16x16x32_bf16 v[112:115], v[168:171], v[184:187], v[112:115]
	v_mfma_f32_16x16x32_bf16 v[116:119], v[160:163], v[184:187], v[116:119]
	v_mfma_f32_16x16x32_bf16 v[116:119], v[156:159], v[180:183], v[116:119]
	v_mfma_f32_16x16x32_bf16 v[108:111], v[156:159], v[188:191], v[108:111]
	v_mfma_f32_16x16x32_bf16 v[108:111], v[160:163], v[192:195], v[108:111]
	v_mfma_f32_16x16x32_bf16 v[104:107], v[168:171], v[192:195], v[104:107]
	v_mfma_f32_16x16x32_bf16 v[104:107], v[164:167], v[188:191], v[104:107]
	v_mfma_f32_16x16x32_bf16 v[96:99], v[164:167], v[196:199], v[96:99]
	v_mfma_f32_16x16x32_bf16 v[96:99], v[168:171], v[200:203], v[96:99]
	v_mfma_f32_16x16x32_bf16 v[100:103], v[160:163], v[200:203], v[100:103]
	v_mfma_f32_16x16x32_bf16 v[100:103], v[156:159], v[196:199], v[100:103]
	s_barrier
	s_add_i32 s45, s40, s17
	s_add_i32 s46, s45, 0x100
	s_mov_b32 s10, s6
	s_mov_b32 s11, s7
	s_mov_b32 m0, s3
	ds_read_b128 v[204:207], v147
	ds_read_b128 v[208:211], v148
	ds_read_b128 v[212:215], v149
	ds_read_b128 v[216:219], v150
	buffer_load_dwordx4 v130, s[8:11], s46 offen lds
	s_mov_b32 m0, s18
	s_nop 0
	buffer_load_dwordx4 v134, s[8:11], s46 offen lds
	s_barrier
	s_waitcnt lgkmcnt(0)
	v_mfma_f32_16x16x32_bf16 v[92:95], v[204:207], v[172:175], v[92:95]
	v_mfma_f32_16x16x32_bf16 v[92:95], v[208:211], v[176:179], v[92:95]
	v_mfma_f32_16x16x32_bf16 v[88:91], v[216:219], v[176:179], v[88:91]
	v_mfma_f32_16x16x32_bf16 v[88:91], v[212:215], v[172:175], v[88:91]
	v_mfma_f32_16x16x32_bf16 v[80:83], v[212:215], v[180:183], v[80:83]
	v_mfma_f32_16x16x32_bf16 v[80:83], v[216:219], v[184:187], v[80:83]
	v_mfma_f32_16x16x32_bf16 v[84:87], v[208:211], v[184:187], v[84:87]
	v_mfma_f32_16x16x32_bf16 v[84:87], v[204:207], v[180:183], v[84:87]
	v_mfma_f32_16x16x32_bf16 v[76:79], v[204:207], v[188:191], v[76:79]
	v_mfma_f32_16x16x32_bf16 v[76:79], v[208:211], v[192:195], v[76:79]
	v_mfma_f32_16x16x32_bf16 v[72:75], v[216:219], v[192:195], v[72:75]
	v_mfma_f32_16x16x32_bf16 v[72:75], v[212:215], v[188:191], v[72:75]
	v_mfma_f32_16x16x32_bf16 v[64:67], v[212:215], v[196:199], v[64:67]
	v_mfma_f32_16x16x32_bf16 v[64:67], v[216:219], v[200:203], v[64:67]
	v_mfma_f32_16x16x32_bf16 v[68:71], v[208:211], v[200:203], v[68:71]
	v_mfma_f32_16x16x32_bf16 v[68:71], v[204:207], v[196:199], v[68:71]
	s_barrier
	s_add_i32 s46, s39, s17
	s_add_i32 s47, s46, 0x100
	s_mov_b32 m0, s0
	ds_read_b128 v[172:175], v131 offset:16384
	ds_read_b128 v[176:179], v131 offset:17408
	ds_read_b128 v[180:183], v138 offset:16384
	ds_read_b128 v[184:187], v138 offset:17408
	ds_read_b128 v[188:191], v137 offset:16384
	ds_read_b128 v[192:195], v137 offset:17408
	ds_read_b128 v[196:199], v135 offset:16384
	ds_read_b128 v[200:203], v135 offset:17408
	buffer_load_dwordx4 v128, s[4:7], s47 offen lds
	s_mov_b32 m0, s19
	s_nop 0
	buffer_load_dwordx4 v132, s[4:7], s47 offen lds
	s_barrier
	s_waitcnt lgkmcnt(0)
	v_mfma_f32_16x16x32_bf16 v[60:63], v[156:159], v[172:175], v[60:63]
	v_mfma_f32_16x16x32_bf16 v[60:63], v[160:163], v[176:179], v[60:63]
	v_mfma_f32_16x16x32_bf16 v[56:59], v[168:171], v[176:179], v[56:59]
	v_mfma_f32_16x16x32_bf16 v[56:59], v[164:167], v[172:175], v[56:59]
	v_mfma_f32_16x16x32_bf16 v[48:51], v[164:167], v[180:183], v[48:51]
	v_mfma_f32_16x16x32_bf16 v[48:51], v[168:171], v[184:187], v[48:51]
	v_mfma_f32_16x16x32_bf16 v[52:55], v[160:163], v[184:187], v[52:55]
	v_mfma_f32_16x16x32_bf16 v[52:55], v[156:159], v[180:183], v[52:55]
	v_mfma_f32_16x16x32_bf16 v[44:47], v[156:159], v[188:191], v[44:47]
	v_mfma_f32_16x16x32_bf16 v[44:47], v[160:163], v[192:195], v[44:47]
	v_mfma_f32_16x16x32_bf16 v[40:43], v[168:171], v[192:195], v[40:43]
	v_mfma_f32_16x16x32_bf16 v[40:43], v[164:167], v[188:191], v[40:43]
	v_mfma_f32_16x16x32_bf16 v[32:35], v[164:167], v[196:199], v[32:35]
	v_mfma_f32_16x16x32_bf16 v[32:35], v[168:171], v[200:203], v[32:35]
	v_mfma_f32_16x16x32_bf16 v[36:39], v[160:163], v[200:203], v[36:39]
	v_mfma_f32_16x16x32_bf16 v[36:39], v[156:159], v[196:199], v[36:39]
	s_barrier
; #define STAGE(P, RS, SOFF, OFF, kt) do { const int _so = (SOFF) + (kt) * (BK * 2); \
;     _Pragma("unroll") for (int _i = 0; _i < 2; ++_i) { \
;       __builtin_amdgcn_raw_ptr_buffer_load_lds(RS, (__attribute__((address_space(3))) void*)((P) + wave * 1024 + _i * 8192), 16, OFF[_i], _so, 0, 0); } } while (0)
; #define LDA(dst, b, h) _Pragma("unroll") for (int m = 0; m < 4; ++m) _Pragma("unroll") for (int k = 0; k < 2; ++k) \
;     dst[m][k] = *reinterpret_cast<const bf16x8*>(SA(b, h) + lds_byte(wr * 64 + m * 16 + fr, k * 32 + fq * 8))
; #define LDB(dst, b, h) _Pragma("unroll") for (int n = 0; n < 2; ++n) _Pragma("unroll") for (int k = 0; k < 2; ++k) \
;     dst[n][k] = *reinterpret_cast<const bf16x8*>(SB(b, h) + lds_byte(wc * 32 + n * 16 + fr, k * 32 + fq * 8))
; #define WAIT_V(n) asm volatile("s_waitcnt vmcnt(" #n ")" ::: "memory")
; #define WAIT_L(n) asm volatile("s_waitcnt lgkmcnt(" #n ")" ::: "memory")
; #define BAR __builtin_amdgcn_s_barrier()
; #define SCHED __builtin_amdgcn_sched_barrier(0)
;     ...
;       STAGE(SB(0, 1), rsB, sB1, offB, t + 2);
;       WAIT_V(6); BAR; MMA(1, 1, At, B1); BAR;
;       LDB(B0, 1, 0); SCHED; LDA(At, 1, 0); STAGE(SA(0, 1), rsA, sA1, offA, t + 2);
;       WAIT_L(8); BAR; WAIT_L(0); MMA(0, 0, At, B0); BAR; SCHED;
;       LDB(B1, 1, 1); STAGE(SB(1, 0), rsB, sB0, offB, t + 3);
;       BAR; WAIT_L(0); MMA(0, 1, At, B1); BAR;
;       LDA(At, 1, 1); STAGE(SA(1, 0), rsA, sA0, offA, t + 3);
	s_add_i32 s47, s41, s17
	s_add_i32 s48, s47, 0x100
	s_mov_b32 m0, s20
	s_nop 0
	buffer_load_dwordx4 v130, s[8:11], s48 offen lds
	s_mov_b32 m0, s21
	s_nop 0
	buffer_load_dwordx4 v134, s[8:11], s48 offen lds
	s_waitcnt vmcnt(6)
	s_barrier
	v_mfma_f32_16x16x32_bf16 v[28:31], v[204:207], v[172:175], v[28:31]
	v_mfma_f32_16x16x32_bf16 v[28:31], v[208:211], v[176:179], v[28:31]
	v_mfma_f32_16x16x32_bf16 v[24:27], v[216:219], v[176:179], v[24:27]
	v_mfma_f32_16x16x32_bf16 v[24:27], v[212:215], v[172:175], v[24:27]
	v_mfma_f32_16x16x32_bf16 v[16:19], v[212:215], v[180:183], v[16:19]
	v_mfma_f32_16x16x32_bf16 v[16:19], v[216:219], v[184:187], v[16:19]
	v_mfma_f32_16x16x32_bf16 v[20:23], v[208:211], v[184:187], v[20:23]
	v_mfma_f32_16x16x32_bf16 v[20:23], v[204:207], v[180:183], v[20:23]
	v_mfma_f32_16x16x32_bf16 v[12:15], v[204:207], v[188:191], v[12:15]
	v_mfma_f32_16x16x32_bf16 v[12:15], v[208:211], v[192:195], v[12:15]
	v_mfma_f32_16x16x32_bf16 v[8:11], v[216:219], v[192:195], v[8:11]
	v_mfma_f32_16x16x32_bf16 v[8:11], v[212:215], v[188:191], v[8:11]
	v_mfma_f32_16x16x32_bf16 v[0:3], v[212:215], v[196:199], v[0:3]
	v_mfma_f32_16x16x32_bf16 v[0:3], v[216:219], v[200:203], v[0:3]
	v_mfma_f32_16x16x32_bf16 v[4:7], v[208:211], v[200:203], v[4:7]
	v_mfma_f32_16x16x32_bf16 v[4:7], v[204:207], v[196:199], v[4:7]
	s_barrier
	ds_read_b128 v[156:159], v143
	ds_read_b128 v[160:163], v144
	ds_read_b128 v[164:167], v145
	ds_read_b128 v[168:171], v146
	s_addk_i32 s44, 0x100
	s_mov_b32 m0, s22
	ds_read_b128 v[172:175], v131 offset:32768
	ds_read_b128 v[176:179], v131 offset:33792
	ds_read_b128 v[180:183], v138 offset:32768
	ds_read_b128 v[184:187], v138 offset:33792
	ds_read_b128 v[188:191], v137 offset:32768
	ds_read_b128 v[192:195], v137 offset:33792
	ds_read_b128 v[196:199], v135 offset:32768
	ds_read_b128 v[200:203], v135 offset:33792
	buffer_load_dwordx4 v128, s[4:7], s44 offen lds
	s_mov_b32 m0, s23
	s_nop 0
	buffer_load_dwordx4 v132, s[4:7], s44 offen lds
	s_waitcnt lgkmcnt(8)
	s_barrier
	s_waitcnt lgkmcnt(0)
	v_mfma_f32_16x16x32_bf16 v[124:127], v[156:159], v[172:175], v[124:127]
	v_mfma_f32_16x16x32_bf16 v[124:127], v[160:163], v[176:179], v[124:127]
	v_mfma_f32_16x16x32_bf16 v[120:123], v[168:171], v[176:179], v[120:123]
	v_mfma_f32_16x16x32_bf16 v[120:123], v[164:167], v[172:175], v[120:123]
	v_mfma_f32_16x16x32_bf16 v[112:115], v[164:167], v[180:183], v[112:115]
	v_mfma_f32_16x16x32_bf16 v[112:115], v[168:171], v[184:187], v[112:115]
	v_mfma_f32_16x16x32_bf16 v[116:119], v[160:163], v[184:187], v[116:119]
	v_mfma_f32_16x16x32_bf16 v[116:119], v[156:159], v[180:183], v[116:119]
	v_mfma_f32_16x16x32_bf16 v[108:111], v[156:159], v[188:191], v[108:111]
	v_mfma_f32_16x16x32_bf16 v[108:111], v[160:163], v[192:195], v[108:111]
	v_mfma_f32_16x16x32_bf16 v[104:107], v[168:171], v[192:195], v[104:107]
	v_mfma_f32_16x16x32_bf16 v[104:107], v[164:167], v[188:191], v[104:107]
	v_mfma_f32_16x16x32_bf16 v[96:99], v[164:167], v[196:199], v[96:99]
	v_mfma_f32_16x16x32_bf16 v[96:99], v[168:171], v[200:203], v[96:99]
	v_mfma_f32_16x16x32_bf16 v[100:103], v[160:163], v[200:203], v[100:103]
	v_mfma_f32_16x16x32_bf16 v[100:103], v[156:159], v[196:199], v[100:103]
	s_barrier
	s_addk_i32 s45, 0x180
	s_mov_b32 m0, s24
	ds_read_b128 v[204:207], v139
	ds_read_b128 v[208:211], v140
	ds_read_b128 v[212:215], v141
	ds_read_b128 v[216:219], v142
	buffer_load_dwordx4 v130, s[8:11], s45 offen lds
	s_mov_b32 m0, s25
	s_nop 0
	buffer_load_dwordx4 v134, s[8:11], s45 offen lds
	s_barrier
	s_waitcnt lgkmcnt(0)
	v_mfma_f32_16x16x32_bf16 v[92:95], v[204:207], v[172:175], v[92:95]
	v_mfma_f32_16x16x32_bf16 v[92:95], v[208:211], v[176:179], v[92:95]
	v_mfma_f32_16x16x32_bf16 v[88:91], v[216:219], v[176:179], v[88:91]
	v_mfma_f32_16x16x32_bf16 v[88:91], v[212:215], v[172:175], v[88:91]
	v_mfma_f32_16x16x32_bf16 v[80:83], v[212:215], v[180:183], v[80:83]
	v_mfma_f32_16x16x32_bf16 v[80:83], v[216:219], v[184:187], v[80:83]
	v_mfma_f32_16x16x32_bf16 v[84:87], v[208:211], v[184:187], v[84:87]
	v_mfma_f32_16x16x32_bf16 v[84:87], v[204:207], v[180:183], v[84:87]
	v_mfma_f32_16x16x32_bf16 v[76:79], v[204:207], v[188:191], v[76:79]
	v_mfma_f32_16x16x32_bf16 v[76:79], v[208:211], v[192:195], v[76:79]
	v_mfma_f32_16x16x32_bf16 v[72:75], v[216:219], v[192:195], v[72:75]
	v_mfma_f32_16x16x32_bf16 v[72:75], v[212:215], v[188:191], v[72:75]
	v_mfma_f32_16x16x32_bf16 v[64:67], v[212:215], v[196:199], v[64:67]
	v_mfma_f32_16x16x32_bf16 v[64:67], v[216:219], v[200:203], v[64:67]
	v_mfma_f32_16x16x32_bf16 v[68:71], v[208:211], v[200:203], v[68:71]
	v_mfma_f32_16x16x32_bf16 v[68:71], v[204:207], v[196:199], v[68:71]
	s_barrier
	s_addk_i32 s46, 0x180
	s_mov_b32 m0, s26
	ds_read_b128 v[172:175], v131 offset:49152
	ds_read_b128 v[176:179], v131 offset:50176
	ds_read_b128 v[180:183], v138 offset:49152
	ds_read_b128 v[184:187], v138 offset:50176
	ds_read_b128 v[188:191], v137 offset:49152
	ds_read_b128 v[192:195], v137 offset:50176
	ds_read_b128 v[196:199], v135 offset:49152
	ds_read_b128 v[200:203], v135 offset:50176
	buffer_load_dwordx4 v128, s[4:7], s46 offen lds
	s_mov_b32 m0, s27
	s_nop 0
	buffer_load_dwordx4 v132, s[4:7], s46 offen lds
	s_barrier
; #define STAGE(P, RS, SOFF, OFF, kt) do { const int _so = (SOFF) + (kt) * (BK * 2); \
;     _Pragma("unroll") for (int _i = 0; _i < 2; ++_i) { \
;       __builtin_amdgcn_raw_ptr_buffer_load_lds(RS, (__attribute__((address_space(3))) void*)((P) + wave * 1024 + _i * 8192), 16, OFF[_i], _so, 0, 0); } } while (0)
; #define LDA(dst, b, h) _Pragma("unroll") for (int m = 0; m < 4; ++m) _Pragma("unroll") for (int k = 0; k < 2; ++k) \
;     dst[m][k] = *reinterpret_cast<const bf16x8*>(SA(b, h) + lds_byte(wr * 64 + m * 16 + fr, k * 32 + fq * 8))
; #define LDB(dst, b, h) _Pragma("unroll") for (int n = 0; n < 2; ++n) _Pragma("unroll") for (int k = 0; k < 2; ++k) \
;     dst[n][k] = *reinterpret_cast<const bf16x8*>(SB(b, h) + lds_byte(wc * 32 + n * 16 + fr, k * 32 + fq * 8))
; #define WAIT_V(n) asm volatile("s_waitcnt vmcnt(" #n ")" ::: "memory")
; #define WAIT_L(n) asm volatile("s_waitcnt lgkmcnt(" #n ")" ::: "memory")
; #define BAR __builtin_amdgcn_s_barrier()
; #define SCHED __builtin_amdgcn_sched_barrier(0)
;     ...
;       BAR; WAIT_L(0); MMA(1, 0, At, B0); BAR; SCHED;
;       STAGE(SB(1, 1), rsB, sB1, offB, t + 3);
;       WAIT_V(6); BAR; MMA(1, 1, At, B1); BAR;
;     }
;     { LDB(B0, 0, 0); LDA(At, 0, 0); STAGE(SA(1, 1), rsA, sA1, offA, nt - 1);
;       BAR; WAIT_L(0); MMA(0, 0, At, B0); BAR;
;       LDB(B1, 0, 1); BAR; WAIT_L(0); MMA(0, 1, At, B1); BAR;
	s_waitcnt lgkmcnt(0)
	v_mfma_f32_16x16x32_bf16 v[60:63], v[156:159], v[172:175], v[60:63]
	v_mfma_f32_16x16x32_bf16 v[60:63], v[160:163], v[176:179], v[60:63]
	v_mfma_f32_16x16x32_bf16 v[56:59], v[168:171], v[176:179], v[56:59]
	v_mfma_f32_16x16x32_bf16 v[56:59], v[164:167], v[172:175], v[56:59]
	v_mfma_f32_16x16x32_bf16 v[48:51], v[164:167], v[180:183], v[48:51]
	v_mfma_f32_16x16x32_bf16 v[48:51], v[168:171], v[184:187], v[48:51]
	v_mfma_f32_16x16x32_bf16 v[52:55], v[160:163], v[184:187], v[52:55]
	v_mfma_f32_16x16x32_bf16 v[52:55], v[156:159], v[180:183], v[52:55]
	v_mfma_f32_16x16x32_bf16 v[44:47], v[156:159], v[188:191], v[44:47]
	v_mfma_f32_16x16x32_bf16 v[44:47], v[160:163], v[192:195], v[44:47]
	v_mfma_f32_16x16x32_bf16 v[40:43], v[168:171], v[192:195], v[40:43]
	v_mfma_f32_16x16x32_bf16 v[40:43], v[164:167], v[188:191], v[40:43]
	v_mfma_f32_16x16x32_bf16 v[32:35], v[164:167], v[196:199], v[32:35]
	v_mfma_f32_16x16x32_bf16 v[32:35], v[168:171], v[200:203], v[32:35]
	v_mfma_f32_16x16x32_bf16 v[36:39], v[160:163], v[200:203], v[36:39]
	v_mfma_f32_16x16x32_bf16 v[36:39], v[156:159], v[196:199], v[36:39]
	s_barrier
	s_addk_i32 s47, 0x180
	s_mov_b32 m0, s28
	s_nop 0
	buffer_load_dwordx4 v130, s[8:11], s47 offen lds
	s_mov_b32 m0, s29
	s_nop 0
	buffer_load_dwordx4 v134, s[8:11], s47 offen lds
	s_add_i32 s16, s16, 2
	s_addk_i32 s17, 0x100
	s_cmp_gt_u32 s16, 3
	s_cbranch_scc0 .LBB0_110
	s_waitcnt vmcnt(6)
	s_barrier
	v_mfma_f32_16x16x32_bf16 v[28:31], v[204:207], v[172:175], v[28:31]
	v_mfma_f32_16x16x32_bf16 v[28:31], v[208:211], v[176:179], v[28:31]
	v_mfma_f32_16x16x32_bf16 v[24:27], v[216:219], v[176:179], v[24:27]
	v_mfma_f32_16x16x32_bf16 v[24:27], v[212:215], v[172:175], v[24:27]
	v_mfma_f32_16x16x32_bf16 v[16:19], v[212:215], v[180:183], v[16:19]
	v_mfma_f32_16x16x32_bf16 v[16:19], v[216:219], v[184:187], v[16:19]
	v_mfma_f32_16x16x32_bf16 v[20:23], v[208:211], v[184:187], v[20:23]
	v_mfma_f32_16x16x32_bf16 v[20:23], v[204:207], v[180:183], v[20:23]
	v_mfma_f32_16x16x32_bf16 v[12:15], v[204:207], v[188:191], v[12:15]
	v_mfma_f32_16x16x32_bf16 v[12:15], v[208:211], v[192:195], v[12:15]
	v_mfma_f32_16x16x32_bf16 v[8:11], v[216:219], v[192:195], v[8:11]
	v_mfma_f32_16x16x32_bf16 v[8:11], v[212:215], v[188:191], v[8:11]
	v_mfma_f32_16x16x32_bf16 v[0:3], v[212:215], v[196:199], v[0:3]
	v_mfma_f32_16x16x32_bf16 v[0:3], v[216:219], v[200:203], v[0:3]
	v_mfma_f32_16x16x32_bf16 v[4:7], v[208:211], v[200:203], v[4:7]
	v_mfma_f32_16x16x32_bf16 v[4:7], v[204:207], v[196:199], v[4:7]
	s_barrier
	s_add_i32 s10, s38, 0x380
	s_mov_b32 m0, s31
	ds_read_b128 v[156:159], v151
	ds_read_b128 v[160:163], v152
	ds_read_b128 v[164:167], v153
	ds_read_b128 v[152:155], v154
	ds_read_b128 v[168:171], v131
	ds_read_b128 v[172:175], v131 offset:1024
	ds_read_b128 v[176:179], v138
	ds_read_b128 v[180:183], v138 offset:1024
	ds_read_b128 v[184:187], v137
	ds_read_b128 v[188:191], v137 offset:1024
	ds_read_b128 v[192:195], v135
	ds_read_b128 v[196:199], v135 offset:1024
	buffer_load_dwordx4 v128, s[4:7], s10 offen lds
	s_mov_b32 m0, s33
	s_nop 0
	buffer_load_dwordx4 v132, s[4:7], s10 offen lds
	s_barrier
	s_waitcnt lgkmcnt(0)
	v_mfma_f32_16x16x32_bf16 v[124:127], v[156:159], v[168:171], v[124:127]
	v_mfma_f32_16x16x32_bf16 v[124:127], v[160:163], v[172:175], v[124:127]
	v_mfma_f32_16x16x32_bf16 v[120:123], v[152:155], v[172:175], v[120:123]
	v_mfma_f32_16x16x32_bf16 v[120:123], v[164:167], v[168:171], v[120:123]
	v_mfma_f32_16x16x32_bf16 v[112:115], v[164:167], v[176:179], v[112:115]
	v_mfma_f32_16x16x32_bf16 v[112:115], v[152:155], v[180:183], v[112:115]
	v_mfma_f32_16x16x32_bf16 v[116:119], v[160:163], v[180:183], v[116:119]
	v_mfma_f32_16x16x32_bf16 v[116:119], v[156:159], v[176:179], v[116:119]
	v_mfma_f32_16x16x32_bf16 v[108:111], v[156:159], v[184:187], v[108:111]
	v_mfma_f32_16x16x32_bf16 v[108:111], v[160:163], v[188:191], v[108:111]
	v_mfma_f32_16x16x32_bf16 v[104:107], v[152:155], v[188:191], v[104:107]
	v_mfma_f32_16x16x32_bf16 v[104:107], v[164:167], v[184:187], v[104:107]
	v_mfma_f32_16x16x32_bf16 v[96:99], v[164:167], v[192:195], v[96:99]
	v_mfma_f32_16x16x32_bf16 v[96:99], v[152:155], v[196:199], v[96:99]
	v_mfma_f32_16x16x32_bf16 v[100:103], v[160:163], v[196:199], v[100:103]
	v_mfma_f32_16x16x32_bf16 v[100:103], v[156:159], v[192:195], v[100:103]
	s_barrier
	ds_read_b128 v[200:203], v147
	ds_read_b128 v[204:207], v148
	ds_read_b128 v[208:211], v149
	ds_read_b128 v[148:151], v150
	s_barrier
	s_waitcnt lgkmcnt(0)
	v_mfma_f32_16x16x32_bf16 v[92:95], v[200:203], v[168:171], v[92:95]
	v_mfma_f32_16x16x32_bf16 v[92:95], v[204:207], v[172:175], v[92:95]
	v_mfma_f32_16x16x32_bf16 v[88:91], v[148:151], v[172:175], v[88:91]
	v_mfma_f32_16x16x32_bf16 v[88:91], v[208:211], v[168:171], v[88:91]
	v_mfma_f32_16x16x32_bf16 v[80:83], v[208:211], v[176:179], v[80:83]
	v_mfma_f32_16x16x32_bf16 v[80:83], v[148:151], v[180:183], v[80:83]
	v_mfma_f32_16x16x32_bf16 v[84:87], v[204:207], v[180:183], v[84:87]
	v_mfma_f32_16x16x32_bf16 v[84:87], v[200:203], v[176:179], v[84:87]
	v_mfma_f32_16x16x32_bf16 v[76:79], v[200:203], v[184:187], v[76:79]
	v_mfma_f32_16x16x32_bf16 v[76:79], v[204:207], v[188:191], v[76:79]
	v_mfma_f32_16x16x32_bf16 v[72:75], v[148:151], v[188:191], v[72:75]
	v_mfma_f32_16x16x32_bf16 v[72:75], v[208:211], v[184:187], v[72:75]
	v_mfma_f32_16x16x32_bf16 v[64:67], v[208:211], v[192:195], v[64:67]
	v_mfma_f32_16x16x32_bf16 v[64:67], v[148:151], v[196:199], v[64:67]
	v_mfma_f32_16x16x32_bf16 v[68:71], v[204:207], v[196:199], v[68:71]
	v_mfma_f32_16x16x32_bf16 v[68:71], v[200:203], v[192:195], v[68:71]
	s_barrier
; #define LDA(dst, b, h) _Pragma("unroll") for (int m = 0; m < 4; ++m) _Pragma("unroll") for (int k = 0; k < 2; ++k) \
;     dst[m][k] = *reinterpret_cast<const bf16x8*>(SA(b, h) + lds_byte(wr * 64 + m * 16 + fr, k * 32 + fq * 8))
; #define LDB(dst, b, h) _Pragma("unroll") for (int n = 0; n < 2; ++n) _Pragma("unroll") for (int k = 0; k < 2; ++k) \
;     dst[n][k] = *reinterpret_cast<const bf16x8*>(SB(b, h) + lds_byte(wc * 32 + n * 16 + fr, k * 32 + fq * 8))
; #define WAIT_V(n) asm volatile("s_waitcnt vmcnt(" #n ")" ::: "memory")
; #define WAIT_L(n) asm volatile("s_waitcnt lgkmcnt(" #n ")" ::: "memory")
; #define BAR __builtin_amdgcn_s_barrier()
;     ...
;       LDA(At, 0, 1); WAIT_V(4); BAR; WAIT_L(0); MMA(1, 0, At, B0); MMA(1, 1, At, B1); BAR; }
;     { LDB(B0, 1, 0); LDA(At, 1, 0); WAIT_V(2); BAR; WAIT_L(0); MMA(0, 0, At, B0); BAR;
	ds_read_b128 v[168:171], v131 offset:16384
	ds_read_b128 v[172:175], v131 offset:17408
	ds_read_b128 v[176:179], v138 offset:16384
	ds_read_b128 v[180:183], v138 offset:17408
	ds_read_b128 v[184:187], v137 offset:16384
	ds_read_b128 v[188:191], v137 offset:17408
	ds_read_b128 v[192:195], v135 offset:16384
	ds_read_b128 v[196:199], v135 offset:17408
	s_waitcnt vmcnt(4)
	s_barrier
	s_waitcnt lgkmcnt(0)
	v_mfma_f32_16x16x32_bf16 v[60:63], v[156:159], v[168:171], v[60:63]
	v_mfma_f32_16x16x32_bf16 v[60:63], v[160:163], v[172:175], v[60:63]
	v_mfma_f32_16x16x32_bf16 v[56:59], v[152:155], v[172:175], v[56:59]
	v_mfma_f32_16x16x32_bf16 v[56:59], v[164:167], v[168:171], v[56:59]
	v_mfma_f32_16x16x32_bf16 v[48:51], v[164:167], v[176:179], v[48:51]
	v_mfma_f32_16x16x32_bf16 v[48:51], v[152:155], v[180:183], v[48:51]
	v_mfma_f32_16x16x32_bf16 v[52:55], v[160:163], v[180:183], v[52:55]
	v_mfma_f32_16x16x32_bf16 v[52:55], v[156:159], v[176:179], v[52:55]
	v_mfma_f32_16x16x32_bf16 v[44:47], v[156:159], v[184:187], v[44:47]
	v_mfma_f32_16x16x32_bf16 v[44:47], v[160:163], v[188:191], v[44:47]
	v_mfma_f32_16x16x32_bf16 v[40:43], v[152:155], v[188:191], v[40:43]
	v_mfma_f32_16x16x32_bf16 v[40:43], v[164:167], v[184:187], v[40:43]
	v_mfma_f32_16x16x32_bf16 v[32:35], v[164:167], v[192:195], v[32:35]
	v_mfma_f32_16x16x32_bf16 v[32:35], v[152:155], v[196:199], v[32:35]
	v_mfma_f32_16x16x32_bf16 v[36:39], v[160:163], v[196:199], v[36:39]
	v_mfma_f32_16x16x32_bf16 v[36:39], v[156:159], v[192:195], v[36:39]
	v_mfma_f32_16x16x32_bf16 v[4:7], v[200:203], v[192:195], v[4:7]
	v_mfma_f32_16x16x32_bf16 v[4:7], v[204:207], v[196:199], v[4:7]
	v_mfma_f32_16x16x32_bf16 v[28:31], v[204:207], v[172:175], v[28:31]
	v_mfma_f32_16x16x32_bf16 v[28:31], v[200:203], v[168:171], v[28:31]
	v_mfma_f32_16x16x32_bf16 v[24:27], v[208:211], v[168:171], v[24:27]
	v_mfma_f32_16x16x32_bf16 v[24:27], v[148:151], v[172:175], v[24:27]
	v_mfma_f32_16x16x32_bf16 v[16:19], v[148:151], v[180:183], v[16:19]
	v_mfma_f32_16x16x32_bf16 v[16:19], v[208:211], v[176:179], v[16:19]
	v_mfma_f32_16x16x32_bf16 v[20:23], v[200:203], v[176:179], v[20:23]
	v_mfma_f32_16x16x32_bf16 v[20:23], v[204:207], v[180:183], v[20:23]
	v_mfma_f32_16x16x32_bf16 v[12:15], v[204:207], v[188:191], v[12:15]
	v_mfma_f32_16x16x32_bf16 v[12:15], v[200:203], v[184:187], v[12:15]
	v_mfma_f32_16x16x32_bf16 v[8:11], v[208:211], v[184:187], v[8:11]
	v_mfma_f32_16x16x32_bf16 v[8:11], v[148:151], v[188:191], v[8:11]
	v_mfma_f32_16x16x32_bf16 v[0:3], v[148:151], v[196:199], v[0:3]
	v_mfma_f32_16x16x32_bf16 v[0:3], v[208:211], v[192:195], v[0:3]
	s_barrier
	ds_read_b128 v[148:151], v143
	ds_read_b128 v[152:155], v144
	ds_read_b128 v[156:159], v145
	ds_read_b128 v[144:147], v146
	ds_read_b128 v[160:163], v131 offset:32768
	ds_read_b128 v[164:167], v131 offset:33792
	ds_read_b128 v[168:171], v138 offset:32768
	ds_read_b128 v[172:175], v138 offset:33792
	ds_read_b128 v[176:179], v137 offset:32768
	ds_read_b128 v[180:183], v137 offset:33792
	ds_read_b128 v[184:187], v135 offset:32768
	ds_read_b128 v[188:191], v135 offset:33792
	s_waitcnt vmcnt(2)
	s_barrier
	s_waitcnt lgkmcnt(0)
	v_mfma_f32_16x16x32_bf16 v[124:127], v[148:151], v[160:163], v[124:127]
	v_mfma_f32_16x16x32_bf16 v[124:127], v[152:155], v[164:167], v[124:127]
	v_mfma_f32_16x16x32_bf16 v[120:123], v[144:147], v[164:167], v[120:123]
	v_mfma_f32_16x16x32_bf16 v[120:123], v[156:159], v[160:163], v[120:123]
	v_mfma_f32_16x16x32_bf16 v[112:115], v[156:159], v[168:171], v[112:115]
	v_mfma_f32_16x16x32_bf16 v[112:115], v[144:147], v[172:175], v[112:115]
	v_mfma_f32_16x16x32_bf16 v[116:119], v[152:155], v[172:175], v[116:119]
	v_mfma_f32_16x16x32_bf16 v[116:119], v[148:151], v[168:171], v[116:119]
	v_mfma_f32_16x16x32_bf16 v[108:111], v[148:151], v[176:179], v[108:111]
	v_mfma_f32_16x16x32_bf16 v[108:111], v[152:155], v[180:183], v[108:111]
	v_mfma_f32_16x16x32_bf16 v[104:107], v[144:147], v[180:183], v[104:107]
	v_mfma_f32_16x16x32_bf16 v[104:107], v[156:159], v[176:179], v[104:107]
	v_mfma_f32_16x16x32_bf16 v[96:99], v[156:159], v[184:187], v[96:99]
	v_mfma_f32_16x16x32_bf16 v[96:99], v[144:147], v[188:191], v[96:99]
	v_mfma_f32_16x16x32_bf16 v[100:103], v[152:155], v[188:191], v[100:103]
	v_mfma_f32_16x16x32_bf16 v[100:103], v[148:151], v[184:187], v[100:103]
	s_barrier
; #define LDA(dst, b, h) _Pragma("unroll") for (int m = 0; m < 4; ++m) _Pragma("unroll") for (int k = 0; k < 2; ++k) \
;     dst[m][k] = *reinterpret_cast<const bf16x8*>(SA(b, h) + lds_byte(wr * 64 + m * 16 + fr, k * 32 + fq * 8))
; #define LDB(dst, b, h) _Pragma("unroll") for (int n = 0; n < 2; ++n) _Pragma("unroll") for (int k = 0; k < 2; ++k) \
;     dst[n][k] = *reinterpret_cast<const bf16x8*>(SB(b, h) + lds_byte(wc * 32 + n * 16 + fr, k * 32 + fq * 8))
; #define WAIT_V(n) asm volatile("s_waitcnt vmcnt(" #n ")" ::: "memory")
; #define WAIT_L(n) asm volatile("s_waitcnt lgkmcnt(" #n ")" ::: "memory")
; #define BAR __builtin_amdgcn_s_barrier()
;     ...
;       LDB(B1, 1, 1); WAIT_V(0); BAR; WAIT_L(0); MMA(0, 1, At, B1); BAR;
;       LDA(At, 1, 1); BAR; WAIT_L(0); MMA(1, 0, At, B0); MMA(1, 1, At, B1); BAR; }
;     if (wr == 0) BAR;
	ds_read_b128 v[192:195], v139
	ds_read_b128 v[196:199], v140
	ds_read_b128 v[200:203], v141
	ds_read_b128 v[140:143], v142
	s_waitcnt vmcnt(0)
	s_barrier
	s_waitcnt lgkmcnt(0)
	v_mfma_f32_16x16x32_bf16 v[92:95], v[192:195], v[160:163], v[92:95]
	v_mfma_f32_16x16x32_bf16 v[92:95], v[196:199], v[164:167], v[92:95]
	v_mfma_f32_16x16x32_bf16 v[88:91], v[140:143], v[164:167], v[88:91]
	v_mfma_f32_16x16x32_bf16 v[88:91], v[200:203], v[160:163], v[88:91]
	v_mfma_f32_16x16x32_bf16 v[80:83], v[200:203], v[168:171], v[80:83]
	v_mfma_f32_16x16x32_bf16 v[80:83], v[140:143], v[172:175], v[80:83]
	v_mfma_f32_16x16x32_bf16 v[84:87], v[196:199], v[172:175], v[84:87]
	v_mfma_f32_16x16x32_bf16 v[84:87], v[192:195], v[168:171], v[84:87]
	v_mfma_f32_16x16x32_bf16 v[76:79], v[192:195], v[176:179], v[76:79]
	v_mfma_f32_16x16x32_bf16 v[76:79], v[196:199], v[180:183], v[76:79]
	v_mfma_f32_16x16x32_bf16 v[72:75], v[140:143], v[180:183], v[72:75]
	v_mfma_f32_16x16x32_bf16 v[72:75], v[200:203], v[176:179], v[72:75]
	v_mfma_f32_16x16x32_bf16 v[64:67], v[200:203], v[184:187], v[64:67]
	v_mfma_f32_16x16x32_bf16 v[64:67], v[140:143], v[188:191], v[64:67]
	v_mfma_f32_16x16x32_bf16 v[68:71], v[196:199], v[188:191], v[68:71]
	v_mfma_f32_16x16x32_bf16 v[68:71], v[192:195], v[184:187], v[68:71]
	s_barrier
	ds_read_b128 v[160:163], v131 offset:49152
	ds_read_b128 v[164:167], v131 offset:50176
	ds_read_b128 v[168:171], v138 offset:49152
	ds_read_b128 v[172:175], v138 offset:50176
	ds_read_b128 v[176:179], v137 offset:49152
	ds_read_b128 v[180:183], v137 offset:50176
	ds_read_b128 v[184:187], v135 offset:49152
	ds_read_b128 v[188:191], v135 offset:50176
	s_barrier
	s_waitcnt lgkmcnt(0)
	v_mfma_f32_16x16x32_bf16 v[60:63], v[148:151], v[160:163], v[60:63]
	v_mfma_f32_16x16x32_bf16 v[60:63], v[152:155], v[164:167], v[60:63]
	v_mfma_f32_16x16x32_bf16 v[56:59], v[144:147], v[164:167], v[56:59]
	v_mfma_f32_16x16x32_bf16 v[56:59], v[156:159], v[160:163], v[56:59]
	v_mfma_f32_16x16x32_bf16 v[48:51], v[156:159], v[168:171], v[48:51]
	v_mfma_f32_16x16x32_bf16 v[48:51], v[144:147], v[172:175], v[48:51]
	v_mfma_f32_16x16x32_bf16 v[52:55], v[152:155], v[172:175], v[52:55]
	v_mfma_f32_16x16x32_bf16 v[52:55], v[148:151], v[168:171], v[52:55]
	v_mfma_f32_16x16x32_bf16 v[44:47], v[148:151], v[176:179], v[44:47]
	v_mfma_f32_16x16x32_bf16 v[44:47], v[152:155], v[180:183], v[44:47]
	v_mfma_f32_16x16x32_bf16 v[40:43], v[144:147], v[180:183], v[40:43]
	v_mfma_f32_16x16x32_bf16 v[40:43], v[156:159], v[176:179], v[40:43]
	v_mfma_f32_16x16x32_bf16 v[32:35], v[156:159], v[184:187], v[32:35]
	v_mfma_f32_16x16x32_bf16 v[32:35], v[144:147], v[188:191], v[32:35]
	v_mfma_f32_16x16x32_bf16 v[36:39], v[152:155], v[188:191], v[36:39]
	v_mfma_f32_16x16x32_bf16 v[36:39], v[148:151], v[184:187], v[36:39]
	v_mfma_f32_16x16x32_bf16 v[4:7], v[192:195], v[184:187], v[4:7]
	v_mfma_f32_16x16x32_bf16 v[4:7], v[196:199], v[188:191], v[4:7]
	v_mfma_f32_16x16x32_bf16 v[28:31], v[196:199], v[164:167], v[28:31]
	v_mfma_f32_16x16x32_bf16 v[28:31], v[192:195], v[160:163], v[28:31]
	v_mfma_f32_16x16x32_bf16 v[24:27], v[200:203], v[160:163], v[24:27]
	v_mfma_f32_16x16x32_bf16 v[24:27], v[140:143], v[164:167], v[24:27]
	v_mfma_f32_16x16x32_bf16 v[16:19], v[140:143], v[172:175], v[16:19]
	v_mfma_f32_16x16x32_bf16 v[16:19], v[200:203], v[168:171], v[16:19]
	v_mfma_f32_16x16x32_bf16 v[20:23], v[192:195], v[168:171], v[20:23]
	v_mfma_f32_16x16x32_bf16 v[20:23], v[196:199], v[172:175], v[20:23]
	v_mfma_f32_16x16x32_bf16 v[12:15], v[196:199], v[180:183], v[12:15]
	v_mfma_f32_16x16x32_bf16 v[12:15], v[192:195], v[176:179], v[12:15]
	v_mfma_f32_16x16x32_bf16 v[8:11], v[200:203], v[176:179], v[8:11]
	v_mfma_f32_16x16x32_bf16 v[8:11], v[140:143], v[180:183], v[8:11]
	v_mfma_f32_16x16x32_bf16 v[0:3], v[140:143], v[188:191], v[0:3]
	v_mfma_f32_16x16x32_bf16 v[0:3], v[200:203], v[184:187], v[0:3]
	v_cmp_gt_u32_e32 vcc, s36, v136
	s_barrier
	s_and_saveexec_b64 s[10:11], vcc
	s_cbranch_execz .LBB0_113
	s_barrier

; #define STAGE(P, RS, SOFF, OFF, kt) do { const int _so = (SOFF) + (kt) * (BK * 2); \
;     _Pragma("unroll") for (int _i = 0; _i < 2; ++_i) { \
;       __builtin_amdgcn_raw_ptr_buffer_load_lds(RS, (__attribute__((address_space(3))) void*)((P) + wave * 1024 + _i * 8192), 16, OFF[_i], _so, 0, 0); } } while (0)
; #define LDA(dst, b, h) _Pragma("unroll") for (int m = 0; m < 4; ++m) _Pragma("unroll") for (int k = 0; k < 2; ++k) \
;     dst[m][k] = *reinterpret_cast<const bf16x8*>(SA(b, h) + lds_byte(wr * 64 + m * 16 + fr, k * 32 + fq * 8))
; #define LDB(dst, b, h) _Pragma("unroll") for (int n = 0; n < 2; ++n) _Pragma("unroll") for (int k = 0; k < 2; ++k) \
;     dst[n][k] = *reinterpret_cast<const bf16x8*>(SB(b, h) + lds_byte(wc * 32 + n * 16 + fr, k * 32 + fq * 8))
; #define WAIT_V(n) asm volatile("s_waitcnt vmcnt(" #n ")" ::: "memory")
; #define WAIT_L(n) asm volatile("s_waitcnt lgkmcnt(" #n ")" ::: "memory")
; #define BAR __builtin_amdgcn_s_barrier()
; #define SCHED __builtin_amdgcn_sched_barrier(0)
;     ...
;       LDB(B0, 0, 0); SCHED; LDA(At, 0, 0); STAGE(SA(1, 1), rsA, sA1, offA, t + 1);
;       WAIT_L(8); BAR; WAIT_L(0); MMA(0, 0, At, B0); BAR; SCHED;
;       LDB(B1, 0, 1); STAGE(SB(0, 0), rsB, sB0, offB, t + 2);
;       BAR; WAIT_L(0); MMA(0, 1, At, B1); BAR;
;       LDA(At, 0, 1); STAGE(SA(0, 0), rsA, sA0, offA, t + 2);
;       BAR; WAIT_L(0); MMA(1, 0, At, B0); BAR; SCHED;
;       STAGE(SB(0, 1), rsB, sB1, offB, t + 2);
;       WAIT_V(6); BAR; MMA(1, 1, At, B1); BAR;
;       LDB(B0, 1, 0); SCHED; LDA(At, 1, 0); STAGE(SA(0, 1), rsA, sA1, offA, t + 2);
;       WAIT_L(8); BAR; WAIT_L(0); MMA(0, 0, At, B0); BAR; SCHED;
;       LDB(B1, 1, 1); STAGE(SB(1, 0), rsB, sB0, offB, t + 3);
;       BAR; WAIT_L(0); MMA(0, 1, At, B1); BAR;
;       LDA(At, 1, 1); STAGE(SA(1, 0), rsA, sA0, offA, t + 3);
;       BAR; WAIT_L(0); MMA(1, 0, At, B0); BAR; SCHED;
;       STAGE(SB(1, 1), rsB, sB1, offB, t + 3);
;       WAIT_V(6); BAR; MMA(1, 1, At, B1); BAR;
.LBB0_148:
	s_waitcnt vmcnt(6)
	s_barrier
	v_mfma_f32_16x16x32_bf16 v[12:15], v[200:203], v[168:171], v[12:15]
	v_mfma_f32_16x16x32_bf16 v[12:15], v[204:207], v[172:175], v[12:15]
	v_mfma_f32_16x16x32_bf16 v[8:11], v[212:215], v[172:175], v[8:11]
	v_mfma_f32_16x16x32_bf16 v[8:11], v[208:211], v[168:171], v[8:11]
	v_mfma_f32_16x16x32_bf16 v[0:3], v[208:211], v[176:179], v[0:3]
	v_mfma_f32_16x16x32_bf16 v[0:3], v[212:215], v[180:183], v[0:3]
	v_mfma_f32_16x16x32_bf16 v[4:7], v[204:207], v[180:183], v[4:7]
	v_mfma_f32_16x16x32_bf16 v[4:7], v[200:203], v[176:179], v[4:7]
	v_mfma_f32_16x16x32_bf16 v[64:67], v[200:203], v[184:187], v[64:67]
	v_mfma_f32_16x16x32_bf16 v[64:67], v[204:207], v[188:191], v[64:67]
	v_mfma_f32_16x16x32_bf16 v[72:75], v[212:215], v[188:191], v[72:75]
	v_mfma_f32_16x16x32_bf16 v[72:75], v[208:211], v[184:187], v[72:75]
	v_mfma_f32_16x16x32_bf16 v[84:87], v[208:211], v[192:195], v[84:87]
	v_mfma_f32_16x16x32_bf16 v[84:87], v[212:215], v[196:199], v[84:87]
	v_mfma_f32_16x16x32_bf16 v[76:79], v[204:207], v[196:199], v[76:79]
	v_mfma_f32_16x16x32_bf16 v[76:79], v[200:203], v[192:195], v[76:79]
	s_barrier
.Lmy_rot_148:
	ds_read_b128 v[152:155], v147
	ds_read_b128 v[156:159], v148
	ds_read_b128 v[160:163], v149
	ds_read_b128 v[164:167], v150
	s_add_i32 s4, s82, s3
	s_add_i32 s5, s4, 0x80
	s_mov_b32 m0, s31
	ds_read_b128 v[168:171], v129
	ds_read_b128 v[172:175], v129 offset:1024
	ds_read_b128 v[176:179], v132
	ds_read_b128 v[180:183], v132 offset:1024
	ds_read_b128 v[184:187], v131
	ds_read_b128 v[188:191], v131 offset:1024
	ds_read_b128 v[192:195], v130
	ds_read_b128 v[196:199], v130 offset:1024
	buffer_load_dwordx4 v141, s[8:11], s5 offen lds
	s_mov_b32 m0, s58
	s_nop 0
	buffer_load_dwordx4 v142, s[8:11], s5 offen lds
	s_waitcnt lgkmcnt(8)
	s_barrier
	s_waitcnt lgkmcnt(0)
	v_mfma_f32_16x16x32_bf16 v[124:127], v[152:155], v[168:171], v[124:127]
	v_mfma_f32_16x16x32_bf16 v[124:127], v[156:159], v[172:175], v[124:127]
	v_mfma_f32_16x16x32_bf16 v[120:123], v[164:167], v[172:175], v[120:123]
	v_mfma_f32_16x16x32_bf16 v[120:123], v[160:163], v[168:171], v[120:123]
	v_mfma_f32_16x16x32_bf16 v[112:115], v[160:163], v[176:179], v[112:115]
	v_mfma_f32_16x16x32_bf16 v[112:115], v[164:167], v[180:183], v[112:115]
	v_mfma_f32_16x16x32_bf16 v[116:119], v[156:159], v[180:183], v[116:119]
	v_mfma_f32_16x16x32_bf16 v[116:119], v[152:155], v[176:179], v[116:119]
	v_mfma_f32_16x16x32_bf16 v[108:111], v[152:155], v[184:187], v[108:111]
	v_mfma_f32_16x16x32_bf16 v[108:111], v[156:159], v[188:191], v[108:111]
	v_mfma_f32_16x16x32_bf16 v[104:107], v[164:167], v[188:191], v[104:107]
	v_mfma_f32_16x16x32_bf16 v[104:107], v[160:163], v[184:187], v[104:107]
	v_mfma_f32_16x16x32_bf16 v[96:99], v[160:163], v[192:195], v[96:99]
	v_mfma_f32_16x16x32_bf16 v[96:99], v[164:167], v[196:199], v[96:99]
	v_mfma_f32_16x16x32_bf16 v[100:103], v[156:159], v[196:199], v[100:103]
	v_mfma_f32_16x16x32_bf16 v[100:103], v[152:155], v[192:195], v[100:103]
	s_barrier
	s_add_i32 s5, s84, s3
	s_add_i32 s6, s5, 0x100
	s_mov_b32 s14, s10
	s_mov_b32 s15, s11
	s_mov_b32 m0, s34
	ds_read_b128 v[200:203], v143
	ds_read_b128 v[204:207], v144
	ds_read_b128 v[208:211], v145
	ds_read_b128 v[212:215], v146
	buffer_load_dwordx4 v141, s[12:15], s6 offen lds
	s_mov_b32 m0, s43
	s_nop 0
	buffer_load_dwordx4 v142, s[12:15], s6 offen lds
	s_barrier
	s_waitcnt lgkmcnt(0)
	v_mfma_f32_16x16x32_bf16 v[92:95], v[200:203], v[168:171], v[92:95]
	v_mfma_f32_16x16x32_bf16 v[92:95], v[204:207], v[172:175], v[92:95]
	v_mfma_f32_16x16x32_bf16 v[88:91], v[212:215], v[172:175], v[88:91]
	v_mfma_f32_16x16x32_bf16 v[88:91], v[208:211], v[168:171], v[88:91]
	v_mfma_f32_16x16x32_bf16 v[68:71], v[208:211], v[176:179], v[68:71]
	v_mfma_f32_16x16x32_bf16 v[68:71], v[212:215], v[180:183], v[68:71]
	v_mfma_f32_16x16x32_bf16 v[80:83], v[204:207], v[180:183], v[80:83]
	v_mfma_f32_16x16x32_bf16 v[80:83], v[200:203], v[176:179], v[80:83]
	v_mfma_f32_16x16x32_bf16 v[60:63], v[200:203], v[184:187], v[60:63]
	v_mfma_f32_16x16x32_bf16 v[60:63], v[204:207], v[188:191], v[60:63]
	v_mfma_f32_16x16x32_bf16 v[56:59], v[212:215], v[188:191], v[56:59]
	v_mfma_f32_16x16x32_bf16 v[56:59], v[208:211], v[184:187], v[56:59]
	v_mfma_f32_16x16x32_bf16 v[48:51], v[208:211], v[192:195], v[48:51]
	v_mfma_f32_16x16x32_bf16 v[48:51], v[212:215], v[196:199], v[48:51]
	v_mfma_f32_16x16x32_bf16 v[52:55], v[204:207], v[196:199], v[52:55]
	v_mfma_f32_16x16x32_bf16 v[52:55], v[200:203], v[192:195], v[52:55]
	s_barrier
	s_add_i32 s6, s83, s3
	s_add_i32 s7, s6, 0x100
	s_mov_b32 m0, s30
	ds_read_b128 v[168:171], v129 offset:16384
	ds_read_b128 v[172:175], v129 offset:17408
	ds_read_b128 v[176:179], v132 offset:16384
	ds_read_b128 v[180:183], v132 offset:17408
	ds_read_b128 v[184:187], v131 offset:16384
	ds_read_b128 v[188:191], v131 offset:17408
	ds_read_b128 v[192:195], v130 offset:16384
	ds_read_b128 v[196:199], v130 offset:17408
	buffer_load_dwordx4 v141, s[8:11], s7 offen lds
	s_mov_b32 m0, s44
	s_nop 0
	buffer_load_dwordx4 v142, s[8:11], s7 offen lds
	s_barrier
	s_waitcnt lgkmcnt(0)
	v_mfma_f32_16x16x32_bf16 v[44:47], v[152:155], v[168:171], v[44:47]
	v_mfma_f32_16x16x32_bf16 v[44:47], v[156:159], v[172:175], v[44:47]
	v_mfma_f32_16x16x32_bf16 v[40:43], v[164:167], v[172:175], v[40:43]
	v_mfma_f32_16x16x32_bf16 v[40:43], v[160:163], v[168:171], v[40:43]
	v_mfma_f32_16x16x32_bf16 v[32:35], v[160:163], v[176:179], v[32:35]
	v_mfma_f32_16x16x32_bf16 v[32:35], v[164:167], v[180:183], v[32:35]
	v_mfma_f32_16x16x32_bf16 v[36:39], v[156:159], v[180:183], v[36:39]
	v_mfma_f32_16x16x32_bf16 v[36:39], v[152:155], v[176:179], v[36:39]
	v_mfma_f32_16x16x32_bf16 v[28:31], v[152:155], v[184:187], v[28:31]
	v_mfma_f32_16x16x32_bf16 v[28:31], v[156:159], v[188:191], v[28:31]
	v_mfma_f32_16x16x32_bf16 v[24:27], v[164:167], v[188:191], v[24:27]
	v_mfma_f32_16x16x32_bf16 v[24:27], v[160:163], v[184:187], v[24:27]
	v_mfma_f32_16x16x32_bf16 v[16:19], v[160:163], v[192:195], v[16:19]
	v_mfma_f32_16x16x32_bf16 v[16:19], v[164:167], v[196:199], v[16:19]
	v_mfma_f32_16x16x32_bf16 v[20:23], v[156:159], v[196:199], v[20:23]
	v_mfma_f32_16x16x32_bf16 v[20:23], v[152:155], v[192:195], v[20:23]
	s_barrier
; #define STAGE(P, RS, SOFF, OFF, kt) do { const int _so = (SOFF) + (kt) * (BK * 2); \
;     _Pragma("unroll") for (int _i = 0; _i < 2; ++_i) { \
;       __builtin_amdgcn_raw_ptr_buffer_load_lds(RS, (__attribute__((address_space(3))) void*)((P) + wave * 1024 + _i * 8192), 16, OFF[_i], _so, 0, 0); } } while (0)
; #define LDA(dst, b, h) _Pragma("unroll") for (int m = 0; m < 4; ++m) _Pragma("unroll") for (int k = 0; k < 2; ++k) \
;     dst[m][k] = *reinterpret_cast<const bf16x8*>(SA(b, h) + lds_byte(wr * 64 + m * 16 + fr, k * 32 + fq * 8))
; #define LDB(dst, b, h) _Pragma("unroll") for (int n = 0; n < 2; ++n) _Pragma("unroll") for (int k = 0; k < 2; ++k) \
;     dst[n][k] = *reinterpret_cast<const bf16x8*>(SB(b, h) + lds_byte(wc * 32 + n * 16 + fr, k * 32 + fq * 8))
; #define WAIT_V(n) asm volatile("s_waitcnt vmcnt(" #n ")" ::: "memory")
; #define WAIT_L(n) asm volatile("s_waitcnt lgkmcnt(" #n ")" ::: "memory")
; #define BAR __builtin_amdgcn_s_barrier()
; #define SCHED __builtin_amdgcn_sched_barrier(0)
;     ...
;       STAGE(SB(0, 1), rsB, sB1, offB, t + 2);
;       WAIT_V(6); BAR; MMA(1, 1, At, B1); BAR;
;       LDB(B0, 1, 0); SCHED; LDA(At, 1, 0); STAGE(SA(0, 1), rsA, sA1, offA, t + 2);
;       WAIT_L(8); BAR; WAIT_L(0); MMA(0, 0, At, B0); BAR; SCHED;
;       LDB(B1, 1, 1); STAGE(SB(1, 0), rsB, sB0, offB, t + 3);
;       BAR; WAIT_L(0); MMA(0, 1, At, B1); BAR;
;       LDA(At, 1, 1); STAGE(SA(1, 0), rsA, sA0, offA, t + 3);
	s_add_i32 s7, s85, s3
	s_add_i32 s19, s7, 0x100
	s_mov_b32 m0, s35
	s_nop 0
	buffer_load_dwordx4 v141, s[12:15], s19 offen lds
	s_mov_b32 m0, s45
	s_nop 0
	buffer_load_dwordx4 v142, s[12:15], s19 offen lds
	s_waitcnt vmcnt(6)
	s_barrier
	v_mfma_f32_16x16x32_bf16 v[12:15], v[200:203], v[168:171], v[12:15]
	v_mfma_f32_16x16x32_bf16 v[12:15], v[204:207], v[172:175], v[12:15]
	v_mfma_f32_16x16x32_bf16 v[8:11], v[212:215], v[172:175], v[8:11]
	v_mfma_f32_16x16x32_bf16 v[8:11], v[208:211], v[168:171], v[8:11]
	v_mfma_f32_16x16x32_bf16 v[0:3], v[208:211], v[176:179], v[0:3]
	v_mfma_f32_16x16x32_bf16 v[0:3], v[212:215], v[180:183], v[0:3]
	v_mfma_f32_16x16x32_bf16 v[4:7], v[204:207], v[180:183], v[4:7]
	v_mfma_f32_16x16x32_bf16 v[4:7], v[200:203], v[176:179], v[4:7]
	v_mfma_f32_16x16x32_bf16 v[64:67], v[200:203], v[184:187], v[64:67]
	v_mfma_f32_16x16x32_bf16 v[64:67], v[204:207], v[188:191], v[64:67]
	v_mfma_f32_16x16x32_bf16 v[72:75], v[212:215], v[188:191], v[72:75]
	v_mfma_f32_16x16x32_bf16 v[72:75], v[208:211], v[184:187], v[72:75]
	v_mfma_f32_16x16x32_bf16 v[84:87], v[208:211], v[192:195], v[84:87]
	v_mfma_f32_16x16x32_bf16 v[84:87], v[212:215], v[196:199], v[84:87]
	v_mfma_f32_16x16x32_bf16 v[76:79], v[204:207], v[196:199], v[76:79]
	v_mfma_f32_16x16x32_bf16 v[76:79], v[200:203], v[192:195], v[76:79]
	s_barrier
	ds_read_b128 v[152:155], v137
	ds_read_b128 v[156:159], v138
	ds_read_b128 v[160:163], v139
	ds_read_b128 v[164:167], v140
	s_addk_i32 s4, 0x100
	s_mov_b32 m0, s36
	ds_read_b128 v[168:171], v129 offset:32768
	ds_read_b128 v[172:175], v129 offset:33792
	ds_read_b128 v[176:179], v132 offset:32768
	ds_read_b128 v[180:183], v132 offset:33792
	ds_read_b128 v[184:187], v131 offset:32768
	ds_read_b128 v[188:191], v131 offset:33792
	ds_read_b128 v[192:195], v130 offset:32768
	ds_read_b128 v[196:199], v130 offset:33792
	buffer_load_dwordx4 v141, s[8:11], s4 offen lds
	s_mov_b32 m0, s48
	s_nop 0
	buffer_load_dwordx4 v142, s[8:11], s4 offen lds
	s_waitcnt lgkmcnt(8)
	s_barrier
	s_waitcnt lgkmcnt(0)
	v_mfma_f32_16x16x32_bf16 v[124:127], v[152:155], v[168:171], v[124:127]
	v_mfma_f32_16x16x32_bf16 v[124:127], v[156:159], v[172:175], v[124:127]
	v_mfma_f32_16x16x32_bf16 v[120:123], v[164:167], v[172:175], v[120:123]
	v_mfma_f32_16x16x32_bf16 v[120:123], v[160:163], v[168:171], v[120:123]
	v_mfma_f32_16x16x32_bf16 v[112:115], v[160:163], v[176:179], v[112:115]
	v_mfma_f32_16x16x32_bf16 v[112:115], v[164:167], v[180:183], v[112:115]
	v_mfma_f32_16x16x32_bf16 v[116:119], v[156:159], v[180:183], v[116:119]
	v_mfma_f32_16x16x32_bf16 v[116:119], v[152:155], v[176:179], v[116:119]
	v_mfma_f32_16x16x32_bf16 v[108:111], v[152:155], v[184:187], v[108:111]
	v_mfma_f32_16x16x32_bf16 v[108:111], v[156:159], v[188:191], v[108:111]
	v_mfma_f32_16x16x32_bf16 v[104:107], v[164:167], v[188:191], v[104:107]
	v_mfma_f32_16x16x32_bf16 v[104:107], v[160:163], v[184:187], v[104:107]
	v_mfma_f32_16x16x32_bf16 v[96:99], v[160:163], v[192:195], v[96:99]
	v_mfma_f32_16x16x32_bf16 v[96:99], v[164:167], v[196:199], v[96:99]
	v_mfma_f32_16x16x32_bf16 v[100:103], v[156:159], v[196:199], v[100:103]
	v_mfma_f32_16x16x32_bf16 v[100:103], v[152:155], v[192:195], v[100:103]
	s_barrier
	s_addk_i32 s5, 0x180
	s_mov_b32 m0, s37
	ds_read_b128 v[200:203], v133
	ds_read_b128 v[204:207], v134
	ds_read_b128 v[208:211], v135
	ds_read_b128 v[212:215], v136
	buffer_load_dwordx4 v141, s[12:15], s5 offen lds
	s_mov_b32 m0, s49
	s_nop 0
	buffer_load_dwordx4 v142, s[12:15], s5 offen lds
	s_barrier
	s_waitcnt lgkmcnt(0)
	v_mfma_f32_16x16x32_bf16 v[92:95], v[200:203], v[168:171], v[92:95]
	v_mfma_f32_16x16x32_bf16 v[92:95], v[204:207], v[172:175], v[92:95]
	v_mfma_f32_16x16x32_bf16 v[88:91], v[212:215], v[172:175], v[88:91]
	v_mfma_f32_16x16x32_bf16 v[88:91], v[208:211], v[168:171], v[88:91]
	v_mfma_f32_16x16x32_bf16 v[68:71], v[208:211], v[176:179], v[68:71]
	v_mfma_f32_16x16x32_bf16 v[68:71], v[212:215], v[180:183], v[68:71]
	v_mfma_f32_16x16x32_bf16 v[80:83], v[204:207], v[180:183], v[80:83]
	v_mfma_f32_16x16x32_bf16 v[80:83], v[200:203], v[176:179], v[80:83]
	v_mfma_f32_16x16x32_bf16 v[60:63], v[200:203], v[184:187], v[60:63]
	v_mfma_f32_16x16x32_bf16 v[60:63], v[204:207], v[188:191], v[60:63]
	v_mfma_f32_16x16x32_bf16 v[56:59], v[212:215], v[188:191], v[56:59]
	v_mfma_f32_16x16x32_bf16 v[56:59], v[208:211], v[184:187], v[56:59]
	v_mfma_f32_16x16x32_bf16 v[48:51], v[208:211], v[192:195], v[48:51]
	v_mfma_f32_16x16x32_bf16 v[48:51], v[212:215], v[196:199], v[48:51]
	v_mfma_f32_16x16x32_bf16 v[52:55], v[204:207], v[196:199], v[52:55]
	v_mfma_f32_16x16x32_bf16 v[52:55], v[200:203], v[192:195], v[52:55]
	s_barrier
	s_addk_i32 s6, 0x180
	s_mov_b32 m0, s38
	ds_read_b128 v[168:171], v129 offset:49152
	ds_read_b128 v[172:175], v129 offset:50176
	ds_read_b128 v[176:179], v132 offset:49152
	ds_read_b128 v[180:183], v132 offset:50176
	ds_read_b128 v[184:187], v131 offset:49152
	ds_read_b128 v[188:191], v131 offset:50176
	ds_read_b128 v[192:195], v130 offset:49152
	ds_read_b128 v[196:199], v130 offset:50176
	buffer_load_dwordx4 v141, s[8:11], s6 offen lds
	s_mov_b32 m0, s54
	s_nop 0
	buffer_load_dwordx4 v142, s[8:11], s6 offen lds
	s_barrier
; #define STAGE(P, RS, SOFF, OFF, kt) do { const int _so = (SOFF) + (kt) * (BK * 2); \
;     _Pragma("unroll") for (int _i = 0; _i < 2; ++_i) { \
;       __builtin_amdgcn_raw_ptr_buffer_load_lds(RS, (__attribute__((address_space(3))) void*)((P) + wave * 1024 + _i * 8192), 16, OFF[_i], _so, 0, 0); } } while (0)
; #define LDA(dst, b, h) _Pragma("unroll") for (int m = 0; m < 4; ++m) _Pragma("unroll") for (int k = 0; k < 2; ++k) \
;     dst[m][k] = *reinterpret_cast<const bf16x8*>(SA(b, h) + lds_byte(wr * 64 + m * 16 + fr, k * 32 + fq * 8))
; #define LDB(dst, b, h) _Pragma("unroll") for (int n = 0; n < 2; ++n) _Pragma("unroll") for (int k = 0; k < 2; ++k) \
;     dst[n][k] = *reinterpret_cast<const bf16x8*>(SB(b, h) + lds_byte(wc * 32 + n * 16 + fr, k * 32 + fq * 8))
; #define WAIT_V(n) asm volatile("s_waitcnt vmcnt(" #n ")" ::: "memory")
; #define WAIT_L(n) asm volatile("s_waitcnt lgkmcnt(" #n ")" ::: "memory")
; #define BAR __builtin_amdgcn_s_barrier()
; #define SCHED __builtin_amdgcn_sched_barrier(0)
;     ...
;       BAR; WAIT_L(0); MMA(1, 0, At, B0); BAR; SCHED;
;       STAGE(SB(1, 1), rsB, sB1, offB, t + 3);
;       WAIT_V(6); BAR; MMA(1, 1, At, B1); BAR;
;     }
;     { LDB(B0, 0, 0); LDA(At, 0, 0); STAGE(SA(1, 1), rsA, sA1, offA, nt - 1);
;       BAR; WAIT_L(0); MMA(0, 0, At, B0); BAR;
;       LDB(B1, 0, 1); BAR; WAIT_L(0); MMA(0, 1, At, B1); BAR;
;       LDA(At, 0, 1); WAIT_V(4); BAR; WAIT_L(0); MMA(1, 0, At, B0); MMA(1, 1, At, B1); BAR; }
	s_waitcnt lgkmcnt(0)
	v_mfma_f32_16x16x32_bf16 v[44:47], v[152:155], v[168:171], v[44:47]
	v_mfma_f32_16x16x32_bf16 v[44:47], v[156:159], v[172:175], v[44:47]
	v_mfma_f32_16x16x32_bf16 v[40:43], v[164:167], v[172:175], v[40:43]
	v_mfma_f32_16x16x32_bf16 v[40:43], v[160:163], v[168:171], v[40:43]
	v_mfma_f32_16x16x32_bf16 v[32:35], v[160:163], v[176:179], v[32:35]
	v_mfma_f32_16x16x32_bf16 v[32:35], v[164:167], v[180:183], v[32:35]
	v_mfma_f32_16x16x32_bf16 v[36:39], v[156:159], v[180:183], v[36:39]
	v_mfma_f32_16x16x32_bf16 v[36:39], v[152:155], v[176:179], v[36:39]
	v_mfma_f32_16x16x32_bf16 v[28:31], v[152:155], v[184:187], v[28:31]
	v_mfma_f32_16x16x32_bf16 v[28:31], v[156:159], v[188:191], v[28:31]
	v_mfma_f32_16x16x32_bf16 v[24:27], v[164:167], v[188:191], v[24:27]
	v_mfma_f32_16x16x32_bf16 v[24:27], v[160:163], v[184:187], v[24:27]
	v_mfma_f32_16x16x32_bf16 v[16:19], v[160:163], v[192:195], v[16:19]
	v_mfma_f32_16x16x32_bf16 v[16:19], v[164:167], v[196:199], v[16:19]
	v_mfma_f32_16x16x32_bf16 v[20:23], v[156:159], v[196:199], v[20:23]
	v_mfma_f32_16x16x32_bf16 v[20:23], v[152:155], v[192:195], v[20:23]
	s_barrier
	s_addk_i32 s7, 0x180
	s_mov_b32 m0, s39
	s_nop 0
	buffer_load_dwordx4 v141, s[12:15], s7 offen lds
	s_mov_b32 m0, s55
	s_nop 0
	buffer_load_dwordx4 v142, s[12:15], s7 offen lds
	s_add_i32 s1, s1, 2
	s_addk_i32 s3, 0x100
	s_cmp_gt_u32 s1, 59
	s_cbranch_scc0 .LBB0_148
	s_waitcnt vmcnt(6)
	s_barrier
	v_mfma_f32_16x16x32_bf16 v[12:15], v[200:203], v[168:171], v[12:15]
	v_mfma_f32_16x16x32_bf16 v[12:15], v[204:207], v[172:175], v[12:15]
	v_mfma_f32_16x16x32_bf16 v[8:11], v[212:215], v[172:175], v[8:11]
	v_mfma_f32_16x16x32_bf16 v[8:11], v[208:211], v[168:171], v[8:11]
	v_mfma_f32_16x16x32_bf16 v[0:3], v[208:211], v[176:179], v[0:3]
	v_mfma_f32_16x16x32_bf16 v[0:3], v[212:215], v[180:183], v[0:3]
	v_mfma_f32_16x16x32_bf16 v[4:7], v[204:207], v[180:183], v[4:7]
	v_mfma_f32_16x16x32_bf16 v[4:7], v[200:203], v[176:179], v[4:7]
	v_mfma_f32_16x16x32_bf16 v[64:67], v[200:203], v[184:187], v[64:67]
	v_mfma_f32_16x16x32_bf16 v[64:67], v[204:207], v[188:191], v[64:67]
	v_mfma_f32_16x16x32_bf16 v[72:75], v[212:215], v[188:191], v[72:75]
	v_mfma_f32_16x16x32_bf16 v[72:75], v[208:211], v[184:187], v[72:75]
	v_mfma_f32_16x16x32_bf16 v[84:87], v[208:211], v[192:195], v[84:87]
	v_mfma_f32_16x16x32_bf16 v[84:87], v[212:215], v[196:199], v[84:87]
	v_mfma_f32_16x16x32_bf16 v[76:79], v[204:207], v[196:199], v[76:79]
	v_mfma_f32_16x16x32_bf16 v[76:79], v[200:203], v[192:195], v[76:79]
	s_barrier
	s_add_i32 s1, s82, 0x1f80
	s_mov_b32 m0, s31
	ds_read_b128 v[152:155], v147
	ds_read_b128 v[156:159], v148
	ds_read_b128 v[160:163], v149
	ds_read_b128 v[148:151], v150
	ds_read_b128 v[164:167], v129
	ds_read_b128 v[168:171], v129 offset:1024
	ds_read_b128 v[172:175], v132
	ds_read_b128 v[176:179], v132 offset:1024
	ds_read_b128 v[180:183], v131
	ds_read_b128 v[184:187], v131 offset:1024
	ds_read_b128 v[188:191], v130
	ds_read_b128 v[192:195], v130 offset:1024
	buffer_load_dwordx4 v141, s[8:11], s1 offen lds
	s_mov_b32 m0, s58
	s_nop 0
	buffer_load_dwordx4 v142, s[8:11], s1 offen lds
	s_barrier
	s_waitcnt lgkmcnt(0)
	v_mfma_f32_16x16x32_bf16 v[124:127], v[152:155], v[164:167], v[124:127]
	v_mfma_f32_16x16x32_bf16 v[124:127], v[156:159], v[168:171], v[124:127]
	v_mfma_f32_16x16x32_bf16 v[120:123], v[148:151], v[168:171], v[120:123]
	v_mfma_f32_16x16x32_bf16 v[120:123], v[160:163], v[164:167], v[120:123]
	v_mfma_f32_16x16x32_bf16 v[112:115], v[160:163], v[172:175], v[112:115]
	v_mfma_f32_16x16x32_bf16 v[112:115], v[148:151], v[176:179], v[112:115]
	v_mfma_f32_16x16x32_bf16 v[116:119], v[156:159], v[176:179], v[116:119]
	v_mfma_f32_16x16x32_bf16 v[116:119], v[152:155], v[172:175], v[116:119]
	v_mfma_f32_16x16x32_bf16 v[108:111], v[152:155], v[180:183], v[108:111]
	v_mfma_f32_16x16x32_bf16 v[108:111], v[156:159], v[184:187], v[108:111]
	v_mfma_f32_16x16x32_bf16 v[104:107], v[148:151], v[184:187], v[104:107]
	v_mfma_f32_16x16x32_bf16 v[104:107], v[160:163], v[180:183], v[104:107]
	v_mfma_f32_16x16x32_bf16 v[96:99], v[160:163], v[188:191], v[96:99]
	v_mfma_f32_16x16x32_bf16 v[96:99], v[148:151], v[192:195], v[96:99]
	v_mfma_f32_16x16x32_bf16 v[100:103], v[156:159], v[192:195], v[100:103]
	v_mfma_f32_16x16x32_bf16 v[100:103], v[152:155], v[188:191], v[100:103]
	s_barrier
	ds_read_b128 v[196:199], v143
	ds_read_b128 v[200:203], v144
	ds_read_b128 v[142:145], v145
	ds_read_b128 v[204:207], v146
	s_barrier
	s_waitcnt lgkmcnt(0)
	v_mfma_f32_16x16x32_bf16 v[88:91], v[142:145], v[164:167], v[88:91]
	v_mfma_f32_16x16x32_bf16 v[80:83], v[196:199], v[172:175], v[80:83]
	v_mfma_f32_16x16x32_bf16 v[60:63], v[196:199], v[180:183], v[60:63]
	v_mfma_f32_16x16x32_bf16 v[56:59], v[142:145], v[180:183], v[56:59]
	v_mfma_f32_16x16x32_bf16 v[52:55], v[196:199], v[188:191], v[52:55]
	v_mfma_f32_16x16x32_bf16 v[48:51], v[142:145], v[188:191], v[48:51]
	v_mfma_f32_16x16x32_bf16 v[92:95], v[196:199], v[164:167], v[92:95]
	v_mfma_f32_16x16x32_bf16 v[68:71], v[142:145], v[172:175], v[68:71]
	v_mfma_f32_16x16x32_bf16 v[88:91], v[204:207], v[168:171], v[88:91]
	v_mfma_f32_16x16x32_bf16 v[80:83], v[200:203], v[176:179], v[80:83]
	v_mfma_f32_16x16x32_bf16 v[60:63], v[200:203], v[184:187], v[60:63]
	v_mfma_f32_16x16x32_bf16 v[56:59], v[204:207], v[184:187], v[56:59]
	v_mfma_f32_16x16x32_bf16 v[52:55], v[200:203], v[192:195], v[52:55]
	v_mfma_f32_16x16x32_bf16 v[48:51], v[204:207], v[192:195], v[48:51]
	v_mfma_f32_16x16x32_bf16 v[164:167], v[200:203], v[168:171], v[92:95]
	v_mfma_f32_16x16x32_bf16 v[168:171], v[204:207], v[176:179], v[68:71]
	s_barrier
; #define LDA(dst, b, h) _Pragma("unroll") for (int m = 0; m < 4; ++m) _Pragma("unroll") for (int k = 0; k < 2; ++k) \
;     dst[m][k] = *reinterpret_cast<const bf16x8*>(SA(b, h) + lds_byte(wr * 64 + m * 16 + fr, k * 32 + fq * 8))
; #define LDB(dst, b, h) _Pragma("unroll") for (int n = 0; n < 2; ++n) _Pragma("unroll") for (int k = 0; k < 2; ++k) \
;     dst[n][k] = *reinterpret_cast<const bf16x8*>(SB(b, h) + lds_byte(wc * 32 + n * 16 + fr, k * 32 + fq * 8))
; #define WAIT_V(n) asm volatile("s_waitcnt vmcnt(" #n ")" ::: "memory")
; #define WAIT_L(n) asm volatile("s_waitcnt lgkmcnt(" #n ")" ::: "memory")
; #define BAR __builtin_amdgcn_s_barrier()
;     ...
;       LDA(At, 0, 1); WAIT_V(4); BAR; WAIT_L(0); MMA(1, 0, At, B0); MMA(1, 1, At, B1); BAR; }
;     { LDB(B0, 1, 0); LDA(At, 1, 0); WAIT_V(2); BAR; WAIT_L(0); MMA(0, 0, At, B0); BAR;
	s_nop 0
	ds_read_b128 v[68:71], v129 offset:16384
	ds_read_b128 v[92:95], v129 offset:17408
	ds_read_b128 v[172:175], v132 offset:16384
	ds_read_b128 v[176:179], v132 offset:17408
	ds_read_b128 v[180:183], v131 offset:16384
	ds_read_b128 v[184:187], v131 offset:17408
	ds_read_b128 v[188:191], v130 offset:16384
	ds_read_b128 v[192:195], v130 offset:17408
	s_waitcnt vmcnt(4)
	s_barrier
	s_waitcnt lgkmcnt(0)
	v_mfma_f32_16x16x32_bf16 v[44:47], v[152:155], v[68:71], v[44:47]
	v_mfma_f32_16x16x32_bf16 v[40:43], v[160:163], v[68:71], v[40:43]
	v_mfma_f32_16x16x32_bf16 v[36:39], v[152:155], v[172:175], v[36:39]
	v_mfma_f32_16x16x32_bf16 v[32:35], v[160:163], v[172:175], v[32:35]
	v_mfma_f32_16x16x32_bf16 v[28:31], v[152:155], v[180:183], v[28:31]
	v_mfma_f32_16x16x32_bf16 v[24:27], v[160:163], v[180:183], v[24:27]
	v_mfma_f32_16x16x32_bf16 v[20:23], v[152:155], v[188:191], v[20:23]
	v_mfma_f32_16x16x32_bf16 v[16:19], v[160:163], v[188:191], v[16:19]
	v_mfma_f32_16x16x32_bf16 v[44:47], v[156:159], v[92:95], v[44:47]
	v_mfma_f32_16x16x32_bf16 v[40:43], v[148:151], v[92:95], v[40:43]
	v_mfma_f32_16x16x32_bf16 v[36:39], v[156:159], v[176:179], v[36:39]
	v_mfma_f32_16x16x32_bf16 v[32:35], v[148:151], v[176:179], v[32:35]
	v_mfma_f32_16x16x32_bf16 v[28:31], v[156:159], v[184:187], v[28:31]
	v_mfma_f32_16x16x32_bf16 v[24:27], v[148:151], v[184:187], v[24:27]
	v_mfma_f32_16x16x32_bf16 v[20:23], v[156:159], v[192:195], v[20:23]
	v_mfma_f32_16x16x32_bf16 v[16:19], v[148:151], v[192:195], v[16:19]
	v_mfma_f32_16x16x32_bf16 v[8:11], v[142:145], v[68:71], v[8:11]
	v_mfma_f32_16x16x32_bf16 v[0:3], v[142:145], v[172:175], v[0:3]
	v_mfma_f32_16x16x32_bf16 v[12:15], v[196:199], v[68:71], v[12:15]
	v_mfma_f32_16x16x32_bf16 v[4:7], v[196:199], v[172:175], v[4:7]
	v_mfma_f32_16x16x32_bf16 v[64:67], v[196:199], v[180:183], v[64:67]
	v_mfma_f32_16x16x32_bf16 v[68:71], v[142:145], v[180:183], v[72:75]
	v_mfma_f32_16x16x32_bf16 v[72:75], v[196:199], v[188:191], v[76:79]
	v_mfma_f32_16x16x32_bf16 v[76:79], v[142:145], v[188:191], v[84:87]
	v_mfma_f32_16x16x32_bf16 v[8:11], v[204:207], v[92:95], v[8:11]
	v_mfma_f32_16x16x32_bf16 v[0:3], v[204:207], v[176:179], v[0:3]
	v_mfma_f32_16x16x32_bf16 v[160:163], v[200:203], v[92:95], v[12:15]
	v_mfma_f32_16x16x32_bf16 v[172:175], v[200:203], v[176:179], v[4:7]
	v_mfma_f32_16x16x32_bf16 v[176:179], v[200:203], v[184:187], v[64:67]
	v_mfma_f32_16x16x32_bf16 v[180:183], v[204:207], v[184:187], v[68:71]
	v_mfma_f32_16x16x32_bf16 v[184:187], v[200:203], v[192:195], v[72:75]
	v_mfma_f32_16x16x32_bf16 v[188:191], v[204:207], v[192:195], v[76:79]
	s_barrier
	ds_read_b128 v[4:7], v137
	ds_read_b128 v[12:15], v138
	ds_read_b128 v[192:195], v139
	ds_read_b128 v[138:141], v140
	ds_read_b128 v[72:75], v129 offset:32768
	ds_read_b128 v[142:145], v129 offset:33792
	ds_read_b128 v[76:79], v132 offset:32768
	ds_read_b128 v[196:199], v132 offset:33792
	ds_read_b128 v[152:155], v131 offset:32768
	ds_read_b128 v[200:203], v131 offset:33792
	ds_read_b128 v[204:207], v130 offset:32768
	ds_read_b128 v[208:211], v130 offset:33792
	s_waitcnt vmcnt(2)
	s_barrier
	s_waitcnt lgkmcnt(0)
	v_mfma_f32_16x16x32_bf16 v[64:67], v[4:7], v[72:75], v[124:127]
	v_mfma_f32_16x16x32_bf16 v[84:87], v[192:195], v[72:75], v[120:123]
	v_mfma_f32_16x16x32_bf16 v[92:95], v[4:7], v[76:79], v[116:119]
	v_mfma_f32_16x16x32_bf16 v[112:115], v[192:195], v[76:79], v[112:115]
	v_mfma_f32_16x16x32_bf16 v[108:111], v[4:7], v[152:155], v[108:111]
	v_mfma_f32_16x16x32_bf16 v[104:107], v[192:195], v[152:155], v[104:107]
	v_mfma_f32_16x16x32_bf16 v[100:103], v[4:7], v[204:207], v[100:103]
	v_mfma_f32_16x16x32_bf16 v[96:99], v[192:195], v[204:207], v[96:99]
	v_mfma_f32_16x16x32_bf16 v[68:71], v[12:15], v[142:145], v[64:67]
	v_mfma_f32_16x16x32_bf16 v[64:67], v[138:141], v[142:145], v[84:87]
	v_mfma_f32_16x16x32_bf16 v[156:159], v[12:15], v[196:199], v[92:95]
	v_mfma_f32_16x16x32_bf16 v[148:151], v[138:141], v[196:199], v[112:115]
	v_mfma_f32_16x16x32_bf16 v[124:127], v[12:15], v[200:203], v[108:111]
	v_mfma_f32_16x16x32_bf16 v[116:119], v[138:141], v[200:203], v[104:107]
	v_mfma_f32_16x16x32_bf16 v[92:95], v[12:15], v[208:211], v[100:103]
	v_mfma_f32_16x16x32_bf16 v[84:87], v[138:141], v[208:211], v[96:99]
	s_barrier
; #define LDA(dst, b, h) _Pragma("unroll") for (int m = 0; m < 4; ++m) _Pragma("unroll") for (int k = 0; k < 2; ++k) \
;     dst[m][k] = *reinterpret_cast<const bf16x8*>(SA(b, h) + lds_byte(wr * 64 + m * 16 + fr, k * 32 + fq * 8))
; #define LDB(dst, b, h) _Pragma("unroll") for (int n = 0; n < 2; ++n) _Pragma("unroll") for (int k = 0; k < 2; ++k) \
;     dst[n][k] = *reinterpret_cast<const bf16x8*>(SB(b, h) + lds_byte(wc * 32 + n * 16 + fr, k * 32 + fq * 8))
; #define WAIT_V(n) asm volatile("s_waitcnt vmcnt(" #n ")" ::: "memory")
; #define WAIT_L(n) asm volatile("s_waitcnt lgkmcnt(" #n ")" ::: "memory")
; #define BAR __builtin_amdgcn_s_barrier()
;     ...
;       LDB(B1, 1, 1); WAIT_V(0); BAR; WAIT_L(0); MMA(0, 1, At, B1); BAR;
;       LDA(At, 1, 1); BAR; WAIT_L(0); MMA(1, 0, At, B0); MMA(1, 1, At, B1); BAR; }
;     if (wr == 0) BAR;
	s_nop 0
	ds_read_b128 v[96:99], v133
	ds_read_b128 v[100:103], v134
	ds_read_b128 v[104:107], v135
	ds_read_b128 v[108:111], v136
	s_waitcnt vmcnt(0)
	s_barrier
	s_waitcnt lgkmcnt(0)
	v_mfma_f32_16x16x32_bf16 v[112:115], v[96:99], v[72:75], v[164:167]
	v_mfma_f32_16x16x32_bf16 v[72:75], v[104:107], v[72:75], v[88:91]
	v_mfma_f32_16x16x32_bf16 v[80:83], v[96:99], v[76:79], v[80:83]
	v_mfma_f32_16x16x32_bf16 v[88:91], v[104:107], v[76:79], v[168:171]
	v_mfma_f32_16x16x32_bf16 v[60:63], v[96:99], v[152:155], v[60:63]
	v_mfma_f32_16x16x32_bf16 v[56:59], v[104:107], v[152:155], v[56:59]
	v_mfma_f32_16x16x32_bf16 v[52:55], v[96:99], v[204:207], v[52:55]
	v_mfma_f32_16x16x32_bf16 v[48:51], v[104:107], v[204:207], v[48:51]
	v_mfma_f32_16x16x32_bf16 v[76:79], v[100:103], v[142:145], v[112:115]
	v_mfma_f32_16x16x32_bf16 v[72:75], v[108:111], v[142:145], v[72:75]
	v_mfma_f32_16x16x32_bf16 v[152:155], v[100:103], v[196:199], v[80:83]
	v_mfma_f32_16x16x32_bf16 v[144:147], v[108:111], v[196:199], v[88:91]
	v_mfma_f32_16x16x32_bf16 v[120:123], v[100:103], v[200:203], v[60:63]
	v_mfma_f32_16x16x32_bf16 v[112:115], v[108:111], v[200:203], v[56:59]
	v_mfma_f32_16x16x32_bf16 v[88:91], v[100:103], v[208:211], v[52:55]
	v_mfma_f32_16x16x32_bf16 v[80:83], v[108:111], v[208:211], v[48:51]
	s_barrier
	s_nop 0
	ds_read_b128 v[48:51], v129 offset:49152
	ds_read_b128 v[134:137], v129 offset:50176
	ds_read_b128 v[56:59], v132 offset:49152
	ds_read_b128 v[164:167], v132 offset:50176
	ds_read_b128 v[168:171], v131 offset:49152
	ds_read_b128 v[196:199], v131 offset:50176
	ds_read_b128 v[200:203], v130 offset:49152
	ds_read_b128 v[130:133], v130 offset:50176
	s_barrier
	s_waitcnt lgkmcnt(0)
	v_mfma_f32_16x16x32_bf16 v[44:47], v[4:7], v[48:51], v[44:47]
	v_mfma_f32_16x16x32_bf16 v[40:43], v[192:195], v[48:51], v[40:43]
	v_mfma_f32_16x16x32_bf16 v[36:39], v[4:7], v[56:59], v[36:39]
	v_mfma_f32_16x16x32_bf16 v[32:35], v[192:195], v[56:59], v[32:35]
	v_mfma_f32_16x16x32_bf16 v[28:31], v[4:7], v[168:171], v[28:31]
	v_mfma_f32_16x16x32_bf16 v[24:27], v[192:195], v[168:171], v[24:27]
	v_mfma_f32_16x16x32_bf16 v[4:7], v[4:7], v[200:203], v[20:23]
	v_mfma_f32_16x16x32_bf16 v[16:19], v[192:195], v[200:203], v[16:19]
	v_mfma_f32_16x16x32_bf16 v[60:63], v[12:15], v[134:137], v[44:47]
	v_mfma_f32_16x16x32_bf16 v[52:55], v[138:141], v[134:137], v[40:43]
	v_mfma_f32_16x16x32_bf16 v[44:47], v[12:15], v[164:167], v[36:39]
	v_mfma_f32_16x16x32_bf16 v[36:39], v[138:141], v[164:167], v[32:35]
	v_mfma_f32_16x16x32_bf16 v[28:31], v[12:15], v[196:199], v[28:31]
	v_mfma_f32_16x16x32_bf16 v[20:23], v[138:141], v[196:199], v[24:27]
	v_mfma_f32_16x16x32_bf16 v[12:15], v[12:15], v[130:133], v[4:7]
	v_mfma_f32_16x16x32_bf16 v[4:7], v[138:141], v[130:133], v[16:19]
	v_mfma_f32_16x16x32_bf16 v[16:19], v[96:99], v[48:51], v[160:163]
	v_mfma_f32_16x16x32_bf16 v[8:11], v[104:107], v[48:51], v[8:11]
	v_mfma_f32_16x16x32_bf16 v[24:27], v[96:99], v[56:59], v[172:175]
	v_mfma_f32_16x16x32_bf16 v[0:3], v[104:107], v[56:59], v[0:3]
	v_mfma_f32_16x16x32_bf16 v[138:141], v[96:99], v[168:171], v[176:179]
	v_mfma_f32_16x16x32_bf16 v[160:163], v[104:107], v[168:171], v[180:183]
	v_mfma_f32_16x16x32_bf16 v[96:99], v[96:99], v[200:203], v[184:187]
	v_mfma_f32_16x16x32_bf16 v[104:107], v[104:107], v[200:203], v[188:191]
	v_mfma_f32_16x16x32_bf16 v[56:59], v[100:103], v[134:137], v[16:19]
	v_mfma_f32_16x16x32_bf16 v[48:51], v[108:111], v[134:137], v[8:11]
	v_mfma_f32_16x16x32_bf16 v[40:43], v[100:103], v[164:167], v[24:27]
	v_mfma_f32_16x16x32_bf16 v[32:35], v[108:111], v[164:167], v[0:3]
	v_mfma_f32_16x16x32_bf16 v[24:27], v[100:103], v[196:199], v[138:141]
	v_mfma_f32_16x16x32_bf16 v[16:19], v[108:111], v[196:199], v[160:163]
	v_mfma_f32_16x16x32_bf16 v[8:11], v[100:103], v[130:133], v[96:99]
	v_mfma_f32_16x16x32_bf16 v[0:3], v[108:111], v[130:133], v[104:107]
	v_cmp_gt_u32_e32 vcc, s60, v128
	s_barrier
	s_and_saveexec_b64 s[4:5], vcc
	s_cbranch_execz .LBB0_151
	s_barrier

; #define STAGE(P, RS, SOFF, OFF, kt) do { const int _so = (SOFF) + (kt) * (BK * 2); \
;     _Pragma("unroll") for (int _i = 0; _i < 2; ++_i) { \
;       __builtin_amdgcn_raw_ptr_buffer_load_lds(RS, (__attribute__((address_space(3))) void*)((P) + wave * 1024 + _i * 8192), 16, OFF[_i], _so, 0, 0); } } while (0)
; #define LDA(dst, b, h) _Pragma("unroll") for (int m = 0; m < 4; ++m) _Pragma("unroll") for (int k = 0; k < 2; ++k) \
;     dst[m][k] = *reinterpret_cast<const bf16x8*>(SA(b, h) + lds_byte(wr * 64 + m * 16 + fr, k * 32 + fq * 8))
; #define LDB(dst, b, h) _Pragma("unroll") for (int n = 0; n < 2; ++n) _Pragma("unroll") for (int k = 0; k < 2; ++k) \
;     dst[n][k] = *reinterpret_cast<const bf16x8*>(SB(b, h) + lds_byte(wc * 32 + n * 16 + fr, k * 32 + fq * 8))
; #define WAIT_V(n) asm volatile("s_waitcnt vmcnt(" #n ")" ::: "memory")
; #define WAIT_L(n) asm volatile("s_waitcnt lgkmcnt(" #n ")" ::: "memory")
; #define BAR __builtin_amdgcn_s_barrier()
; #define SCHED __builtin_amdgcn_sched_barrier(0)
;     ...
;     for (int t = 0; t < nt - 2; t += 2) {
;       LDB(B0, 0, 0); SCHED; LDA(At, 0, 0); STAGE(SA(1, 1), rsA, sA1, offA, t + 1);
;       WAIT_L(8); BAR; WAIT_L(0); MMA(0, 0, At, B0); BAR; SCHED;
;       LDB(B1, 0, 1); STAGE(SB(0, 0), rsB, sB0, offB, t + 2);
;       BAR; WAIT_L(0); MMA(0, 1, At, B1); BAR;
;       LDA(At, 0, 1); STAGE(SA(0, 0), rsA, sA0, offA, t + 2);
;       BAR; WAIT_L(0); MMA(1, 0, At, B0); BAR; SCHED;
;       STAGE(SB(0, 1), rsB, sB1, offB, t + 2);
;       WAIT_V(6); BAR; MMA(1, 1, At, B1); BAR;
.Lmy_rot_210:
	ds_read_b128 v[154:157], v149
	ds_read_b128 v[158:161], v150
	ds_read_b128 v[162:165], v151
	ds_read_b128 v[166:169], v152
	s_add_i32 s44, s38, s17
	s_add_i32 s10, s44, 0x80
	s_mov_b32 m0, s30
	ds_read_b128 v[170:173], v131
	ds_read_b128 v[174:177], v131 offset:1024
	ds_read_b128 v[178:181], v134
	ds_read_b128 v[182:185], v134 offset:1024
	ds_read_b128 v[186:189], v133
	ds_read_b128 v[190:193], v133 offset:1024
	ds_read_b128 v[194:197], v132
	ds_read_b128 v[198:201], v132 offset:1024
	buffer_load_dwordx4 v143, s[4:7], s10 offen lds
	s_mov_b32 m0, s31
	s_nop 0
	buffer_load_dwordx4 v144, s[4:7], s10 offen lds
	s_waitcnt lgkmcnt(8)
	s_barrier
	s_waitcnt lgkmcnt(0)
	v_mfma_f32_16x16x32_bf16 v[124:127], v[154:157], v[170:173], v[124:127]
	v_mfma_f32_16x16x32_bf16 v[124:127], v[158:161], v[174:177], v[124:127]
	v_mfma_f32_16x16x32_bf16 v[120:123], v[166:169], v[174:177], v[120:123]
	v_mfma_f32_16x16x32_bf16 v[120:123], v[162:165], v[170:173], v[120:123]
	v_mfma_f32_16x16x32_bf16 v[112:115], v[162:165], v[178:181], v[112:115]
	v_mfma_f32_16x16x32_bf16 v[112:115], v[166:169], v[182:185], v[112:115]
	v_mfma_f32_16x16x32_bf16 v[116:119], v[158:161], v[182:185], v[116:119]
	v_mfma_f32_16x16x32_bf16 v[116:119], v[154:157], v[178:181], v[116:119]
	v_mfma_f32_16x16x32_bf16 v[108:111], v[154:157], v[186:189], v[108:111]
	v_mfma_f32_16x16x32_bf16 v[108:111], v[158:161], v[190:193], v[108:111]
	v_mfma_f32_16x16x32_bf16 v[104:107], v[166:169], v[190:193], v[104:107]
	v_mfma_f32_16x16x32_bf16 v[104:107], v[162:165], v[186:189], v[104:107]
	v_mfma_f32_16x16x32_bf16 v[96:99], v[162:165], v[194:197], v[96:99]
	v_mfma_f32_16x16x32_bf16 v[96:99], v[166:169], v[198:201], v[96:99]
	v_mfma_f32_16x16x32_bf16 v[100:103], v[158:161], v[198:201], v[100:103]
	v_mfma_f32_16x16x32_bf16 v[100:103], v[154:157], v[194:197], v[100:103]
	s_barrier
	s_add_i32 s45, s40, s17
	s_add_i32 s46, s45, 0x100
	s_mov_b32 s10, s6
	s_mov_b32 s11, s7
	s_mov_b32 m0, s1
	ds_read_b128 v[202:205], v145
	ds_read_b128 v[206:209], v146
	ds_read_b128 v[210:213], v147
	ds_read_b128 v[214:217], v148
	buffer_load_dwordx4 v143, s[8:11], s46 offen lds
	s_mov_b32 m0, s3
	s_nop 0
	buffer_load_dwordx4 v144, s[8:11], s46 offen lds
	s_barrier
	s_waitcnt lgkmcnt(0)
	v_mfma_f32_16x16x32_bf16 v[92:95], v[202:205], v[170:173], v[92:95]
	v_mfma_f32_16x16x32_bf16 v[92:95], v[206:209], v[174:177], v[92:95]
	v_mfma_f32_16x16x32_bf16 v[88:91], v[214:217], v[174:177], v[88:91]
	v_mfma_f32_16x16x32_bf16 v[88:91], v[210:213], v[170:173], v[88:91]
	v_mfma_f32_16x16x32_bf16 v[80:83], v[210:213], v[178:181], v[80:83]
	v_mfma_f32_16x16x32_bf16 v[80:83], v[214:217], v[182:185], v[80:83]
	v_mfma_f32_16x16x32_bf16 v[84:87], v[206:209], v[182:185], v[84:87]
	v_mfma_f32_16x16x32_bf16 v[84:87], v[202:205], v[178:181], v[84:87]
	v_mfma_f32_16x16x32_bf16 v[76:79], v[202:205], v[186:189], v[76:79]
	v_mfma_f32_16x16x32_bf16 v[76:79], v[206:209], v[190:193], v[76:79]
	v_mfma_f32_16x16x32_bf16 v[72:75], v[214:217], v[190:193], v[72:75]
	v_mfma_f32_16x16x32_bf16 v[72:75], v[210:213], v[186:189], v[72:75]
	v_mfma_f32_16x16x32_bf16 v[64:67], v[210:213], v[194:197], v[64:67]
	v_mfma_f32_16x16x32_bf16 v[64:67], v[214:217], v[198:201], v[64:67]
	v_mfma_f32_16x16x32_bf16 v[68:71], v[206:209], v[198:201], v[68:71]
	v_mfma_f32_16x16x32_bf16 v[68:71], v[202:205], v[194:197], v[68:71]
	s_barrier
	s_add_i32 s46, s39, s17
	s_add_i32 s47, s46, 0x100
	s_mov_b32 m0, s0
	ds_read_b128 v[170:173], v131 offset:16384
	ds_read_b128 v[174:177], v131 offset:17408
	ds_read_b128 v[178:181], v134 offset:16384
	ds_read_b128 v[182:185], v134 offset:17408
	ds_read_b128 v[186:189], v133 offset:16384
	ds_read_b128 v[190:193], v133 offset:17408
	ds_read_b128 v[194:197], v132 offset:16384
	ds_read_b128 v[198:201], v132 offset:17408
	buffer_load_dwordx4 v143, s[4:7], s47 offen lds
	s_mov_b32 m0, s18
	s_nop 0
	buffer_load_dwordx4 v144, s[4:7], s47 offen lds
	s_barrier
	s_waitcnt lgkmcnt(0)
	v_mfma_f32_16x16x32_bf16 v[60:63], v[154:157], v[170:173], v[60:63]
	v_mfma_f32_16x16x32_bf16 v[60:63], v[158:161], v[174:177], v[60:63]
	v_mfma_f32_16x16x32_bf16 v[56:59], v[166:169], v[174:177], v[56:59]
	v_mfma_f32_16x16x32_bf16 v[56:59], v[162:165], v[170:173], v[56:59]
	v_mfma_f32_16x16x32_bf16 v[48:51], v[162:165], v[178:181], v[48:51]
	v_mfma_f32_16x16x32_bf16 v[48:51], v[166:169], v[182:185], v[48:51]
	v_mfma_f32_16x16x32_bf16 v[52:55], v[158:161], v[182:185], v[52:55]
	v_mfma_f32_16x16x32_bf16 v[52:55], v[154:157], v[178:181], v[52:55]
	v_mfma_f32_16x16x32_bf16 v[44:47], v[154:157], v[186:189], v[44:47]
	v_mfma_f32_16x16x32_bf16 v[44:47], v[158:161], v[190:193], v[44:47]
	v_mfma_f32_16x16x32_bf16 v[40:43], v[166:169], v[190:193], v[40:43]
	v_mfma_f32_16x16x32_bf16 v[40:43], v[162:165], v[186:189], v[40:43]
	v_mfma_f32_16x16x32_bf16 v[32:35], v[162:165], v[194:197], v[32:35]
	v_mfma_f32_16x16x32_bf16 v[32:35], v[166:169], v[198:201], v[32:35]
	v_mfma_f32_16x16x32_bf16 v[36:39], v[158:161], v[198:201], v[36:39]
	v_mfma_f32_16x16x32_bf16 v[36:39], v[154:157], v[194:197], v[36:39]
	s_barrier
	s_add_i32 s47, s41, s17
	s_add_i32 s48, s47, 0x100
	s_mov_b32 m0, s19
	s_nop 0
	buffer_load_dwordx4 v143, s[8:11], s48 offen lds
	s_mov_b32 m0, s20
	s_nop 0
	buffer_load_dwordx4 v144, s[8:11], s48 offen lds
	s_waitcnt vmcnt(6)
	s_barrier
; #define STAGE(P, RS, SOFF, OFF, kt) do { const int _so = (SOFF) + (kt) * (BK * 2); \
;     _Pragma("unroll") for (int _i = 0; _i < 2; ++_i) { \
;       __builtin_amdgcn_raw_ptr_buffer_load_lds(RS, (__attribute__((address_space(3))) void*)((P) + wave * 1024 + _i * 8192), 16, OFF[_i], _so, 0, 0); } } while (0)
; #define LDA(dst, b, h) _Pragma("unroll") for (int m = 0; m < 4; ++m) _Pragma("unroll") for (int k = 0; k < 2; ++k) \
;     dst[m][k] = *reinterpret_cast<const bf16x8*>(SA(b, h) + lds_byte(wr * 64 + m * 16 + fr, k * 32 + fq * 8))
; #define LDB(dst, b, h) _Pragma("unroll") for (int n = 0; n < 2; ++n) _Pragma("unroll") for (int k = 0; k < 2; ++k) \
;     dst[n][k] = *reinterpret_cast<const bf16x8*>(SB(b, h) + lds_byte(wc * 32 + n * 16 + fr, k * 32 + fq * 8))
; #define WAIT_V(n) asm volatile("s_waitcnt vmcnt(" #n ")" ::: "memory")
; #define WAIT_L(n) asm volatile("s_waitcnt lgkmcnt(" #n ")" ::: "memory")
; #define BAR __builtin_amdgcn_s_barrier()
; #define SCHED __builtin_amdgcn_sched_barrier(0)
;     ...
;       WAIT_V(6); BAR; MMA(1, 1, At, B1); BAR;
;       LDB(B0, 1, 0); SCHED; LDA(At, 1, 0); STAGE(SA(0, 1), rsA, sA1, offA, t + 2);
;       WAIT_L(8); BAR; WAIT_L(0); MMA(0, 0, At, B0); BAR; SCHED;
;       LDB(B1, 1, 1); STAGE(SB(1, 0), rsB, sB0, offB, t + 3);
;       BAR; WAIT_L(0); MMA(0, 1, At, B1); BAR;
;       LDA(At, 1, 1); STAGE(SA(1, 0), rsA, sA0, offA, t + 3);
;       BAR; WAIT_L(0); MMA(1, 0, At, B0); BAR; SCHED;
	v_mfma_f32_16x16x32_bf16 v[28:31], v[202:205], v[170:173], v[28:31]
	v_mfma_f32_16x16x32_bf16 v[28:31], v[206:209], v[174:177], v[28:31]
	v_mfma_f32_16x16x32_bf16 v[24:27], v[214:217], v[174:177], v[24:27]
	v_mfma_f32_16x16x32_bf16 v[24:27], v[210:213], v[170:173], v[24:27]
	v_mfma_f32_16x16x32_bf16 v[16:19], v[210:213], v[178:181], v[16:19]
	v_mfma_f32_16x16x32_bf16 v[16:19], v[214:217], v[182:185], v[16:19]
	v_mfma_f32_16x16x32_bf16 v[20:23], v[206:209], v[182:185], v[20:23]
	v_mfma_f32_16x16x32_bf16 v[20:23], v[202:205], v[178:181], v[20:23]
	v_mfma_f32_16x16x32_bf16 v[12:15], v[202:205], v[186:189], v[12:15]
	v_mfma_f32_16x16x32_bf16 v[12:15], v[206:209], v[190:193], v[12:15]
	v_mfma_f32_16x16x32_bf16 v[8:11], v[214:217], v[190:193], v[8:11]
	v_mfma_f32_16x16x32_bf16 v[8:11], v[210:213], v[186:189], v[8:11]
	v_mfma_f32_16x16x32_bf16 v[0:3], v[210:213], v[194:197], v[0:3]
	v_mfma_f32_16x16x32_bf16 v[0:3], v[214:217], v[198:201], v[0:3]
	v_mfma_f32_16x16x32_bf16 v[4:7], v[206:209], v[198:201], v[4:7]
	v_mfma_f32_16x16x32_bf16 v[4:7], v[202:205], v[194:197], v[4:7]
	s_barrier
	ds_read_b128 v[154:157], v139
	ds_read_b128 v[158:161], v140
	ds_read_b128 v[162:165], v141
	ds_read_b128 v[166:169], v142
	s_addk_i32 s44, 0x100
	s_mov_b32 m0, s21
	ds_read_b128 v[170:173], v131 offset:32768
	ds_read_b128 v[174:177], v131 offset:33792
	ds_read_b128 v[178:181], v134 offset:32768
	ds_read_b128 v[182:185], v134 offset:33792
	ds_read_b128 v[186:189], v133 offset:32768
	ds_read_b128 v[190:193], v133 offset:33792
	ds_read_b128 v[194:197], v132 offset:32768
	ds_read_b128 v[198:201], v132 offset:33792
	buffer_load_dwordx4 v143, s[4:7], s44 offen lds
	s_mov_b32 m0, s22
	s_nop 0
	buffer_load_dwordx4 v144, s[4:7], s44 offen lds
	s_waitcnt lgkmcnt(8)
	s_barrier
	s_waitcnt lgkmcnt(0)
	v_mfma_f32_16x16x32_bf16 v[124:127], v[154:157], v[170:173], v[124:127]
	v_mfma_f32_16x16x32_bf16 v[124:127], v[158:161], v[174:177], v[124:127]
	v_mfma_f32_16x16x32_bf16 v[120:123], v[166:169], v[174:177], v[120:123]
	v_mfma_f32_16x16x32_bf16 v[120:123], v[162:165], v[170:173], v[120:123]
	v_mfma_f32_16x16x32_bf16 v[112:115], v[162:165], v[178:181], v[112:115]
	v_mfma_f32_16x16x32_bf16 v[112:115], v[166:169], v[182:185], v[112:115]
	v_mfma_f32_16x16x32_bf16 v[116:119], v[158:161], v[182:185], v[116:119]
	v_mfma_f32_16x16x32_bf16 v[116:119], v[154:157], v[178:181], v[116:119]
	v_mfma_f32_16x16x32_bf16 v[108:111], v[154:157], v[186:189], v[108:111]
	v_mfma_f32_16x16x32_bf16 v[108:111], v[158:161], v[190:193], v[108:111]
	v_mfma_f32_16x16x32_bf16 v[104:107], v[166:169], v[190:193], v[104:107]
	v_mfma_f32_16x16x32_bf16 v[104:107], v[162:165], v[186:189], v[104:107]
	v_mfma_f32_16x16x32_bf16 v[96:99], v[162:165], v[194:197], v[96:99]
	v_mfma_f32_16x16x32_bf16 v[96:99], v[166:169], v[198:201], v[96:99]
	v_mfma_f32_16x16x32_bf16 v[100:103], v[158:161], v[198:201], v[100:103]
	v_mfma_f32_16x16x32_bf16 v[100:103], v[154:157], v[194:197], v[100:103]
	s_barrier
	s_addk_i32 s45, 0x180
	s_mov_b32 m0, s23
	ds_read_b128 v[202:205], v135
	ds_read_b128 v[206:209], v136
	ds_read_b128 v[210:213], v137
	ds_read_b128 v[214:217], v138
	buffer_load_dwordx4 v143, s[8:11], s45 offen lds
	s_mov_b32 m0, s24
	s_nop 0
	buffer_load_dwordx4 v144, s[8:11], s45 offen lds
	s_barrier
	s_waitcnt lgkmcnt(0)
	v_mfma_f32_16x16x32_bf16 v[92:95], v[202:205], v[170:173], v[92:95]
	v_mfma_f32_16x16x32_bf16 v[92:95], v[206:209], v[174:177], v[92:95]
	v_mfma_f32_16x16x32_bf16 v[88:91], v[214:217], v[174:177], v[88:91]
	v_mfma_f32_16x16x32_bf16 v[88:91], v[210:213], v[170:173], v[88:91]
	v_mfma_f32_16x16x32_bf16 v[80:83], v[210:213], v[178:181], v[80:83]
	v_mfma_f32_16x16x32_bf16 v[80:83], v[214:217], v[182:185], v[80:83]
	v_mfma_f32_16x16x32_bf16 v[84:87], v[206:209], v[182:185], v[84:87]
	v_mfma_f32_16x16x32_bf16 v[84:87], v[202:205], v[178:181], v[84:87]
	v_mfma_f32_16x16x32_bf16 v[76:79], v[202:205], v[186:189], v[76:79]
	v_mfma_f32_16x16x32_bf16 v[76:79], v[206:209], v[190:193], v[76:79]
	v_mfma_f32_16x16x32_bf16 v[72:75], v[214:217], v[190:193], v[72:75]
	v_mfma_f32_16x16x32_bf16 v[72:75], v[210:213], v[186:189], v[72:75]
	v_mfma_f32_16x16x32_bf16 v[64:67], v[210:213], v[194:197], v[64:67]
	v_mfma_f32_16x16x32_bf16 v[64:67], v[214:217], v[198:201], v[64:67]
	v_mfma_f32_16x16x32_bf16 v[68:71], v[206:209], v[198:201], v[68:71]
	v_mfma_f32_16x16x32_bf16 v[68:71], v[202:205], v[194:197], v[68:71]
	s_barrier
	s_addk_i32 s46, 0x180
	s_mov_b32 m0, s25
	ds_read_b128 v[170:173], v131 offset:49152
	ds_read_b128 v[174:177], v131 offset:50176
	ds_read_b128 v[178:181], v134 offset:49152
	ds_read_b128 v[182:185], v134 offset:50176
	ds_read_b128 v[186:189], v133 offset:49152
	ds_read_b128 v[190:193], v133 offset:50176
	ds_read_b128 v[194:197], v132 offset:49152
	ds_read_b128 v[198:201], v132 offset:50176
	buffer_load_dwordx4 v143, s[4:7], s46 offen lds
	s_mov_b32 m0, s26
	s_nop 0
	buffer_load_dwordx4 v144, s[4:7], s46 offen lds
	s_barrier
	s_waitcnt lgkmcnt(0)
	v_mfma_f32_16x16x32_bf16 v[60:63], v[154:157], v[170:173], v[60:63]
	v_mfma_f32_16x16x32_bf16 v[60:63], v[158:161], v[174:177], v[60:63]
	v_mfma_f32_16x16x32_bf16 v[56:59], v[166:169], v[174:177], v[56:59]
	v_mfma_f32_16x16x32_bf16 v[56:59], v[162:165], v[170:173], v[56:59]
	v_mfma_f32_16x16x32_bf16 v[48:51], v[162:165], v[178:181], v[48:51]
	v_mfma_f32_16x16x32_bf16 v[48:51], v[166:169], v[182:185], v[48:51]
	v_mfma_f32_16x16x32_bf16 v[52:55], v[158:161], v[182:185], v[52:55]
	v_mfma_f32_16x16x32_bf16 v[52:55], v[154:157], v[178:181], v[52:55]
	v_mfma_f32_16x16x32_bf16 v[44:47], v[154:157], v[186:189], v[44:47]
	v_mfma_f32_16x16x32_bf16 v[44:47], v[158:161], v[190:193], v[44:47]
	v_mfma_f32_16x16x32_bf16 v[40:43], v[166:169], v[190:193], v[40:43]
	v_mfma_f32_16x16x32_bf16 v[40:43], v[162:165], v[186:189], v[40:43]
	v_mfma_f32_16x16x32_bf16 v[32:35], v[162:165], v[194:197], v[32:35]
	v_mfma_f32_16x16x32_bf16 v[32:35], v[166:169], v[198:201], v[32:35]
	v_mfma_f32_16x16x32_bf16 v[36:39], v[158:161], v[198:201], v[36:39]
	v_mfma_f32_16x16x32_bf16 v[36:39], v[154:157], v[194:197], v[36:39]
	s_barrier
; #define STAGE(P, RS, SOFF, OFF, kt) do { const int _so = (SOFF) + (kt) * (BK * 2); \
;     _Pragma("unroll") for (int _i = 0; _i < 2; ++_i) { \
;       __builtin_amdgcn_raw_ptr_buffer_load_lds(RS, (__attribute__((address_space(3))) void*)((P) + wave * 1024 + _i * 8192), 16, OFF[_i], _so, 0, 0); } } while (0)
; #define LDA(dst, b, h) _Pragma("unroll") for (int m = 0; m < 4; ++m) _Pragma("unroll") for (int k = 0; k < 2; ++k) \
;     dst[m][k] = *reinterpret_cast<const bf16x8*>(SA(b, h) + lds_byte(wr * 64 + m * 16 + fr, k * 32 + fq * 8))
; #define LDB(dst, b, h) _Pragma("unroll") for (int n = 0; n < 2; ++n) _Pragma("unroll") for (int k = 0; k < 2; ++k) \
;     dst[n][k] = *reinterpret_cast<const bf16x8*>(SB(b, h) + lds_byte(wc * 32 + n * 16 + fr, k * 32 + fq * 8))
; #define WAIT_V(n) asm volatile("s_waitcnt vmcnt(" #n ")" ::: "memory")
; #define WAIT_L(n) asm volatile("s_waitcnt lgkmcnt(" #n ")" ::: "memory")
; #define BAR __builtin_amdgcn_s_barrier()
;     ...
;       STAGE(SB(1, 1), rsB, sB1, offB, t + 3);
;       WAIT_V(6); BAR; MMA(1, 1, At, B1); BAR;
;     }
;     { LDB(B0, 0, 0); LDA(At, 0, 0); STAGE(SA(1, 1), rsA, sA1, offA, nt - 1);
;       BAR; WAIT_L(0); MMA(0, 0, At, B0); BAR;
;       LDB(B1, 0, 1); BAR; WAIT_L(0); MMA(0, 1, At, B1); BAR;
;       LDA(At, 0, 1); WAIT_V(4); BAR; WAIT_L(0); MMA(1, 0, At, B0); MMA(1, 1, At, B1); BAR; }
	s_addk_i32 s47, 0x180
	s_mov_b32 m0, s27
	s_nop 0
	buffer_load_dwordx4 v143, s[8:11], s47 offen lds
	s_mov_b32 m0, s28
	s_nop 0
	buffer_load_dwordx4 v144, s[8:11], s47 offen lds
	s_add_i32 s16, s16, 2
	s_addk_i32 s17, 0x100
	s_cmp_gt_u32 s16, 27
	s_cbranch_scc0 .LBB0_210
	s_waitcnt vmcnt(6)
	s_barrier
	v_mfma_f32_16x16x32_bf16 v[28:31], v[202:205], v[170:173], v[28:31]
	v_mfma_f32_16x16x32_bf16 v[28:31], v[206:209], v[174:177], v[28:31]
	v_mfma_f32_16x16x32_bf16 v[24:27], v[214:217], v[174:177], v[24:27]
	v_mfma_f32_16x16x32_bf16 v[24:27], v[210:213], v[170:173], v[24:27]
	v_mfma_f32_16x16x32_bf16 v[16:19], v[210:213], v[178:181], v[16:19]
	v_mfma_f32_16x16x32_bf16 v[16:19], v[214:217], v[182:185], v[16:19]
	v_mfma_f32_16x16x32_bf16 v[20:23], v[206:209], v[182:185], v[20:23]
	v_mfma_f32_16x16x32_bf16 v[20:23], v[202:205], v[178:181], v[20:23]
	v_mfma_f32_16x16x32_bf16 v[12:15], v[202:205], v[186:189], v[12:15]
	v_mfma_f32_16x16x32_bf16 v[12:15], v[206:209], v[190:193], v[12:15]
	v_mfma_f32_16x16x32_bf16 v[8:11], v[214:217], v[190:193], v[8:11]
	v_mfma_f32_16x16x32_bf16 v[8:11], v[210:213], v[186:189], v[8:11]
	v_mfma_f32_16x16x32_bf16 v[0:3], v[210:213], v[194:197], v[0:3]
	v_mfma_f32_16x16x32_bf16 v[0:3], v[214:217], v[198:201], v[0:3]
	v_mfma_f32_16x16x32_bf16 v[4:7], v[206:209], v[198:201], v[4:7]
	v_mfma_f32_16x16x32_bf16 v[4:7], v[202:205], v[194:197], v[4:7]
	s_barrier
	s_add_i32 s10, s38, 0xf80
	s_mov_b32 m0, s30
	ds_read_b128 v[154:157], v149
	ds_read_b128 v[158:161], v150
	ds_read_b128 v[162:165], v151
	ds_read_b128 v[150:153], v152
	ds_read_b128 v[166:169], v131
	ds_read_b128 v[170:173], v131 offset:1024
	ds_read_b128 v[174:177], v134
	ds_read_b128 v[178:181], v134 offset:1024
	ds_read_b128 v[182:185], v133
	ds_read_b128 v[186:189], v133 offset:1024
	ds_read_b128 v[190:193], v132
	ds_read_b128 v[194:197], v132 offset:1024
	buffer_load_dwordx4 v143, s[4:7], s10 offen lds
	s_mov_b32 m0, s31
	s_nop 0
	buffer_load_dwordx4 v144, s[4:7], s10 offen lds
	s_barrier
	s_waitcnt lgkmcnt(0)
	v_mfma_f32_16x16x32_bf16 v[124:127], v[154:157], v[166:169], v[124:127]
	v_mfma_f32_16x16x32_bf16 v[124:127], v[158:161], v[170:173], v[124:127]
	v_mfma_f32_16x16x32_bf16 v[120:123], v[150:153], v[170:173], v[120:123]
	v_mfma_f32_16x16x32_bf16 v[120:123], v[162:165], v[166:169], v[120:123]
	v_mfma_f32_16x16x32_bf16 v[112:115], v[162:165], v[174:177], v[112:115]
	v_mfma_f32_16x16x32_bf16 v[112:115], v[150:153], v[178:181], v[112:115]
	v_mfma_f32_16x16x32_bf16 v[116:119], v[158:161], v[178:181], v[116:119]
	v_mfma_f32_16x16x32_bf16 v[116:119], v[154:157], v[174:177], v[116:119]
	v_mfma_f32_16x16x32_bf16 v[108:111], v[154:157], v[182:185], v[108:111]
	v_mfma_f32_16x16x32_bf16 v[108:111], v[158:161], v[186:189], v[108:111]
	v_mfma_f32_16x16x32_bf16 v[104:107], v[150:153], v[186:189], v[104:107]
	v_mfma_f32_16x16x32_bf16 v[104:107], v[162:165], v[182:185], v[104:107]
	v_mfma_f32_16x16x32_bf16 v[96:99], v[162:165], v[190:193], v[96:99]
	v_mfma_f32_16x16x32_bf16 v[96:99], v[150:153], v[194:197], v[96:99]
	v_mfma_f32_16x16x32_bf16 v[100:103], v[158:161], v[194:197], v[100:103]
	v_mfma_f32_16x16x32_bf16 v[100:103], v[154:157], v[190:193], v[100:103]
	s_barrier
	ds_read_b128 v[198:201], v145
	ds_read_b128 v[202:205], v146
	ds_read_b128 v[144:147], v147
	ds_read_b128 v[206:209], v148
	s_barrier
	s_waitcnt lgkmcnt(0)
	v_mfma_f32_16x16x32_bf16 v[92:95], v[198:201], v[166:169], v[92:95]
	v_mfma_f32_16x16x32_bf16 v[92:95], v[202:205], v[170:173], v[92:95]
	v_mfma_f32_16x16x32_bf16 v[88:91], v[206:209], v[170:173], v[88:91]
	v_mfma_f32_16x16x32_bf16 v[88:91], v[144:147], v[166:169], v[88:91]
	v_mfma_f32_16x16x32_bf16 v[80:83], v[144:147], v[174:177], v[80:83]
	v_mfma_f32_16x16x32_bf16 v[80:83], v[206:209], v[178:181], v[80:83]
	v_mfma_f32_16x16x32_bf16 v[84:87], v[202:205], v[178:181], v[84:87]
	v_mfma_f32_16x16x32_bf16 v[84:87], v[198:201], v[174:177], v[84:87]
	v_mfma_f32_16x16x32_bf16 v[76:79], v[198:201], v[182:185], v[76:79]
	v_mfma_f32_16x16x32_bf16 v[76:79], v[202:205], v[186:189], v[76:79]
	v_mfma_f32_16x16x32_bf16 v[72:75], v[206:209], v[186:189], v[72:75]
	v_mfma_f32_16x16x32_bf16 v[72:75], v[144:147], v[182:185], v[72:75]
	v_mfma_f32_16x16x32_bf16 v[64:67], v[144:147], v[190:193], v[64:67]
	v_mfma_f32_16x16x32_bf16 v[64:67], v[206:209], v[194:197], v[64:67]
	v_mfma_f32_16x16x32_bf16 v[68:71], v[202:205], v[194:197], v[68:71]
	v_mfma_f32_16x16x32_bf16 v[68:71], v[198:201], v[190:193], v[68:71]
	s_barrier
	ds_read_b128 v[166:169], v131 offset:16384
	ds_read_b128 v[170:173], v131 offset:17408
	ds_read_b128 v[174:177], v134 offset:16384
	ds_read_b128 v[178:181], v134 offset:17408
	ds_read_b128 v[182:185], v133 offset:16384
	ds_read_b128 v[186:189], v133 offset:17408
	ds_read_b128 v[190:193], v132 offset:16384
	ds_read_b128 v[194:197], v132 offset:17408
	s_waitcnt vmcnt(4)
	s_barrier
; #define LDA(dst, b, h) _Pragma("unroll") for (int m = 0; m < 4; ++m) _Pragma("unroll") for (int k = 0; k < 2; ++k) \
;     dst[m][k] = *reinterpret_cast<const bf16x8*>(SA(b, h) + lds_byte(wr * 64 + m * 16 + fr, k * 32 + fq * 8))
; #define LDB(dst, b, h) _Pragma("unroll") for (int n = 0; n < 2; ++n) _Pragma("unroll") for (int k = 0; k < 2; ++k) \
;     dst[n][k] = *reinterpret_cast<const bf16x8*>(SB(b, h) + lds_byte(wc * 32 + n * 16 + fr, k * 32 + fq * 8))
; #define WAIT_V(n) asm volatile("s_waitcnt vmcnt(" #n ")" ::: "memory")
; #define WAIT_L(n) asm volatile("s_waitcnt lgkmcnt(" #n ")" ::: "memory")
; #define BAR __builtin_amdgcn_s_barrier()
;     ...
;       LDA(At, 0, 1); WAIT_V(4); BAR; WAIT_L(0); MMA(1, 0, At, B0); MMA(1, 1, At, B1); BAR; }
;     { LDB(B0, 1, 0); LDA(At, 1, 0); WAIT_V(2); BAR; WAIT_L(0); MMA(0, 0, At, B0); BAR;
	s_waitcnt lgkmcnt(0)
	v_mfma_f32_16x16x32_bf16 v[60:63], v[154:157], v[166:169], v[60:63]
	v_mfma_f32_16x16x32_bf16 v[60:63], v[158:161], v[170:173], v[60:63]
	v_mfma_f32_16x16x32_bf16 v[56:59], v[150:153], v[170:173], v[56:59]
	v_mfma_f32_16x16x32_bf16 v[56:59], v[162:165], v[166:169], v[56:59]
	v_mfma_f32_16x16x32_bf16 v[48:51], v[162:165], v[174:177], v[48:51]
	v_mfma_f32_16x16x32_bf16 v[48:51], v[150:153], v[178:181], v[48:51]
	v_mfma_f32_16x16x32_bf16 v[52:55], v[158:161], v[178:181], v[52:55]
	v_mfma_f32_16x16x32_bf16 v[52:55], v[154:157], v[174:177], v[52:55]
	v_mfma_f32_16x16x32_bf16 v[44:47], v[154:157], v[182:185], v[44:47]
	v_mfma_f32_16x16x32_bf16 v[44:47], v[158:161], v[186:189], v[44:47]
	v_mfma_f32_16x16x32_bf16 v[40:43], v[150:153], v[186:189], v[40:43]
	v_mfma_f32_16x16x32_bf16 v[40:43], v[162:165], v[182:185], v[40:43]
	v_mfma_f32_16x16x32_bf16 v[32:35], v[162:165], v[190:193], v[32:35]
	v_mfma_f32_16x16x32_bf16 v[32:35], v[150:153], v[194:197], v[32:35]
	v_mfma_f32_16x16x32_bf16 v[36:39], v[158:161], v[194:197], v[36:39]
	v_mfma_f32_16x16x32_bf16 v[36:39], v[154:157], v[190:193], v[36:39]
	v_mfma_f32_16x16x32_bf16 v[4:7], v[198:201], v[190:193], v[4:7]
	v_mfma_f32_16x16x32_bf16 v[4:7], v[202:205], v[194:197], v[4:7]
	v_mfma_f32_16x16x32_bf16 v[28:31], v[202:205], v[170:173], v[28:31]
	v_mfma_f32_16x16x32_bf16 v[28:31], v[198:201], v[166:169], v[28:31]
	v_mfma_f32_16x16x32_bf16 v[24:27], v[144:147], v[166:169], v[24:27]
	v_mfma_f32_16x16x32_bf16 v[24:27], v[206:209], v[170:173], v[24:27]
	v_mfma_f32_16x16x32_bf16 v[16:19], v[206:209], v[178:181], v[16:19]
	v_mfma_f32_16x16x32_bf16 v[16:19], v[144:147], v[174:177], v[16:19]
	v_mfma_f32_16x16x32_bf16 v[20:23], v[198:201], v[174:177], v[20:23]
	v_mfma_f32_16x16x32_bf16 v[20:23], v[202:205], v[178:181], v[20:23]
	v_mfma_f32_16x16x32_bf16 v[12:15], v[202:205], v[186:189], v[12:15]
	v_mfma_f32_16x16x32_bf16 v[12:15], v[198:201], v[182:185], v[12:15]
	v_mfma_f32_16x16x32_bf16 v[8:11], v[144:147], v[182:185], v[8:11]
	v_mfma_f32_16x16x32_bf16 v[8:11], v[206:209], v[186:189], v[8:11]
	v_mfma_f32_16x16x32_bf16 v[0:3], v[206:209], v[194:197], v[0:3]
	v_mfma_f32_16x16x32_bf16 v[0:3], v[144:147], v[190:193], v[0:3]
	s_barrier
	ds_read_b128 v[144:147], v139
	ds_read_b128 v[148:151], v140
	ds_read_b128 v[152:155], v141
	ds_read_b128 v[140:143], v142
	ds_read_b128 v[156:159], v131 offset:32768
	ds_read_b128 v[160:163], v131 offset:33792
	ds_read_b128 v[164:167], v134 offset:32768
	ds_read_b128 v[168:171], v134 offset:33792
	ds_read_b128 v[172:175], v133 offset:32768
	ds_read_b128 v[176:179], v133 offset:33792
	ds_read_b128 v[180:183], v132 offset:32768
	ds_read_b128 v[184:187], v132 offset:33792
	s_waitcnt vmcnt(2)
	s_barrier
	s_waitcnt lgkmcnt(0)
	v_mfma_f32_16x16x32_bf16 v[124:127], v[144:147], v[156:159], v[124:127]
	v_mfma_f32_16x16x32_bf16 v[124:127], v[148:151], v[160:163], v[124:127]
	v_mfma_f32_16x16x32_bf16 v[120:123], v[140:143], v[160:163], v[120:123]
	v_mfma_f32_16x16x32_bf16 v[120:123], v[152:155], v[156:159], v[120:123]
	v_mfma_f32_16x16x32_bf16 v[112:115], v[152:155], v[164:167], v[112:115]
	v_mfma_f32_16x16x32_bf16 v[112:115], v[140:143], v[168:171], v[112:115]
	v_mfma_f32_16x16x32_bf16 v[116:119], v[148:151], v[168:171], v[116:119]
	v_mfma_f32_16x16x32_bf16 v[116:119], v[144:147], v[164:167], v[116:119]
	v_mfma_f32_16x16x32_bf16 v[108:111], v[144:147], v[172:175], v[108:111]
	v_mfma_f32_16x16x32_bf16 v[108:111], v[148:151], v[176:179], v[108:111]
	v_mfma_f32_16x16x32_bf16 v[104:107], v[140:143], v[176:179], v[104:107]
	v_mfma_f32_16x16x32_bf16 v[104:107], v[152:155], v[172:175], v[104:107]
	v_mfma_f32_16x16x32_bf16 v[96:99], v[152:155], v[180:183], v[96:99]
	v_mfma_f32_16x16x32_bf16 v[96:99], v[140:143], v[184:187], v[96:99]
	v_mfma_f32_16x16x32_bf16 v[100:103], v[148:151], v[184:187], v[100:103]
	v_mfma_f32_16x16x32_bf16 v[100:103], v[144:147], v[180:183], v[100:103]
	s_barrier
; #define LDA(dst, b, h) _Pragma("unroll") for (int m = 0; m < 4; ++m) _Pragma("unroll") for (int k = 0; k < 2; ++k) \
;     dst[m][k] = *reinterpret_cast<const bf16x8*>(SA(b, h) + lds_byte(wr * 64 + m * 16 + fr, k * 32 + fq * 8))
; #define LDB(dst, b, h) _Pragma("unroll") for (int n = 0; n < 2; ++n) _Pragma("unroll") for (int k = 0; k < 2; ++k) \
;     dst[n][k] = *reinterpret_cast<const bf16x8*>(SB(b, h) + lds_byte(wc * 32 + n * 16 + fr, k * 32 + fq * 8))
; #define WAIT_V(n) asm volatile("s_waitcnt vmcnt(" #n ")" ::: "memory")
; #define WAIT_L(n) asm volatile("s_waitcnt lgkmcnt(" #n ")" ::: "memory")
; #define BAR __builtin_amdgcn_s_barrier()
;     ...
;     { LDB(B0, 1, 0); LDA(At, 1, 0); WAIT_V(2); BAR; WAIT_L(0); MMA(0, 0, At, B0); BAR;
;       LDB(B1, 1, 1); WAIT_V(0); BAR; WAIT_L(0); MMA(0, 1, At, B1); BAR;
;       LDA(At, 1, 1); BAR; WAIT_L(0); MMA(1, 0, At, B0); MMA(1, 1, At, B1); BAR; }
;     if (wr == 0) BAR;
	ds_read_b128 v[188:191], v135
	ds_read_b128 v[192:195], v136
	ds_read_b128 v[196:199], v137
	ds_read_b128 v[136:139], v138
	s_waitcnt vmcnt(0)
	s_barrier
	s_waitcnt lgkmcnt(0)
	v_mfma_f32_16x16x32_bf16 v[92:95], v[188:191], v[156:159], v[92:95]
	v_mfma_f32_16x16x32_bf16 v[92:95], v[192:195], v[160:163], v[92:95]
	v_mfma_f32_16x16x32_bf16 v[88:91], v[136:139], v[160:163], v[88:91]
	v_mfma_f32_16x16x32_bf16 v[88:91], v[196:199], v[156:159], v[88:91]
	v_mfma_f32_16x16x32_bf16 v[80:83], v[196:199], v[164:167], v[80:83]
	v_mfma_f32_16x16x32_bf16 v[80:83], v[136:139], v[168:171], v[80:83]
	v_mfma_f32_16x16x32_bf16 v[84:87], v[192:195], v[168:171], v[84:87]
	v_mfma_f32_16x16x32_bf16 v[84:87], v[188:191], v[164:167], v[84:87]
	v_mfma_f32_16x16x32_bf16 v[76:79], v[188:191], v[172:175], v[76:79]
	v_mfma_f32_16x16x32_bf16 v[76:79], v[192:195], v[176:179], v[76:79]
	v_mfma_f32_16x16x32_bf16 v[72:75], v[136:139], v[176:179], v[72:75]
	v_mfma_f32_16x16x32_bf16 v[72:75], v[196:199], v[172:175], v[72:75]
	v_mfma_f32_16x16x32_bf16 v[64:67], v[196:199], v[180:183], v[64:67]
	v_mfma_f32_16x16x32_bf16 v[64:67], v[136:139], v[184:187], v[64:67]
	v_mfma_f32_16x16x32_bf16 v[68:71], v[192:195], v[184:187], v[68:71]
	v_mfma_f32_16x16x32_bf16 v[68:71], v[188:191], v[180:183], v[68:71]
	s_barrier
	ds_read_b128 v[156:159], v131 offset:49152
	ds_read_b128 v[160:163], v131 offset:50176
	ds_read_b128 v[164:167], v134 offset:49152
	ds_read_b128 v[168:171], v134 offset:50176
	ds_read_b128 v[172:175], v133 offset:49152
	ds_read_b128 v[176:179], v133 offset:50176
	ds_read_b128 v[180:183], v132 offset:49152
	ds_read_b128 v[132:135], v132 offset:50176
	s_barrier
	s_waitcnt lgkmcnt(0)
	v_mfma_f32_16x16x32_bf16 v[60:63], v[144:147], v[156:159], v[60:63]
	v_mfma_f32_16x16x32_bf16 v[60:63], v[148:151], v[160:163], v[60:63]
	v_mfma_f32_16x16x32_bf16 v[56:59], v[140:143], v[160:163], v[56:59]
	v_mfma_f32_16x16x32_bf16 v[56:59], v[152:155], v[156:159], v[56:59]
	v_mfma_f32_16x16x32_bf16 v[48:51], v[152:155], v[164:167], v[48:51]
	v_mfma_f32_16x16x32_bf16 v[48:51], v[140:143], v[168:171], v[48:51]
	v_mfma_f32_16x16x32_bf16 v[52:55], v[148:151], v[168:171], v[52:55]
	v_mfma_f32_16x16x32_bf16 v[52:55], v[144:147], v[164:167], v[52:55]
	v_mfma_f32_16x16x32_bf16 v[44:47], v[144:147], v[172:175], v[44:47]
	v_mfma_f32_16x16x32_bf16 v[44:47], v[148:151], v[176:179], v[44:47]
	v_mfma_f32_16x16x32_bf16 v[40:43], v[140:143], v[176:179], v[40:43]
	v_mfma_f32_16x16x32_bf16 v[40:43], v[152:155], v[172:175], v[40:43]
	v_mfma_f32_16x16x32_bf16 v[32:35], v[152:155], v[180:183], v[32:35]
	v_mfma_f32_16x16x32_bf16 v[32:35], v[140:143], v[132:135], v[32:35]
	v_mfma_f32_16x16x32_bf16 v[36:39], v[148:151], v[132:135], v[36:39]
	v_mfma_f32_16x16x32_bf16 v[36:39], v[144:147], v[180:183], v[36:39]
	v_mfma_f32_16x16x32_bf16 v[4:7], v[188:191], v[180:183], v[4:7]
	v_mfma_f32_16x16x32_bf16 v[4:7], v[192:195], v[132:135], v[4:7]
	v_mfma_f32_16x16x32_bf16 v[28:31], v[192:195], v[160:163], v[28:31]
	v_mfma_f32_16x16x32_bf16 v[28:31], v[188:191], v[156:159], v[28:31]
	v_mfma_f32_16x16x32_bf16 v[24:27], v[196:199], v[156:159], v[24:27]
	v_mfma_f32_16x16x32_bf16 v[24:27], v[136:139], v[160:163], v[24:27]
	v_mfma_f32_16x16x32_bf16 v[16:19], v[136:139], v[168:171], v[16:19]
	v_mfma_f32_16x16x32_bf16 v[16:19], v[196:199], v[164:167], v[16:19]
	v_mfma_f32_16x16x32_bf16 v[20:23], v[188:191], v[164:167], v[20:23]
	v_mfma_f32_16x16x32_bf16 v[20:23], v[192:195], v[168:171], v[20:23]
	v_mfma_f32_16x16x32_bf16 v[12:15], v[192:195], v[176:179], v[12:15]
	v_mfma_f32_16x16x32_bf16 v[12:15], v[188:191], v[172:175], v[12:15]
	v_mfma_f32_16x16x32_bf16 v[8:11], v[196:199], v[172:175], v[8:11]
	v_mfma_f32_16x16x32_bf16 v[8:11], v[136:139], v[176:179], v[8:11]
	v_mfma_f32_16x16x32_bf16 v[0:3], v[136:139], v[132:135], v[0:3]
	v_mfma_f32_16x16x32_bf16 v[0:3], v[196:199], v[180:183], v[0:3]
	v_cmp_gt_u32_e32 vcc, s35, v130
	s_barrier
	s_and_saveexec_b64 s[10:11], vcc
	s_cbranch_execz .LBB0_213
	s_barrier

; #define STAGE(P, RS, SOFF, OFF, kt) do { const int _so = (SOFF) + (kt) * (BK * 2); \
;     _Pragma("unroll") for (int _i = 0; _i < 2; ++_i) { \
;       __builtin_amdgcn_raw_ptr_buffer_load_lds(RS, (__attribute__((address_space(3))) void*)((P) + wave * 1024 + _i * 8192), 16, OFF[_i], _so, 0, 0); } } while (0)
; #define LDA(dst, b, h) _Pragma("unroll") for (int m = 0; m < 4; ++m) _Pragma("unroll") for (int k = 0; k < 2; ++k) \
;     dst[m][k] = *reinterpret_cast<const bf16x8*>(SA(b, h) + lds_byte(wr * 64 + m * 16 + fr, k * 32 + fq * 8))
; #define LDB(dst, b, h) _Pragma("unroll") for (int n = 0; n < 2; ++n) _Pragma("unroll") for (int k = 0; k < 2; ++k) \
;     dst[n][k] = *reinterpret_cast<const bf16x8*>(SB(b, h) + lds_byte(wc * 32 + n * 16 + fr, k * 32 + fq * 8))
; #define WAIT_V(n) asm volatile("s_waitcnt vmcnt(" #n ")" ::: "memory")
; #define WAIT_L(n) asm volatile("s_waitcnt lgkmcnt(" #n ")" ::: "memory")
; #define BAR __builtin_amdgcn_s_barrier()
; #define SCHED __builtin_amdgcn_sched_barrier(0)
;     ...
;     for (int t = 0; t < nt - 2; t += 2) {
;       LDB(B0, 0, 0); SCHED; LDA(At, 0, 0); STAGE(SA(1, 1), rsA, sA1, offA, t + 1);
;       WAIT_L(8); BAR; WAIT_L(0); MMA(0, 0, At, B0); BAR; SCHED;
;       LDB(B1, 0, 1); STAGE(SB(0, 0), rsB, sB0, offB, t + 2);
;       BAR; WAIT_L(0); MMA(0, 1, At, B1); BAR;
;       LDA(At, 0, 1); STAGE(SA(0, 0), rsA, sA0, offA, t + 2);
;       BAR; WAIT_L(0); MMA(1, 0, At, B0); BAR; SCHED;
;       STAGE(SB(0, 1), rsB, sB1, offB, t + 2);
;       WAIT_V(6); BAR; MMA(1, 1, At, B1); BAR;
.LBB0_225:
	s_waitcnt vmcnt(6)
	s_barrier
	v_mfma_f32_16x16x32_bf16 v[28:31], v[168:171], v[200:203], v[28:31]
	v_mfma_f32_16x16x32_bf16 v[28:31], v[172:175], v[204:207], v[28:31]
	v_mfma_f32_16x16x32_bf16 v[24:27], v[172:175], v[212:215], v[24:27]
	v_mfma_f32_16x16x32_bf16 v[24:27], v[168:171], v[208:211], v[24:27]
	v_mfma_f32_16x16x32_bf16 v[16:19], v[176:179], v[208:211], v[16:19]
	v_mfma_f32_16x16x32_bf16 v[16:19], v[180:183], v[212:215], v[16:19]
	v_mfma_f32_16x16x32_bf16 v[20:23], v[180:183], v[204:207], v[20:23]
	v_mfma_f32_16x16x32_bf16 v[20:23], v[176:179], v[200:203], v[20:23]
	v_mfma_f32_16x16x32_bf16 v[12:15], v[184:187], v[200:203], v[12:15]
	v_mfma_f32_16x16x32_bf16 v[12:15], v[188:191], v[204:207], v[12:15]
	v_mfma_f32_16x16x32_bf16 v[8:11], v[188:191], v[212:215], v[8:11]
	v_mfma_f32_16x16x32_bf16 v[8:11], v[184:187], v[208:211], v[8:11]
	v_mfma_f32_16x16x32_bf16 v[0:3], v[192:195], v[208:211], v[0:3]
	v_mfma_f32_16x16x32_bf16 v[0:3], v[196:199], v[212:215], v[0:3]
	v_mfma_f32_16x16x32_bf16 v[4:7], v[196:199], v[204:207], v[4:7]
	v_mfma_f32_16x16x32_bf16 v[4:7], v[192:195], v[200:203], v[4:7]
	s_barrier
.Lmy_rot_225:
	ds_read_b128 v[152:155], v148
	ds_read_b128 v[156:159], v149
	ds_read_b128 v[160:163], v150
	ds_read_b128 v[164:167], v151
	s_add_i32 s18, s41, s17
	s_add_i32 s19, s18, 0x80
	s_mov_b32 m0, s33
	ds_read_b128 v[168:171], v130
	ds_read_b128 v[172:175], v130 offset:1024
	ds_read_b128 v[176:179], v133
	ds_read_b128 v[180:183], v133 offset:1024
	ds_read_b128 v[184:187], v132
	ds_read_b128 v[188:191], v132 offset:1024
	ds_read_b128 v[192:195], v131
	ds_read_b128 v[196:199], v131 offset:1024
	buffer_load_dwordx4 v142, s[4:7], s19 offen lds
	s_mov_b32 m0, s34
	s_nop 0
	buffer_load_dwordx4 v143, s[4:7], s19 offen lds
	s_waitcnt lgkmcnt(8)
	s_barrier
	s_waitcnt lgkmcnt(0)
	v_mfma_f32_16x16x32_bf16 v[124:127], v[168:171], v[152:155], v[124:127]
	v_mfma_f32_16x16x32_bf16 v[124:127], v[172:175], v[156:159], v[124:127]
	v_mfma_f32_16x16x32_bf16 v[120:123], v[172:175], v[164:167], v[120:123]
	v_mfma_f32_16x16x32_bf16 v[120:123], v[168:171], v[160:163], v[120:123]
	v_mfma_f32_16x16x32_bf16 v[112:115], v[176:179], v[160:163], v[112:115]
	v_mfma_f32_16x16x32_bf16 v[112:115], v[180:183], v[164:167], v[112:115]
	v_mfma_f32_16x16x32_bf16 v[116:119], v[180:183], v[156:159], v[116:119]
	v_mfma_f32_16x16x32_bf16 v[116:119], v[176:179], v[152:155], v[116:119]
	v_mfma_f32_16x16x32_bf16 v[108:111], v[184:187], v[152:155], v[108:111]
	v_mfma_f32_16x16x32_bf16 v[108:111], v[188:191], v[156:159], v[108:111]
	v_mfma_f32_16x16x32_bf16 v[104:107], v[188:191], v[164:167], v[104:107]
	v_mfma_f32_16x16x32_bf16 v[104:107], v[184:187], v[160:163], v[104:107]
	v_mfma_f32_16x16x32_bf16 v[96:99], v[192:195], v[160:163], v[96:99]
	v_mfma_f32_16x16x32_bf16 v[96:99], v[196:199], v[164:167], v[96:99]
	v_mfma_f32_16x16x32_bf16 v[100:103], v[196:199], v[156:159], v[100:103]
	v_mfma_f32_16x16x32_bf16 v[100:103], v[192:195], v[152:155], v[100:103]
	s_barrier
	s_add_i32 s19, s43, s17
	s_add_i32 s47, s19, 0x100
	s_mov_b32 m0, s1
	ds_read_b128 v[200:203], v144
	ds_read_b128 v[204:207], v145
	ds_read_b128 v[208:211], v146
	ds_read_b128 v[212:215], v147
	buffer_load_dwordx4 v142, s[8:11], s47 offen lds
	s_mov_b32 m0, s3
	s_nop 0
	buffer_load_dwordx4 v143, s[8:11], s47 offen lds
	s_barrier
	s_waitcnt lgkmcnt(0)
	v_mfma_f32_16x16x32_bf16 v[92:95], v[168:171], v[200:203], v[92:95]
	v_mfma_f32_16x16x32_bf16 v[92:95], v[172:175], v[204:207], v[92:95]
	v_mfma_f32_16x16x32_bf16 v[88:91], v[172:175], v[212:215], v[88:91]
	v_mfma_f32_16x16x32_bf16 v[88:91], v[168:171], v[208:211], v[88:91]
	v_mfma_f32_16x16x32_bf16 v[80:83], v[176:179], v[208:211], v[80:83]
	v_mfma_f32_16x16x32_bf16 v[80:83], v[180:183], v[212:215], v[80:83]
	v_mfma_f32_16x16x32_bf16 v[84:87], v[180:183], v[204:207], v[84:87]
	v_mfma_f32_16x16x32_bf16 v[84:87], v[176:179], v[200:203], v[84:87]
	v_mfma_f32_16x16x32_bf16 v[76:79], v[184:187], v[200:203], v[76:79]
	v_mfma_f32_16x16x32_bf16 v[76:79], v[188:191], v[204:207], v[76:79]
	v_mfma_f32_16x16x32_bf16 v[72:75], v[188:191], v[212:215], v[72:75]
	v_mfma_f32_16x16x32_bf16 v[72:75], v[184:187], v[208:211], v[72:75]
	v_mfma_f32_16x16x32_bf16 v[64:67], v[192:195], v[208:211], v[64:67]
	v_mfma_f32_16x16x32_bf16 v[64:67], v[196:199], v[212:215], v[64:67]
	v_mfma_f32_16x16x32_bf16 v[68:71], v[196:199], v[204:207], v[68:71]
	v_mfma_f32_16x16x32_bf16 v[68:71], v[192:195], v[200:203], v[68:71]
	s_barrier
	s_add_i32 s47, s42, s17
	s_add_i32 s48, s47, 0x100
	s_mov_b32 m0, s0
	ds_read_b128 v[168:171], v130 offset:16384
	ds_read_b128 v[172:175], v130 offset:17408
	ds_read_b128 v[176:179], v133 offset:16384
	ds_read_b128 v[180:183], v133 offset:17408
	ds_read_b128 v[184:187], v132 offset:16384
	ds_read_b128 v[188:191], v132 offset:17408
	ds_read_b128 v[192:195], v131 offset:16384
	ds_read_b128 v[196:199], v131 offset:17408
	buffer_load_dwordx4 v142, s[4:7], s48 offen lds
	s_mov_b32 m0, s20
	s_nop 0
	buffer_load_dwordx4 v143, s[4:7], s48 offen lds
	s_barrier
	s_waitcnt lgkmcnt(0)
	v_mfma_f32_16x16x32_bf16 v[60:63], v[168:171], v[152:155], v[60:63]
	v_mfma_f32_16x16x32_bf16 v[60:63], v[172:175], v[156:159], v[60:63]
	v_mfma_f32_16x16x32_bf16 v[56:59], v[172:175], v[164:167], v[56:59]
	v_mfma_f32_16x16x32_bf16 v[56:59], v[168:171], v[160:163], v[56:59]
	v_mfma_f32_16x16x32_bf16 v[48:51], v[176:179], v[160:163], v[48:51]
	v_mfma_f32_16x16x32_bf16 v[48:51], v[180:183], v[164:167], v[48:51]
	v_mfma_f32_16x16x32_bf16 v[52:55], v[180:183], v[156:159], v[52:55]
	v_mfma_f32_16x16x32_bf16 v[52:55], v[176:179], v[152:155], v[52:55]
	v_mfma_f32_16x16x32_bf16 v[44:47], v[184:187], v[152:155], v[44:47]
	v_mfma_f32_16x16x32_bf16 v[44:47], v[188:191], v[156:159], v[44:47]
	v_mfma_f32_16x16x32_bf16 v[40:43], v[188:191], v[164:167], v[40:43]
	v_mfma_f32_16x16x32_bf16 v[40:43], v[184:187], v[160:163], v[40:43]
	v_mfma_f32_16x16x32_bf16 v[32:35], v[192:195], v[160:163], v[32:35]
	v_mfma_f32_16x16x32_bf16 v[32:35], v[196:199], v[164:167], v[32:35]
	v_mfma_f32_16x16x32_bf16 v[36:39], v[196:199], v[156:159], v[36:39]
	v_mfma_f32_16x16x32_bf16 v[36:39], v[192:195], v[152:155], v[36:39]
	s_barrier
; #define STAGE(P, RS, SOFF, OFF, kt) do { const int _so = (SOFF) + (kt) * (BK * 2); \
;     _Pragma("unroll") for (int _i = 0; _i < 2; ++_i) { \
;       __builtin_amdgcn_raw_ptr_buffer_load_lds(RS, (__attribute__((address_space(3))) void*)((P) + wave * 1024 + _i * 8192), 16, OFF[_i], _so, 0, 0); } } while (0)
; #define LDA(dst, b, h) _Pragma("unroll") for (int m = 0; m < 4; ++m) _Pragma("unroll") for (int k = 0; k < 2; ++k) \
;     dst[m][k] = *reinterpret_cast<const bf16x8*>(SA(b, h) + lds_byte(wr * 64 + m * 16 + fr, k * 32 + fq * 8))
; #define LDB(dst, b, h) _Pragma("unroll") for (int n = 0; n < 2; ++n) _Pragma("unroll") for (int k = 0; k < 2; ++k) \
;     dst[n][k] = *reinterpret_cast<const bf16x8*>(SB(b, h) + lds_byte(wc * 32 + n * 16 + fr, k * 32 + fq * 8))
; #define WAIT_V(n) asm volatile("s_waitcnt vmcnt(" #n ")" ::: "memory")
; #define WAIT_L(n) asm volatile("s_waitcnt lgkmcnt(" #n ")" ::: "memory")
; #define BAR __builtin_amdgcn_s_barrier()
; #define SCHED __builtin_amdgcn_sched_barrier(0)
;     ...
;       WAIT_V(6); BAR; MMA(1, 1, At, B1); BAR;
;       LDB(B0, 1, 0); SCHED; LDA(At, 1, 0); STAGE(SA(0, 1), rsA, sA1, offA, t + 2);
;       WAIT_L(8); BAR; WAIT_L(0); MMA(0, 0, At, B0); BAR; SCHED;
;       LDB(B1, 1, 1); STAGE(SB(1, 0), rsB, sB0, offB, t + 3);
;       BAR; WAIT_L(0); MMA(0, 1, At, B1); BAR;
;       LDA(At, 1, 1); STAGE(SA(1, 0), rsA, sA0, offA, t + 3);
;       BAR; WAIT_L(0); MMA(1, 0, At, B0); BAR; SCHED;
	s_add_i32 s48, s44, s17
	s_add_i32 s49, s48, 0x100
	s_mov_b32 m0, s21
	s_nop 0
	buffer_load_dwordx4 v142, s[8:11], s49 offen lds
	s_mov_b32 m0, s22
	s_nop 0
	buffer_load_dwordx4 v143, s[8:11], s49 offen lds
	s_waitcnt vmcnt(6)
	s_barrier
	v_mfma_f32_16x16x32_bf16 v[28:31], v[168:171], v[200:203], v[28:31]
	v_mfma_f32_16x16x32_bf16 v[28:31], v[172:175], v[204:207], v[28:31]
	v_mfma_f32_16x16x32_bf16 v[24:27], v[172:175], v[212:215], v[24:27]
	v_mfma_f32_16x16x32_bf16 v[24:27], v[168:171], v[208:211], v[24:27]
	v_mfma_f32_16x16x32_bf16 v[16:19], v[176:179], v[208:211], v[16:19]
	v_mfma_f32_16x16x32_bf16 v[16:19], v[180:183], v[212:215], v[16:19]
	v_mfma_f32_16x16x32_bf16 v[20:23], v[180:183], v[204:207], v[20:23]
	v_mfma_f32_16x16x32_bf16 v[20:23], v[176:179], v[200:203], v[20:23]
	v_mfma_f32_16x16x32_bf16 v[12:15], v[184:187], v[200:203], v[12:15]
	v_mfma_f32_16x16x32_bf16 v[12:15], v[188:191], v[204:207], v[12:15]
	v_mfma_f32_16x16x32_bf16 v[8:11], v[188:191], v[212:215], v[8:11]
	v_mfma_f32_16x16x32_bf16 v[8:11], v[184:187], v[208:211], v[8:11]
	v_mfma_f32_16x16x32_bf16 v[0:3], v[192:195], v[208:211], v[0:3]
	v_mfma_f32_16x16x32_bf16 v[0:3], v[196:199], v[212:215], v[0:3]
	v_mfma_f32_16x16x32_bf16 v[4:7], v[196:199], v[204:207], v[4:7]
	v_mfma_f32_16x16x32_bf16 v[4:7], v[192:195], v[200:203], v[4:7]
	s_barrier
	ds_read_b128 v[152:155], v138
	ds_read_b128 v[156:159], v139
	ds_read_b128 v[160:163], v140
	ds_read_b128 v[164:167], v141
	s_addk_i32 s18, 0x100
	s_mov_b32 m0, s23
	ds_read_b128 v[168:171], v130 offset:32768
	ds_read_b128 v[172:175], v130 offset:33792
	ds_read_b128 v[176:179], v133 offset:32768
	ds_read_b128 v[180:183], v133 offset:33792
	ds_read_b128 v[184:187], v132 offset:32768
	ds_read_b128 v[188:191], v132 offset:33792
	ds_read_b128 v[192:195], v131 offset:32768
	ds_read_b128 v[196:199], v131 offset:33792
	buffer_load_dwordx4 v142, s[4:7], s18 offen lds
	s_mov_b32 m0, s24
	s_nop 0
	buffer_load_dwordx4 v143, s[4:7], s18 offen lds
	s_waitcnt lgkmcnt(8)
	s_barrier
	s_waitcnt lgkmcnt(0)
	v_mfma_f32_16x16x32_bf16 v[124:127], v[168:171], v[152:155], v[124:127]
	v_mfma_f32_16x16x32_bf16 v[124:127], v[172:175], v[156:159], v[124:127]
	v_mfma_f32_16x16x32_bf16 v[120:123], v[172:175], v[164:167], v[120:123]
	v_mfma_f32_16x16x32_bf16 v[120:123], v[168:171], v[160:163], v[120:123]
	v_mfma_f32_16x16x32_bf16 v[112:115], v[176:179], v[160:163], v[112:115]
	v_mfma_f32_16x16x32_bf16 v[112:115], v[180:183], v[164:167], v[112:115]
	v_mfma_f32_16x16x32_bf16 v[116:119], v[180:183], v[156:159], v[116:119]
	v_mfma_f32_16x16x32_bf16 v[116:119], v[176:179], v[152:155], v[116:119]
	v_mfma_f32_16x16x32_bf16 v[108:111], v[184:187], v[152:155], v[108:111]
	v_mfma_f32_16x16x32_bf16 v[108:111], v[188:191], v[156:159], v[108:111]
	v_mfma_f32_16x16x32_bf16 v[104:107], v[188:191], v[164:167], v[104:107]
	v_mfma_f32_16x16x32_bf16 v[104:107], v[184:187], v[160:163], v[104:107]
	v_mfma_f32_16x16x32_bf16 v[96:99], v[192:195], v[160:163], v[96:99]
	v_mfma_f32_16x16x32_bf16 v[96:99], v[196:199], v[164:167], v[96:99]
	v_mfma_f32_16x16x32_bf16 v[100:103], v[196:199], v[156:159], v[100:103]
	v_mfma_f32_16x16x32_bf16 v[100:103], v[192:195], v[152:155], v[100:103]
	s_barrier
	s_addk_i32 s19, 0x180
	s_mov_b32 m0, s25
	ds_read_b128 v[200:203], v134
	ds_read_b128 v[204:207], v135
	ds_read_b128 v[208:211], v136
	ds_read_b128 v[212:215], v137
	buffer_load_dwordx4 v142, s[8:11], s19 offen lds
	s_mov_b32 m0, s26
	s_nop 0
	buffer_load_dwordx4 v143, s[8:11], s19 offen lds
	s_barrier
	s_waitcnt lgkmcnt(0)
	v_mfma_f32_16x16x32_bf16 v[92:95], v[168:171], v[200:203], v[92:95]
	v_mfma_f32_16x16x32_bf16 v[92:95], v[172:175], v[204:207], v[92:95]
	v_mfma_f32_16x16x32_bf16 v[88:91], v[172:175], v[212:215], v[88:91]
	v_mfma_f32_16x16x32_bf16 v[88:91], v[168:171], v[208:211], v[88:91]
	v_mfma_f32_16x16x32_bf16 v[80:83], v[176:179], v[208:211], v[80:83]
	v_mfma_f32_16x16x32_bf16 v[80:83], v[180:183], v[212:215], v[80:83]
	v_mfma_f32_16x16x32_bf16 v[84:87], v[180:183], v[204:207], v[84:87]
	v_mfma_f32_16x16x32_bf16 v[84:87], v[176:179], v[200:203], v[84:87]
	v_mfma_f32_16x16x32_bf16 v[76:79], v[184:187], v[200:203], v[76:79]
	v_mfma_f32_16x16x32_bf16 v[76:79], v[188:191], v[204:207], v[76:79]
	v_mfma_f32_16x16x32_bf16 v[72:75], v[188:191], v[212:215], v[72:75]
	v_mfma_f32_16x16x32_bf16 v[72:75], v[184:187], v[208:211], v[72:75]
	v_mfma_f32_16x16x32_bf16 v[64:67], v[192:195], v[208:211], v[64:67]
	v_mfma_f32_16x16x32_bf16 v[64:67], v[196:199], v[212:215], v[64:67]
	v_mfma_f32_16x16x32_bf16 v[68:71], v[196:199], v[204:207], v[68:71]
	v_mfma_f32_16x16x32_bf16 v[68:71], v[192:195], v[200:203], v[68:71]
	s_barrier
	s_addk_i32 s47, 0x180
	s_mov_b32 m0, s27
	ds_read_b128 v[168:171], v130 offset:49152
	ds_read_b128 v[172:175], v130 offset:50176
	ds_read_b128 v[176:179], v133 offset:49152
	ds_read_b128 v[180:183], v133 offset:50176
	ds_read_b128 v[184:187], v132 offset:49152
	ds_read_b128 v[188:191], v132 offset:50176
	ds_read_b128 v[192:195], v131 offset:49152
	ds_read_b128 v[196:199], v131 offset:50176
	buffer_load_dwordx4 v142, s[4:7], s47 offen lds
	s_mov_b32 m0, s28
	s_nop 0
	buffer_load_dwordx4 v143, s[4:7], s47 offen lds
	s_barrier
; #define STAGE(P, RS, SOFF, OFF, kt) do { const int _so = (SOFF) + (kt) * (BK * 2); \
;     _Pragma("unroll") for (int _i = 0; _i < 2; ++_i) { \
;       __builtin_amdgcn_raw_ptr_buffer_load_lds(RS, (__attribute__((address_space(3))) void*)((P) + wave * 1024 + _i * 8192), 16, OFF[_i], _so, 0, 0); } } while (0)
; #define LDA(dst, b, h) _Pragma("unroll") for (int m = 0; m < 4; ++m) _Pragma("unroll") for (int k = 0; k < 2; ++k) \
;     dst[m][k] = *reinterpret_cast<const bf16x8*>(SA(b, h) + lds_byte(wr * 64 + m * 16 + fr, k * 32 + fq * 8))
; #define LDB(dst, b, h) _Pragma("unroll") for (int n = 0; n < 2; ++n) _Pragma("unroll") for (int k = 0; k < 2; ++k) \
;     dst[n][k] = *reinterpret_cast<const bf16x8*>(SB(b, h) + lds_byte(wc * 32 + n * 16 + fr, k * 32 + fq * 8))
; #define WAIT_V(n) asm volatile("s_waitcnt vmcnt(" #n ")" ::: "memory")
; #define WAIT_L(n) asm volatile("s_waitcnt lgkmcnt(" #n ")" ::: "memory")
; #define BAR __builtin_amdgcn_s_barrier()
;     ...
;       STAGE(SB(1, 1), rsB, sB1, offB, t + 3);
;       WAIT_V(6); BAR; MMA(1, 1, At, B1); BAR;
;     }
;     { LDB(B0, 0, 0); LDA(At, 0, 0); STAGE(SA(1, 1), rsA, sA1, offA, nt - 1);
;       BAR; WAIT_L(0); MMA(0, 0, At, B0); BAR;
;       LDB(B1, 0, 1); BAR; WAIT_L(0); MMA(0, 1, At, B1); BAR;
;       LDA(At, 0, 1); WAIT_V(4); BAR; WAIT_L(0); MMA(1, 0, At, B0); MMA(1, 1, At, B1); BAR; }
	s_waitcnt lgkmcnt(0)
	v_mfma_f32_16x16x32_bf16 v[60:63], v[168:171], v[152:155], v[60:63]
	v_mfma_f32_16x16x32_bf16 v[60:63], v[172:175], v[156:159], v[60:63]
	v_mfma_f32_16x16x32_bf16 v[56:59], v[172:175], v[164:167], v[56:59]
	v_mfma_f32_16x16x32_bf16 v[56:59], v[168:171], v[160:163], v[56:59]
	v_mfma_f32_16x16x32_bf16 v[48:51], v[176:179], v[160:163], v[48:51]
	v_mfma_f32_16x16x32_bf16 v[48:51], v[180:183], v[164:167], v[48:51]
	v_mfma_f32_16x16x32_bf16 v[52:55], v[180:183], v[156:159], v[52:55]
	v_mfma_f32_16x16x32_bf16 v[52:55], v[176:179], v[152:155], v[52:55]
	v_mfma_f32_16x16x32_bf16 v[44:47], v[184:187], v[152:155], v[44:47]
	v_mfma_f32_16x16x32_bf16 v[44:47], v[188:191], v[156:159], v[44:47]
	v_mfma_f32_16x16x32_bf16 v[40:43], v[188:191], v[164:167], v[40:43]
	v_mfma_f32_16x16x32_bf16 v[40:43], v[184:187], v[160:163], v[40:43]
	v_mfma_f32_16x16x32_bf16 v[32:35], v[192:195], v[160:163], v[32:35]
	v_mfma_f32_16x16x32_bf16 v[32:35], v[196:199], v[164:167], v[32:35]
	v_mfma_f32_16x16x32_bf16 v[36:39], v[196:199], v[156:159], v[36:39]
	v_mfma_f32_16x16x32_bf16 v[36:39], v[192:195], v[152:155], v[36:39]
	s_barrier
	s_addk_i32 s48, 0x180
	s_mov_b32 m0, s29
	s_nop 0
	buffer_load_dwordx4 v142, s[8:11], s48 offen lds
	s_mov_b32 m0, s30
	s_nop 0
	buffer_load_dwordx4 v143, s[8:11], s48 offen lds
	s_add_i32 s16, s16, 2
	s_addk_i32 s17, 0x100
	s_cmp_gt_u32 s16, 27
	s_cbranch_scc0 .LBB0_225
	s_waitcnt vmcnt(6)
	s_barrier
	v_mfma_f32_16x16x32_bf16 v[28:31], v[168:171], v[200:203], v[28:31]
	v_mfma_f32_16x16x32_bf16 v[28:31], v[172:175], v[204:207], v[28:31]
	v_mfma_f32_16x16x32_bf16 v[24:27], v[172:175], v[212:215], v[24:27]
	v_mfma_f32_16x16x32_bf16 v[24:27], v[168:171], v[208:211], v[24:27]
	v_mfma_f32_16x16x32_bf16 v[16:19], v[176:179], v[208:211], v[16:19]
	v_mfma_f32_16x16x32_bf16 v[16:19], v[180:183], v[212:215], v[16:19]
	v_mfma_f32_16x16x32_bf16 v[20:23], v[180:183], v[204:207], v[20:23]
	v_mfma_f32_16x16x32_bf16 v[20:23], v[176:179], v[200:203], v[20:23]
	v_mfma_f32_16x16x32_bf16 v[12:15], v[184:187], v[200:203], v[12:15]
	v_mfma_f32_16x16x32_bf16 v[12:15], v[188:191], v[204:207], v[12:15]
	v_mfma_f32_16x16x32_bf16 v[8:11], v[188:191], v[212:215], v[8:11]
	v_mfma_f32_16x16x32_bf16 v[8:11], v[184:187], v[208:211], v[8:11]
	v_mfma_f32_16x16x32_bf16 v[0:3], v[192:195], v[208:211], v[0:3]
	v_mfma_f32_16x16x32_bf16 v[0:3], v[196:199], v[212:215], v[0:3]
	v_mfma_f32_16x16x32_bf16 v[4:7], v[196:199], v[204:207], v[4:7]
	v_mfma_f32_16x16x32_bf16 v[4:7], v[192:195], v[200:203], v[4:7]
	s_barrier
	s_add_i32 s16, s41, 0xf80
	s_mov_b32 m0, s33
	ds_read_b128 v[152:155], v148
	ds_read_b128 v[156:159], v149
	ds_read_b128 v[160:163], v150
	ds_read_b128 v[148:151], v151
	ds_read_b128 v[164:167], v130
	ds_read_b128 v[168:171], v130 offset:1024
	ds_read_b128 v[172:175], v133
	ds_read_b128 v[176:179], v133 offset:1024
	ds_read_b128 v[180:183], v132
	ds_read_b128 v[184:187], v132 offset:1024
	ds_read_b128 v[188:191], v131
	ds_read_b128 v[192:195], v131 offset:1024
	buffer_load_dwordx4 v142, s[4:7], s16 offen lds
	s_mov_b32 m0, s34
	s_nop 0
	buffer_load_dwordx4 v143, s[4:7], s16 offen lds
	s_barrier
	s_waitcnt lgkmcnt(0)
	v_mfma_f32_16x16x32_bf16 v[124:127], v[164:167], v[152:155], v[124:127]
	v_mfma_f32_16x16x32_bf16 v[124:127], v[168:171], v[156:159], v[124:127]
	v_mfma_f32_16x16x32_bf16 v[120:123], v[168:171], v[148:151], v[120:123]
	v_mfma_f32_16x16x32_bf16 v[120:123], v[164:167], v[160:163], v[120:123]
	v_mfma_f32_16x16x32_bf16 v[112:115], v[172:175], v[160:163], v[112:115]
	v_mfma_f32_16x16x32_bf16 v[112:115], v[176:179], v[148:151], v[112:115]
	v_mfma_f32_16x16x32_bf16 v[116:119], v[176:179], v[156:159], v[116:119]
	v_mfma_f32_16x16x32_bf16 v[116:119], v[172:175], v[152:155], v[116:119]
	v_mfma_f32_16x16x32_bf16 v[108:111], v[180:183], v[152:155], v[108:111]
	v_mfma_f32_16x16x32_bf16 v[108:111], v[184:187], v[156:159], v[108:111]
	v_mfma_f32_16x16x32_bf16 v[104:107], v[184:187], v[148:151], v[104:107]
	v_mfma_f32_16x16x32_bf16 v[104:107], v[180:183], v[160:163], v[104:107]
	v_mfma_f32_16x16x32_bf16 v[96:99], v[188:191], v[160:163], v[96:99]
	v_mfma_f32_16x16x32_bf16 v[96:99], v[192:195], v[148:151], v[96:99]
	v_mfma_f32_16x16x32_bf16 v[100:103], v[192:195], v[156:159], v[100:103]
	v_mfma_f32_16x16x32_bf16 v[100:103], v[188:191], v[152:155], v[100:103]
	s_barrier
	ds_read_b128 v[196:199], v144
	ds_read_b128 v[142:145], v145
	ds_read_b128 v[200:203], v146
	ds_read_b128 v[204:207], v147
	s_barrier
	s_waitcnt lgkmcnt(0)
	v_mfma_f32_16x16x32_bf16 v[88:91], v[164:167], v[200:203], v[88:91]
	v_mfma_f32_16x16x32_bf16 v[84:87], v[172:175], v[196:199], v[84:87]
	v_mfma_f32_16x16x32_bf16 v[80:83], v[172:175], v[200:203], v[80:83]
	v_mfma_f32_16x16x32_bf16 v[76:79], v[180:183], v[196:199], v[76:79]
	v_mfma_f32_16x16x32_bf16 v[72:75], v[180:183], v[200:203], v[72:75]
	v_mfma_f32_16x16x32_bf16 v[68:71], v[188:191], v[196:199], v[68:71]
	v_mfma_f32_16x16x32_bf16 v[64:67], v[188:191], v[200:203], v[64:67]
	v_mfma_f32_16x16x32_bf16 v[92:95], v[164:167], v[196:199], v[92:95]
	v_mfma_f32_16x16x32_bf16 v[88:91], v[168:171], v[204:207], v[88:91]
	v_mfma_f32_16x16x32_bf16 v[84:87], v[176:179], v[142:145], v[84:87]
	v_mfma_f32_16x16x32_bf16 v[80:83], v[176:179], v[204:207], v[80:83]
	v_mfma_f32_16x16x32_bf16 v[76:79], v[184:187], v[142:145], v[76:79]
	v_mfma_f32_16x16x32_bf16 v[72:75], v[184:187], v[204:207], v[72:75]
	v_mfma_f32_16x16x32_bf16 v[68:71], v[192:195], v[142:145], v[68:71]
	v_mfma_f32_16x16x32_bf16 v[64:67], v[192:195], v[204:207], v[64:67]
	v_mfma_f32_16x16x32_bf16 v[164:167], v[168:171], v[142:145], v[92:95]
	s_barrier
; #define LDA(dst, b, h) _Pragma("unroll") for (int m = 0; m < 4; ++m) _Pragma("unroll") for (int k = 0; k < 2; ++k) \
;     dst[m][k] = *reinterpret_cast<const bf16x8*>(SA(b, h) + lds_byte(wr * 64 + m * 16 + fr, k * 32 + fq * 8))
; #define LDB(dst, b, h) _Pragma("unroll") for (int n = 0; n < 2; ++n) _Pragma("unroll") for (int k = 0; k < 2; ++k) \
;     dst[n][k] = *reinterpret_cast<const bf16x8*>(SB(b, h) + lds_byte(wc * 32 + n * 16 + fr, k * 32 + fq * 8))
; #define WAIT_V(n) asm volatile("s_waitcnt vmcnt(" #n ")" ::: "memory")
; #define WAIT_L(n) asm volatile("s_waitcnt lgkmcnt(" #n ")" ::: "memory")
; #define BAR __builtin_amdgcn_s_barrier()
;     ...
;       LDA(At, 0, 1); WAIT_V(4); BAR; WAIT_L(0); MMA(1, 0, At, B0); MMA(1, 1, At, B1); BAR; }
;     { LDB(B0, 1, 0); LDA(At, 1, 0); WAIT_V(2); BAR; WAIT_L(0); MMA(0, 0, At, B0); BAR;
	s_nop 0
	ds_read_b128 v[92:95], v130 offset:16384
	ds_read_b128 v[168:171], v130 offset:17408
	ds_read_b128 v[172:175], v133 offset:16384
	ds_read_b128 v[176:179], v133 offset:17408
	ds_read_b128 v[180:183], v132 offset:16384
	ds_read_b128 v[184:187], v132 offset:17408
	ds_read_b128 v[188:191], v131 offset:16384
	ds_read_b128 v[192:195], v131 offset:17408
	s_waitcnt vmcnt(4)
	s_barrier
	s_waitcnt lgkmcnt(0)
	v_mfma_f32_16x16x32_bf16 v[60:63], v[92:95], v[152:155], v[60:63]
	v_mfma_f32_16x16x32_bf16 v[60:63], v[168:171], v[156:159], v[60:63]
	v_mfma_f32_16x16x32_bf16 v[56:59], v[168:171], v[148:151], v[56:59]
	v_mfma_f32_16x16x32_bf16 v[56:59], v[92:95], v[160:163], v[56:59]
	v_mfma_f32_16x16x32_bf16 v[48:51], v[172:175], v[160:163], v[48:51]
	v_mfma_f32_16x16x32_bf16 v[48:51], v[176:179], v[148:151], v[48:51]
	v_mfma_f32_16x16x32_bf16 v[52:55], v[176:179], v[156:159], v[52:55]
	v_mfma_f32_16x16x32_bf16 v[52:55], v[172:175], v[152:155], v[52:55]
	v_mfma_f32_16x16x32_bf16 v[44:47], v[180:183], v[152:155], v[44:47]
	v_mfma_f32_16x16x32_bf16 v[44:47], v[184:187], v[156:159], v[44:47]
	v_mfma_f32_16x16x32_bf16 v[40:43], v[184:187], v[148:151], v[40:43]
	v_mfma_f32_16x16x32_bf16 v[40:43], v[180:183], v[160:163], v[40:43]
	v_mfma_f32_16x16x32_bf16 v[32:35], v[188:191], v[160:163], v[32:35]
	v_mfma_f32_16x16x32_bf16 v[32:35], v[192:195], v[148:151], v[32:35]
	v_mfma_f32_16x16x32_bf16 v[36:39], v[192:195], v[156:159], v[36:39]
	v_mfma_f32_16x16x32_bf16 v[36:39], v[188:191], v[152:155], v[36:39]
	v_mfma_f32_16x16x32_bf16 v[4:7], v[188:191], v[196:199], v[4:7]
	v_mfma_f32_16x16x32_bf16 v[4:7], v[192:195], v[142:145], v[4:7]
	v_mfma_f32_16x16x32_bf16 v[28:31], v[168:171], v[142:145], v[28:31]
	v_mfma_f32_16x16x32_bf16 v[28:31], v[92:95], v[196:199], v[28:31]
	v_mfma_f32_16x16x32_bf16 v[24:27], v[92:95], v[200:203], v[24:27]
	v_mfma_f32_16x16x32_bf16 v[24:27], v[168:171], v[204:207], v[24:27]
	v_mfma_f32_16x16x32_bf16 v[16:19], v[176:179], v[204:207], v[16:19]
	v_mfma_f32_16x16x32_bf16 v[16:19], v[172:175], v[200:203], v[16:19]
	v_mfma_f32_16x16x32_bf16 v[20:23], v[172:175], v[196:199], v[20:23]
	v_mfma_f32_16x16x32_bf16 v[20:23], v[176:179], v[142:145], v[20:23]
	v_mfma_f32_16x16x32_bf16 v[12:15], v[184:187], v[142:145], v[12:15]
	v_mfma_f32_16x16x32_bf16 v[12:15], v[180:183], v[196:199], v[12:15]
	v_mfma_f32_16x16x32_bf16 v[8:11], v[180:183], v[200:203], v[8:11]
	v_mfma_f32_16x16x32_bf16 v[8:11], v[184:187], v[204:207], v[8:11]
	v_mfma_f32_16x16x32_bf16 v[0:3], v[192:195], v[204:207], v[0:3]
	v_mfma_f32_16x16x32_bf16 v[0:3], v[188:191], v[200:203], v[0:3]
	s_barrier
	ds_read_b128 v[142:145], v138
	ds_read_b128 v[146:149], v139
	ds_read_b128 v[150:153], v140
	ds_read_b128 v[138:141], v141
	ds_read_b128 v[154:157], v130 offset:32768
	ds_read_b128 v[158:161], v130 offset:33792
	ds_read_b128 v[168:171], v133 offset:32768
	ds_read_b128 v[172:175], v133 offset:33792
	ds_read_b128 v[176:179], v132 offset:32768
	ds_read_b128 v[180:183], v132 offset:33792
	ds_read_b128 v[184:187], v131 offset:32768
	ds_read_b128 v[188:191], v131 offset:33792
	s_waitcnt vmcnt(2)
	s_barrier
	s_waitcnt lgkmcnt(0)
	v_mfma_f32_16x16x32_bf16 v[92:95], v[154:157], v[142:145], v[124:127]
	v_mfma_f32_16x16x32_bf16 v[120:123], v[154:157], v[150:153], v[120:123]
	v_mfma_f32_16x16x32_bf16 v[116:119], v[168:171], v[142:145], v[116:119]
	v_mfma_f32_16x16x32_bf16 v[112:115], v[168:171], v[150:153], v[112:115]
	v_mfma_f32_16x16x32_bf16 v[108:111], v[176:179], v[142:145], v[108:111]
	v_mfma_f32_16x16x32_bf16 v[104:107], v[176:179], v[150:153], v[104:107]
	v_mfma_f32_16x16x32_bf16 v[100:103], v[184:187], v[142:145], v[100:103]
	v_mfma_f32_16x16x32_bf16 v[96:99], v[184:187], v[150:153], v[96:99]
	v_mfma_f32_16x16x32_bf16 v[124:127], v[158:161], v[146:149], v[92:95]
	v_mfma_f32_16x16x32_bf16 v[120:123], v[158:161], v[138:141], v[120:123]
	v_mfma_f32_16x16x32_bf16 v[116:119], v[172:175], v[146:149], v[116:119]
	v_mfma_f32_16x16x32_bf16 v[112:115], v[172:175], v[138:141], v[112:115]
	v_mfma_f32_16x16x32_bf16 v[108:111], v[180:183], v[146:149], v[108:111]
	v_mfma_f32_16x16x32_bf16 v[104:107], v[180:183], v[138:141], v[104:107]
	v_mfma_f32_16x16x32_bf16 v[100:103], v[188:191], v[146:149], v[100:103]
	v_mfma_f32_16x16x32_bf16 v[92:95], v[188:191], v[138:141], v[96:99]
	s_barrier
; #define LDA(dst, b, h) _Pragma("unroll") for (int m = 0; m < 4; ++m) _Pragma("unroll") for (int k = 0; k < 2; ++k) \
;     dst[m][k] = *reinterpret_cast<const bf16x8*>(SA(b, h) + lds_byte(wr * 64 + m * 16 + fr, k * 32 + fq * 8))
; #define LDB(dst, b, h) _Pragma("unroll") for (int n = 0; n < 2; ++n) _Pragma("unroll") for (int k = 0; k < 2; ++k) \
;     dst[n][k] = *reinterpret_cast<const bf16x8*>(SB(b, h) + lds_byte(wc * 32 + n * 16 + fr, k * 32 + fq * 8))
; #define WAIT_V(n) asm volatile("s_waitcnt vmcnt(" #n ")" ::: "memory")
; #define WAIT_L(n) asm volatile("s_waitcnt lgkmcnt(" #n ")" ::: "memory")
; #define BAR __builtin_amdgcn_s_barrier()
;     ...
;     { LDB(B0, 1, 0); LDA(At, 1, 0); WAIT_V(2); BAR; WAIT_L(0); MMA(0, 0, At, B0); BAR;
;       LDB(B1, 1, 1); WAIT_V(0); BAR; WAIT_L(0); MMA(0, 1, At, B1); BAR;
;       LDA(At, 1, 1); BAR; WAIT_L(0); MMA(1, 0, At, B0); MMA(1, 1, At, B1); BAR; }
;     if (wr == 0) BAR;
	ds_read_b128 v[192:195], v134
	ds_read_b128 v[196:199], v135
	ds_read_b128 v[200:203], v136
	ds_read_b128 v[134:137], v137
	s_waitcnt vmcnt(0)
	s_barrier
	s_waitcnt lgkmcnt(0)
	v_mfma_f32_16x16x32_bf16 v[96:99], v[154:157], v[192:195], v[164:167]
	v_mfma_f32_16x16x32_bf16 v[88:91], v[154:157], v[200:203], v[88:91]
	v_mfma_f32_16x16x32_bf16 v[84:87], v[168:171], v[192:195], v[84:87]
	v_mfma_f32_16x16x32_bf16 v[80:83], v[168:171], v[200:203], v[80:83]
	v_mfma_f32_16x16x32_bf16 v[76:79], v[176:179], v[192:195], v[76:79]
	v_mfma_f32_16x16x32_bf16 v[72:75], v[176:179], v[200:203], v[72:75]
	v_mfma_f32_16x16x32_bf16 v[68:71], v[184:187], v[192:195], v[68:71]
	v_mfma_f32_16x16x32_bf16 v[64:67], v[184:187], v[200:203], v[64:67]
	v_mfma_f32_16x16x32_bf16 v[96:99], v[158:161], v[196:199], v[96:99]
	v_mfma_f32_16x16x32_bf16 v[88:91], v[158:161], v[134:137], v[88:91]
	v_mfma_f32_16x16x32_bf16 v[84:87], v[172:175], v[196:199], v[84:87]
	v_mfma_f32_16x16x32_bf16 v[80:83], v[172:175], v[134:137], v[80:83]
	v_mfma_f32_16x16x32_bf16 v[76:79], v[180:183], v[196:199], v[76:79]
	v_mfma_f32_16x16x32_bf16 v[72:75], v[180:183], v[134:137], v[72:75]
	v_mfma_f32_16x16x32_bf16 v[68:71], v[188:191], v[196:199], v[68:71]
	v_mfma_f32_16x16x32_bf16 v[64:67], v[188:191], v[134:137], v[64:67]
	s_barrier
	ds_read_b128 v[154:157], v130 offset:49152
	ds_read_b128 v[158:161], v130 offset:50176
	ds_read_b128 v[162:165], v133 offset:49152
	ds_read_b128 v[166:169], v133 offset:50176
	ds_read_b128 v[170:173], v132 offset:49152
	ds_read_b128 v[174:177], v132 offset:50176
	ds_read_b128 v[178:181], v131 offset:49152
	ds_read_b128 v[130:133], v131 offset:50176
	s_barrier
	s_waitcnt lgkmcnt(0)
	v_mfma_f32_16x16x32_bf16 v[60:63], v[154:157], v[142:145], v[60:63]
	v_mfma_f32_16x16x32_bf16 v[60:63], v[158:161], v[146:149], v[60:63]
	v_mfma_f32_16x16x32_bf16 v[56:59], v[158:161], v[138:141], v[56:59]
	v_mfma_f32_16x16x32_bf16 v[56:59], v[154:157], v[150:153], v[56:59]
	v_mfma_f32_16x16x32_bf16 v[48:51], v[162:165], v[150:153], v[48:51]
	v_mfma_f32_16x16x32_bf16 v[48:51], v[166:169], v[138:141], v[48:51]
	v_mfma_f32_16x16x32_bf16 v[52:55], v[166:169], v[146:149], v[52:55]
	v_mfma_f32_16x16x32_bf16 v[52:55], v[162:165], v[142:145], v[52:55]
	v_mfma_f32_16x16x32_bf16 v[44:47], v[170:173], v[142:145], v[44:47]
	v_mfma_f32_16x16x32_bf16 v[44:47], v[174:177], v[146:149], v[44:47]
	v_mfma_f32_16x16x32_bf16 v[40:43], v[174:177], v[138:141], v[40:43]
	v_mfma_f32_16x16x32_bf16 v[40:43], v[170:173], v[150:153], v[40:43]
	v_mfma_f32_16x16x32_bf16 v[32:35], v[178:181], v[150:153], v[32:35]
	v_mfma_f32_16x16x32_bf16 v[32:35], v[130:133], v[138:141], v[32:35]
	v_mfma_f32_16x16x32_bf16 v[36:39], v[130:133], v[146:149], v[36:39]
	v_mfma_f32_16x16x32_bf16 v[36:39], v[178:181], v[142:145], v[36:39]
	v_mfma_f32_16x16x32_bf16 v[4:7], v[178:181], v[192:195], v[4:7]
	v_mfma_f32_16x16x32_bf16 v[4:7], v[130:133], v[196:199], v[4:7]
	v_mfma_f32_16x16x32_bf16 v[28:31], v[158:161], v[196:199], v[28:31]
	v_mfma_f32_16x16x32_bf16 v[28:31], v[154:157], v[192:195], v[28:31]
	v_mfma_f32_16x16x32_bf16 v[24:27], v[154:157], v[200:203], v[24:27]
	v_mfma_f32_16x16x32_bf16 v[24:27], v[158:161], v[134:137], v[24:27]
	v_mfma_f32_16x16x32_bf16 v[16:19], v[166:169], v[134:137], v[16:19]
	v_mfma_f32_16x16x32_bf16 v[16:19], v[162:165], v[200:203], v[16:19]
	v_mfma_f32_16x16x32_bf16 v[20:23], v[162:165], v[192:195], v[20:23]
	v_mfma_f32_16x16x32_bf16 v[20:23], v[166:169], v[196:199], v[20:23]
	v_mfma_f32_16x16x32_bf16 v[12:15], v[174:177], v[196:199], v[12:15]
	v_mfma_f32_16x16x32_bf16 v[12:15], v[170:173], v[192:195], v[12:15]
	v_mfma_f32_16x16x32_bf16 v[8:11], v[170:173], v[200:203], v[8:11]
	v_mfma_f32_16x16x32_bf16 v[8:11], v[174:177], v[134:137], v[8:11]
	v_mfma_f32_16x16x32_bf16 v[0:3], v[130:133], v[134:137], v[0:3]
	v_mfma_f32_16x16x32_bf16 v[0:3], v[178:181], v[200:203], v[0:3]
	v_cmp_gt_u32_e32 vcc, s37, v129
	s_barrier
	s_and_saveexec_b64 s[16:17], vcc
	s_cbranch_execz .LBB0_228
	s_barrier

; #define STAGE(P, RS, SOFF, OFF, kt) do { const int _so = (SOFF) + (kt) * (BK * 2); \
;     _Pragma("unroll") for (int _i = 0; _i < 2; ++_i) { \
;       __builtin_amdgcn_raw_ptr_buffer_load_lds(RS, (__attribute__((address_space(3))) void*)((P) + wave * 1024 + _i * 8192), 16, OFF[_i], _so, 0, 0); } } while (0)
; #define LDA(dst, b, h) _Pragma("unroll") for (int m = 0; m < 4; ++m) _Pragma("unroll") for (int k = 0; k < 2; ++k) \
;     dst[m][k] = *reinterpret_cast<const bf16x8*>(SA(b, h) + lds_byte(wr * 64 + m * 16 + fr, k * 32 + fq * 8))
; #define LDB(dst, b, h) _Pragma("unroll") for (int n = 0; n < 2; ++n) _Pragma("unroll") for (int k = 0; k < 2; ++k) \
;     dst[n][k] = *reinterpret_cast<const bf16x8*>(SB(b, h) + lds_byte(wc * 32 + n * 16 + fr, k * 32 + fq * 8))
; #define WAIT_V(n) asm volatile("s_waitcnt vmcnt(" #n ")" ::: "memory")
; #define WAIT_L(n) asm volatile("s_waitcnt lgkmcnt(" #n ")" ::: "memory")
; #define BAR __builtin_amdgcn_s_barrier()
; #define SCHED __builtin_amdgcn_sched_barrier(0)
;     ...
;     for (int t = 0; t < nt - 2; t += 2) {
;       LDB(B0, 0, 0); SCHED; LDA(At, 0, 0); STAGE(SA(1, 1), rsA, sA1, offA, t + 1);
;       WAIT_L(8); BAR; WAIT_L(0); MMA(0, 0, At, B0); BAR; SCHED;
;       LDB(B1, 0, 1); STAGE(SB(0, 0), rsB, sB0, offB, t + 2);
;       BAR; WAIT_L(0); MMA(0, 1, At, B1); BAR;
;       LDA(At, 0, 1); STAGE(SA(0, 0), rsA, sA0, offA, t + 2);
;       BAR; WAIT_L(0); MMA(1, 0, At, B0); BAR; SCHED;
;       STAGE(SB(0, 1), rsB, sB1, offB, t + 2);
;       WAIT_V(6); BAR; MMA(1, 1, At, B1); BAR;
.Lmy_rot_291:
	ds_read_b128 v[152:155], v147
	ds_read_b128 v[156:159], v148
	ds_read_b128 v[160:163], v149
	ds_read_b128 v[164:167], v150
	s_add_i32 s5, s94, s3
	s_add_i32 s6, s5, 0x80
	s_mov_b32 m0, s36
	ds_read_b128 v[168:171], v129
	ds_read_b128 v[172:175], v129 offset:1024
	ds_read_b128 v[176:179], v132
	ds_read_b128 v[180:183], v132 offset:1024
	ds_read_b128 v[184:187], v131
	ds_read_b128 v[188:191], v131 offset:1024
	ds_read_b128 v[192:195], v130
	ds_read_b128 v[196:199], v130 offset:1024
	buffer_load_dwordx4 v141, s[8:11], s6 offen lds
	s_mov_b32 m0, s61
	s_nop 0
	buffer_load_dwordx4 v142, s[8:11], s6 offen lds
	s_waitcnt lgkmcnt(8)
	s_barrier
	s_waitcnt lgkmcnt(0)
	v_mfma_f32_16x16x32_bf16 v[124:127], v[152:155], v[168:171], v[124:127]
	v_mfma_f32_16x16x32_bf16 v[124:127], v[156:159], v[172:175], v[124:127]
	v_mfma_f32_16x16x32_bf16 v[120:123], v[164:167], v[172:175], v[120:123]
	v_mfma_f32_16x16x32_bf16 v[120:123], v[160:163], v[168:171], v[120:123]
	v_mfma_f32_16x16x32_bf16 v[112:115], v[160:163], v[176:179], v[112:115]
	v_mfma_f32_16x16x32_bf16 v[112:115], v[164:167], v[180:183], v[112:115]
	v_mfma_f32_16x16x32_bf16 v[116:119], v[156:159], v[180:183], v[116:119]
	v_mfma_f32_16x16x32_bf16 v[116:119], v[152:155], v[176:179], v[116:119]
	v_mfma_f32_16x16x32_bf16 v[108:111], v[152:155], v[184:187], v[108:111]
	v_mfma_f32_16x16x32_bf16 v[108:111], v[156:159], v[188:191], v[108:111]
	v_mfma_f32_16x16x32_bf16 v[104:107], v[164:167], v[188:191], v[104:107]
	v_mfma_f32_16x16x32_bf16 v[104:107], v[160:163], v[184:187], v[104:107]
	v_mfma_f32_16x16x32_bf16 v[96:99], v[160:163], v[192:195], v[96:99]
	v_mfma_f32_16x16x32_bf16 v[96:99], v[164:167], v[196:199], v[96:99]
	v_mfma_f32_16x16x32_bf16 v[100:103], v[156:159], v[196:199], v[100:103]
	v_mfma_f32_16x16x32_bf16 v[100:103], v[152:155], v[192:195], v[100:103]
	s_barrier
	s_add_i32 s6, s96, s3
	s_add_i32 s7, s6, 0x100
	s_mov_b32 s14, s10
	s_mov_b32 s15, s11
	s_mov_b32 m0, s37
	ds_read_b128 v[200:203], v143
	ds_read_b128 v[204:207], v144
	ds_read_b128 v[208:211], v145
	ds_read_b128 v[212:215], v146
	buffer_load_dwordx4 v141, s[12:15], s7 offen lds
	s_mov_b32 m0, s48
	s_nop 0
	buffer_load_dwordx4 v142, s[12:15], s7 offen lds
	s_barrier
	s_waitcnt lgkmcnt(0)
	v_mfma_f32_16x16x32_bf16 v[92:95], v[200:203], v[168:171], v[92:95]
	v_mfma_f32_16x16x32_bf16 v[92:95], v[204:207], v[172:175], v[92:95]
	v_mfma_f32_16x16x32_bf16 v[88:91], v[212:215], v[172:175], v[88:91]
	v_mfma_f32_16x16x32_bf16 v[88:91], v[208:211], v[168:171], v[88:91]
	v_mfma_f32_16x16x32_bf16 v[68:71], v[208:211], v[176:179], v[68:71]
	v_mfma_f32_16x16x32_bf16 v[68:71], v[212:215], v[180:183], v[68:71]
	v_mfma_f32_16x16x32_bf16 v[80:83], v[204:207], v[180:183], v[80:83]
	v_mfma_f32_16x16x32_bf16 v[80:83], v[200:203], v[176:179], v[80:83]
	v_mfma_f32_16x16x32_bf16 v[60:63], v[200:203], v[184:187], v[60:63]
	v_mfma_f32_16x16x32_bf16 v[60:63], v[204:207], v[188:191], v[60:63]
	v_mfma_f32_16x16x32_bf16 v[56:59], v[212:215], v[188:191], v[56:59]
	v_mfma_f32_16x16x32_bf16 v[56:59], v[208:211], v[184:187], v[56:59]
	v_mfma_f32_16x16x32_bf16 v[48:51], v[208:211], v[192:195], v[48:51]
	v_mfma_f32_16x16x32_bf16 v[48:51], v[212:215], v[196:199], v[48:51]
	v_mfma_f32_16x16x32_bf16 v[52:55], v[204:207], v[196:199], v[52:55]
	v_mfma_f32_16x16x32_bf16 v[52:55], v[200:203], v[192:195], v[52:55]
	s_barrier
	s_add_i32 s7, s95, s3
	s_add_i32 s22, s7, 0x100
	s_mov_b32 m0, s35
	ds_read_b128 v[168:171], v129 offset:16384
	ds_read_b128 v[172:175], v129 offset:17408
	ds_read_b128 v[176:179], v132 offset:16384
	ds_read_b128 v[180:183], v132 offset:17408
	ds_read_b128 v[184:187], v131 offset:16384
	ds_read_b128 v[188:191], v131 offset:17408
	ds_read_b128 v[192:195], v130 offset:16384
	ds_read_b128 v[196:199], v130 offset:17408
	buffer_load_dwordx4 v141, s[8:11], s22 offen lds
	s_mov_b32 m0, s49
	s_nop 0
	buffer_load_dwordx4 v142, s[8:11], s22 offen lds
	s_barrier
	s_waitcnt lgkmcnt(0)
	v_mfma_f32_16x16x32_bf16 v[44:47], v[152:155], v[168:171], v[44:47]
	v_mfma_f32_16x16x32_bf16 v[44:47], v[156:159], v[172:175], v[44:47]
	v_mfma_f32_16x16x32_bf16 v[40:43], v[164:167], v[172:175], v[40:43]
	v_mfma_f32_16x16x32_bf16 v[40:43], v[160:163], v[168:171], v[40:43]
	v_mfma_f32_16x16x32_bf16 v[32:35], v[160:163], v[176:179], v[32:35]
	v_mfma_f32_16x16x32_bf16 v[32:35], v[164:167], v[180:183], v[32:35]
	v_mfma_f32_16x16x32_bf16 v[36:39], v[156:159], v[180:183], v[36:39]
	v_mfma_f32_16x16x32_bf16 v[36:39], v[152:155], v[176:179], v[36:39]
	v_mfma_f32_16x16x32_bf16 v[28:31], v[152:155], v[184:187], v[28:31]
	v_mfma_f32_16x16x32_bf16 v[28:31], v[156:159], v[188:191], v[28:31]
	v_mfma_f32_16x16x32_bf16 v[24:27], v[164:167], v[188:191], v[24:27]
	v_mfma_f32_16x16x32_bf16 v[24:27], v[160:163], v[184:187], v[24:27]
	v_mfma_f32_16x16x32_bf16 v[16:19], v[160:163], v[192:195], v[16:19]
	v_mfma_f32_16x16x32_bf16 v[16:19], v[164:167], v[196:199], v[16:19]
	v_mfma_f32_16x16x32_bf16 v[20:23], v[156:159], v[196:199], v[20:23]
	v_mfma_f32_16x16x32_bf16 v[20:23], v[152:155], v[192:195], v[20:23]
	s_barrier
	s_add_i32 s22, s97, s3
	s_add_i32 s23, s22, 0x100
	s_mov_b32 m0, s38
	s_nop 0
	buffer_load_dwordx4 v141, s[12:15], s23 offen lds
	s_mov_b32 m0, s54
	s_nop 0
	buffer_load_dwordx4 v142, s[12:15], s23 offen lds
	s_waitcnt vmcnt(6)
	s_barrier
; #define STAGE(P, RS, SOFF, OFF, kt) do { const int _so = (SOFF) + (kt) * (BK * 2); \
;     _Pragma("unroll") for (int _i = 0; _i < 2; ++_i) { \
;       __builtin_amdgcn_raw_ptr_buffer_load_lds(RS, (__attribute__((address_space(3))) void*)((P) + wave * 1024 + _i * 8192), 16, OFF[_i], _so, 0, 0); } } while (0)
; #define LDA(dst, b, h) _Pragma("unroll") for (int m = 0; m < 4; ++m) _Pragma("unroll") for (int k = 0; k < 2; ++k) \
;     dst[m][k] = *reinterpret_cast<const bf16x8*>(SA(b, h) + lds_byte(wr * 64 + m * 16 + fr, k * 32 + fq * 8))
; #define LDB(dst, b, h) _Pragma("unroll") for (int n = 0; n < 2; ++n) _Pragma("unroll") for (int k = 0; k < 2; ++k) \
;     dst[n][k] = *reinterpret_cast<const bf16x8*>(SB(b, h) + lds_byte(wc * 32 + n * 16 + fr, k * 32 + fq * 8))
; #define WAIT_V(n) asm volatile("s_waitcnt vmcnt(" #n ")" ::: "memory")
; #define WAIT_L(n) asm volatile("s_waitcnt lgkmcnt(" #n ")" ::: "memory")
; #define BAR __builtin_amdgcn_s_barrier()
; #define SCHED __builtin_amdgcn_sched_barrier(0)
;     ...
;       WAIT_V(6); BAR; MMA(1, 1, At, B1); BAR;
;       LDB(B0, 1, 0); SCHED; LDA(At, 1, 0); STAGE(SA(0, 1), rsA, sA1, offA, t + 2);
;       WAIT_L(8); BAR; WAIT_L(0); MMA(0, 0, At, B0); BAR; SCHED;
;       LDB(B1, 1, 1); STAGE(SB(1, 0), rsB, sB0, offB, t + 3);
;       BAR; WAIT_L(0); MMA(0, 1, At, B1); BAR;
;       LDA(At, 1, 1); STAGE(SA(1, 0), rsA, sA0, offA, t + 3);
;       BAR; WAIT_L(0); MMA(1, 0, At, B0); BAR; SCHED;
	v_mfma_f32_16x16x32_bf16 v[12:15], v[200:203], v[168:171], v[12:15]
	v_mfma_f32_16x16x32_bf16 v[12:15], v[204:207], v[172:175], v[12:15]
	v_mfma_f32_16x16x32_bf16 v[8:11], v[212:215], v[172:175], v[8:11]
	v_mfma_f32_16x16x32_bf16 v[8:11], v[208:211], v[168:171], v[8:11]
	v_mfma_f32_16x16x32_bf16 v[0:3], v[208:211], v[176:179], v[0:3]
	v_mfma_f32_16x16x32_bf16 v[0:3], v[212:215], v[180:183], v[0:3]
	v_mfma_f32_16x16x32_bf16 v[4:7], v[204:207], v[180:183], v[4:7]
	v_mfma_f32_16x16x32_bf16 v[4:7], v[200:203], v[176:179], v[4:7]
	v_mfma_f32_16x16x32_bf16 v[64:67], v[200:203], v[184:187], v[64:67]
	v_mfma_f32_16x16x32_bf16 v[64:67], v[204:207], v[188:191], v[64:67]
	v_mfma_f32_16x16x32_bf16 v[72:75], v[212:215], v[188:191], v[72:75]
	v_mfma_f32_16x16x32_bf16 v[72:75], v[208:211], v[184:187], v[72:75]
	v_mfma_f32_16x16x32_bf16 v[84:87], v[208:211], v[192:195], v[84:87]
	v_mfma_f32_16x16x32_bf16 v[84:87], v[212:215], v[196:199], v[84:87]
	v_mfma_f32_16x16x32_bf16 v[76:79], v[204:207], v[196:199], v[76:79]
	v_mfma_f32_16x16x32_bf16 v[76:79], v[200:203], v[192:195], v[76:79]
	s_barrier
	ds_read_b128 v[152:155], v137
	ds_read_b128 v[156:159], v138
	ds_read_b128 v[160:163], v139
	ds_read_b128 v[164:167], v140
	s_addk_i32 s5, 0x100
	s_mov_b32 m0, s39
	ds_read_b128 v[168:171], v129 offset:32768
	ds_read_b128 v[172:175], v129 offset:33792
	ds_read_b128 v[176:179], v132 offset:32768
	ds_read_b128 v[180:183], v132 offset:33792
	ds_read_b128 v[184:187], v131 offset:32768
	ds_read_b128 v[188:191], v131 offset:33792
	ds_read_b128 v[192:195], v130 offset:32768
	ds_read_b128 v[196:199], v130 offset:33792
	buffer_load_dwordx4 v141, s[8:11], s5 offen lds
	s_mov_b32 m0, s55
	s_nop 0
	buffer_load_dwordx4 v142, s[8:11], s5 offen lds
	s_waitcnt lgkmcnt(8)
	s_barrier
	s_waitcnt lgkmcnt(0)
	v_mfma_f32_16x16x32_bf16 v[124:127], v[152:155], v[168:171], v[124:127]
	v_mfma_f32_16x16x32_bf16 v[124:127], v[156:159], v[172:175], v[124:127]
	v_mfma_f32_16x16x32_bf16 v[120:123], v[164:167], v[172:175], v[120:123]
	v_mfma_f32_16x16x32_bf16 v[120:123], v[160:163], v[168:171], v[120:123]
	v_mfma_f32_16x16x32_bf16 v[112:115], v[160:163], v[176:179], v[112:115]
	v_mfma_f32_16x16x32_bf16 v[112:115], v[164:167], v[180:183], v[112:115]
	v_mfma_f32_16x16x32_bf16 v[116:119], v[156:159], v[180:183], v[116:119]
	v_mfma_f32_16x16x32_bf16 v[116:119], v[152:155], v[176:179], v[116:119]
	v_mfma_f32_16x16x32_bf16 v[108:111], v[152:155], v[184:187], v[108:111]
	v_mfma_f32_16x16x32_bf16 v[108:111], v[156:159], v[188:191], v[108:111]
	v_mfma_f32_16x16x32_bf16 v[104:107], v[164:167], v[188:191], v[104:107]
	v_mfma_f32_16x16x32_bf16 v[104:107], v[160:163], v[184:187], v[104:107]
	v_mfma_f32_16x16x32_bf16 v[96:99], v[160:163], v[192:195], v[96:99]
	v_mfma_f32_16x16x32_bf16 v[96:99], v[164:167], v[196:199], v[96:99]
	v_mfma_f32_16x16x32_bf16 v[100:103], v[156:159], v[196:199], v[100:103]
	v_mfma_f32_16x16x32_bf16 v[100:103], v[152:155], v[192:195], v[100:103]
	s_barrier
	s_addk_i32 s6, 0x180
	s_mov_b32 m0, s42
	ds_read_b128 v[200:203], v133
	ds_read_b128 v[204:207], v134
	ds_read_b128 v[208:211], v135
	ds_read_b128 v[212:215], v136
	buffer_load_dwordx4 v141, s[12:15], s6 offen lds
	s_mov_b32 m0, s58
	s_nop 0
	buffer_load_dwordx4 v142, s[12:15], s6 offen lds
	s_barrier
	s_waitcnt lgkmcnt(0)
	v_mfma_f32_16x16x32_bf16 v[92:95], v[200:203], v[168:171], v[92:95]
	v_mfma_f32_16x16x32_bf16 v[92:95], v[204:207], v[172:175], v[92:95]
	v_mfma_f32_16x16x32_bf16 v[88:91], v[212:215], v[172:175], v[88:91]
	v_mfma_f32_16x16x32_bf16 v[88:91], v[208:211], v[168:171], v[88:91]
	v_mfma_f32_16x16x32_bf16 v[68:71], v[208:211], v[176:179], v[68:71]
	v_mfma_f32_16x16x32_bf16 v[68:71], v[212:215], v[180:183], v[68:71]
	v_mfma_f32_16x16x32_bf16 v[80:83], v[204:207], v[180:183], v[80:83]
	v_mfma_f32_16x16x32_bf16 v[80:83], v[200:203], v[176:179], v[80:83]
	v_mfma_f32_16x16x32_bf16 v[60:63], v[200:203], v[184:187], v[60:63]
	v_mfma_f32_16x16x32_bf16 v[60:63], v[204:207], v[188:191], v[60:63]
	v_mfma_f32_16x16x32_bf16 v[56:59], v[212:215], v[188:191], v[56:59]
	v_mfma_f32_16x16x32_bf16 v[56:59], v[208:211], v[184:187], v[56:59]
	v_mfma_f32_16x16x32_bf16 v[48:51], v[208:211], v[192:195], v[48:51]
	v_mfma_f32_16x16x32_bf16 v[48:51], v[212:215], v[196:199], v[48:51]
	v_mfma_f32_16x16x32_bf16 v[52:55], v[204:207], v[196:199], v[52:55]
	v_mfma_f32_16x16x32_bf16 v[52:55], v[200:203], v[192:195], v[52:55]
	s_barrier
	s_addk_i32 s7, 0x180
	s_mov_b32 m0, s43
	ds_read_b128 v[168:171], v129 offset:49152
	ds_read_b128 v[172:175], v129 offset:50176
	ds_read_b128 v[176:179], v132 offset:49152
	ds_read_b128 v[180:183], v132 offset:50176
	ds_read_b128 v[184:187], v131 offset:49152
	ds_read_b128 v[188:191], v131 offset:50176
	ds_read_b128 v[192:195], v130 offset:49152
	ds_read_b128 v[196:199], v130 offset:50176
	buffer_load_dwordx4 v141, s[8:11], s7 offen lds
	s_mov_b32 m0, s59
	s_nop 0
	buffer_load_dwordx4 v142, s[8:11], s7 offen lds
	s_barrier
	s_waitcnt lgkmcnt(0)
	v_mfma_f32_16x16x32_bf16 v[44:47], v[152:155], v[168:171], v[44:47]
	v_mfma_f32_16x16x32_bf16 v[44:47], v[156:159], v[172:175], v[44:47]
	v_mfma_f32_16x16x32_bf16 v[40:43], v[164:167], v[172:175], v[40:43]
	v_mfma_f32_16x16x32_bf16 v[40:43], v[160:163], v[168:171], v[40:43]
	v_mfma_f32_16x16x32_bf16 v[32:35], v[160:163], v[176:179], v[32:35]
	v_mfma_f32_16x16x32_bf16 v[32:35], v[164:167], v[180:183], v[32:35]
	v_mfma_f32_16x16x32_bf16 v[36:39], v[156:159], v[180:183], v[36:39]
	v_mfma_f32_16x16x32_bf16 v[36:39], v[152:155], v[176:179], v[36:39]
	v_mfma_f32_16x16x32_bf16 v[28:31], v[152:155], v[184:187], v[28:31]
	v_mfma_f32_16x16x32_bf16 v[28:31], v[156:159], v[188:191], v[28:31]
	v_mfma_f32_16x16x32_bf16 v[24:27], v[164:167], v[188:191], v[24:27]
	v_mfma_f32_16x16x32_bf16 v[24:27], v[160:163], v[184:187], v[24:27]
	v_mfma_f32_16x16x32_bf16 v[16:19], v[160:163], v[192:195], v[16:19]
	v_mfma_f32_16x16x32_bf16 v[16:19], v[164:167], v[196:199], v[16:19]
	v_mfma_f32_16x16x32_bf16 v[20:23], v[156:159], v[196:199], v[20:23]
	v_mfma_f32_16x16x32_bf16 v[20:23], v[152:155], v[192:195], v[20:23]
	s_barrier
; #define STAGE(P, RS, SOFF, OFF, kt) do { const int _so = (SOFF) + (kt) * (BK * 2); \
;     _Pragma("unroll") for (int _i = 0; _i < 2; ++_i) { \
;       __builtin_amdgcn_raw_ptr_buffer_load_lds(RS, (__attribute__((address_space(3))) void*)((P) + wave * 1024 + _i * 8192), 16, OFF[_i], _so, 0, 0); } } while (0)
; #define LDA(dst, b, h) _Pragma("unroll") for (int m = 0; m < 4; ++m) _Pragma("unroll") for (int k = 0; k < 2; ++k) \
;     dst[m][k] = *reinterpret_cast<const bf16x8*>(SA(b, h) + lds_byte(wr * 64 + m * 16 + fr, k * 32 + fq * 8))
; #define LDB(dst, b, h) _Pragma("unroll") for (int n = 0; n < 2; ++n) _Pragma("unroll") for (int k = 0; k < 2; ++k) \
;     dst[n][k] = *reinterpret_cast<const bf16x8*>(SB(b, h) + lds_byte(wc * 32 + n * 16 + fr, k * 32 + fq * 8))
; #define WAIT_V(n) asm volatile("s_waitcnt vmcnt(" #n ")" ::: "memory")
; #define WAIT_L(n) asm volatile("s_waitcnt lgkmcnt(" #n ")" ::: "memory")
; #define BAR __builtin_amdgcn_s_barrier()
;     ...
;       STAGE(SB(1, 1), rsB, sB1, offB, t + 3);
;       WAIT_V(6); BAR; MMA(1, 1, At, B1); BAR;
;     }
;     { LDB(B0, 0, 0); LDA(At, 0, 0); STAGE(SA(1, 1), rsA, sA1, offA, nt - 1);
;       BAR; WAIT_L(0); MMA(0, 0, At, B0); BAR;
;       LDB(B1, 0, 1); BAR; WAIT_L(0); MMA(0, 1, At, B1); BAR;
;       LDA(At, 0, 1); WAIT_V(4); BAR; WAIT_L(0); MMA(1, 0, At, B0); MMA(1, 1, At, B1); BAR; }
	s_addk_i32 s22, 0x180
	s_mov_b32 m0, s44
	s_nop 0
	buffer_load_dwordx4 v141, s[12:15], s22 offen lds
	s_mov_b32 m0, s60
	s_nop 0
	buffer_load_dwordx4 v142, s[12:15], s22 offen lds
	s_add_i32 s1, s1, 2
	s_addk_i32 s3, 0x100
	s_cmp_gt_u32 s1, 11
	s_cbranch_scc0 .LBB0_291
	s_waitcnt vmcnt(6)
	s_barrier
	v_mfma_f32_16x16x32_bf16 v[12:15], v[200:203], v[168:171], v[12:15]
	v_mfma_f32_16x16x32_bf16 v[12:15], v[204:207], v[172:175], v[12:15]
	v_mfma_f32_16x16x32_bf16 v[8:11], v[212:215], v[172:175], v[8:11]
	v_mfma_f32_16x16x32_bf16 v[8:11], v[208:211], v[168:171], v[8:11]
	v_mfma_f32_16x16x32_bf16 v[0:3], v[208:211], v[176:179], v[0:3]
	v_mfma_f32_16x16x32_bf16 v[0:3], v[212:215], v[180:183], v[0:3]
	v_mfma_f32_16x16x32_bf16 v[4:7], v[204:207], v[180:183], v[4:7]
	v_mfma_f32_16x16x32_bf16 v[4:7], v[200:203], v[176:179], v[4:7]
	v_mfma_f32_16x16x32_bf16 v[64:67], v[200:203], v[184:187], v[64:67]
	v_mfma_f32_16x16x32_bf16 v[64:67], v[204:207], v[188:191], v[64:67]
	v_mfma_f32_16x16x32_bf16 v[72:75], v[212:215], v[188:191], v[72:75]
	v_mfma_f32_16x16x32_bf16 v[72:75], v[208:211], v[184:187], v[72:75]
	v_mfma_f32_16x16x32_bf16 v[84:87], v[208:211], v[192:195], v[84:87]
	v_mfma_f32_16x16x32_bf16 v[84:87], v[212:215], v[196:199], v[84:87]
	v_mfma_f32_16x16x32_bf16 v[76:79], v[204:207], v[196:199], v[76:79]
	v_mfma_f32_16x16x32_bf16 v[76:79], v[200:203], v[192:195], v[76:79]
	s_barrier
	s_add_i32 s1, s94, 0x780
	s_mov_b32 m0, s36
	ds_read_b128 v[152:155], v147
	ds_read_b128 v[156:159], v148
	ds_read_b128 v[160:163], v149
	ds_read_b128 v[148:151], v150
	ds_read_b128 v[164:167], v129
	ds_read_b128 v[168:171], v129 offset:1024
	ds_read_b128 v[172:175], v132
	ds_read_b128 v[176:179], v132 offset:1024
	ds_read_b128 v[180:183], v131
	ds_read_b128 v[184:187], v131 offset:1024
	ds_read_b128 v[188:191], v130
	ds_read_b128 v[192:195], v130 offset:1024
	buffer_load_dwordx4 v141, s[8:11], s1 offen lds
	s_mov_b32 m0, s61
	s_nop 0
	buffer_load_dwordx4 v142, s[8:11], s1 offen lds
	s_barrier
	s_waitcnt lgkmcnt(0)
	v_mfma_f32_16x16x32_bf16 v[124:127], v[152:155], v[164:167], v[124:127]
	v_mfma_f32_16x16x32_bf16 v[124:127], v[156:159], v[168:171], v[124:127]
	v_mfma_f32_16x16x32_bf16 v[120:123], v[148:151], v[168:171], v[120:123]
	v_mfma_f32_16x16x32_bf16 v[120:123], v[160:163], v[164:167], v[120:123]
	v_mfma_f32_16x16x32_bf16 v[112:115], v[160:163], v[172:175], v[112:115]
	v_mfma_f32_16x16x32_bf16 v[112:115], v[148:151], v[176:179], v[112:115]
	v_mfma_f32_16x16x32_bf16 v[116:119], v[156:159], v[176:179], v[116:119]
	v_mfma_f32_16x16x32_bf16 v[116:119], v[152:155], v[172:175], v[116:119]
	v_mfma_f32_16x16x32_bf16 v[108:111], v[152:155], v[180:183], v[108:111]
	v_mfma_f32_16x16x32_bf16 v[108:111], v[156:159], v[184:187], v[108:111]
	v_mfma_f32_16x16x32_bf16 v[104:107], v[148:151], v[184:187], v[104:107]
	v_mfma_f32_16x16x32_bf16 v[104:107], v[160:163], v[180:183], v[104:107]
	v_mfma_f32_16x16x32_bf16 v[96:99], v[160:163], v[188:191], v[96:99]
	v_mfma_f32_16x16x32_bf16 v[96:99], v[148:151], v[192:195], v[96:99]
	v_mfma_f32_16x16x32_bf16 v[100:103], v[156:159], v[192:195], v[100:103]
	v_mfma_f32_16x16x32_bf16 v[100:103], v[152:155], v[188:191], v[100:103]
	s_barrier
	ds_read_b128 v[196:199], v143
	ds_read_b128 v[200:203], v144
	ds_read_b128 v[142:145], v145
	ds_read_b128 v[204:207], v146
	s_barrier
	s_waitcnt lgkmcnt(0)
	v_mfma_f32_16x16x32_bf16 v[88:91], v[142:145], v[164:167], v[88:91]
	v_mfma_f32_16x16x32_bf16 v[80:83], v[196:199], v[172:175], v[80:83]
	v_mfma_f32_16x16x32_bf16 v[60:63], v[196:199], v[180:183], v[60:63]
	v_mfma_f32_16x16x32_bf16 v[56:59], v[142:145], v[180:183], v[56:59]
	v_mfma_f32_16x16x32_bf16 v[52:55], v[196:199], v[188:191], v[52:55]
	v_mfma_f32_16x16x32_bf16 v[48:51], v[142:145], v[188:191], v[48:51]
	v_mfma_f32_16x16x32_bf16 v[92:95], v[196:199], v[164:167], v[92:95]
	v_mfma_f32_16x16x32_bf16 v[68:71], v[142:145], v[172:175], v[68:71]
	v_mfma_f32_16x16x32_bf16 v[88:91], v[204:207], v[168:171], v[88:91]
	v_mfma_f32_16x16x32_bf16 v[80:83], v[200:203], v[176:179], v[80:83]
	v_mfma_f32_16x16x32_bf16 v[60:63], v[200:203], v[184:187], v[60:63]
	v_mfma_f32_16x16x32_bf16 v[56:59], v[204:207], v[184:187], v[56:59]
	v_mfma_f32_16x16x32_bf16 v[52:55], v[200:203], v[192:195], v[52:55]
	v_mfma_f32_16x16x32_bf16 v[48:51], v[204:207], v[192:195], v[48:51]
	v_mfma_f32_16x16x32_bf16 v[164:167], v[200:203], v[168:171], v[92:95]
	v_mfma_f32_16x16x32_bf16 v[168:171], v[204:207], v[176:179], v[68:71]
	s_barrier
	s_nop 0
	ds_read_b128 v[68:71], v129 offset:16384
	ds_read_b128 v[92:95], v129 offset:17408
	ds_read_b128 v[172:175], v132 offset:16384
	ds_read_b128 v[176:179], v132 offset:17408
	ds_read_b128 v[180:183], v131 offset:16384
	ds_read_b128 v[184:187], v131 offset:17408
	ds_read_b128 v[188:191], v130 offset:16384
	ds_read_b128 v[192:195], v130 offset:17408
	s_waitcnt vmcnt(4)
	s_barrier
; #define LDA(dst, b, h) _Pragma("unroll") for (int m = 0; m < 4; ++m) _Pragma("unroll") for (int k = 0; k < 2; ++k) \
;     dst[m][k] = *reinterpret_cast<const bf16x8*>(SA(b, h) + lds_byte(wr * 64 + m * 16 + fr, k * 32 + fq * 8))
; #define LDB(dst, b, h) _Pragma("unroll") for (int n = 0; n < 2; ++n) _Pragma("unroll") for (int k = 0; k < 2; ++k) \
;     dst[n][k] = *reinterpret_cast<const bf16x8*>(SB(b, h) + lds_byte(wc * 32 + n * 16 + fr, k * 32 + fq * 8))
; #define WAIT_V(n) asm volatile("s_waitcnt vmcnt(" #n ")" ::: "memory")
; #define WAIT_L(n) asm volatile("s_waitcnt lgkmcnt(" #n ")" ::: "memory")
; #define BAR __builtin_amdgcn_s_barrier()
;     ...
;       LDA(At, 0, 1); WAIT_V(4); BAR; WAIT_L(0); MMA(1, 0, At, B0); MMA(1, 1, At, B1); BAR; }
;     { LDB(B0, 1, 0); LDA(At, 1, 0); WAIT_V(2); BAR; WAIT_L(0); MMA(0, 0, At, B0); BAR;
;       LDB(B1, 1, 1); WAIT_V(0); BAR; WAIT_L(0); MMA(0, 1, At, B1); BAR;
	s_waitcnt lgkmcnt(0)
	v_mfma_f32_16x16x32_bf16 v[44:47], v[152:155], v[68:71], v[44:47]
	v_mfma_f32_16x16x32_bf16 v[40:43], v[160:163], v[68:71], v[40:43]
	v_mfma_f32_16x16x32_bf16 v[36:39], v[152:155], v[172:175], v[36:39]
	v_mfma_f32_16x16x32_bf16 v[32:35], v[160:163], v[172:175], v[32:35]
	v_mfma_f32_16x16x32_bf16 v[28:31], v[152:155], v[180:183], v[28:31]
	v_mfma_f32_16x16x32_bf16 v[24:27], v[160:163], v[180:183], v[24:27]
	v_mfma_f32_16x16x32_bf16 v[20:23], v[152:155], v[188:191], v[20:23]
	v_mfma_f32_16x16x32_bf16 v[16:19], v[160:163], v[188:191], v[16:19]
	v_mfma_f32_16x16x32_bf16 v[44:47], v[156:159], v[92:95], v[44:47]
	v_mfma_f32_16x16x32_bf16 v[40:43], v[148:151], v[92:95], v[40:43]
	v_mfma_f32_16x16x32_bf16 v[36:39], v[156:159], v[176:179], v[36:39]
	v_mfma_f32_16x16x32_bf16 v[32:35], v[148:151], v[176:179], v[32:35]
	v_mfma_f32_16x16x32_bf16 v[28:31], v[156:159], v[184:187], v[28:31]
	v_mfma_f32_16x16x32_bf16 v[24:27], v[148:151], v[184:187], v[24:27]
	v_mfma_f32_16x16x32_bf16 v[20:23], v[156:159], v[192:195], v[20:23]
	v_mfma_f32_16x16x32_bf16 v[16:19], v[148:151], v[192:195], v[16:19]
	v_mfma_f32_16x16x32_bf16 v[4:7], v[196:199], v[172:175], v[4:7]
	v_mfma_f32_16x16x32_bf16 v[0:3], v[142:145], v[172:175], v[0:3]
	v_mfma_f32_16x16x32_bf16 v[12:15], v[196:199], v[68:71], v[12:15]
	v_mfma_f32_16x16x32_bf16 v[8:11], v[142:145], v[68:71], v[8:11]
	v_mfma_f32_16x16x32_bf16 v[64:67], v[196:199], v[180:183], v[64:67]
	v_mfma_f32_16x16x32_bf16 v[68:71], v[142:145], v[180:183], v[72:75]
	v_mfma_f32_16x16x32_bf16 v[72:75], v[196:199], v[188:191], v[76:79]
	v_mfma_f32_16x16x32_bf16 v[76:79], v[142:145], v[188:191], v[84:87]
	v_mfma_f32_16x16x32_bf16 v[4:7], v[200:203], v[176:179], v[4:7]
	v_mfma_f32_16x16x32_bf16 v[0:3], v[204:207], v[176:179], v[0:3]
	v_mfma_f32_16x16x32_bf16 v[142:145], v[200:203], v[92:95], v[12:15]
	v_mfma_f32_16x16x32_bf16 v[146:149], v[204:207], v[92:95], v[8:11]
	v_mfma_f32_16x16x32_bf16 v[150:153], v[200:203], v[184:187], v[64:67]
	v_mfma_f32_16x16x32_bf16 v[154:157], v[204:207], v[184:187], v[68:71]
	v_mfma_f32_16x16x32_bf16 v[158:161], v[200:203], v[192:195], v[72:75]
	v_mfma_f32_16x16x32_bf16 v[172:175], v[204:207], v[192:195], v[76:79]
	s_barrier
	ds_read_b128 v[8:11], v137
	ds_read_b128 v[12:15], v138
	ds_read_b128 v[176:179], v139
	ds_read_b128 v[138:141], v140
	ds_read_b128 v[64:67], v129 offset:32768
	ds_read_b128 v[72:75], v129 offset:33792
	ds_read_b128 v[180:183], v132 offset:32768
	ds_read_b128 v[184:187], v132 offset:33792
	ds_read_b128 v[188:191], v131 offset:32768
	ds_read_b128 v[192:195], v131 offset:33792
	ds_read_b128 v[196:199], v130 offset:32768
	ds_read_b128 v[200:203], v130 offset:33792
	s_waitcnt vmcnt(2)
	s_barrier
	s_waitcnt lgkmcnt(0)
	v_mfma_f32_16x16x32_bf16 v[68:71], v[8:11], v[64:67], v[124:127]
	v_mfma_f32_16x16x32_bf16 v[76:79], v[176:179], v[64:67], v[120:123]
	v_mfma_f32_16x16x32_bf16 v[84:87], v[8:11], v[180:183], v[116:119]
	v_mfma_f32_16x16x32_bf16 v[92:95], v[176:179], v[180:183], v[112:115]
	v_mfma_f32_16x16x32_bf16 v[112:115], v[8:11], v[188:191], v[108:111]
	v_mfma_f32_16x16x32_bf16 v[104:107], v[176:179], v[188:191], v[104:107]
	v_mfma_f32_16x16x32_bf16 v[120:123], v[8:11], v[196:199], v[100:103]
	v_mfma_f32_16x16x32_bf16 v[96:99], v[176:179], v[196:199], v[96:99]
	v_mfma_f32_16x16x32_bf16 v[124:127], v[12:15], v[72:75], v[68:71]
	v_mfma_f32_16x16x32_bf16 v[116:119], v[138:141], v[72:75], v[76:79]
	v_mfma_f32_16x16x32_bf16 v[108:111], v[12:15], v[184:187], v[84:87]
	v_mfma_f32_16x16x32_bf16 v[100:103], v[138:141], v[184:187], v[92:95]
	v_mfma_f32_16x16x32_bf16 v[92:95], v[12:15], v[192:195], v[112:115]
	v_mfma_f32_16x16x32_bf16 v[84:87], v[138:141], v[192:195], v[104:107]
	v_mfma_f32_16x16x32_bf16 v[76:79], v[12:15], v[200:203], v[120:123]
	v_mfma_f32_16x16x32_bf16 v[68:71], v[138:141], v[200:203], v[96:99]
	s_barrier
; #define LDA(dst, b, h) _Pragma("unroll") for (int m = 0; m < 4; ++m) _Pragma("unroll") for (int k = 0; k < 2; ++k) \
;     dst[m][k] = *reinterpret_cast<const bf16x8*>(SA(b, h) + lds_byte(wr * 64 + m * 16 + fr, k * 32 + fq * 8))
; #define LDB(dst, b, h) _Pragma("unroll") for (int n = 0; n < 2; ++n) _Pragma("unroll") for (int k = 0; k < 2; ++k) \
;     dst[n][k] = *reinterpret_cast<const bf16x8*>(SB(b, h) + lds_byte(wc * 32 + n * 16 + fr, k * 32 + fq * 8))
; #define WAIT_V(n) asm volatile("s_waitcnt vmcnt(" #n ")" ::: "memory")
; #define WAIT_L(n) asm volatile("s_waitcnt lgkmcnt(" #n ")" ::: "memory")
; #define BAR __builtin_amdgcn_s_barrier()
;     ...
;       LDB(B1, 1, 1); WAIT_V(0); BAR; WAIT_L(0); MMA(0, 1, At, B1); BAR;
;       LDA(At, 1, 1); BAR; WAIT_L(0); MMA(1, 0, At, B0); MMA(1, 1, At, B1); BAR; }
;     if (wr == 0) BAR;
	ds_read_b128 v[204:207], v133
	ds_read_b128 v[208:211], v134
	ds_read_b128 v[212:215], v135
	ds_read_b128 v[134:137], v136
	s_waitcnt vmcnt(0)
	s_barrier
	s_waitcnt lgkmcnt(0)
	v_mfma_f32_16x16x32_bf16 v[96:99], v[204:207], v[64:67], v[164:167]
	v_mfma_f32_16x16x32_bf16 v[64:67], v[212:215], v[64:67], v[88:91]
	v_mfma_f32_16x16x32_bf16 v[80:83], v[204:207], v[180:183], v[80:83]
	v_mfma_f32_16x16x32_bf16 v[88:91], v[212:215], v[180:183], v[168:171]
	v_mfma_f32_16x16x32_bf16 v[60:63], v[204:207], v[188:191], v[60:63]
	v_mfma_f32_16x16x32_bf16 v[56:59], v[212:215], v[188:191], v[56:59]
	v_mfma_f32_16x16x32_bf16 v[52:55], v[204:207], v[196:199], v[52:55]
	v_mfma_f32_16x16x32_bf16 v[48:51], v[212:215], v[196:199], v[48:51]
	v_mfma_f32_16x16x32_bf16 v[120:123], v[208:211], v[72:75], v[96:99]
	v_mfma_f32_16x16x32_bf16 v[112:115], v[134:137], v[72:75], v[64:67]
	v_mfma_f32_16x16x32_bf16 v[104:107], v[208:211], v[184:187], v[80:83]
	v_mfma_f32_16x16x32_bf16 v[96:99], v[134:137], v[184:187], v[88:91]
	v_mfma_f32_16x16x32_bf16 v[88:91], v[208:211], v[192:195], v[60:63]
	v_mfma_f32_16x16x32_bf16 v[80:83], v[134:137], v[192:195], v[56:59]
	v_mfma_f32_16x16x32_bf16 v[72:75], v[208:211], v[200:203], v[52:55]
	v_mfma_f32_16x16x32_bf16 v[64:67], v[134:137], v[200:203], v[48:51]
	s_barrier
	s_nop 0
	ds_read_b128 v[48:51], v129 offset:49152
	ds_read_b128 v[162:165], v129 offset:50176
	ds_read_b128 v[52:55], v132 offset:49152
	ds_read_b128 v[166:169], v132 offset:50176
	ds_read_b128 v[180:183], v131 offset:49152
	ds_read_b128 v[184:187], v131 offset:50176
	ds_read_b128 v[188:191], v130 offset:49152
	ds_read_b128 v[130:133], v130 offset:50176
	s_barrier
	s_waitcnt lgkmcnt(0)
	v_mfma_f32_16x16x32_bf16 v[44:47], v[8:11], v[48:51], v[44:47]
	v_mfma_f32_16x16x32_bf16 v[40:43], v[176:179], v[48:51], v[40:43]
	v_mfma_f32_16x16x32_bf16 v[36:39], v[8:11], v[52:55], v[36:39]
	v_mfma_f32_16x16x32_bf16 v[32:35], v[176:179], v[52:55], v[32:35]
	v_mfma_f32_16x16x32_bf16 v[28:31], v[8:11], v[180:183], v[28:31]
	v_mfma_f32_16x16x32_bf16 v[24:27], v[176:179], v[180:183], v[24:27]
	v_mfma_f32_16x16x32_bf16 v[8:11], v[8:11], v[188:191], v[20:23]
	v_mfma_f32_16x16x32_bf16 v[16:19], v[176:179], v[188:191], v[16:19]
	v_mfma_f32_16x16x32_bf16 v[60:63], v[12:15], v[162:165], v[44:47]
	v_mfma_f32_16x16x32_bf16 v[56:59], v[138:141], v[162:165], v[40:43]
	v_mfma_f32_16x16x32_bf16 v[44:47], v[12:15], v[166:169], v[36:39]
	v_mfma_f32_16x16x32_bf16 v[40:43], v[138:141], v[166:169], v[32:35]
	v_mfma_f32_16x16x32_bf16 v[28:31], v[12:15], v[184:187], v[28:31]
	v_mfma_f32_16x16x32_bf16 v[24:27], v[138:141], v[184:187], v[24:27]
	v_mfma_f32_16x16x32_bf16 v[12:15], v[12:15], v[130:133], v[8:11]
	v_mfma_f32_16x16x32_bf16 v[8:11], v[138:141], v[130:133], v[16:19]
	v_mfma_f32_16x16x32_bf16 v[16:19], v[204:207], v[48:51], v[142:145]
	v_mfma_f32_16x16x32_bf16 v[20:23], v[212:215], v[48:51], v[146:149]
	v_mfma_f32_16x16x32_bf16 v[4:7], v[204:207], v[52:55], v[4:7]
	v_mfma_f32_16x16x32_bf16 v[0:3], v[212:215], v[52:55], v[0:3]
	v_mfma_f32_16x16x32_bf16 v[138:141], v[204:207], v[180:183], v[150:153]
	v_mfma_f32_16x16x32_bf16 v[142:145], v[212:215], v[180:183], v[154:157]
	v_mfma_f32_16x16x32_bf16 v[146:149], v[204:207], v[188:191], v[158:161]
	v_mfma_f32_16x16x32_bf16 v[150:153], v[212:215], v[188:191], v[172:175]
	v_mfma_f32_16x16x32_bf16 v[52:55], v[208:211], v[162:165], v[16:19]
	v_mfma_f32_16x16x32_bf16 v[48:51], v[134:137], v[162:165], v[20:23]
	v_mfma_f32_16x16x32_bf16 v[36:39], v[208:211], v[166:169], v[4:7]
	v_mfma_f32_16x16x32_bf16 v[32:35], v[134:137], v[166:169], v[0:3]
	v_mfma_f32_16x16x32_bf16 v[20:23], v[208:211], v[184:187], v[138:141]
	v_mfma_f32_16x16x32_bf16 v[16:19], v[134:137], v[184:187], v[142:145]
	v_mfma_f32_16x16x32_bf16 v[4:7], v[208:211], v[130:133], v[146:149]
	v_mfma_f32_16x16x32_bf16 v[0:3], v[134:137], v[130:133], v[150:153]
	v_cmp_gt_u32_e32 vcc, s46, v128
	s_barrier
	s_and_saveexec_b64 s[6:7], vcc
	s_cbranch_execz .LBB0_294
	s_barrier

; #define STAGE(P, RS, SOFF, OFF, kt) do { const int _so = (SOFF) + (kt) * (BK * 2); \
;     _Pragma("unroll") for (int _i = 0; _i < 2; ++_i) { \
;       __builtin_amdgcn_raw_ptr_buffer_load_lds(RS, (__attribute__((address_space(3))) void*)((P) + wave * 1024 + _i * 8192), 16, OFF[_i], _so, 0, 0); } } while (0)
; #define LDA(dst, b, h) _Pragma("unroll") for (int m = 0; m < 4; ++m) _Pragma("unroll") for (int k = 0; k < 2; ++k) \
;     dst[m][k] = *reinterpret_cast<const bf16x8*>(SA(b, h) + lds_byte(wr * 64 + m * 16 + fr, k * 32 + fq * 8))
; #define LDB(dst, b, h) _Pragma("unroll") for (int n = 0; n < 2; ++n) _Pragma("unroll") for (int k = 0; k < 2; ++k) \
;     dst[n][k] = *reinterpret_cast<const bf16x8*>(SB(b, h) + lds_byte(wc * 32 + n * 16 + fr, k * 32 + fq * 8))
; #define WAIT_V(n) asm volatile("s_waitcnt vmcnt(" #n ")" ::: "memory")
; #define WAIT_L(n) asm volatile("s_waitcnt lgkmcnt(" #n ")" ::: "memory")
; #define BAR __builtin_amdgcn_s_barrier()
; #define SCHED __builtin_amdgcn_sched_barrier(0)
;     ...
;     for (int t = 0; t < nt - 2; t += 2) {
;       LDB(B0, 0, 0); SCHED; LDA(At, 0, 0); STAGE(SA(1, 1), rsA, sA1, offA, t + 1);
;       WAIT_L(8); BAR; WAIT_L(0); MMA(0, 0, At, B0); BAR; SCHED;
;       LDB(B1, 0, 1); STAGE(SB(0, 0), rsB, sB0, offB, t + 2);
;       BAR; WAIT_L(0); MMA(0, 1, At, B1); BAR;
;       LDA(At, 0, 1); STAGE(SA(0, 0), rsA, sA0, offA, t + 2);
;       BAR; WAIT_L(0); MMA(1, 0, At, B0); BAR; SCHED;
;       STAGE(SB(0, 1), rsB, sB1, offB, t + 2);
;       WAIT_V(6); BAR; MMA(1, 1, At, B1); BAR;
.Lmy_rot_354:
	ds_read_b128 v[154:157], v149
	ds_read_b128 v[158:161], v150
	ds_read_b128 v[162:165], v151
	ds_read_b128 v[166:169], v152
	s_add_i32 s43, s37, s17
	s_add_i32 s10, s43, 0x80
	s_mov_b32 m0, s30
	ds_read_b128 v[170:173], v131
	ds_read_b128 v[174:177], v131 offset:1024
	ds_read_b128 v[178:181], v134
	ds_read_b128 v[182:185], v134 offset:1024
	ds_read_b128 v[186:189], v133
	ds_read_b128 v[190:193], v133 offset:1024
	ds_read_b128 v[194:197], v132
	ds_read_b128 v[198:201], v132 offset:1024
	buffer_load_dwordx4 v143, s[4:7], s10 offen lds
	s_mov_b32 m0, s31
	s_nop 0
	buffer_load_dwordx4 v144, s[4:7], s10 offen lds
	s_waitcnt lgkmcnt(8)
	s_barrier
	s_waitcnt lgkmcnt(0)
	v_mfma_f32_16x16x32_bf16 v[124:127], v[154:157], v[170:173], v[124:127]
	v_mfma_f32_16x16x32_bf16 v[124:127], v[158:161], v[174:177], v[124:127]
	v_mfma_f32_16x16x32_bf16 v[120:123], v[166:169], v[174:177], v[120:123]
	v_mfma_f32_16x16x32_bf16 v[120:123], v[162:165], v[170:173], v[120:123]
	v_mfma_f32_16x16x32_bf16 v[112:115], v[162:165], v[178:181], v[112:115]
	v_mfma_f32_16x16x32_bf16 v[112:115], v[166:169], v[182:185], v[112:115]
	v_mfma_f32_16x16x32_bf16 v[116:119], v[158:161], v[182:185], v[116:119]
	v_mfma_f32_16x16x32_bf16 v[116:119], v[154:157], v[178:181], v[116:119]
	v_mfma_f32_16x16x32_bf16 v[108:111], v[154:157], v[186:189], v[108:111]
	v_mfma_f32_16x16x32_bf16 v[108:111], v[158:161], v[190:193], v[108:111]
	v_mfma_f32_16x16x32_bf16 v[104:107], v[166:169], v[190:193], v[104:107]
	v_mfma_f32_16x16x32_bf16 v[104:107], v[162:165], v[186:189], v[104:107]
	v_mfma_f32_16x16x32_bf16 v[96:99], v[162:165], v[194:197], v[96:99]
	v_mfma_f32_16x16x32_bf16 v[96:99], v[166:169], v[198:201], v[96:99]
	v_mfma_f32_16x16x32_bf16 v[100:103], v[158:161], v[198:201], v[100:103]
	v_mfma_f32_16x16x32_bf16 v[100:103], v[154:157], v[194:197], v[100:103]
	s_barrier
	s_add_i32 s44, s39, s17
	s_add_i32 s45, s44, 0x100
	s_mov_b32 s10, s6
	s_mov_b32 s11, s7
	s_mov_b32 m0, s1
	ds_read_b128 v[202:205], v145
	ds_read_b128 v[206:209], v146
	ds_read_b128 v[210:213], v147
	ds_read_b128 v[214:217], v148
	buffer_load_dwordx4 v143, s[8:11], s45 offen lds
	s_mov_b32 m0, s3
	s_nop 0
	buffer_load_dwordx4 v144, s[8:11], s45 offen lds
	s_barrier
	s_waitcnt lgkmcnt(0)
	v_mfma_f32_16x16x32_bf16 v[92:95], v[202:205], v[170:173], v[92:95]
	v_mfma_f32_16x16x32_bf16 v[92:95], v[206:209], v[174:177], v[92:95]
	v_mfma_f32_16x16x32_bf16 v[88:91], v[214:217], v[174:177], v[88:91]
	v_mfma_f32_16x16x32_bf16 v[88:91], v[210:213], v[170:173], v[88:91]
	v_mfma_f32_16x16x32_bf16 v[80:83], v[210:213], v[178:181], v[80:83]
	v_mfma_f32_16x16x32_bf16 v[80:83], v[214:217], v[182:185], v[80:83]
	v_mfma_f32_16x16x32_bf16 v[84:87], v[206:209], v[182:185], v[84:87]
	v_mfma_f32_16x16x32_bf16 v[84:87], v[202:205], v[178:181], v[84:87]
	v_mfma_f32_16x16x32_bf16 v[76:79], v[202:205], v[186:189], v[76:79]
	v_mfma_f32_16x16x32_bf16 v[76:79], v[206:209], v[190:193], v[76:79]
	v_mfma_f32_16x16x32_bf16 v[72:75], v[214:217], v[190:193], v[72:75]
	v_mfma_f32_16x16x32_bf16 v[72:75], v[210:213], v[186:189], v[72:75]
	v_mfma_f32_16x16x32_bf16 v[64:67], v[210:213], v[194:197], v[64:67]
	v_mfma_f32_16x16x32_bf16 v[64:67], v[214:217], v[198:201], v[64:67]
	v_mfma_f32_16x16x32_bf16 v[68:71], v[206:209], v[198:201], v[68:71]
	v_mfma_f32_16x16x32_bf16 v[68:71], v[202:205], v[194:197], v[68:71]
	s_barrier
	s_add_i32 s45, s38, s17
	s_add_i32 s46, s45, 0x100
	s_mov_b32 m0, s0
	ds_read_b128 v[170:173], v131 offset:16384
	ds_read_b128 v[174:177], v131 offset:17408
	ds_read_b128 v[178:181], v134 offset:16384
	ds_read_b128 v[182:185], v134 offset:17408
	ds_read_b128 v[186:189], v133 offset:16384
	ds_read_b128 v[190:193], v133 offset:17408
	ds_read_b128 v[194:197], v132 offset:16384
	ds_read_b128 v[198:201], v132 offset:17408
	buffer_load_dwordx4 v143, s[4:7], s46 offen lds
	s_mov_b32 m0, s18
	s_nop 0
	buffer_load_dwordx4 v144, s[4:7], s46 offen lds
	s_barrier
	s_waitcnt lgkmcnt(0)
	v_mfma_f32_16x16x32_bf16 v[60:63], v[154:157], v[170:173], v[60:63]
	v_mfma_f32_16x16x32_bf16 v[60:63], v[158:161], v[174:177], v[60:63]
	v_mfma_f32_16x16x32_bf16 v[56:59], v[166:169], v[174:177], v[56:59]
	v_mfma_f32_16x16x32_bf16 v[56:59], v[162:165], v[170:173], v[56:59]
	v_mfma_f32_16x16x32_bf16 v[48:51], v[162:165], v[178:181], v[48:51]
	v_mfma_f32_16x16x32_bf16 v[48:51], v[166:169], v[182:185], v[48:51]
	v_mfma_f32_16x16x32_bf16 v[52:55], v[158:161], v[182:185], v[52:55]
	v_mfma_f32_16x16x32_bf16 v[52:55], v[154:157], v[178:181], v[52:55]
	v_mfma_f32_16x16x32_bf16 v[44:47], v[154:157], v[186:189], v[44:47]
	v_mfma_f32_16x16x32_bf16 v[44:47], v[158:161], v[190:193], v[44:47]
	v_mfma_f32_16x16x32_bf16 v[40:43], v[166:169], v[190:193], v[40:43]
	v_mfma_f32_16x16x32_bf16 v[40:43], v[162:165], v[186:189], v[40:43]
	v_mfma_f32_16x16x32_bf16 v[32:35], v[162:165], v[194:197], v[32:35]
	v_mfma_f32_16x16x32_bf16 v[32:35], v[166:169], v[198:201], v[32:35]
	v_mfma_f32_16x16x32_bf16 v[36:39], v[158:161], v[198:201], v[36:39]
	v_mfma_f32_16x16x32_bf16 v[36:39], v[154:157], v[194:197], v[36:39]
	s_barrier
	s_add_i32 s46, s40, s17
	s_add_i32 s47, s46, 0x100
	s_mov_b32 m0, s19
	s_nop 0
	buffer_load_dwordx4 v143, s[8:11], s47 offen lds
	s_mov_b32 m0, s20
	s_nop 0
	buffer_load_dwordx4 v144, s[8:11], s47 offen lds
	s_waitcnt vmcnt(6)
	s_barrier
; #define STAGE(P, RS, SOFF, OFF, kt) do { const int _so = (SOFF) + (kt) * (BK * 2); \
;     _Pragma("unroll") for (int _i = 0; _i < 2; ++_i) { \
;       __builtin_amdgcn_raw_ptr_buffer_load_lds(RS, (__attribute__((address_space(3))) void*)((P) + wave * 1024 + _i * 8192), 16, OFF[_i], _so, 0, 0); } } while (0)
; #define LDA(dst, b, h) _Pragma("unroll") for (int m = 0; m < 4; ++m) _Pragma("unroll") for (int k = 0; k < 2; ++k) \
;     dst[m][k] = *reinterpret_cast<const bf16x8*>(SA(b, h) + lds_byte(wr * 64 + m * 16 + fr, k * 32 + fq * 8))
; #define LDB(dst, b, h) _Pragma("unroll") for (int n = 0; n < 2; ++n) _Pragma("unroll") for (int k = 0; k < 2; ++k) \
;     dst[n][k] = *reinterpret_cast<const bf16x8*>(SB(b, h) + lds_byte(wc * 32 + n * 16 + fr, k * 32 + fq * 8))
; #define WAIT_V(n) asm volatile("s_waitcnt vmcnt(" #n ")" ::: "memory")
; #define WAIT_L(n) asm volatile("s_waitcnt lgkmcnt(" #n ")" ::: "memory")
; #define BAR __builtin_amdgcn_s_barrier()
; #define SCHED __builtin_amdgcn_sched_barrier(0)
;     ...
;       WAIT_V(6); BAR; MMA(1, 1, At, B1); BAR;
;       LDB(B0, 1, 0); SCHED; LDA(At, 1, 0); STAGE(SA(0, 1), rsA, sA1, offA, t + 2);
;       WAIT_L(8); BAR; WAIT_L(0); MMA(0, 0, At, B0); BAR; SCHED;
;       LDB(B1, 1, 1); STAGE(SB(1, 0), rsB, sB0, offB, t + 3);
;       BAR; WAIT_L(0); MMA(0, 1, At, B1); BAR;
;       LDA(At, 1, 1); STAGE(SA(1, 0), rsA, sA0, offA, t + 3);
;       BAR; WAIT_L(0); MMA(1, 0, At, B0); BAR; SCHED;
	v_mfma_f32_16x16x32_bf16 v[28:31], v[202:205], v[170:173], v[28:31]
	v_mfma_f32_16x16x32_bf16 v[28:31], v[206:209], v[174:177], v[28:31]
	v_mfma_f32_16x16x32_bf16 v[24:27], v[214:217], v[174:177], v[24:27]
	v_mfma_f32_16x16x32_bf16 v[24:27], v[210:213], v[170:173], v[24:27]
	v_mfma_f32_16x16x32_bf16 v[16:19], v[210:213], v[178:181], v[16:19]
	v_mfma_f32_16x16x32_bf16 v[16:19], v[214:217], v[182:185], v[16:19]
	v_mfma_f32_16x16x32_bf16 v[20:23], v[206:209], v[182:185], v[20:23]
	v_mfma_f32_16x16x32_bf16 v[20:23], v[202:205], v[178:181], v[20:23]
	v_mfma_f32_16x16x32_bf16 v[12:15], v[202:205], v[186:189], v[12:15]
	v_mfma_f32_16x16x32_bf16 v[12:15], v[206:209], v[190:193], v[12:15]
	v_mfma_f32_16x16x32_bf16 v[8:11], v[214:217], v[190:193], v[8:11]
	v_mfma_f32_16x16x32_bf16 v[8:11], v[210:213], v[186:189], v[8:11]
	v_mfma_f32_16x16x32_bf16 v[0:3], v[210:213], v[194:197], v[0:3]
	v_mfma_f32_16x16x32_bf16 v[0:3], v[214:217], v[198:201], v[0:3]
	v_mfma_f32_16x16x32_bf16 v[4:7], v[206:209], v[198:201], v[4:7]
	v_mfma_f32_16x16x32_bf16 v[4:7], v[202:205], v[194:197], v[4:7]
	s_barrier
	ds_read_b128 v[154:157], v139
	ds_read_b128 v[158:161], v140
	ds_read_b128 v[162:165], v141
	ds_read_b128 v[166:169], v142
	s_addk_i32 s43, 0x100
	s_mov_b32 m0, s21
	ds_read_b128 v[170:173], v131 offset:32768
	ds_read_b128 v[174:177], v131 offset:33792
	ds_read_b128 v[178:181], v134 offset:32768
	ds_read_b128 v[182:185], v134 offset:33792
	ds_read_b128 v[186:189], v133 offset:32768
	ds_read_b128 v[190:193], v133 offset:33792
	ds_read_b128 v[194:197], v132 offset:32768
	ds_read_b128 v[198:201], v132 offset:33792
	buffer_load_dwordx4 v143, s[4:7], s43 offen lds
	s_mov_b32 m0, s22
	s_nop 0
	buffer_load_dwordx4 v144, s[4:7], s43 offen lds
	s_waitcnt lgkmcnt(8)
	s_barrier
	s_waitcnt lgkmcnt(0)
	v_mfma_f32_16x16x32_bf16 v[124:127], v[154:157], v[170:173], v[124:127]
	v_mfma_f32_16x16x32_bf16 v[124:127], v[158:161], v[174:177], v[124:127]
	v_mfma_f32_16x16x32_bf16 v[120:123], v[166:169], v[174:177], v[120:123]
	v_mfma_f32_16x16x32_bf16 v[120:123], v[162:165], v[170:173], v[120:123]
	v_mfma_f32_16x16x32_bf16 v[112:115], v[162:165], v[178:181], v[112:115]
	v_mfma_f32_16x16x32_bf16 v[112:115], v[166:169], v[182:185], v[112:115]
	v_mfma_f32_16x16x32_bf16 v[116:119], v[158:161], v[182:185], v[116:119]
	v_mfma_f32_16x16x32_bf16 v[116:119], v[154:157], v[178:181], v[116:119]
	v_mfma_f32_16x16x32_bf16 v[108:111], v[154:157], v[186:189], v[108:111]
	v_mfma_f32_16x16x32_bf16 v[108:111], v[158:161], v[190:193], v[108:111]
	v_mfma_f32_16x16x32_bf16 v[104:107], v[166:169], v[190:193], v[104:107]
	v_mfma_f32_16x16x32_bf16 v[104:107], v[162:165], v[186:189], v[104:107]
	v_mfma_f32_16x16x32_bf16 v[96:99], v[162:165], v[194:197], v[96:99]
	v_mfma_f32_16x16x32_bf16 v[96:99], v[166:169], v[198:201], v[96:99]
	v_mfma_f32_16x16x32_bf16 v[100:103], v[158:161], v[198:201], v[100:103]
	v_mfma_f32_16x16x32_bf16 v[100:103], v[154:157], v[194:197], v[100:103]
	s_barrier
	s_addk_i32 s44, 0x180
	s_mov_b32 m0, s23
	ds_read_b128 v[202:205], v135
	ds_read_b128 v[206:209], v136
	ds_read_b128 v[210:213], v137
	ds_read_b128 v[214:217], v138
	buffer_load_dwordx4 v143, s[8:11], s44 offen lds
	s_mov_b32 m0, s24
	s_nop 0
	buffer_load_dwordx4 v144, s[8:11], s44 offen lds
	s_barrier
	s_waitcnt lgkmcnt(0)
	v_mfma_f32_16x16x32_bf16 v[92:95], v[202:205], v[170:173], v[92:95]
	v_mfma_f32_16x16x32_bf16 v[92:95], v[206:209], v[174:177], v[92:95]
	v_mfma_f32_16x16x32_bf16 v[88:91], v[214:217], v[174:177], v[88:91]
	v_mfma_f32_16x16x32_bf16 v[88:91], v[210:213], v[170:173], v[88:91]
	v_mfma_f32_16x16x32_bf16 v[80:83], v[210:213], v[178:181], v[80:83]
	v_mfma_f32_16x16x32_bf16 v[80:83], v[214:217], v[182:185], v[80:83]
	v_mfma_f32_16x16x32_bf16 v[84:87], v[206:209], v[182:185], v[84:87]
	v_mfma_f32_16x16x32_bf16 v[84:87], v[202:205], v[178:181], v[84:87]
	v_mfma_f32_16x16x32_bf16 v[76:79], v[202:205], v[186:189], v[76:79]
	v_mfma_f32_16x16x32_bf16 v[76:79], v[206:209], v[190:193], v[76:79]
	v_mfma_f32_16x16x32_bf16 v[72:75], v[214:217], v[190:193], v[72:75]
	v_mfma_f32_16x16x32_bf16 v[72:75], v[210:213], v[186:189], v[72:75]
	v_mfma_f32_16x16x32_bf16 v[64:67], v[210:213], v[194:197], v[64:67]
	v_mfma_f32_16x16x32_bf16 v[64:67], v[214:217], v[198:201], v[64:67]
	v_mfma_f32_16x16x32_bf16 v[68:71], v[206:209], v[198:201], v[68:71]
	v_mfma_f32_16x16x32_bf16 v[68:71], v[202:205], v[194:197], v[68:71]
	s_barrier
	s_addk_i32 s45, 0x180
	s_mov_b32 m0, s25
	ds_read_b128 v[170:173], v131 offset:49152
	ds_read_b128 v[174:177], v131 offset:50176
	ds_read_b128 v[178:181], v134 offset:49152
	ds_read_b128 v[182:185], v134 offset:50176
	ds_read_b128 v[186:189], v133 offset:49152
	ds_read_b128 v[190:193], v133 offset:50176
	ds_read_b128 v[194:197], v132 offset:49152
	ds_read_b128 v[198:201], v132 offset:50176
	buffer_load_dwordx4 v143, s[4:7], s45 offen lds
	s_mov_b32 m0, s26
	s_nop 0
	buffer_load_dwordx4 v144, s[4:7], s45 offen lds
	s_barrier
	s_waitcnt lgkmcnt(0)
	v_mfma_f32_16x16x32_bf16 v[60:63], v[154:157], v[170:173], v[60:63]
	v_mfma_f32_16x16x32_bf16 v[60:63], v[158:161], v[174:177], v[60:63]
	v_mfma_f32_16x16x32_bf16 v[56:59], v[166:169], v[174:177], v[56:59]
	v_mfma_f32_16x16x32_bf16 v[56:59], v[162:165], v[170:173], v[56:59]
	v_mfma_f32_16x16x32_bf16 v[48:51], v[162:165], v[178:181], v[48:51]
	v_mfma_f32_16x16x32_bf16 v[48:51], v[166:169], v[182:185], v[48:51]
	v_mfma_f32_16x16x32_bf16 v[52:55], v[158:161], v[182:185], v[52:55]
	v_mfma_f32_16x16x32_bf16 v[52:55], v[154:157], v[178:181], v[52:55]
	v_mfma_f32_16x16x32_bf16 v[44:47], v[154:157], v[186:189], v[44:47]
	v_mfma_f32_16x16x32_bf16 v[44:47], v[158:161], v[190:193], v[44:47]
	v_mfma_f32_16x16x32_bf16 v[40:43], v[166:169], v[190:193], v[40:43]
	v_mfma_f32_16x16x32_bf16 v[40:43], v[162:165], v[186:189], v[40:43]
	v_mfma_f32_16x16x32_bf16 v[32:35], v[162:165], v[194:197], v[32:35]
	v_mfma_f32_16x16x32_bf16 v[32:35], v[166:169], v[198:201], v[32:35]
	v_mfma_f32_16x16x32_bf16 v[36:39], v[158:161], v[198:201], v[36:39]
	v_mfma_f32_16x16x32_bf16 v[36:39], v[154:157], v[194:197], v[36:39]
	s_barrier
; #define STAGE(P, RS, SOFF, OFF, kt) do { const int _so = (SOFF) + (kt) * (BK * 2); \
;     _Pragma("unroll") for (int _i = 0; _i < 2; ++_i) { \
;       __builtin_amdgcn_raw_ptr_buffer_load_lds(RS, (__attribute__((address_space(3))) void*)((P) + wave * 1024 + _i * 8192), 16, OFF[_i], _so, 0, 0); } } while (0)
; #define LDA(dst, b, h) _Pragma("unroll") for (int m = 0; m < 4; ++m) _Pragma("unroll") for (int k = 0; k < 2; ++k) \
;     dst[m][k] = *reinterpret_cast<const bf16x8*>(SA(b, h) + lds_byte(wr * 64 + m * 16 + fr, k * 32 + fq * 8))
; #define LDB(dst, b, h) _Pragma("unroll") for (int n = 0; n < 2; ++n) _Pragma("unroll") for (int k = 0; k < 2; ++k) \
;     dst[n][k] = *reinterpret_cast<const bf16x8*>(SB(b, h) + lds_byte(wc * 32 + n * 16 + fr, k * 32 + fq * 8))
; #define WAIT_V(n) asm volatile("s_waitcnt vmcnt(" #n ")" ::: "memory")
; #define WAIT_L(n) asm volatile("s_waitcnt lgkmcnt(" #n ")" ::: "memory")
; #define BAR __builtin_amdgcn_s_barrier()
;     ...
;       STAGE(SB(1, 1), rsB, sB1, offB, t + 3);
;       WAIT_V(6); BAR; MMA(1, 1, At, B1); BAR;
;     }
;     { LDB(B0, 0, 0); LDA(At, 0, 0); STAGE(SA(1, 1), rsA, sA1, offA, nt - 1);
;       BAR; WAIT_L(0); MMA(0, 0, At, B0); BAR;
;       LDB(B1, 0, 1); BAR; WAIT_L(0); MMA(0, 1, At, B1); BAR;
;       LDA(At, 0, 1); WAIT_V(4); BAR; WAIT_L(0); MMA(1, 0, At, B0); MMA(1, 1, At, B1); BAR; }
	s_addk_i32 s46, 0x180
	s_mov_b32 m0, s27
	s_nop 0
	buffer_load_dwordx4 v143, s[8:11], s46 offen lds
	s_mov_b32 m0, s28
	s_nop 0
	buffer_load_dwordx4 v144, s[8:11], s46 offen lds
	s_add_i32 s16, s16, 2
	s_addk_i32 s17, 0x100
	s_cmp_gt_u32 s16, 27
	s_cbranch_scc0 .LBB0_354
	s_waitcnt vmcnt(6)
	s_barrier
	v_mfma_f32_16x16x32_bf16 v[28:31], v[202:205], v[170:173], v[28:31]
	v_mfma_f32_16x16x32_bf16 v[28:31], v[206:209], v[174:177], v[28:31]
	v_mfma_f32_16x16x32_bf16 v[24:27], v[214:217], v[174:177], v[24:27]
	v_mfma_f32_16x16x32_bf16 v[24:27], v[210:213], v[170:173], v[24:27]
	v_mfma_f32_16x16x32_bf16 v[16:19], v[210:213], v[178:181], v[16:19]
	v_mfma_f32_16x16x32_bf16 v[16:19], v[214:217], v[182:185], v[16:19]
	v_mfma_f32_16x16x32_bf16 v[20:23], v[206:209], v[182:185], v[20:23]
	v_mfma_f32_16x16x32_bf16 v[20:23], v[202:205], v[178:181], v[20:23]
	v_mfma_f32_16x16x32_bf16 v[12:15], v[202:205], v[186:189], v[12:15]
	v_mfma_f32_16x16x32_bf16 v[12:15], v[206:209], v[190:193], v[12:15]
	v_mfma_f32_16x16x32_bf16 v[8:11], v[214:217], v[190:193], v[8:11]
	v_mfma_f32_16x16x32_bf16 v[8:11], v[210:213], v[186:189], v[8:11]
	v_mfma_f32_16x16x32_bf16 v[0:3], v[210:213], v[194:197], v[0:3]
	v_mfma_f32_16x16x32_bf16 v[0:3], v[214:217], v[198:201], v[0:3]
	v_mfma_f32_16x16x32_bf16 v[4:7], v[206:209], v[198:201], v[4:7]
	v_mfma_f32_16x16x32_bf16 v[4:7], v[202:205], v[194:197], v[4:7]
	s_barrier
	s_add_i32 s10, s37, 0xf80
	s_mov_b32 m0, s30
	ds_read_b128 v[154:157], v149
	ds_read_b128 v[158:161], v150
	ds_read_b128 v[162:165], v151
	ds_read_b128 v[150:153], v152
	ds_read_b128 v[166:169], v131
	ds_read_b128 v[170:173], v131 offset:1024
	ds_read_b128 v[174:177], v134
	ds_read_b128 v[178:181], v134 offset:1024
	ds_read_b128 v[182:185], v133
	ds_read_b128 v[186:189], v133 offset:1024
	ds_read_b128 v[190:193], v132
	ds_read_b128 v[194:197], v132 offset:1024
	buffer_load_dwordx4 v143, s[4:7], s10 offen lds
	s_mov_b32 m0, s31
	s_nop 0
	buffer_load_dwordx4 v144, s[4:7], s10 offen lds
	s_barrier
	s_waitcnt lgkmcnt(0)
	v_mfma_f32_16x16x32_bf16 v[124:127], v[154:157], v[166:169], v[124:127]
	v_mfma_f32_16x16x32_bf16 v[124:127], v[158:161], v[170:173], v[124:127]
	v_mfma_f32_16x16x32_bf16 v[120:123], v[150:153], v[170:173], v[120:123]
	v_mfma_f32_16x16x32_bf16 v[120:123], v[162:165], v[166:169], v[120:123]
	v_mfma_f32_16x16x32_bf16 v[112:115], v[162:165], v[174:177], v[112:115]
	v_mfma_f32_16x16x32_bf16 v[112:115], v[150:153], v[178:181], v[112:115]
	v_mfma_f32_16x16x32_bf16 v[116:119], v[158:161], v[178:181], v[116:119]
	v_mfma_f32_16x16x32_bf16 v[116:119], v[154:157], v[174:177], v[116:119]
	v_mfma_f32_16x16x32_bf16 v[108:111], v[154:157], v[182:185], v[108:111]
	v_mfma_f32_16x16x32_bf16 v[108:111], v[158:161], v[186:189], v[108:111]
	v_mfma_f32_16x16x32_bf16 v[104:107], v[150:153], v[186:189], v[104:107]
	v_mfma_f32_16x16x32_bf16 v[104:107], v[162:165], v[182:185], v[104:107]
	v_mfma_f32_16x16x32_bf16 v[96:99], v[162:165], v[190:193], v[96:99]
	v_mfma_f32_16x16x32_bf16 v[96:99], v[150:153], v[194:197], v[96:99]
	v_mfma_f32_16x16x32_bf16 v[100:103], v[158:161], v[194:197], v[100:103]
	v_mfma_f32_16x16x32_bf16 v[100:103], v[154:157], v[190:193], v[100:103]
	s_barrier
	ds_read_b128 v[198:201], v145
	ds_read_b128 v[202:205], v146
	ds_read_b128 v[144:147], v147
	ds_read_b128 v[206:209], v148
	s_barrier
	s_waitcnt lgkmcnt(0)
	v_mfma_f32_16x16x32_bf16 v[92:95], v[198:201], v[166:169], v[92:95]
	v_mfma_f32_16x16x32_bf16 v[84:87], v[198:201], v[174:177], v[84:87]
	v_mfma_f32_16x16x32_bf16 v[76:79], v[198:201], v[182:185], v[76:79]
	v_mfma_f32_16x16x32_bf16 v[68:71], v[198:201], v[190:193], v[68:71]
	v_mfma_f32_16x16x32_bf16 v[88:91], v[144:147], v[166:169], v[88:91]
	v_mfma_f32_16x16x32_bf16 v[80:83], v[144:147], v[174:177], v[80:83]
	v_mfma_f32_16x16x32_bf16 v[72:75], v[144:147], v[182:185], v[72:75]
	v_mfma_f32_16x16x32_bf16 v[64:67], v[144:147], v[190:193], v[64:67]
	v_mfma_f32_16x16x32_bf16 v[92:95], v[202:205], v[170:173], v[92:95]
	v_mfma_f32_16x16x32_bf16 v[84:87], v[202:205], v[178:181], v[84:87]
	v_mfma_f32_16x16x32_bf16 v[76:79], v[202:205], v[186:189], v[76:79]
	v_mfma_f32_16x16x32_bf16 v[68:71], v[202:205], v[194:197], v[68:71]
	v_mfma_f32_16x16x32_bf16 v[166:169], v[206:209], v[170:173], v[88:91]
	v_mfma_f32_16x16x32_bf16 v[170:173], v[206:209], v[178:181], v[80:83]
	v_mfma_f32_16x16x32_bf16 v[174:177], v[206:209], v[186:189], v[72:75]
	v_mfma_f32_16x16x32_bf16 v[178:181], v[206:209], v[194:197], v[64:67]
	s_barrier
	s_nop 0
	ds_read_b128 v[64:67], v131 offset:16384
	ds_read_b128 v[72:75], v131 offset:17408
	ds_read_b128 v[80:83], v134 offset:16384
	ds_read_b128 v[88:91], v134 offset:17408
	ds_read_b128 v[182:185], v133 offset:16384
	ds_read_b128 v[186:189], v133 offset:17408
	ds_read_b128 v[190:193], v132 offset:16384
	ds_read_b128 v[194:197], v132 offset:17408
	s_waitcnt vmcnt(4)
	s_barrier
; #define LDA(dst, b, h) _Pragma("unroll") for (int m = 0; m < 4; ++m) _Pragma("unroll") for (int k = 0; k < 2; ++k) \
;     dst[m][k] = *reinterpret_cast<const bf16x8*>(SA(b, h) + lds_byte(wr * 64 + m * 16 + fr, k * 32 + fq * 8))
; #define LDB(dst, b, h) _Pragma("unroll") for (int n = 0; n < 2; ++n) _Pragma("unroll") for (int k = 0; k < 2; ++k) \
;     dst[n][k] = *reinterpret_cast<const bf16x8*>(SB(b, h) + lds_byte(wc * 32 + n * 16 + fr, k * 32 + fq * 8))
; #define WAIT_V(n) asm volatile("s_waitcnt vmcnt(" #n ")" ::: "memory")
; #define WAIT_L(n) asm volatile("s_waitcnt lgkmcnt(" #n ")" ::: "memory")
; #define BAR __builtin_amdgcn_s_barrier()
;     ...
;       LDA(At, 0, 1); WAIT_V(4); BAR; WAIT_L(0); MMA(1, 0, At, B0); MMA(1, 1, At, B1); BAR; }
;     { LDB(B0, 1, 0); LDA(At, 1, 0); WAIT_V(2); BAR; WAIT_L(0); MMA(0, 0, At, B0); BAR;
;       LDB(B1, 1, 1); WAIT_V(0); BAR; WAIT_L(0); MMA(0, 1, At, B1); BAR;
	s_waitcnt lgkmcnt(0)
	v_mfma_f32_16x16x32_bf16 v[60:63], v[154:157], v[64:67], v[60:63]
	v_mfma_f32_16x16x32_bf16 v[56:59], v[162:165], v[64:67], v[56:59]
	v_mfma_f32_16x16x32_bf16 v[52:55], v[154:157], v[80:83], v[52:55]
	v_mfma_f32_16x16x32_bf16 v[48:51], v[162:165], v[80:83], v[48:51]
	v_mfma_f32_16x16x32_bf16 v[44:47], v[154:157], v[182:185], v[44:47]
	v_mfma_f32_16x16x32_bf16 v[40:43], v[162:165], v[182:185], v[40:43]
	v_mfma_f32_16x16x32_bf16 v[36:39], v[154:157], v[190:193], v[36:39]
	v_mfma_f32_16x16x32_bf16 v[32:35], v[162:165], v[190:193], v[32:35]
	v_mfma_f32_16x16x32_bf16 v[60:63], v[158:161], v[72:75], v[60:63]
	v_mfma_f32_16x16x32_bf16 v[56:59], v[150:153], v[72:75], v[56:59]
	v_mfma_f32_16x16x32_bf16 v[52:55], v[158:161], v[88:91], v[52:55]
	v_mfma_f32_16x16x32_bf16 v[48:51], v[150:153], v[88:91], v[48:51]
	v_mfma_f32_16x16x32_bf16 v[44:47], v[158:161], v[186:189], v[44:47]
	v_mfma_f32_16x16x32_bf16 v[40:43], v[150:153], v[186:189], v[40:43]
	v_mfma_f32_16x16x32_bf16 v[36:39], v[158:161], v[194:197], v[36:39]
	v_mfma_f32_16x16x32_bf16 v[32:35], v[150:153], v[194:197], v[32:35]
	v_mfma_f32_16x16x32_bf16 v[28:31], v[198:201], v[64:67], v[28:31]
	v_mfma_f32_16x16x32_bf16 v[20:23], v[198:201], v[80:83], v[20:23]
	v_mfma_f32_16x16x32_bf16 v[12:15], v[198:201], v[182:185], v[12:15]
	v_mfma_f32_16x16x32_bf16 v[4:7], v[198:201], v[190:193], v[4:7]
	v_mfma_f32_16x16x32_bf16 v[24:27], v[144:147], v[64:67], v[24:27]
	v_mfma_f32_16x16x32_bf16 v[16:19], v[144:147], v[80:83], v[16:19]
	v_mfma_f32_16x16x32_bf16 v[8:11], v[144:147], v[182:185], v[8:11]
	v_mfma_f32_16x16x32_bf16 v[0:3], v[144:147], v[190:193], v[0:3]
	v_mfma_f32_16x16x32_bf16 v[28:31], v[202:205], v[72:75], v[28:31]
	v_mfma_f32_16x16x32_bf16 v[20:23], v[202:205], v[88:91], v[20:23]
	v_mfma_f32_16x16x32_bf16 v[12:15], v[202:205], v[186:189], v[12:15]
	v_mfma_f32_16x16x32_bf16 v[4:7], v[202:205], v[194:197], v[4:7]
	v_mfma_f32_16x16x32_bf16 v[144:147], v[206:209], v[72:75], v[24:27]
	v_mfma_f32_16x16x32_bf16 v[148:151], v[206:209], v[88:91], v[16:19]
	v_mfma_f32_16x16x32_bf16 v[152:155], v[206:209], v[186:189], v[8:11]
	v_mfma_f32_16x16x32_bf16 v[156:159], v[206:209], v[194:197], v[0:3]
	s_barrier
	s_nop 0
	ds_read_b128 v[0:3], v139
	ds_read_b128 v[8:11], v140
	ds_read_b128 v[16:19], v141
	ds_read_b128 v[140:143], v142
	ds_read_b128 v[24:27], v131 offset:32768
	ds_read_b128 v[160:163], v131 offset:33792
	ds_read_b128 v[182:185], v134 offset:32768
	ds_read_b128 v[186:189], v134 offset:33792
	ds_read_b128 v[190:193], v133 offset:32768
	ds_read_b128 v[194:197], v133 offset:33792
	ds_read_b128 v[198:201], v132 offset:32768
	ds_read_b128 v[202:205], v132 offset:33792
	s_waitcnt vmcnt(2)
	s_barrier
	s_waitcnt lgkmcnt(0)
	v_mfma_f32_16x16x32_bf16 v[64:67], v[0:3], v[24:27], v[124:127]
	v_mfma_f32_16x16x32_bf16 v[72:75], v[16:19], v[24:27], v[120:123]
	v_mfma_f32_16x16x32_bf16 v[80:83], v[0:3], v[182:185], v[116:119]
	v_mfma_f32_16x16x32_bf16 v[88:91], v[16:19], v[182:185], v[112:115]
	v_mfma_f32_16x16x32_bf16 v[108:111], v[0:3], v[190:193], v[108:111]
	v_mfma_f32_16x16x32_bf16 v[116:119], v[16:19], v[190:193], v[104:107]
	v_mfma_f32_16x16x32_bf16 v[100:103], v[0:3], v[198:201], v[100:103]
	v_mfma_f32_16x16x32_bf16 v[124:127], v[16:19], v[198:201], v[96:99]
	v_mfma_f32_16x16x32_bf16 v[120:123], v[8:11], v[160:163], v[64:67]
	v_mfma_f32_16x16x32_bf16 v[112:115], v[140:143], v[160:163], v[72:75]
	v_mfma_f32_16x16x32_bf16 v[104:107], v[8:11], v[186:189], v[80:83]
	v_mfma_f32_16x16x32_bf16 v[96:99], v[140:143], v[186:189], v[88:91]
	v_mfma_f32_16x16x32_bf16 v[88:91], v[8:11], v[194:197], v[108:111]
	v_mfma_f32_16x16x32_bf16 v[80:83], v[140:143], v[194:197], v[116:119]
	v_mfma_f32_16x16x32_bf16 v[72:75], v[8:11], v[202:205], v[100:103]
	v_mfma_f32_16x16x32_bf16 v[64:67], v[140:143], v[202:205], v[124:127]
	s_barrier
	ds_read_b128 v[206:209], v135
	ds_read_b128 v[210:213], v136
	ds_read_b128 v[214:217], v137
	ds_read_b128 v[136:139], v138
	s_waitcnt vmcnt(0)
	s_barrier
; #define LDA(dst, b, h) _Pragma("unroll") for (int m = 0; m < 4; ++m) _Pragma("unroll") for (int k = 0; k < 2; ++k) \
;     dst[m][k] = *reinterpret_cast<const bf16x8*>(SA(b, h) + lds_byte(wr * 64 + m * 16 + fr, k * 32 + fq * 8))
; #define LDB(dst, b, h) _Pragma("unroll") for (int n = 0; n < 2; ++n) _Pragma("unroll") for (int k = 0; k < 2; ++k) \
;     dst[n][k] = *reinterpret_cast<const bf16x8*>(SB(b, h) + lds_byte(wc * 32 + n * 16 + fr, k * 32 + fq * 8))
; #define WAIT_V(n) asm volatile("s_waitcnt vmcnt(" #n ")" ::: "memory")
; #define WAIT_L(n) asm volatile("s_waitcnt lgkmcnt(" #n ")" ::: "memory")
; #define BAR __builtin_amdgcn_s_barrier()
;     ...
;       LDB(B1, 1, 1); WAIT_V(0); BAR; WAIT_L(0); MMA(0, 1, At, B1); BAR;
;       LDA(At, 1, 1); BAR; WAIT_L(0); MMA(1, 0, At, B0); MMA(1, 1, At, B1); BAR; }
;     if (wr == 0) BAR;
	s_waitcnt lgkmcnt(0)
	v_mfma_f32_16x16x32_bf16 v[92:95], v[206:209], v[24:27], v[92:95]
	v_mfma_f32_16x16x32_bf16 v[24:27], v[214:217], v[24:27], v[166:169]
	v_mfma_f32_16x16x32_bf16 v[84:87], v[206:209], v[182:185], v[84:87]
	v_mfma_f32_16x16x32_bf16 v[100:103], v[214:217], v[182:185], v[170:173]
	v_mfma_f32_16x16x32_bf16 v[76:79], v[206:209], v[190:193], v[76:79]
	v_mfma_f32_16x16x32_bf16 v[164:167], v[214:217], v[190:193], v[174:177]
	v_mfma_f32_16x16x32_bf16 v[68:71], v[206:209], v[198:201], v[68:71]
	v_mfma_f32_16x16x32_bf16 v[168:171], v[214:217], v[198:201], v[178:181]
	v_mfma_f32_16x16x32_bf16 v[124:127], v[210:213], v[160:163], v[92:95]
	v_mfma_f32_16x16x32_bf16 v[116:119], v[136:139], v[160:163], v[24:27]
	v_mfma_f32_16x16x32_bf16 v[108:111], v[210:213], v[186:189], v[84:87]
	v_mfma_f32_16x16x32_bf16 v[100:103], v[136:139], v[186:189], v[100:103]
	v_mfma_f32_16x16x32_bf16 v[92:95], v[210:213], v[194:197], v[76:79]
	v_mfma_f32_16x16x32_bf16 v[84:87], v[136:139], v[194:197], v[164:167]
	v_mfma_f32_16x16x32_bf16 v[76:79], v[210:213], v[202:205], v[68:71]
	v_mfma_f32_16x16x32_bf16 v[68:71], v[136:139], v[202:205], v[168:171]
	s_barrier
	ds_read_b128 v[160:163], v131 offset:49152
	ds_read_b128 v[164:167], v131 offset:50176
	ds_read_b128 v[168:171], v134 offset:49152
	ds_read_b128 v[172:175], v134 offset:50176
	ds_read_b128 v[176:179], v133 offset:49152
	ds_read_b128 v[180:183], v133 offset:50176
	ds_read_b128 v[184:187], v132 offset:49152
	ds_read_b128 v[132:135], v132 offset:50176
	s_barrier
	s_waitcnt lgkmcnt(0)
	v_mfma_f32_16x16x32_bf16 v[24:27], v[0:3], v[160:163], v[60:63]
	v_mfma_f32_16x16x32_bf16 v[60:63], v[16:19], v[160:163], v[56:59]
	v_mfma_f32_16x16x32_bf16 v[52:55], v[0:3], v[168:171], v[52:55]
	v_mfma_f32_16x16x32_bf16 v[188:191], v[16:19], v[168:171], v[48:51]
	v_mfma_f32_16x16x32_bf16 v[44:47], v[0:3], v[176:179], v[44:47]
	v_mfma_f32_16x16x32_bf16 v[192:195], v[16:19], v[176:179], v[40:43]
	v_mfma_f32_16x16x32_bf16 v[0:3], v[0:3], v[184:187], v[36:39]
	v_mfma_f32_16x16x32_bf16 v[36:39], v[16:19], v[184:187], v[32:35]
	v_mfma_f32_16x16x32_bf16 v[56:59], v[8:11], v[164:167], v[24:27]
	v_mfma_f32_16x16x32_bf16 v[48:51], v[140:143], v[164:167], v[60:63]
	v_mfma_f32_16x16x32_bf16 v[40:43], v[8:11], v[172:175], v[52:55]
	v_mfma_f32_16x16x32_bf16 v[32:35], v[140:143], v[172:175], v[188:191]
	v_mfma_f32_16x16x32_bf16 v[24:27], v[8:11], v[180:183], v[44:47]
	v_mfma_f32_16x16x32_bf16 v[16:19], v[140:143], v[180:183], v[192:195]
	v_mfma_f32_16x16x32_bf16 v[8:11], v[8:11], v[132:135], v[0:3]
	v_mfma_f32_16x16x32_bf16 v[0:3], v[140:143], v[132:135], v[36:39]
	v_mfma_f32_16x16x32_bf16 v[28:31], v[206:209], v[160:163], v[28:31]
	v_mfma_f32_16x16x32_bf16 v[36:39], v[214:217], v[160:163], v[144:147]
	v_mfma_f32_16x16x32_bf16 v[20:23], v[206:209], v[168:171], v[20:23]
	v_mfma_f32_16x16x32_bf16 v[140:143], v[214:217], v[168:171], v[148:151]
	v_mfma_f32_16x16x32_bf16 v[12:15], v[206:209], v[176:179], v[12:15]
	v_mfma_f32_16x16x32_bf16 v[144:147], v[214:217], v[176:179], v[152:155]
	v_mfma_f32_16x16x32_bf16 v[4:7], v[206:209], v[184:187], v[4:7]
	v_mfma_f32_16x16x32_bf16 v[148:151], v[214:217], v[184:187], v[156:159]
	v_mfma_f32_16x16x32_bf16 v[60:63], v[210:213], v[164:167], v[28:31]
	v_mfma_f32_16x16x32_bf16 v[52:55], v[136:139], v[164:167], v[36:39]
	v_mfma_f32_16x16x32_bf16 v[44:47], v[210:213], v[172:175], v[20:23]
	v_mfma_f32_16x16x32_bf16 v[36:39], v[136:139], v[172:175], v[140:143]
	v_mfma_f32_16x16x32_bf16 v[28:31], v[210:213], v[180:183], v[12:15]
	v_mfma_f32_16x16x32_bf16 v[20:23], v[136:139], v[180:183], v[144:147]
	v_mfma_f32_16x16x32_bf16 v[12:15], v[210:213], v[132:135], v[4:7]
	v_mfma_f32_16x16x32_bf16 v[4:7], v[136:139], v[132:135], v[148:151]
	v_cmp_gt_u32_e32 vcc, s35, v130
	s_barrier
	s_and_saveexec_b64 s[10:11], vcc
	s_cbranch_execz .LBB0_357
	s_barrier

; #define STAGE(P, RS, SOFF, OFF, kt) do { const int _so = (SOFF) + (kt) * (BK * 2); \
;     _Pragma("unroll") for (int _i = 0; _i < 2; ++_i) { \
;       __builtin_amdgcn_raw_ptr_buffer_load_lds(RS, (__attribute__((address_space(3))) void*)((P) + wave * 1024 + _i * 8192), 16, OFF[_i], _so, 0, 0); } } while (0)
; #define LDA(dst, b, h) _Pragma("unroll") for (int m = 0; m < 4; ++m) _Pragma("unroll") for (int k = 0; k < 2; ++k) \
;     dst[m][k] = *reinterpret_cast<const bf16x8*>(SA(b, h) + lds_byte(wr * 64 + m * 16 + fr, k * 32 + fq * 8))
; #define LDB(dst, b, h) _Pragma("unroll") for (int n = 0; n < 2; ++n) _Pragma("unroll") for (int k = 0; k < 2; ++k) \
;     dst[n][k] = *reinterpret_cast<const bf16x8*>(SB(b, h) + lds_byte(wc * 32 + n * 16 + fr, k * 32 + fq * 8))
; #define WAIT_V(n) asm volatile("s_waitcnt vmcnt(" #n ")" ::: "memory")
; #define WAIT_L(n) asm volatile("s_waitcnt lgkmcnt(" #n ")" ::: "memory")
; #define BAR __builtin_amdgcn_s_barrier()
; #define SCHED __builtin_amdgcn_sched_barrier(0)
;     ...
;     for (int t = 0; t < nt - 2; t += 2) {
;       LDB(B0, 0, 0); SCHED; LDA(At, 0, 0); STAGE(SA(1, 1), rsA, sA1, offA, t + 1);
;       WAIT_L(8); BAR; WAIT_L(0); MMA(0, 0, At, B0); BAR; SCHED;
;       LDB(B1, 0, 1); STAGE(SB(0, 0), rsB, sB0, offB, t + 2);
;       BAR; WAIT_L(0); MMA(0, 1, At, B1); BAR;
;       LDA(At, 0, 1); STAGE(SA(0, 0), rsA, sA0, offA, t + 2);
;       BAR; WAIT_L(0); MMA(1, 0, At, B0); BAR; SCHED;
;       STAGE(SB(0, 1), rsB, sB1, offB, t + 2);
;       WAIT_V(6); BAR; MMA(1, 1, At, B1); BAR;
.Lmy_rot_392:
	ds_read_b128 v[152:155], v147
	ds_read_b128 v[156:159], v148
	ds_read_b128 v[160:163], v149
	ds_read_b128 v[164:167], v150
	s_add_i32 s5, s86, s3
	s_add_i32 s6, s5, 0x80
	s_mov_b32 m0, s36
	ds_read_b128 v[168:171], v129
	ds_read_b128 v[172:175], v129 offset:1024
	ds_read_b128 v[176:179], v132
	ds_read_b128 v[180:183], v132 offset:1024
	ds_read_b128 v[184:187], v131
	ds_read_b128 v[188:191], v131 offset:1024
	ds_read_b128 v[192:195], v130
	ds_read_b128 v[196:199], v130 offset:1024
	buffer_load_dwordx4 v141, s[8:11], s6 offen lds
	s_mov_b32 m0, s59
	s_nop 0
	buffer_load_dwordx4 v142, s[8:11], s6 offen lds
	s_waitcnt lgkmcnt(8)
	s_barrier
	s_waitcnt lgkmcnt(0)
	v_mfma_f32_16x16x32_bf16 v[124:127], v[152:155], v[168:171], v[124:127]
	v_mfma_f32_16x16x32_bf16 v[124:127], v[156:159], v[172:175], v[124:127]
	v_mfma_f32_16x16x32_bf16 v[120:123], v[164:167], v[172:175], v[120:123]
	v_mfma_f32_16x16x32_bf16 v[120:123], v[160:163], v[168:171], v[120:123]
	v_mfma_f32_16x16x32_bf16 v[112:115], v[160:163], v[176:179], v[112:115]
	v_mfma_f32_16x16x32_bf16 v[112:115], v[164:167], v[180:183], v[112:115]
	v_mfma_f32_16x16x32_bf16 v[116:119], v[156:159], v[180:183], v[116:119]
	v_mfma_f32_16x16x32_bf16 v[116:119], v[152:155], v[176:179], v[116:119]
	v_mfma_f32_16x16x32_bf16 v[108:111], v[152:155], v[184:187], v[108:111]
	v_mfma_f32_16x16x32_bf16 v[108:111], v[156:159], v[188:191], v[108:111]
	v_mfma_f32_16x16x32_bf16 v[104:107], v[164:167], v[188:191], v[104:107]
	v_mfma_f32_16x16x32_bf16 v[104:107], v[160:163], v[184:187], v[104:107]
	v_mfma_f32_16x16x32_bf16 v[96:99], v[160:163], v[192:195], v[96:99]
	v_mfma_f32_16x16x32_bf16 v[96:99], v[164:167], v[196:199], v[96:99]
	v_mfma_f32_16x16x32_bf16 v[100:103], v[156:159], v[196:199], v[100:103]
	v_mfma_f32_16x16x32_bf16 v[100:103], v[152:155], v[192:195], v[100:103]
	s_barrier
	s_add_i32 s6, s92, s3
	s_add_i32 s7, s6, 0x100
	s_mov_b32 s14, s10
	s_mov_b32 s15, s11
	s_mov_b32 m0, s37
	ds_read_b128 v[200:203], v143
	ds_read_b128 v[204:207], v144
	ds_read_b128 v[208:211], v145
	ds_read_b128 v[212:215], v146
	buffer_load_dwordx4 v141, s[12:15], s7 offen lds
	s_mov_b32 m0, s48
	s_nop 0
	buffer_load_dwordx4 v142, s[12:15], s7 offen lds
	s_barrier
	s_waitcnt lgkmcnt(0)
	v_mfma_f32_16x16x32_bf16 v[92:95], v[200:203], v[168:171], v[92:95]
	v_mfma_f32_16x16x32_bf16 v[92:95], v[204:207], v[172:175], v[92:95]
	v_mfma_f32_16x16x32_bf16 v[88:91], v[212:215], v[172:175], v[88:91]
	v_mfma_f32_16x16x32_bf16 v[88:91], v[208:211], v[168:171], v[88:91]
	v_mfma_f32_16x16x32_bf16 v[68:71], v[208:211], v[176:179], v[68:71]
	v_mfma_f32_16x16x32_bf16 v[68:71], v[212:215], v[180:183], v[68:71]
	v_mfma_f32_16x16x32_bf16 v[80:83], v[204:207], v[180:183], v[80:83]
	v_mfma_f32_16x16x32_bf16 v[80:83], v[200:203], v[176:179], v[80:83]
	v_mfma_f32_16x16x32_bf16 v[60:63], v[200:203], v[184:187], v[60:63]
	v_mfma_f32_16x16x32_bf16 v[60:63], v[204:207], v[188:191], v[60:63]
	v_mfma_f32_16x16x32_bf16 v[56:59], v[212:215], v[188:191], v[56:59]
	v_mfma_f32_16x16x32_bf16 v[56:59], v[208:211], v[184:187], v[56:59]
	v_mfma_f32_16x16x32_bf16 v[48:51], v[208:211], v[192:195], v[48:51]
	v_mfma_f32_16x16x32_bf16 v[48:51], v[212:215], v[196:199], v[48:51]
	v_mfma_f32_16x16x32_bf16 v[52:55], v[204:207], v[196:199], v[52:55]
	v_mfma_f32_16x16x32_bf16 v[52:55], v[200:203], v[192:195], v[52:55]
	s_barrier
	s_add_i32 s7, s87, s3
	s_add_i32 s22, s7, 0x100
	s_mov_b32 m0, s35
	ds_read_b128 v[168:171], v129 offset:16384
	ds_read_b128 v[172:175], v129 offset:17408
	ds_read_b128 v[176:179], v132 offset:16384
	ds_read_b128 v[180:183], v132 offset:17408
	ds_read_b128 v[184:187], v131 offset:16384
	ds_read_b128 v[188:191], v131 offset:17408
	ds_read_b128 v[192:195], v130 offset:16384
	ds_read_b128 v[196:199], v130 offset:17408
	buffer_load_dwordx4 v141, s[8:11], s22 offen lds
	s_mov_b32 m0, s49
	s_nop 0
	buffer_load_dwordx4 v142, s[8:11], s22 offen lds
	s_barrier
	s_waitcnt lgkmcnt(0)
	v_mfma_f32_16x16x32_bf16 v[44:47], v[152:155], v[168:171], v[44:47]
	v_mfma_f32_16x16x32_bf16 v[44:47], v[156:159], v[172:175], v[44:47]
	v_mfma_f32_16x16x32_bf16 v[40:43], v[164:167], v[172:175], v[40:43]
	v_mfma_f32_16x16x32_bf16 v[40:43], v[160:163], v[168:171], v[40:43]
	v_mfma_f32_16x16x32_bf16 v[32:35], v[160:163], v[176:179], v[32:35]
	v_mfma_f32_16x16x32_bf16 v[32:35], v[164:167], v[180:183], v[32:35]
	v_mfma_f32_16x16x32_bf16 v[36:39], v[156:159], v[180:183], v[36:39]
	v_mfma_f32_16x16x32_bf16 v[36:39], v[152:155], v[176:179], v[36:39]
	v_mfma_f32_16x16x32_bf16 v[28:31], v[152:155], v[184:187], v[28:31]
	v_mfma_f32_16x16x32_bf16 v[28:31], v[156:159], v[188:191], v[28:31]
	v_mfma_f32_16x16x32_bf16 v[24:27], v[164:167], v[188:191], v[24:27]
	v_mfma_f32_16x16x32_bf16 v[24:27], v[160:163], v[184:187], v[24:27]
	v_mfma_f32_16x16x32_bf16 v[16:19], v[160:163], v[192:195], v[16:19]
	v_mfma_f32_16x16x32_bf16 v[16:19], v[164:167], v[196:199], v[16:19]
	v_mfma_f32_16x16x32_bf16 v[20:23], v[156:159], v[196:199], v[20:23]
	v_mfma_f32_16x16x32_bf16 v[20:23], v[152:155], v[192:195], v[20:23]
	s_barrier
	s_add_i32 s22, s93, s3
	s_add_i32 s23, s22, 0x100
	s_mov_b32 m0, s38
	s_nop 0
	buffer_load_dwordx4 v141, s[12:15], s23 offen lds
	s_mov_b32 m0, s54
	s_nop 0
	buffer_load_dwordx4 v142, s[12:15], s23 offen lds
	s_waitcnt vmcnt(6)
	s_barrier
; #define STAGE(P, RS, SOFF, OFF, kt) do { const int _so = (SOFF) + (kt) * (BK * 2); \
;     _Pragma("unroll") for (int _i = 0; _i < 2; ++_i) { \
;       __builtin_amdgcn_raw_ptr_buffer_load_lds(RS, (__attribute__((address_space(3))) void*)((P) + wave * 1024 + _i * 8192), 16, OFF[_i], _so, 0, 0); } } while (0)
; #define LDA(dst, b, h) _Pragma("unroll") for (int m = 0; m < 4; ++m) _Pragma("unroll") for (int k = 0; k < 2; ++k) \
;     dst[m][k] = *reinterpret_cast<const bf16x8*>(SA(b, h) + lds_byte(wr * 64 + m * 16 + fr, k * 32 + fq * 8))
; #define LDB(dst, b, h) _Pragma("unroll") for (int n = 0; n < 2; ++n) _Pragma("unroll") for (int k = 0; k < 2; ++k) \
;     dst[n][k] = *reinterpret_cast<const bf16x8*>(SB(b, h) + lds_byte(wc * 32 + n * 16 + fr, k * 32 + fq * 8))
; #define WAIT_V(n) asm volatile("s_waitcnt vmcnt(" #n ")" ::: "memory")
; #define WAIT_L(n) asm volatile("s_waitcnt lgkmcnt(" #n ")" ::: "memory")
; #define BAR __builtin_amdgcn_s_barrier()
; #define SCHED __builtin_amdgcn_sched_barrier(0)
;     ...
;       WAIT_V(6); BAR; MMA(1, 1, At, B1); BAR;
;       LDB(B0, 1, 0); SCHED; LDA(At, 1, 0); STAGE(SA(0, 1), rsA, sA1, offA, t + 2);
;       WAIT_L(8); BAR; WAIT_L(0); MMA(0, 0, At, B0); BAR; SCHED;
;       LDB(B1, 1, 1); STAGE(SB(1, 0), rsB, sB0, offB, t + 3);
;       BAR; WAIT_L(0); MMA(0, 1, At, B1); BAR;
;       LDA(At, 1, 1); STAGE(SA(1, 0), rsA, sA0, offA, t + 3);
;       BAR; WAIT_L(0); MMA(1, 0, At, B0); BAR; SCHED;
	v_mfma_f32_16x16x32_bf16 v[12:15], v[200:203], v[168:171], v[12:15]
	v_mfma_f32_16x16x32_bf16 v[12:15], v[204:207], v[172:175], v[12:15]
	v_mfma_f32_16x16x32_bf16 v[8:11], v[212:215], v[172:175], v[8:11]
	v_mfma_f32_16x16x32_bf16 v[8:11], v[208:211], v[168:171], v[8:11]
	v_mfma_f32_16x16x32_bf16 v[0:3], v[208:211], v[176:179], v[0:3]
	v_mfma_f32_16x16x32_bf16 v[0:3], v[212:215], v[180:183], v[0:3]
	v_mfma_f32_16x16x32_bf16 v[4:7], v[204:207], v[180:183], v[4:7]
	v_mfma_f32_16x16x32_bf16 v[4:7], v[200:203], v[176:179], v[4:7]
	v_mfma_f32_16x16x32_bf16 v[64:67], v[200:203], v[184:187], v[64:67]
	v_mfma_f32_16x16x32_bf16 v[64:67], v[204:207], v[188:191], v[64:67]
	v_mfma_f32_16x16x32_bf16 v[72:75], v[212:215], v[188:191], v[72:75]
	v_mfma_f32_16x16x32_bf16 v[72:75], v[208:211], v[184:187], v[72:75]
	v_mfma_f32_16x16x32_bf16 v[84:87], v[208:211], v[192:195], v[84:87]
	v_mfma_f32_16x16x32_bf16 v[84:87], v[212:215], v[196:199], v[84:87]
	v_mfma_f32_16x16x32_bf16 v[76:79], v[204:207], v[196:199], v[76:79]
	v_mfma_f32_16x16x32_bf16 v[76:79], v[200:203], v[192:195], v[76:79]
	s_barrier
	ds_read_b128 v[152:155], v137
	ds_read_b128 v[156:159], v138
	ds_read_b128 v[160:163], v139
	ds_read_b128 v[164:167], v140
	s_addk_i32 s5, 0x100
	s_mov_b32 m0, s39
	ds_read_b128 v[168:171], v129 offset:32768
	ds_read_b128 v[172:175], v129 offset:33792
	ds_read_b128 v[176:179], v132 offset:32768
	ds_read_b128 v[180:183], v132 offset:33792
	ds_read_b128 v[184:187], v131 offset:32768
	ds_read_b128 v[188:191], v131 offset:33792
	ds_read_b128 v[192:195], v130 offset:32768
	ds_read_b128 v[196:199], v130 offset:33792
	buffer_load_dwordx4 v141, s[8:11], s5 offen lds
	s_mov_b32 m0, s55
	s_nop 0
	buffer_load_dwordx4 v142, s[8:11], s5 offen lds
	s_waitcnt lgkmcnt(8)
	s_barrier
	s_waitcnt lgkmcnt(0)
	v_mfma_f32_16x16x32_bf16 v[124:127], v[152:155], v[168:171], v[124:127]
	v_mfma_f32_16x16x32_bf16 v[124:127], v[156:159], v[172:175], v[124:127]
	v_mfma_f32_16x16x32_bf16 v[120:123], v[164:167], v[172:175], v[120:123]
	v_mfma_f32_16x16x32_bf16 v[120:123], v[160:163], v[168:171], v[120:123]
	v_mfma_f32_16x16x32_bf16 v[112:115], v[160:163], v[176:179], v[112:115]
	v_mfma_f32_16x16x32_bf16 v[112:115], v[164:167], v[180:183], v[112:115]
	v_mfma_f32_16x16x32_bf16 v[116:119], v[156:159], v[180:183], v[116:119]
	v_mfma_f32_16x16x32_bf16 v[116:119], v[152:155], v[176:179], v[116:119]
	v_mfma_f32_16x16x32_bf16 v[108:111], v[152:155], v[184:187], v[108:111]
	v_mfma_f32_16x16x32_bf16 v[108:111], v[156:159], v[188:191], v[108:111]
	v_mfma_f32_16x16x32_bf16 v[104:107], v[164:167], v[188:191], v[104:107]
	v_mfma_f32_16x16x32_bf16 v[104:107], v[160:163], v[184:187], v[104:107]
	v_mfma_f32_16x16x32_bf16 v[96:99], v[160:163], v[192:195], v[96:99]
	v_mfma_f32_16x16x32_bf16 v[96:99], v[164:167], v[196:199], v[96:99]
	v_mfma_f32_16x16x32_bf16 v[100:103], v[156:159], v[196:199], v[100:103]
	v_mfma_f32_16x16x32_bf16 v[100:103], v[152:155], v[192:195], v[100:103]
	s_barrier
	s_addk_i32 s6, 0x180
	s_mov_b32 m0, s42
	ds_read_b128 v[200:203], v133
	ds_read_b128 v[204:207], v134
	ds_read_b128 v[208:211], v135
	ds_read_b128 v[212:215], v136
	buffer_load_dwordx4 v141, s[12:15], s6 offen lds
	s_mov_b32 m0, s56
	s_nop 0
	buffer_load_dwordx4 v142, s[12:15], s6 offen lds
	s_barrier
	s_waitcnt lgkmcnt(0)
	v_mfma_f32_16x16x32_bf16 v[92:95], v[200:203], v[168:171], v[92:95]
	v_mfma_f32_16x16x32_bf16 v[92:95], v[204:207], v[172:175], v[92:95]
	v_mfma_f32_16x16x32_bf16 v[88:91], v[212:215], v[172:175], v[88:91]
	v_mfma_f32_16x16x32_bf16 v[88:91], v[208:211], v[168:171], v[88:91]
	v_mfma_f32_16x16x32_bf16 v[68:71], v[208:211], v[176:179], v[68:71]
	v_mfma_f32_16x16x32_bf16 v[68:71], v[212:215], v[180:183], v[68:71]
	v_mfma_f32_16x16x32_bf16 v[80:83], v[204:207], v[180:183], v[80:83]
	v_mfma_f32_16x16x32_bf16 v[80:83], v[200:203], v[176:179], v[80:83]
	v_mfma_f32_16x16x32_bf16 v[60:63], v[200:203], v[184:187], v[60:63]
	v_mfma_f32_16x16x32_bf16 v[60:63], v[204:207], v[188:191], v[60:63]
	v_mfma_f32_16x16x32_bf16 v[56:59], v[212:215], v[188:191], v[56:59]
	v_mfma_f32_16x16x32_bf16 v[56:59], v[208:211], v[184:187], v[56:59]
	v_mfma_f32_16x16x32_bf16 v[48:51], v[208:211], v[192:195], v[48:51]
	v_mfma_f32_16x16x32_bf16 v[48:51], v[212:215], v[196:199], v[48:51]
	v_mfma_f32_16x16x32_bf16 v[52:55], v[204:207], v[196:199], v[52:55]
	v_mfma_f32_16x16x32_bf16 v[52:55], v[200:203], v[192:195], v[52:55]
	s_barrier
	s_addk_i32 s7, 0x180
	s_mov_b32 m0, s43
	ds_read_b128 v[168:171], v129 offset:49152
	ds_read_b128 v[172:175], v129 offset:50176
	ds_read_b128 v[176:179], v132 offset:49152
	ds_read_b128 v[180:183], v132 offset:50176
	ds_read_b128 v[184:187], v131 offset:49152
	ds_read_b128 v[188:191], v131 offset:50176
	ds_read_b128 v[192:195], v130 offset:49152
	ds_read_b128 v[196:199], v130 offset:50176
	buffer_load_dwordx4 v141, s[8:11], s7 offen lds
	s_mov_b32 m0, s57
	s_nop 0
	buffer_load_dwordx4 v142, s[8:11], s7 offen lds
	s_barrier
	s_waitcnt lgkmcnt(0)
	v_mfma_f32_16x16x32_bf16 v[44:47], v[152:155], v[168:171], v[44:47]
	v_mfma_f32_16x16x32_bf16 v[44:47], v[156:159], v[172:175], v[44:47]
	v_mfma_f32_16x16x32_bf16 v[40:43], v[164:167], v[172:175], v[40:43]
	v_mfma_f32_16x16x32_bf16 v[40:43], v[160:163], v[168:171], v[40:43]
	v_mfma_f32_16x16x32_bf16 v[32:35], v[160:163], v[176:179], v[32:35]
	v_mfma_f32_16x16x32_bf16 v[32:35], v[164:167], v[180:183], v[32:35]
	v_mfma_f32_16x16x32_bf16 v[36:39], v[156:159], v[180:183], v[36:39]
	v_mfma_f32_16x16x32_bf16 v[36:39], v[152:155], v[176:179], v[36:39]
	v_mfma_f32_16x16x32_bf16 v[28:31], v[152:155], v[184:187], v[28:31]
	v_mfma_f32_16x16x32_bf16 v[28:31], v[156:159], v[188:191], v[28:31]
	v_mfma_f32_16x16x32_bf16 v[24:27], v[164:167], v[188:191], v[24:27]
	v_mfma_f32_16x16x32_bf16 v[24:27], v[160:163], v[184:187], v[24:27]
	v_mfma_f32_16x16x32_bf16 v[16:19], v[160:163], v[192:195], v[16:19]
	v_mfma_f32_16x16x32_bf16 v[16:19], v[164:167], v[196:199], v[16:19]
	v_mfma_f32_16x16x32_bf16 v[20:23], v[156:159], v[196:199], v[20:23]
	v_mfma_f32_16x16x32_bf16 v[20:23], v[152:155], v[192:195], v[20:23]
	s_barrier
; #define STAGE(P, RS, SOFF, OFF, kt) do { const int _so = (SOFF) + (kt) * (BK * 2); \
;     _Pragma("unroll") for (int _i = 0; _i < 2; ++_i) { \
;       __builtin_amdgcn_raw_ptr_buffer_load_lds(RS, (__attribute__((address_space(3))) void*)((P) + wave * 1024 + _i * 8192), 16, OFF[_i], _so, 0, 0); } } while (0)
; #define LDA(dst, b, h) _Pragma("unroll") for (int m = 0; m < 4; ++m) _Pragma("unroll") for (int k = 0; k < 2; ++k) \
;     dst[m][k] = *reinterpret_cast<const bf16x8*>(SA(b, h) + lds_byte(wr * 64 + m * 16 + fr, k * 32 + fq * 8))
; #define LDB(dst, b, h) _Pragma("unroll") for (int n = 0; n < 2; ++n) _Pragma("unroll") for (int k = 0; k < 2; ++k) \
;     dst[n][k] = *reinterpret_cast<const bf16x8*>(SB(b, h) + lds_byte(wc * 32 + n * 16 + fr, k * 32 + fq * 8))
; #define WAIT_V(n) asm volatile("s_waitcnt vmcnt(" #n ")" ::: "memory")
; #define WAIT_L(n) asm volatile("s_waitcnt lgkmcnt(" #n ")" ::: "memory")
; #define BAR __builtin_amdgcn_s_barrier()
;     ...
;       STAGE(SB(1, 1), rsB, sB1, offB, t + 3);
;       WAIT_V(6); BAR; MMA(1, 1, At, B1); BAR;
;     }
;     { LDB(B0, 0, 0); LDA(At, 0, 0); STAGE(SA(1, 1), rsA, sA1, offA, nt - 1);
;       BAR; WAIT_L(0); MMA(0, 0, At, B0); BAR;
;       LDB(B1, 0, 1); BAR; WAIT_L(0); MMA(0, 1, At, B1); BAR;
;       LDA(At, 0, 1); WAIT_V(4); BAR; WAIT_L(0); MMA(1, 0, At, B0); MMA(1, 1, At, B1); BAR; }
	s_addk_i32 s22, 0x180
	s_mov_b32 m0, s44
	s_nop 0
	buffer_load_dwordx4 v141, s[12:15], s22 offen lds
	s_mov_b32 m0, s58
	s_nop 0
	buffer_load_dwordx4 v142, s[12:15], s22 offen lds
	s_add_i32 s1, s1, 2
	s_addk_i32 s3, 0x100
	s_cmp_gt_u32 s1, 59
	s_cbranch_scc0 .LBB0_392
	s_waitcnt vmcnt(6)
	s_barrier
	v_mfma_f32_16x16x32_bf16 v[12:15], v[200:203], v[168:171], v[12:15]
	v_mfma_f32_16x16x32_bf16 v[12:15], v[204:207], v[172:175], v[12:15]
	v_mfma_f32_16x16x32_bf16 v[8:11], v[212:215], v[172:175], v[8:11]
	v_mfma_f32_16x16x32_bf16 v[8:11], v[208:211], v[168:171], v[8:11]
	v_mfma_f32_16x16x32_bf16 v[0:3], v[208:211], v[176:179], v[0:3]
	v_mfma_f32_16x16x32_bf16 v[0:3], v[212:215], v[180:183], v[0:3]
	v_mfma_f32_16x16x32_bf16 v[4:7], v[204:207], v[180:183], v[4:7]
	v_mfma_f32_16x16x32_bf16 v[4:7], v[200:203], v[176:179], v[4:7]
	v_mfma_f32_16x16x32_bf16 v[64:67], v[200:203], v[184:187], v[64:67]
	v_mfma_f32_16x16x32_bf16 v[64:67], v[204:207], v[188:191], v[64:67]
	v_mfma_f32_16x16x32_bf16 v[72:75], v[212:215], v[188:191], v[72:75]
	v_mfma_f32_16x16x32_bf16 v[72:75], v[208:211], v[184:187], v[72:75]
	v_mfma_f32_16x16x32_bf16 v[84:87], v[208:211], v[192:195], v[84:87]
	v_mfma_f32_16x16x32_bf16 v[84:87], v[212:215], v[196:199], v[84:87]
	v_mfma_f32_16x16x32_bf16 v[76:79], v[204:207], v[196:199], v[76:79]
	v_mfma_f32_16x16x32_bf16 v[76:79], v[200:203], v[192:195], v[76:79]
	s_barrier
	s_add_i32 s1, s86, 0x1f80
	s_mov_b32 m0, s36
	ds_read_b128 v[152:155], v147
	ds_read_b128 v[156:159], v148
	ds_read_b128 v[160:163], v149
	ds_read_b128 v[148:151], v150
	ds_read_b128 v[164:167], v129
	ds_read_b128 v[168:171], v129 offset:1024
	ds_read_b128 v[172:175], v132
	ds_read_b128 v[176:179], v132 offset:1024
	ds_read_b128 v[180:183], v131
	ds_read_b128 v[184:187], v131 offset:1024
	ds_read_b128 v[188:191], v130
	ds_read_b128 v[192:195], v130 offset:1024
	buffer_load_dwordx4 v141, s[8:11], s1 offen lds
	s_mov_b32 m0, s59
	s_nop 0
	buffer_load_dwordx4 v142, s[8:11], s1 offen lds
	s_barrier
	s_waitcnt lgkmcnt(0)
	v_mfma_f32_16x16x32_bf16 v[124:127], v[152:155], v[164:167], v[124:127]
	v_mfma_f32_16x16x32_bf16 v[124:127], v[156:159], v[168:171], v[124:127]
	v_mfma_f32_16x16x32_bf16 v[120:123], v[148:151], v[168:171], v[120:123]
	v_mfma_f32_16x16x32_bf16 v[120:123], v[160:163], v[164:167], v[120:123]
	v_mfma_f32_16x16x32_bf16 v[112:115], v[160:163], v[172:175], v[112:115]
	v_mfma_f32_16x16x32_bf16 v[112:115], v[148:151], v[176:179], v[112:115]
	v_mfma_f32_16x16x32_bf16 v[116:119], v[156:159], v[176:179], v[116:119]
	v_mfma_f32_16x16x32_bf16 v[116:119], v[152:155], v[172:175], v[116:119]
	v_mfma_f32_16x16x32_bf16 v[108:111], v[152:155], v[180:183], v[108:111]
	v_mfma_f32_16x16x32_bf16 v[108:111], v[156:159], v[184:187], v[108:111]
	v_mfma_f32_16x16x32_bf16 v[104:107], v[148:151], v[184:187], v[104:107]
	v_mfma_f32_16x16x32_bf16 v[104:107], v[160:163], v[180:183], v[104:107]
	v_mfma_f32_16x16x32_bf16 v[96:99], v[160:163], v[188:191], v[96:99]
	v_mfma_f32_16x16x32_bf16 v[96:99], v[148:151], v[192:195], v[96:99]
	v_mfma_f32_16x16x32_bf16 v[100:103], v[156:159], v[192:195], v[100:103]
	v_mfma_f32_16x16x32_bf16 v[100:103], v[152:155], v[188:191], v[100:103]
	s_barrier
	ds_read_b128 v[196:199], v143
	ds_read_b128 v[200:203], v144
	ds_read_b128 v[142:145], v145
	ds_read_b128 v[204:207], v146
	s_barrier
	s_waitcnt lgkmcnt(0)
	v_mfma_f32_16x16x32_bf16 v[80:83], v[196:199], v[172:175], v[80:83]
	v_mfma_f32_16x16x32_bf16 v[68:71], v[142:145], v[172:175], v[68:71]
	v_mfma_f32_16x16x32_bf16 v[60:63], v[196:199], v[180:183], v[60:63]
	v_mfma_f32_16x16x32_bf16 v[56:59], v[142:145], v[180:183], v[56:59]
	v_mfma_f32_16x16x32_bf16 v[52:55], v[196:199], v[188:191], v[52:55]
	v_mfma_f32_16x16x32_bf16 v[48:51], v[142:145], v[188:191], v[48:51]
	v_mfma_f32_16x16x32_bf16 v[92:95], v[196:199], v[164:167], v[92:95]
	v_mfma_f32_16x16x32_bf16 v[88:91], v[142:145], v[164:167], v[88:91]
	v_mfma_f32_16x16x32_bf16 v[80:83], v[200:203], v[176:179], v[80:83]
	v_mfma_f32_16x16x32_bf16 v[68:71], v[204:207], v[176:179], v[68:71]
	v_mfma_f32_16x16x32_bf16 v[60:63], v[200:203], v[184:187], v[60:63]
	v_mfma_f32_16x16x32_bf16 v[56:59], v[204:207], v[184:187], v[56:59]
	v_mfma_f32_16x16x32_bf16 v[52:55], v[200:203], v[192:195], v[52:55]
	v_mfma_f32_16x16x32_bf16 v[48:51], v[204:207], v[192:195], v[48:51]
	v_mfma_f32_16x16x32_bf16 v[164:167], v[200:203], v[168:171], v[92:95]
	v_mfma_f32_16x16x32_bf16 v[168:171], v[204:207], v[168:171], v[88:91]
	s_barrier
	s_nop 0
	ds_read_b128 v[88:91], v129 offset:16384
	ds_read_b128 v[92:95], v129 offset:17408
	ds_read_b128 v[172:175], v132 offset:16384
	ds_read_b128 v[176:179], v132 offset:17408
	ds_read_b128 v[180:183], v131 offset:16384
	ds_read_b128 v[184:187], v131 offset:17408
	ds_read_b128 v[188:191], v130 offset:16384
	ds_read_b128 v[192:195], v130 offset:17408
	s_waitcnt vmcnt(4)
	s_barrier
; #define LDA(dst, b, h) _Pragma("unroll") for (int m = 0; m < 4; ++m) _Pragma("unroll") for (int k = 0; k < 2; ++k) \
;     dst[m][k] = *reinterpret_cast<const bf16x8*>(SA(b, h) + lds_byte(wr * 64 + m * 16 + fr, k * 32 + fq * 8))
; #define LDB(dst, b, h) _Pragma("unroll") for (int n = 0; n < 2; ++n) _Pragma("unroll") for (int k = 0; k < 2; ++k) \
;     dst[n][k] = *reinterpret_cast<const bf16x8*>(SB(b, h) + lds_byte(wc * 32 + n * 16 + fr, k * 32 + fq * 8))
; #define WAIT_V(n) asm volatile("s_waitcnt vmcnt(" #n ")" ::: "memory")
; #define WAIT_L(n) asm volatile("s_waitcnt lgkmcnt(" #n ")" ::: "memory")
; #define BAR __builtin_amdgcn_s_barrier()
;     ...
;       LDA(At, 0, 1); WAIT_V(4); BAR; WAIT_L(0); MMA(1, 0, At, B0); MMA(1, 1, At, B1); BAR; }
;     { LDB(B0, 1, 0); LDA(At, 1, 0); WAIT_V(2); BAR; WAIT_L(0); MMA(0, 0, At, B0); BAR;
	s_waitcnt lgkmcnt(0)
	v_mfma_f32_16x16x32_bf16 v[44:47], v[152:155], v[88:91], v[44:47]
	v_mfma_f32_16x16x32_bf16 v[40:43], v[160:163], v[88:91], v[40:43]
	v_mfma_f32_16x16x32_bf16 v[36:39], v[152:155], v[172:175], v[36:39]
	v_mfma_f32_16x16x32_bf16 v[32:35], v[160:163], v[172:175], v[32:35]
	v_mfma_f32_16x16x32_bf16 v[28:31], v[152:155], v[180:183], v[28:31]
	v_mfma_f32_16x16x32_bf16 v[24:27], v[160:163], v[180:183], v[24:27]
	v_mfma_f32_16x16x32_bf16 v[20:23], v[152:155], v[188:191], v[20:23]
	v_mfma_f32_16x16x32_bf16 v[16:19], v[160:163], v[188:191], v[16:19]
	v_mfma_f32_16x16x32_bf16 v[44:47], v[156:159], v[92:95], v[44:47]
	v_mfma_f32_16x16x32_bf16 v[40:43], v[148:151], v[92:95], v[40:43]
	v_mfma_f32_16x16x32_bf16 v[36:39], v[156:159], v[176:179], v[36:39]
	v_mfma_f32_16x16x32_bf16 v[32:35], v[148:151], v[176:179], v[32:35]
	v_mfma_f32_16x16x32_bf16 v[28:31], v[156:159], v[184:187], v[28:31]
	v_mfma_f32_16x16x32_bf16 v[24:27], v[148:151], v[184:187], v[24:27]
	v_mfma_f32_16x16x32_bf16 v[20:23], v[156:159], v[192:195], v[20:23]
	v_mfma_f32_16x16x32_bf16 v[16:19], v[148:151], v[192:195], v[16:19]
	v_mfma_f32_16x16x32_bf16 v[4:7], v[196:199], v[172:175], v[4:7]
	v_mfma_f32_16x16x32_bf16 v[0:3], v[142:145], v[172:175], v[0:3]
	v_mfma_f32_16x16x32_bf16 v[12:15], v[196:199], v[88:91], v[12:15]
	v_mfma_f32_16x16x32_bf16 v[8:11], v[142:145], v[88:91], v[8:11]
	v_mfma_f32_16x16x32_bf16 v[64:67], v[196:199], v[180:183], v[64:67]
	v_mfma_f32_16x16x32_bf16 v[72:75], v[142:145], v[180:183], v[72:75]
	v_mfma_f32_16x16x32_bf16 v[76:79], v[196:199], v[188:191], v[76:79]
	v_mfma_f32_16x16x32_bf16 v[84:87], v[142:145], v[188:191], v[84:87]
	v_mfma_f32_16x16x32_bf16 v[4:7], v[200:203], v[176:179], v[4:7]
	v_mfma_f32_16x16x32_bf16 v[0:3], v[204:207], v[176:179], v[0:3]
	v_mfma_f32_16x16x32_bf16 v[142:145], v[200:203], v[92:95], v[12:15]
	v_mfma_f32_16x16x32_bf16 v[146:149], v[204:207], v[92:95], v[8:11]
	v_mfma_f32_16x16x32_bf16 v[150:153], v[200:203], v[184:187], v[64:67]
	v_mfma_f32_16x16x32_bf16 v[154:157], v[204:207], v[184:187], v[72:75]
	v_mfma_f32_16x16x32_bf16 v[158:161], v[200:203], v[192:195], v[76:79]
	v_mfma_f32_16x16x32_bf16 v[172:175], v[204:207], v[192:195], v[84:87]
	s_barrier
	ds_read_b128 v[8:11], v137
	ds_read_b128 v[12:15], v138
	ds_read_b128 v[176:179], v139
	ds_read_b128 v[138:141], v140
	ds_read_b128 v[64:67], v129 offset:32768
	ds_read_b128 v[84:87], v129 offset:33792
	ds_read_b128 v[180:183], v132 offset:32768
	ds_read_b128 v[184:187], v132 offset:33792
	ds_read_b128 v[188:191], v131 offset:32768
	ds_read_b128 v[192:195], v131 offset:33792
	ds_read_b128 v[196:199], v130 offset:32768
	ds_read_b128 v[200:203], v130 offset:33792
	s_waitcnt vmcnt(2)
	s_barrier
	s_waitcnt lgkmcnt(0)
	v_mfma_f32_16x16x32_bf16 v[72:75], v[8:11], v[64:67], v[124:127]
	v_mfma_f32_16x16x32_bf16 v[76:79], v[176:179], v[64:67], v[120:123]
	v_mfma_f32_16x16x32_bf16 v[88:91], v[8:11], v[180:183], v[116:119]
	v_mfma_f32_16x16x32_bf16 v[92:95], v[176:179], v[180:183], v[112:115]
	v_mfma_f32_16x16x32_bf16 v[112:115], v[8:11], v[188:191], v[108:111]
	v_mfma_f32_16x16x32_bf16 v[120:123], v[176:179], v[188:191], v[104:107]
	v_mfma_f32_16x16x32_bf16 v[100:103], v[8:11], v[196:199], v[100:103]
	v_mfma_f32_16x16x32_bf16 v[96:99], v[176:179], v[196:199], v[96:99]
	v_mfma_f32_16x16x32_bf16 v[124:127], v[12:15], v[84:87], v[72:75]
	v_mfma_f32_16x16x32_bf16 v[116:119], v[138:141], v[84:87], v[76:79]
	v_mfma_f32_16x16x32_bf16 v[108:111], v[12:15], v[184:187], v[88:91]
	v_mfma_f32_16x16x32_bf16 v[104:107], v[138:141], v[184:187], v[92:95]
	v_mfma_f32_16x16x32_bf16 v[92:95], v[12:15], v[192:195], v[112:115]
	v_mfma_f32_16x16x32_bf16 v[88:91], v[138:141], v[192:195], v[120:123]
	v_mfma_f32_16x16x32_bf16 v[76:79], v[12:15], v[200:203], v[100:103]
	v_mfma_f32_16x16x32_bf16 v[72:75], v[138:141], v[200:203], v[96:99]
	s_barrier
; #define LDA(dst, b, h) _Pragma("unroll") for (int m = 0; m < 4; ++m) _Pragma("unroll") for (int k = 0; k < 2; ++k) \
;     dst[m][k] = *reinterpret_cast<const bf16x8*>(SA(b, h) + lds_byte(wr * 64 + m * 16 + fr, k * 32 + fq * 8))
; #define LDB(dst, b, h) _Pragma("unroll") for (int n = 0; n < 2; ++n) _Pragma("unroll") for (int k = 0; k < 2; ++k) \
;     dst[n][k] = *reinterpret_cast<const bf16x8*>(SB(b, h) + lds_byte(wc * 32 + n * 16 + fr, k * 32 + fq * 8))
; #define WAIT_V(n) asm volatile("s_waitcnt vmcnt(" #n ")" ::: "memory")
; #define WAIT_L(n) asm volatile("s_waitcnt lgkmcnt(" #n ")" ::: "memory")
; #define BAR __builtin_amdgcn_s_barrier()
;     ...
;       LDB(B1, 1, 1); WAIT_V(0); BAR; WAIT_L(0); MMA(0, 1, At, B1); BAR;
;       LDA(At, 1, 1); BAR; WAIT_L(0); MMA(1, 0, At, B0); MMA(1, 1, At, B1); BAR; }
;     if (wr == 0) BAR;
	ds_read_b128 v[204:207], v133
	ds_read_b128 v[208:211], v134
	ds_read_b128 v[212:215], v135
	ds_read_b128 v[134:137], v136
	s_waitcnt vmcnt(0)
	s_barrier
	s_waitcnt lgkmcnt(0)
	v_mfma_f32_16x16x32_bf16 v[96:99], v[204:207], v[64:67], v[164:167]
	v_mfma_f32_16x16x32_bf16 v[64:67], v[212:215], v[64:67], v[168:171]
	v_mfma_f32_16x16x32_bf16 v[80:83], v[204:207], v[180:183], v[80:83]
	v_mfma_f32_16x16x32_bf16 v[68:71], v[212:215], v[180:183], v[68:71]
	v_mfma_f32_16x16x32_bf16 v[60:63], v[204:207], v[188:191], v[60:63]
	v_mfma_f32_16x16x32_bf16 v[56:59], v[212:215], v[188:191], v[56:59]
	v_mfma_f32_16x16x32_bf16 v[52:55], v[204:207], v[196:199], v[52:55]
	v_mfma_f32_16x16x32_bf16 v[48:51], v[212:215], v[196:199], v[48:51]
	v_mfma_f32_16x16x32_bf16 v[120:123], v[208:211], v[84:87], v[96:99]
	v_mfma_f32_16x16x32_bf16 v[112:115], v[134:137], v[84:87], v[64:67]
	v_mfma_f32_16x16x32_bf16 v[100:103], v[208:211], v[184:187], v[80:83]
	v_mfma_f32_16x16x32_bf16 v[96:99], v[134:137], v[184:187], v[68:71]
	v_mfma_f32_16x16x32_bf16 v[84:87], v[208:211], v[192:195], v[60:63]
	v_mfma_f32_16x16x32_bf16 v[80:83], v[134:137], v[192:195], v[56:59]
	v_mfma_f32_16x16x32_bf16 v[68:71], v[208:211], v[200:203], v[52:55]
	v_mfma_f32_16x16x32_bf16 v[64:67], v[134:137], v[200:203], v[48:51]
	s_barrier
	s_nop 0
	ds_read_b128 v[48:51], v129 offset:49152
	ds_read_b128 v[162:165], v129 offset:50176
	ds_read_b128 v[52:55], v132 offset:49152
	ds_read_b128 v[166:169], v132 offset:50176
	ds_read_b128 v[180:183], v131 offset:49152
	ds_read_b128 v[184:187], v131 offset:50176
	ds_read_b128 v[188:191], v130 offset:49152
	ds_read_b128 v[130:133], v130 offset:50176
	s_barrier
	s_waitcnt lgkmcnt(0)
	v_mfma_f32_16x16x32_bf16 v[44:47], v[8:11], v[48:51], v[44:47]
	v_mfma_f32_16x16x32_bf16 v[40:43], v[176:179], v[48:51], v[40:43]
	v_mfma_f32_16x16x32_bf16 v[36:39], v[8:11], v[52:55], v[36:39]
	v_mfma_f32_16x16x32_bf16 v[32:35], v[176:179], v[52:55], v[32:35]
	v_mfma_f32_16x16x32_bf16 v[28:31], v[8:11], v[180:183], v[28:31]
	v_mfma_f32_16x16x32_bf16 v[24:27], v[176:179], v[180:183], v[24:27]
	v_mfma_f32_16x16x32_bf16 v[8:11], v[8:11], v[188:191], v[20:23]
	v_mfma_f32_16x16x32_bf16 v[16:19], v[176:179], v[188:191], v[16:19]
	v_mfma_f32_16x16x32_bf16 v[60:63], v[12:15], v[162:165], v[44:47]
	v_mfma_f32_16x16x32_bf16 v[56:59], v[138:141], v[162:165], v[40:43]
	v_mfma_f32_16x16x32_bf16 v[44:47], v[12:15], v[166:169], v[36:39]
	v_mfma_f32_16x16x32_bf16 v[40:43], v[138:141], v[166:169], v[32:35]
	v_mfma_f32_16x16x32_bf16 v[28:31], v[12:15], v[184:187], v[28:31]
	v_mfma_f32_16x16x32_bf16 v[24:27], v[138:141], v[184:187], v[24:27]
	v_mfma_f32_16x16x32_bf16 v[12:15], v[12:15], v[130:133], v[8:11]
	v_mfma_f32_16x16x32_bf16 v[8:11], v[138:141], v[130:133], v[16:19]
	v_mfma_f32_16x16x32_bf16 v[16:19], v[204:207], v[48:51], v[142:145]
	v_mfma_f32_16x16x32_bf16 v[20:23], v[212:215], v[48:51], v[146:149]
	v_mfma_f32_16x16x32_bf16 v[4:7], v[204:207], v[52:55], v[4:7]
	v_mfma_f32_16x16x32_bf16 v[0:3], v[212:215], v[52:55], v[0:3]
	v_mfma_f32_16x16x32_bf16 v[138:141], v[204:207], v[180:183], v[150:153]
	v_mfma_f32_16x16x32_bf16 v[142:145], v[212:215], v[180:183], v[154:157]
	v_mfma_f32_16x16x32_bf16 v[146:149], v[204:207], v[188:191], v[158:161]
	v_mfma_f32_16x16x32_bf16 v[150:153], v[212:215], v[188:191], v[172:175]
	v_mfma_f32_16x16x32_bf16 v[52:55], v[208:211], v[162:165], v[16:19]
	v_mfma_f32_16x16x32_bf16 v[48:51], v[134:137], v[162:165], v[20:23]
	v_mfma_f32_16x16x32_bf16 v[36:39], v[208:211], v[166:169], v[4:7]
	v_mfma_f32_16x16x32_bf16 v[32:35], v[134:137], v[166:169], v[0:3]
	v_mfma_f32_16x16x32_bf16 v[20:23], v[208:211], v[184:187], v[138:141]
	v_mfma_f32_16x16x32_bf16 v[16:19], v[134:137], v[184:187], v[142:145]
	v_mfma_f32_16x16x32_bf16 v[4:7], v[208:211], v[130:133], v[146:149]
	v_mfma_f32_16x16x32_bf16 v[0:3], v[134:137], v[130:133], v[150:153]
	v_cmp_gt_u32_e32 vcc, s40, v128
	s_barrier
	s_and_saveexec_b64 s[6:7], vcc
	s_cbranch_execz .LBB0_395
	s_barrier

; #define STAGE(P, RS, SOFF, OFF, kt) do { const int _so = (SOFF) + (kt) * (BK * 2); \
;     _Pragma("unroll") for (int _i = 0; _i < 2; ++_i) { \
;       __builtin_amdgcn_raw_ptr_buffer_load_lds(RS, (__attribute__((address_space(3))) void*)((P) + wave * 1024 + _i * 8192), 16, OFF[_i], _so, 0, 0); } } while (0)
; #define LDA(dst, b, h) _Pragma("unroll") for (int m = 0; m < 4; ++m) _Pragma("unroll") for (int k = 0; k < 2; ++k) \
;     dst[m][k] = *reinterpret_cast<const bf16x8*>(SA(b, h) + lds_byte(wr * 64 + m * 16 + fr, k * 32 + fq * 8))
; #define LDB(dst, b, h) _Pragma("unroll") for (int n = 0; n < 2; ++n) _Pragma("unroll") for (int k = 0; k < 2; ++k) \
;     dst[n][k] = *reinterpret_cast<const bf16x8*>(SB(b, h) + lds_byte(wc * 32 + n * 16 + fr, k * 32 + fq * 8))
; #define WAIT_V(n) asm volatile("s_waitcnt vmcnt(" #n ")" ::: "memory")
; #define WAIT_L(n) asm volatile("s_waitcnt lgkmcnt(" #n ")" ::: "memory")
; #define BAR __builtin_amdgcn_s_barrier()
; #define SCHED __builtin_amdgcn_sched_barrier(0)
;     ...
;       LDB(B0, 0, 0); SCHED; LDA(At, 0, 0); STAGE(SA(1, 1), rsA, sA1, offA, t + 1);
;       WAIT_L(8); BAR; WAIT_L(0); MMA(0, 0, At, B0); BAR; SCHED;
;       LDB(B1, 0, 1); STAGE(SB(0, 0), rsB, sB0, offB, t + 2);
;       BAR; WAIT_L(0); MMA(0, 1, At, B1); BAR;
;       LDA(At, 0, 1); STAGE(SA(0, 0), rsA, sA0, offA, t + 2);
;       BAR; WAIT_L(0); MMA(1, 0, At, B0); BAR; SCHED;
;       STAGE(SB(0, 1), rsB, sB1, offB, t + 2);
;       WAIT_V(6); BAR; MMA(1, 1, At, B1); BAR;
.Lmy_rot_494:
	ds_read_b128 v[152:155], v147
	ds_read_b128 v[156:159], v148
	ds_read_b128 v[160:163], v149
	ds_read_b128 v[164:167], v150
	s_add_i32 s5, s82, s3
	s_add_i32 s6, s5, 0x80
	s_mov_b32 m0, s36
	ds_read_b128 v[168:171], v129
	ds_read_b128 v[172:175], v129 offset:1024
	ds_read_b128 v[176:179], v132
	ds_read_b128 v[180:183], v132 offset:1024
	ds_read_b128 v[184:187], v131
	ds_read_b128 v[188:191], v131 offset:1024
	ds_read_b128 v[192:195], v130
	ds_read_b128 v[196:199], v130 offset:1024
	buffer_load_dwordx4 v141, s[8:11], s6 offen lds
	s_mov_b32 m0, s59
	s_nop 0
	buffer_load_dwordx4 v142, s[8:11], s6 offen lds
	s_waitcnt lgkmcnt(8)
	s_barrier
	s_waitcnt lgkmcnt(0)
	v_mfma_f32_16x16x32_bf16 v[124:127], v[152:155], v[168:171], v[124:127]
	v_mfma_f32_16x16x32_bf16 v[124:127], v[156:159], v[172:175], v[124:127]
	v_mfma_f32_16x16x32_bf16 v[120:123], v[164:167], v[172:175], v[120:123]
	v_mfma_f32_16x16x32_bf16 v[120:123], v[160:163], v[168:171], v[120:123]
	v_mfma_f32_16x16x32_bf16 v[112:115], v[160:163], v[176:179], v[112:115]
	v_mfma_f32_16x16x32_bf16 v[112:115], v[164:167], v[180:183], v[112:115]
	v_mfma_f32_16x16x32_bf16 v[116:119], v[156:159], v[180:183], v[116:119]
	v_mfma_f32_16x16x32_bf16 v[116:119], v[152:155], v[176:179], v[116:119]
	v_mfma_f32_16x16x32_bf16 v[108:111], v[152:155], v[184:187], v[108:111]
	v_mfma_f32_16x16x32_bf16 v[108:111], v[156:159], v[188:191], v[108:111]
	v_mfma_f32_16x16x32_bf16 v[104:107], v[164:167], v[188:191], v[104:107]
	v_mfma_f32_16x16x32_bf16 v[104:107], v[160:163], v[184:187], v[104:107]
	v_mfma_f32_16x16x32_bf16 v[96:99], v[160:163], v[192:195], v[96:99]
	v_mfma_f32_16x16x32_bf16 v[96:99], v[164:167], v[196:199], v[96:99]
	v_mfma_f32_16x16x32_bf16 v[100:103], v[156:159], v[196:199], v[100:103]
	v_mfma_f32_16x16x32_bf16 v[100:103], v[152:155], v[192:195], v[100:103]
	s_barrier
	s_add_i32 s6, s84, s3
	s_add_i32 s7, s6, 0x100
	s_mov_b32 s14, s10
	s_mov_b32 s15, s11
	s_mov_b32 m0, s37
	ds_read_b128 v[200:203], v143
	ds_read_b128 v[204:207], v144
	ds_read_b128 v[208:211], v145
	ds_read_b128 v[212:215], v146
	buffer_load_dwordx4 v141, s[12:15], s7 offen lds
	s_mov_b32 m0, s70
	s_nop 0
	buffer_load_dwordx4 v142, s[12:15], s7 offen lds
	s_barrier
	s_waitcnt lgkmcnt(0)
	v_mfma_f32_16x16x32_bf16 v[92:95], v[200:203], v[168:171], v[92:95]
	v_mfma_f32_16x16x32_bf16 v[92:95], v[204:207], v[172:175], v[92:95]
	v_mfma_f32_16x16x32_bf16 v[88:91], v[212:215], v[172:175], v[88:91]
	v_mfma_f32_16x16x32_bf16 v[88:91], v[208:211], v[168:171], v[88:91]
	v_mfma_f32_16x16x32_bf16 v[68:71], v[208:211], v[176:179], v[68:71]
	v_mfma_f32_16x16x32_bf16 v[68:71], v[212:215], v[180:183], v[68:71]
	v_mfma_f32_16x16x32_bf16 v[80:83], v[204:207], v[180:183], v[80:83]
	v_mfma_f32_16x16x32_bf16 v[80:83], v[200:203], v[176:179], v[80:83]
	v_mfma_f32_16x16x32_bf16 v[60:63], v[200:203], v[184:187], v[60:63]
	v_mfma_f32_16x16x32_bf16 v[60:63], v[204:207], v[188:191], v[60:63]
	v_mfma_f32_16x16x32_bf16 v[56:59], v[212:215], v[188:191], v[56:59]
	v_mfma_f32_16x16x32_bf16 v[56:59], v[208:211], v[184:187], v[56:59]
	v_mfma_f32_16x16x32_bf16 v[48:51], v[208:211], v[192:195], v[48:51]
	v_mfma_f32_16x16x32_bf16 v[48:51], v[212:215], v[196:199], v[48:51]
	v_mfma_f32_16x16x32_bf16 v[52:55], v[204:207], v[196:199], v[52:55]
	v_mfma_f32_16x16x32_bf16 v[52:55], v[200:203], v[192:195], v[52:55]
	s_barrier
	s_add_i32 s7, s83, s3
	s_add_i32 s22, s7, 0x100
	s_mov_b32 m0, s35
	ds_read_b128 v[168:171], v129 offset:16384
	ds_read_b128 v[172:175], v129 offset:17408
	ds_read_b128 v[176:179], v132 offset:16384
	ds_read_b128 v[180:183], v132 offset:17408
	ds_read_b128 v[184:187], v131 offset:16384
	ds_read_b128 v[188:191], v131 offset:17408
	ds_read_b128 v[192:195], v130 offset:16384
	ds_read_b128 v[196:199], v130 offset:17408
	buffer_load_dwordx4 v141, s[8:11], s22 offen lds
	s_mov_b32 m0, s95
	s_nop 0
	buffer_load_dwordx4 v142, s[8:11], s22 offen lds
	s_barrier
	s_waitcnt lgkmcnt(0)
	v_mfma_f32_16x16x32_bf16 v[44:47], v[152:155], v[168:171], v[44:47]
	v_mfma_f32_16x16x32_bf16 v[44:47], v[156:159], v[172:175], v[44:47]
	v_mfma_f32_16x16x32_bf16 v[40:43], v[164:167], v[172:175], v[40:43]
	v_mfma_f32_16x16x32_bf16 v[40:43], v[160:163], v[168:171], v[40:43]
	v_mfma_f32_16x16x32_bf16 v[32:35], v[160:163], v[176:179], v[32:35]
	v_mfma_f32_16x16x32_bf16 v[32:35], v[164:167], v[180:183], v[32:35]
	v_mfma_f32_16x16x32_bf16 v[36:39], v[156:159], v[180:183], v[36:39]
	v_mfma_f32_16x16x32_bf16 v[36:39], v[152:155], v[176:179], v[36:39]
	v_mfma_f32_16x16x32_bf16 v[28:31], v[152:155], v[184:187], v[28:31]
	v_mfma_f32_16x16x32_bf16 v[28:31], v[156:159], v[188:191], v[28:31]
	v_mfma_f32_16x16x32_bf16 v[24:27], v[164:167], v[188:191], v[24:27]
	v_mfma_f32_16x16x32_bf16 v[24:27], v[160:163], v[184:187], v[24:27]
	v_mfma_f32_16x16x32_bf16 v[16:19], v[160:163], v[192:195], v[16:19]
	v_mfma_f32_16x16x32_bf16 v[16:19], v[164:167], v[196:199], v[16:19]
	v_mfma_f32_16x16x32_bf16 v[20:23], v[156:159], v[196:199], v[20:23]
	v_mfma_f32_16x16x32_bf16 v[20:23], v[152:155], v[192:195], v[20:23]
	s_barrier
	s_add_i32 s22, s85, s3
	s_add_i32 s23, s22, 0x100
	s_mov_b32 m0, s38
	s_nop 0
	buffer_load_dwordx4 v141, s[12:15], s23 offen lds
	s_mov_b32 m0, s71
	s_nop 0
	buffer_load_dwordx4 v142, s[12:15], s23 offen lds
	s_waitcnt vmcnt(6)
	s_barrier
; #define STAGE(P, RS, SOFF, OFF, kt) do { const int _so = (SOFF) + (kt) * (BK * 2); \
;     _Pragma("unroll") for (int _i = 0; _i < 2; ++_i) { \
;       __builtin_amdgcn_raw_ptr_buffer_load_lds(RS, (__attribute__((address_space(3))) void*)((P) + wave * 1024 + _i * 8192), 16, OFF[_i], _so, 0, 0); } } while (0)
; #define LDA(dst, b, h) _Pragma("unroll") for (int m = 0; m < 4; ++m) _Pragma("unroll") for (int k = 0; k < 2; ++k) \
;     dst[m][k] = *reinterpret_cast<const bf16x8*>(SA(b, h) + lds_byte(wr * 64 + m * 16 + fr, k * 32 + fq * 8))
; #define LDB(dst, b, h) _Pragma("unroll") for (int n = 0; n < 2; ++n) _Pragma("unroll") for (int k = 0; k < 2; ++k) \
;     dst[n][k] = *reinterpret_cast<const bf16x8*>(SB(b, h) + lds_byte(wc * 32 + n * 16 + fr, k * 32 + fq * 8))
; #define WAIT_V(n) asm volatile("s_waitcnt vmcnt(" #n ")" ::: "memory")
; #define WAIT_L(n) asm volatile("s_waitcnt lgkmcnt(" #n ")" ::: "memory")
; #define BAR __builtin_amdgcn_s_barrier()
; #define SCHED __builtin_amdgcn_sched_barrier(0)
;     ...
;       WAIT_V(6); BAR; MMA(1, 1, At, B1); BAR;
;       LDB(B0, 1, 0); SCHED; LDA(At, 1, 0); STAGE(SA(0, 1), rsA, sA1, offA, t + 2);
;       WAIT_L(8); BAR; WAIT_L(0); MMA(0, 0, At, B0); BAR; SCHED;
;       LDB(B1, 1, 1); STAGE(SB(1, 0), rsB, sB0, offB, t + 3);
;       BAR; WAIT_L(0); MMA(0, 1, At, B1); BAR;
;       LDA(At, 1, 1); STAGE(SA(1, 0), rsA, sA0, offA, t + 3);
;       BAR; WAIT_L(0); MMA(1, 0, At, B0); BAR; SCHED;
	v_mfma_f32_16x16x32_bf16 v[12:15], v[200:203], v[168:171], v[12:15]
	v_mfma_f32_16x16x32_bf16 v[12:15], v[204:207], v[172:175], v[12:15]
	v_mfma_f32_16x16x32_bf16 v[8:11], v[212:215], v[172:175], v[8:11]
	v_mfma_f32_16x16x32_bf16 v[8:11], v[208:211], v[168:171], v[8:11]
	v_mfma_f32_16x16x32_bf16 v[0:3], v[208:211], v[176:179], v[0:3]
	v_mfma_f32_16x16x32_bf16 v[0:3], v[212:215], v[180:183], v[0:3]
	v_mfma_f32_16x16x32_bf16 v[4:7], v[204:207], v[180:183], v[4:7]
	v_mfma_f32_16x16x32_bf16 v[4:7], v[200:203], v[176:179], v[4:7]
	v_mfma_f32_16x16x32_bf16 v[64:67], v[200:203], v[184:187], v[64:67]
	v_mfma_f32_16x16x32_bf16 v[64:67], v[204:207], v[188:191], v[64:67]
	v_mfma_f32_16x16x32_bf16 v[72:75], v[212:215], v[188:191], v[72:75]
	v_mfma_f32_16x16x32_bf16 v[72:75], v[208:211], v[184:187], v[72:75]
	v_mfma_f32_16x16x32_bf16 v[84:87], v[208:211], v[192:195], v[84:87]
	v_mfma_f32_16x16x32_bf16 v[84:87], v[212:215], v[196:199], v[84:87]
	v_mfma_f32_16x16x32_bf16 v[76:79], v[204:207], v[196:199], v[76:79]
	v_mfma_f32_16x16x32_bf16 v[76:79], v[200:203], v[192:195], v[76:79]
	s_barrier
	ds_read_b128 v[152:155], v137
	ds_read_b128 v[156:159], v138
	ds_read_b128 v[160:163], v139
	ds_read_b128 v[164:167], v140
	s_addk_i32 s5, 0x100
	s_mov_b32 m0, s39
	ds_read_b128 v[168:171], v129 offset:32768
	ds_read_b128 v[172:175], v129 offset:33792
	ds_read_b128 v[176:179], v132 offset:32768
	ds_read_b128 v[180:183], v132 offset:33792
	ds_read_b128 v[184:187], v131 offset:32768
	ds_read_b128 v[188:191], v131 offset:33792
	ds_read_b128 v[192:195], v130 offset:32768
	ds_read_b128 v[196:199], v130 offset:33792
	buffer_load_dwordx4 v141, s[8:11], s5 offen lds
	s_mov_b32 m0, s97
	s_nop 0
	buffer_load_dwordx4 v142, s[8:11], s5 offen lds
	s_waitcnt lgkmcnt(8)
	s_barrier
	s_waitcnt lgkmcnt(0)
	v_mfma_f32_16x16x32_bf16 v[124:127], v[152:155], v[168:171], v[124:127]
	v_mfma_f32_16x16x32_bf16 v[124:127], v[156:159], v[172:175], v[124:127]
	v_mfma_f32_16x16x32_bf16 v[120:123], v[164:167], v[172:175], v[120:123]
	v_mfma_f32_16x16x32_bf16 v[120:123], v[160:163], v[168:171], v[120:123]
	v_mfma_f32_16x16x32_bf16 v[112:115], v[160:163], v[176:179], v[112:115]
	v_mfma_f32_16x16x32_bf16 v[112:115], v[164:167], v[180:183], v[112:115]
	v_mfma_f32_16x16x32_bf16 v[116:119], v[156:159], v[180:183], v[116:119]
	v_mfma_f32_16x16x32_bf16 v[116:119], v[152:155], v[176:179], v[116:119]
	v_mfma_f32_16x16x32_bf16 v[108:111], v[152:155], v[184:187], v[108:111]
	v_mfma_f32_16x16x32_bf16 v[108:111], v[156:159], v[188:191], v[108:111]
	v_mfma_f32_16x16x32_bf16 v[104:107], v[164:167], v[188:191], v[104:107]
	v_mfma_f32_16x16x32_bf16 v[104:107], v[160:163], v[184:187], v[104:107]
	v_mfma_f32_16x16x32_bf16 v[96:99], v[160:163], v[192:195], v[96:99]
	v_mfma_f32_16x16x32_bf16 v[96:99], v[164:167], v[196:199], v[96:99]
	v_mfma_f32_16x16x32_bf16 v[100:103], v[156:159], v[196:199], v[100:103]
	v_mfma_f32_16x16x32_bf16 v[100:103], v[152:155], v[192:195], v[100:103]
	s_barrier
	s_addk_i32 s6, 0x180
	s_mov_b32 m0, s92
	ds_read_b128 v[200:203], v133
	ds_read_b128 v[204:207], v134
	ds_read_b128 v[208:211], v135
	ds_read_b128 v[212:215], v136
	buffer_load_dwordx4 v141, s[12:15], s6 offen lds
	s_mov_b32 m0, s56
	s_nop 0
	buffer_load_dwordx4 v142, s[12:15], s6 offen lds
	s_barrier
	s_waitcnt lgkmcnt(0)
	v_mfma_f32_16x16x32_bf16 v[92:95], v[200:203], v[168:171], v[92:95]
	v_mfma_f32_16x16x32_bf16 v[92:95], v[204:207], v[172:175], v[92:95]
	v_mfma_f32_16x16x32_bf16 v[88:91], v[212:215], v[172:175], v[88:91]
	v_mfma_f32_16x16x32_bf16 v[88:91], v[208:211], v[168:171], v[88:91]
	v_mfma_f32_16x16x32_bf16 v[68:71], v[208:211], v[176:179], v[68:71]
	v_mfma_f32_16x16x32_bf16 v[68:71], v[212:215], v[180:183], v[68:71]
	v_mfma_f32_16x16x32_bf16 v[80:83], v[204:207], v[180:183], v[80:83]
	v_mfma_f32_16x16x32_bf16 v[80:83], v[200:203], v[176:179], v[80:83]
	v_mfma_f32_16x16x32_bf16 v[60:63], v[200:203], v[184:187], v[60:63]
	v_mfma_f32_16x16x32_bf16 v[60:63], v[204:207], v[188:191], v[60:63]
	v_mfma_f32_16x16x32_bf16 v[56:59], v[212:215], v[188:191], v[56:59]
	v_mfma_f32_16x16x32_bf16 v[56:59], v[208:211], v[184:187], v[56:59]
	v_mfma_f32_16x16x32_bf16 v[48:51], v[208:211], v[192:195], v[48:51]
	v_mfma_f32_16x16x32_bf16 v[48:51], v[212:215], v[196:199], v[48:51]
	v_mfma_f32_16x16x32_bf16 v[52:55], v[204:207], v[196:199], v[52:55]
	v_mfma_f32_16x16x32_bf16 v[52:55], v[200:203], v[192:195], v[52:55]
	s_barrier
	s_addk_i32 s7, 0x180
	s_mov_b32 m0, s93
	ds_read_b128 v[168:171], v129 offset:49152
	ds_read_b128 v[172:175], v129 offset:50176
	ds_read_b128 v[176:179], v132 offset:49152
	ds_read_b128 v[180:183], v132 offset:50176
	ds_read_b128 v[184:187], v131 offset:49152
	ds_read_b128 v[188:191], v131 offset:50176
	ds_read_b128 v[192:195], v130 offset:49152
	ds_read_b128 v[196:199], v130 offset:50176
	buffer_load_dwordx4 v141, s[8:11], s7 offen lds
	s_mov_b32 m0, s57
	s_nop 0
	buffer_load_dwordx4 v142, s[8:11], s7 offen lds
	s_barrier
	s_waitcnt lgkmcnt(0)
	v_mfma_f32_16x16x32_bf16 v[44:47], v[152:155], v[168:171], v[44:47]
	v_mfma_f32_16x16x32_bf16 v[44:47], v[156:159], v[172:175], v[44:47]
	v_mfma_f32_16x16x32_bf16 v[40:43], v[164:167], v[172:175], v[40:43]
	v_mfma_f32_16x16x32_bf16 v[40:43], v[160:163], v[168:171], v[40:43]
	v_mfma_f32_16x16x32_bf16 v[32:35], v[160:163], v[176:179], v[32:35]
	v_mfma_f32_16x16x32_bf16 v[32:35], v[164:167], v[180:183], v[32:35]
	v_mfma_f32_16x16x32_bf16 v[36:39], v[156:159], v[180:183], v[36:39]
	v_mfma_f32_16x16x32_bf16 v[36:39], v[152:155], v[176:179], v[36:39]
	v_mfma_f32_16x16x32_bf16 v[28:31], v[152:155], v[184:187], v[28:31]
	v_mfma_f32_16x16x32_bf16 v[28:31], v[156:159], v[188:191], v[28:31]
	v_mfma_f32_16x16x32_bf16 v[24:27], v[164:167], v[188:191], v[24:27]
	v_mfma_f32_16x16x32_bf16 v[24:27], v[160:163], v[184:187], v[24:27]
	v_mfma_f32_16x16x32_bf16 v[16:19], v[160:163], v[192:195], v[16:19]
	v_mfma_f32_16x16x32_bf16 v[16:19], v[164:167], v[196:199], v[16:19]
	v_mfma_f32_16x16x32_bf16 v[20:23], v[156:159], v[196:199], v[20:23]
	v_mfma_f32_16x16x32_bf16 v[20:23], v[152:155], v[192:195], v[20:23]
	s_barrier
; #define STAGE(P, RS, SOFF, OFF, kt) do { const int _so = (SOFF) + (kt) * (BK * 2); \
;     _Pragma("unroll") for (int _i = 0; _i < 2; ++_i) { \
;       __builtin_amdgcn_raw_ptr_buffer_load_lds(RS, (__attribute__((address_space(3))) void*)((P) + wave * 1024 + _i * 8192), 16, OFF[_i], _so, 0, 0); } } while (0)
; #define LDA(dst, b, h) _Pragma("unroll") for (int m = 0; m < 4; ++m) _Pragma("unroll") for (int k = 0; k < 2; ++k) \
;     dst[m][k] = *reinterpret_cast<const bf16x8*>(SA(b, h) + lds_byte(wr * 64 + m * 16 + fr, k * 32 + fq * 8))
; #define LDB(dst, b, h) _Pragma("unroll") for (int n = 0; n < 2; ++n) _Pragma("unroll") for (int k = 0; k < 2; ++k) \
;     dst[n][k] = *reinterpret_cast<const bf16x8*>(SB(b, h) + lds_byte(wc * 32 + n * 16 + fr, k * 32 + fq * 8))
; #define WAIT_V(n) asm volatile("s_waitcnt vmcnt(" #n ")" ::: "memory")
; #define WAIT_L(n) asm volatile("s_waitcnt lgkmcnt(" #n ")" ::: "memory")
; #define BAR __builtin_amdgcn_s_barrier()
;     ...
;       STAGE(SB(1, 1), rsB, sB1, offB, t + 3);
;       WAIT_V(6); BAR; MMA(1, 1, At, B1); BAR;
;     }
;     { LDB(B0, 0, 0); LDA(At, 0, 0); STAGE(SA(1, 1), rsA, sA1, offA, nt - 1);
;       BAR; WAIT_L(0); MMA(0, 0, At, B0); BAR;
;       LDB(B1, 0, 1); BAR; WAIT_L(0); MMA(0, 1, At, B1); BAR;
;       LDA(At, 0, 1); WAIT_V(4); BAR; WAIT_L(0); MMA(1, 0, At, B0); MMA(1, 1, At, B1); BAR; }
	s_addk_i32 s22, 0x180
	s_mov_b32 m0, s94
	s_nop 0
	buffer_load_dwordx4 v141, s[12:15], s22 offen lds
	s_mov_b32 m0, s58
	s_nop 0
	buffer_load_dwordx4 v142, s[12:15], s22 offen lds
	s_add_i32 s1, s1, 2
	s_addk_i32 s3, 0x100
	s_cmp_gt_u32 s1, 59
	s_cbranch_scc0 .LBB0_494
	s_waitcnt vmcnt(6)
	s_barrier
	v_mfma_f32_16x16x32_bf16 v[12:15], v[200:203], v[168:171], v[12:15]
	v_mfma_f32_16x16x32_bf16 v[12:15], v[204:207], v[172:175], v[12:15]
	v_mfma_f32_16x16x32_bf16 v[8:11], v[212:215], v[172:175], v[8:11]
	v_mfma_f32_16x16x32_bf16 v[8:11], v[208:211], v[168:171], v[8:11]
	v_mfma_f32_16x16x32_bf16 v[0:3], v[208:211], v[176:179], v[0:3]
	v_mfma_f32_16x16x32_bf16 v[0:3], v[212:215], v[180:183], v[0:3]
	v_mfma_f32_16x16x32_bf16 v[4:7], v[204:207], v[180:183], v[4:7]
	v_mfma_f32_16x16x32_bf16 v[4:7], v[200:203], v[176:179], v[4:7]
	v_mfma_f32_16x16x32_bf16 v[64:67], v[200:203], v[184:187], v[64:67]
	v_mfma_f32_16x16x32_bf16 v[64:67], v[204:207], v[188:191], v[64:67]
	v_mfma_f32_16x16x32_bf16 v[72:75], v[212:215], v[188:191], v[72:75]
	v_mfma_f32_16x16x32_bf16 v[72:75], v[208:211], v[184:187], v[72:75]
	v_mfma_f32_16x16x32_bf16 v[84:87], v[208:211], v[192:195], v[84:87]
	v_mfma_f32_16x16x32_bf16 v[84:87], v[212:215], v[196:199], v[84:87]
	v_mfma_f32_16x16x32_bf16 v[76:79], v[204:207], v[196:199], v[76:79]
	v_mfma_f32_16x16x32_bf16 v[76:79], v[200:203], v[192:195], v[76:79]
	s_barrier
	s_add_i32 s1, s82, 0x1f80
	s_mov_b32 m0, s36
	ds_read_b128 v[152:155], v147
	ds_read_b128 v[156:159], v148
	ds_read_b128 v[160:163], v149
	ds_read_b128 v[148:151], v150
	ds_read_b128 v[164:167], v129
	ds_read_b128 v[168:171], v129 offset:1024
	ds_read_b128 v[172:175], v132
	ds_read_b128 v[176:179], v132 offset:1024
	ds_read_b128 v[180:183], v131
	ds_read_b128 v[184:187], v131 offset:1024
	ds_read_b128 v[188:191], v130
	ds_read_b128 v[192:195], v130 offset:1024
	buffer_load_dwordx4 v141, s[8:11], s1 offen lds
	s_mov_b32 m0, s59
	s_nop 0
	buffer_load_dwordx4 v142, s[8:11], s1 offen lds
	s_barrier
	s_waitcnt lgkmcnt(0)
	v_mfma_f32_16x16x32_bf16 v[124:127], v[152:155], v[164:167], v[124:127]
	v_mfma_f32_16x16x32_bf16 v[124:127], v[156:159], v[168:171], v[124:127]
	v_mfma_f32_16x16x32_bf16 v[120:123], v[148:151], v[168:171], v[120:123]
	v_mfma_f32_16x16x32_bf16 v[120:123], v[160:163], v[164:167], v[120:123]
	v_mfma_f32_16x16x32_bf16 v[112:115], v[160:163], v[172:175], v[112:115]
	v_mfma_f32_16x16x32_bf16 v[112:115], v[148:151], v[176:179], v[112:115]
	v_mfma_f32_16x16x32_bf16 v[116:119], v[156:159], v[176:179], v[116:119]
	v_mfma_f32_16x16x32_bf16 v[116:119], v[152:155], v[172:175], v[116:119]
	v_mfma_f32_16x16x32_bf16 v[108:111], v[152:155], v[180:183], v[108:111]
	v_mfma_f32_16x16x32_bf16 v[108:111], v[156:159], v[184:187], v[108:111]
	v_mfma_f32_16x16x32_bf16 v[104:107], v[148:151], v[184:187], v[104:107]
	v_mfma_f32_16x16x32_bf16 v[104:107], v[160:163], v[180:183], v[104:107]
	v_mfma_f32_16x16x32_bf16 v[96:99], v[160:163], v[188:191], v[96:99]
	v_mfma_f32_16x16x32_bf16 v[96:99], v[148:151], v[192:195], v[96:99]
	v_mfma_f32_16x16x32_bf16 v[100:103], v[156:159], v[192:195], v[100:103]
	v_mfma_f32_16x16x32_bf16 v[100:103], v[152:155], v[188:191], v[100:103]
	s_barrier
	ds_read_b128 v[196:199], v143
	ds_read_b128 v[200:203], v144
	ds_read_b128 v[142:145], v145
	ds_read_b128 v[204:207], v146
	s_barrier
	s_waitcnt lgkmcnt(0)
	v_mfma_f32_16x16x32_bf16 v[80:83], v[196:199], v[172:175], v[80:83]
	v_mfma_f32_16x16x32_bf16 v[68:71], v[142:145], v[172:175], v[68:71]
	v_mfma_f32_16x16x32_bf16 v[60:63], v[196:199], v[180:183], v[60:63]
	v_mfma_f32_16x16x32_bf16 v[56:59], v[142:145], v[180:183], v[56:59]
	v_mfma_f32_16x16x32_bf16 v[52:55], v[196:199], v[188:191], v[52:55]
	v_mfma_f32_16x16x32_bf16 v[48:51], v[142:145], v[188:191], v[48:51]
	v_mfma_f32_16x16x32_bf16 v[92:95], v[196:199], v[164:167], v[92:95]
	v_mfma_f32_16x16x32_bf16 v[88:91], v[142:145], v[164:167], v[88:91]
	v_mfma_f32_16x16x32_bf16 v[80:83], v[200:203], v[176:179], v[80:83]
	v_mfma_f32_16x16x32_bf16 v[68:71], v[204:207], v[176:179], v[68:71]
	v_mfma_f32_16x16x32_bf16 v[60:63], v[200:203], v[184:187], v[60:63]
	v_mfma_f32_16x16x32_bf16 v[56:59], v[204:207], v[184:187], v[56:59]
	v_mfma_f32_16x16x32_bf16 v[52:55], v[200:203], v[192:195], v[52:55]
	v_mfma_f32_16x16x32_bf16 v[48:51], v[204:207], v[192:195], v[48:51]
	v_mfma_f32_16x16x32_bf16 v[164:167], v[200:203], v[168:171], v[92:95]
	v_mfma_f32_16x16x32_bf16 v[168:171], v[204:207], v[168:171], v[88:91]
	s_barrier
	s_nop 0
	ds_read_b128 v[88:91], v129 offset:16384
	ds_read_b128 v[92:95], v129 offset:17408
	ds_read_b128 v[172:175], v132 offset:16384
	ds_read_b128 v[176:179], v132 offset:17408
	ds_read_b128 v[180:183], v131 offset:16384
	ds_read_b128 v[184:187], v131 offset:17408
	ds_read_b128 v[188:191], v130 offset:16384
	ds_read_b128 v[192:195], v130 offset:17408
	s_waitcnt vmcnt(4)
	s_barrier
; #define LDA(dst, b, h) _Pragma("unroll") for (int m = 0; m < 4; ++m) _Pragma("unroll") for (int k = 0; k < 2; ++k) \
;     dst[m][k] = *reinterpret_cast<const bf16x8*>(SA(b, h) + lds_byte(wr * 64 + m * 16 + fr, k * 32 + fq * 8))
; #define LDB(dst, b, h) _Pragma("unroll") for (int n = 0; n < 2; ++n) _Pragma("unroll") for (int k = 0; k < 2; ++k) \
;     dst[n][k] = *reinterpret_cast<const bf16x8*>(SB(b, h) + lds_byte(wc * 32 + n * 16 + fr, k * 32 + fq * 8))
; #define WAIT_V(n) asm volatile("s_waitcnt vmcnt(" #n ")" ::: "memory")
; #define WAIT_L(n) asm volatile("s_waitcnt lgkmcnt(" #n ")" ::: "memory")
; #define BAR __builtin_amdgcn_s_barrier()
;     ...
;       LDA(At, 0, 1); WAIT_V(4); BAR; WAIT_L(0); MMA(1, 0, At, B0); MMA(1, 1, At, B1); BAR; }
;     { LDB(B0, 1, 0); LDA(At, 1, 0); WAIT_V(2); BAR; WAIT_L(0); MMA(0, 0, At, B0); BAR;
	s_waitcnt lgkmcnt(0)
	v_mfma_f32_16x16x32_bf16 v[44:47], v[152:155], v[88:91], v[44:47]
	v_mfma_f32_16x16x32_bf16 v[40:43], v[160:163], v[88:91], v[40:43]
	v_mfma_f32_16x16x32_bf16 v[36:39], v[152:155], v[172:175], v[36:39]
	v_mfma_f32_16x16x32_bf16 v[32:35], v[160:163], v[172:175], v[32:35]
	v_mfma_f32_16x16x32_bf16 v[28:31], v[152:155], v[180:183], v[28:31]
	v_mfma_f32_16x16x32_bf16 v[24:27], v[160:163], v[180:183], v[24:27]
	v_mfma_f32_16x16x32_bf16 v[20:23], v[152:155], v[188:191], v[20:23]
	v_mfma_f32_16x16x32_bf16 v[16:19], v[160:163], v[188:191], v[16:19]
	v_mfma_f32_16x16x32_bf16 v[44:47], v[156:159], v[92:95], v[44:47]
	v_mfma_f32_16x16x32_bf16 v[40:43], v[148:151], v[92:95], v[40:43]
	v_mfma_f32_16x16x32_bf16 v[36:39], v[156:159], v[176:179], v[36:39]
	v_mfma_f32_16x16x32_bf16 v[32:35], v[148:151], v[176:179], v[32:35]
	v_mfma_f32_16x16x32_bf16 v[28:31], v[156:159], v[184:187], v[28:31]
	v_mfma_f32_16x16x32_bf16 v[24:27], v[148:151], v[184:187], v[24:27]
	v_mfma_f32_16x16x32_bf16 v[20:23], v[156:159], v[192:195], v[20:23]
	v_mfma_f32_16x16x32_bf16 v[16:19], v[148:151], v[192:195], v[16:19]
	v_mfma_f32_16x16x32_bf16 v[4:7], v[196:199], v[172:175], v[4:7]
	v_mfma_f32_16x16x32_bf16 v[0:3], v[142:145], v[172:175], v[0:3]
	v_mfma_f32_16x16x32_bf16 v[12:15], v[196:199], v[88:91], v[12:15]
	v_mfma_f32_16x16x32_bf16 v[8:11], v[142:145], v[88:91], v[8:11]
	v_mfma_f32_16x16x32_bf16 v[64:67], v[196:199], v[180:183], v[64:67]
	v_mfma_f32_16x16x32_bf16 v[72:75], v[142:145], v[180:183], v[72:75]
	v_mfma_f32_16x16x32_bf16 v[76:79], v[196:199], v[188:191], v[76:79]
	v_mfma_f32_16x16x32_bf16 v[84:87], v[142:145], v[188:191], v[84:87]
	v_mfma_f32_16x16x32_bf16 v[4:7], v[200:203], v[176:179], v[4:7]
	v_mfma_f32_16x16x32_bf16 v[0:3], v[204:207], v[176:179], v[0:3]
	v_mfma_f32_16x16x32_bf16 v[142:145], v[200:203], v[92:95], v[12:15]
	v_mfma_f32_16x16x32_bf16 v[146:149], v[204:207], v[92:95], v[8:11]
	v_mfma_f32_16x16x32_bf16 v[150:153], v[200:203], v[184:187], v[64:67]
	v_mfma_f32_16x16x32_bf16 v[154:157], v[204:207], v[184:187], v[72:75]
	v_mfma_f32_16x16x32_bf16 v[158:161], v[200:203], v[192:195], v[76:79]
	v_mfma_f32_16x16x32_bf16 v[172:175], v[204:207], v[192:195], v[84:87]
	s_barrier
	ds_read_b128 v[8:11], v137
	ds_read_b128 v[12:15], v138
	ds_read_b128 v[176:179], v139
	ds_read_b128 v[138:141], v140
	ds_read_b128 v[64:67], v129 offset:32768
	ds_read_b128 v[84:87], v129 offset:33792
	ds_read_b128 v[180:183], v132 offset:32768
	ds_read_b128 v[184:187], v132 offset:33792
	ds_read_b128 v[188:191], v131 offset:32768
	ds_read_b128 v[192:195], v131 offset:33792
	ds_read_b128 v[196:199], v130 offset:32768
	ds_read_b128 v[200:203], v130 offset:33792
	s_waitcnt vmcnt(2)
	s_barrier
	s_waitcnt lgkmcnt(0)
	v_mfma_f32_16x16x32_bf16 v[72:75], v[8:11], v[64:67], v[124:127]
	v_mfma_f32_16x16x32_bf16 v[76:79], v[176:179], v[64:67], v[120:123]
	v_mfma_f32_16x16x32_bf16 v[88:91], v[8:11], v[180:183], v[116:119]
	v_mfma_f32_16x16x32_bf16 v[92:95], v[176:179], v[180:183], v[112:115]
	v_mfma_f32_16x16x32_bf16 v[112:115], v[8:11], v[188:191], v[108:111]
	v_mfma_f32_16x16x32_bf16 v[120:123], v[176:179], v[188:191], v[104:107]
	v_mfma_f32_16x16x32_bf16 v[100:103], v[8:11], v[196:199], v[100:103]
	v_mfma_f32_16x16x32_bf16 v[96:99], v[176:179], v[196:199], v[96:99]
	v_mfma_f32_16x16x32_bf16 v[124:127], v[12:15], v[84:87], v[72:75]
	v_mfma_f32_16x16x32_bf16 v[116:119], v[138:141], v[84:87], v[76:79]
	v_mfma_f32_16x16x32_bf16 v[108:111], v[12:15], v[184:187], v[88:91]
	v_mfma_f32_16x16x32_bf16 v[104:107], v[138:141], v[184:187], v[92:95]
	v_mfma_f32_16x16x32_bf16 v[92:95], v[12:15], v[192:195], v[112:115]
	v_mfma_f32_16x16x32_bf16 v[88:91], v[138:141], v[192:195], v[120:123]
	v_mfma_f32_16x16x32_bf16 v[76:79], v[12:15], v[200:203], v[100:103]
	v_mfma_f32_16x16x32_bf16 v[72:75], v[138:141], v[200:203], v[96:99]
	s_barrier
; #define LDA(dst, b, h) _Pragma("unroll") for (int m = 0; m < 4; ++m) _Pragma("unroll") for (int k = 0; k < 2; ++k) \
;     dst[m][k] = *reinterpret_cast<const bf16x8*>(SA(b, h) + lds_byte(wr * 64 + m * 16 + fr, k * 32 + fq * 8))
; #define LDB(dst, b, h) _Pragma("unroll") for (int n = 0; n < 2; ++n) _Pragma("unroll") for (int k = 0; k < 2; ++k) \
;     dst[n][k] = *reinterpret_cast<const bf16x8*>(SB(b, h) + lds_byte(wc * 32 + n * 16 + fr, k * 32 + fq * 8))
; #define WAIT_V(n) asm volatile("s_waitcnt vmcnt(" #n ")" ::: "memory")
; #define WAIT_L(n) asm volatile("s_waitcnt lgkmcnt(" #n ")" ::: "memory")
; #define BAR __builtin_amdgcn_s_barrier()
;     ...
;       LDB(B1, 1, 1); WAIT_V(0); BAR; WAIT_L(0); MMA(0, 1, At, B1); BAR;
;       LDA(At, 1, 1); BAR; WAIT_L(0); MMA(1, 0, At, B0); MMA(1, 1, At, B1); BAR; }
;     if (wr == 0) BAR;
	ds_read_b128 v[204:207], v133
	ds_read_b128 v[208:211], v134
	ds_read_b128 v[212:215], v135
	ds_read_b128 v[134:137], v136
	s_waitcnt vmcnt(0)
	s_barrier
	s_waitcnt lgkmcnt(0)
	v_mfma_f32_16x16x32_bf16 v[96:99], v[204:207], v[64:67], v[164:167]
	v_mfma_f32_16x16x32_bf16 v[64:67], v[212:215], v[64:67], v[168:171]
	v_mfma_f32_16x16x32_bf16 v[80:83], v[204:207], v[180:183], v[80:83]
	v_mfma_f32_16x16x32_bf16 v[68:71], v[212:215], v[180:183], v[68:71]
	v_mfma_f32_16x16x32_bf16 v[60:63], v[204:207], v[188:191], v[60:63]
	v_mfma_f32_16x16x32_bf16 v[56:59], v[212:215], v[188:191], v[56:59]
	v_mfma_f32_16x16x32_bf16 v[52:55], v[204:207], v[196:199], v[52:55]
	v_mfma_f32_16x16x32_bf16 v[48:51], v[212:215], v[196:199], v[48:51]
	v_mfma_f32_16x16x32_bf16 v[120:123], v[208:211], v[84:87], v[96:99]
	v_mfma_f32_16x16x32_bf16 v[112:115], v[134:137], v[84:87], v[64:67]
	v_mfma_f32_16x16x32_bf16 v[100:103], v[208:211], v[184:187], v[80:83]
	v_mfma_f32_16x16x32_bf16 v[96:99], v[134:137], v[184:187], v[68:71]
	v_mfma_f32_16x16x32_bf16 v[84:87], v[208:211], v[192:195], v[60:63]
	v_mfma_f32_16x16x32_bf16 v[80:83], v[134:137], v[192:195], v[56:59]
	v_mfma_f32_16x16x32_bf16 v[68:71], v[208:211], v[200:203], v[52:55]
	v_mfma_f32_16x16x32_bf16 v[64:67], v[134:137], v[200:203], v[48:51]
	s_barrier
	s_nop 0
	ds_read_b128 v[48:51], v129 offset:49152
	ds_read_b128 v[162:165], v129 offset:50176
	ds_read_b128 v[52:55], v132 offset:49152
	ds_read_b128 v[166:169], v132 offset:50176
	ds_read_b128 v[180:183], v131 offset:49152
	ds_read_b128 v[184:187], v131 offset:50176
	ds_read_b128 v[188:191], v130 offset:49152
	ds_read_b128 v[130:133], v130 offset:50176
	s_barrier
	s_waitcnt lgkmcnt(0)
	v_mfma_f32_16x16x32_bf16 v[44:47], v[8:11], v[48:51], v[44:47]
	v_mfma_f32_16x16x32_bf16 v[40:43], v[176:179], v[48:51], v[40:43]
	v_mfma_f32_16x16x32_bf16 v[36:39], v[8:11], v[52:55], v[36:39]
	v_mfma_f32_16x16x32_bf16 v[32:35], v[176:179], v[52:55], v[32:35]
	v_mfma_f32_16x16x32_bf16 v[28:31], v[8:11], v[180:183], v[28:31]
	v_mfma_f32_16x16x32_bf16 v[24:27], v[176:179], v[180:183], v[24:27]
	v_mfma_f32_16x16x32_bf16 v[8:11], v[8:11], v[188:191], v[20:23]
	v_mfma_f32_16x16x32_bf16 v[16:19], v[176:179], v[188:191], v[16:19]
	v_mfma_f32_16x16x32_bf16 v[60:63], v[12:15], v[162:165], v[44:47]
	v_mfma_f32_16x16x32_bf16 v[56:59], v[138:141], v[162:165], v[40:43]
	v_mfma_f32_16x16x32_bf16 v[44:47], v[12:15], v[166:169], v[36:39]
	v_mfma_f32_16x16x32_bf16 v[40:43], v[138:141], v[166:169], v[32:35]
	v_mfma_f32_16x16x32_bf16 v[28:31], v[12:15], v[184:187], v[28:31]
	v_mfma_f32_16x16x32_bf16 v[24:27], v[138:141], v[184:187], v[24:27]
	v_mfma_f32_16x16x32_bf16 v[12:15], v[12:15], v[130:133], v[8:11]
	v_mfma_f32_16x16x32_bf16 v[8:11], v[138:141], v[130:133], v[16:19]
	v_mfma_f32_16x16x32_bf16 v[16:19], v[204:207], v[48:51], v[142:145]
	v_mfma_f32_16x16x32_bf16 v[20:23], v[212:215], v[48:51], v[146:149]
	v_mfma_f32_16x16x32_bf16 v[4:7], v[204:207], v[52:55], v[4:7]
	v_mfma_f32_16x16x32_bf16 v[0:3], v[212:215], v[52:55], v[0:3]
	v_mfma_f32_16x16x32_bf16 v[138:141], v[204:207], v[180:183], v[150:153]
	v_mfma_f32_16x16x32_bf16 v[142:145], v[212:215], v[180:183], v[154:157]
	v_mfma_f32_16x16x32_bf16 v[146:149], v[204:207], v[188:191], v[158:161]
	v_mfma_f32_16x16x32_bf16 v[150:153], v[212:215], v[188:191], v[172:175]
	v_mfma_f32_16x16x32_bf16 v[52:55], v[208:211], v[162:165], v[16:19]
	v_mfma_f32_16x16x32_bf16 v[48:51], v[134:137], v[162:165], v[20:23]
	v_mfma_f32_16x16x32_bf16 v[36:39], v[208:211], v[166:169], v[4:7]
	v_mfma_f32_16x16x32_bf16 v[32:35], v[134:137], v[166:169], v[0:3]
	v_mfma_f32_16x16x32_bf16 v[20:23], v[208:211], v[184:187], v[138:141]
	v_mfma_f32_16x16x32_bf16 v[16:19], v[134:137], v[184:187], v[142:145]
	v_mfma_f32_16x16x32_bf16 v[4:7], v[208:211], v[130:133], v[146:149]
	v_mfma_f32_16x16x32_bf16 v[0:3], v[134:137], v[130:133], v[150:153]
	v_cmp_gt_u32_e32 vcc, s76, v128
	s_barrier
	s_and_saveexec_b64 s[6:7], vcc
	s_cbranch_execz .LBB0_497
	s_barrier

; #define STAGE(P, RS, SOFF, OFF, kt) do { const int _so = (SOFF) + (kt) * (BK * 2); \
;     _Pragma("unroll") for (int _i = 0; _i < 2; ++_i) { \
;       __builtin_amdgcn_raw_ptr_buffer_load_lds(RS, (__attribute__((address_space(3))) void*)((P) + wave * 1024 + _i * 8192), 16, OFF[_i], _so, 0, 0); } } while (0)
; #define LDA(dst, b, h) _Pragma("unroll") for (int m = 0; m < 4; ++m) _Pragma("unroll") for (int k = 0; k < 2; ++k) \
;     dst[m][k] = *reinterpret_cast<const bf16x8*>(SA(b, h) + lds_byte(wr * 64 + m * 16 + fr, k * 32 + fq * 8))
; #define LDB(dst, b, h) _Pragma("unroll") for (int n = 0; n < 2; ++n) _Pragma("unroll") for (int k = 0; k < 2; ++k) \
;     dst[n][k] = *reinterpret_cast<const bf16x8*>(SB(b, h) + lds_byte(wc * 32 + n * 16 + fr, k * 32 + fq * 8))
; #define WAIT_V(n) asm volatile("s_waitcnt vmcnt(" #n ")" ::: "memory")
; #define WAIT_L(n) asm volatile("s_waitcnt lgkmcnt(" #n ")" ::: "memory")
; #define BAR __builtin_amdgcn_s_barrier()
; #define SCHED __builtin_amdgcn_sched_barrier(0)
;     ...
;       LDB(B0, 0, 0); SCHED; LDA(At, 0, 0); STAGE(SA(1, 1), rsA, sA1, offA, t + 1);
;       WAIT_L(8); BAR; WAIT_L(0); MMA(0, 0, At, B0); BAR; SCHED;
;       LDB(B1, 0, 1); STAGE(SB(0, 0), rsB, sB0, offB, t + 2);
;       BAR; WAIT_L(0); MMA(0, 1, At, B1); BAR;
;       LDA(At, 0, 1); STAGE(SA(0, 0), rsA, sA0, offA, t + 2);
;       BAR; WAIT_L(0); MMA(1, 0, At, B0); BAR; SCHED;
;       STAGE(SB(0, 1), rsB, sB1, offB, t + 2);
;       WAIT_V(6); BAR; MMA(1, 1, At, B1); BAR;
.Lmy_rot_556:
	ds_read_b128 v[154:157], v149
	ds_read_b128 v[158:161], v150
	ds_read_b128 v[162:165], v151
	ds_read_b128 v[166:169], v152
	s_add_i32 s43, s37, s17
	s_add_i32 s10, s43, 0x80
	s_mov_b32 m0, s30
	ds_read_b128 v[170:173], v131
	ds_read_b128 v[174:177], v131 offset:1024
	ds_read_b128 v[178:181], v134
	ds_read_b128 v[182:185], v134 offset:1024
	ds_read_b128 v[186:189], v133
	ds_read_b128 v[190:193], v133 offset:1024
	ds_read_b128 v[194:197], v132
	ds_read_b128 v[198:201], v132 offset:1024
	buffer_load_dwordx4 v143, s[4:7], s10 offen lds
	s_mov_b32 m0, s31
	s_nop 0
	buffer_load_dwordx4 v144, s[4:7], s10 offen lds
	s_waitcnt lgkmcnt(8)
	s_barrier
	s_waitcnt lgkmcnt(0)
	v_mfma_f32_16x16x32_bf16 v[124:127], v[154:157], v[170:173], v[124:127]
	v_mfma_f32_16x16x32_bf16 v[124:127], v[158:161], v[174:177], v[124:127]
	v_mfma_f32_16x16x32_bf16 v[120:123], v[166:169], v[174:177], v[120:123]
	v_mfma_f32_16x16x32_bf16 v[120:123], v[162:165], v[170:173], v[120:123]
	v_mfma_f32_16x16x32_bf16 v[112:115], v[162:165], v[178:181], v[112:115]
	v_mfma_f32_16x16x32_bf16 v[112:115], v[166:169], v[182:185], v[112:115]
	v_mfma_f32_16x16x32_bf16 v[116:119], v[158:161], v[182:185], v[116:119]
	v_mfma_f32_16x16x32_bf16 v[116:119], v[154:157], v[178:181], v[116:119]
	v_mfma_f32_16x16x32_bf16 v[108:111], v[154:157], v[186:189], v[108:111]
	v_mfma_f32_16x16x32_bf16 v[108:111], v[158:161], v[190:193], v[108:111]
	v_mfma_f32_16x16x32_bf16 v[104:107], v[166:169], v[190:193], v[104:107]
	v_mfma_f32_16x16x32_bf16 v[104:107], v[162:165], v[186:189], v[104:107]
	v_mfma_f32_16x16x32_bf16 v[96:99], v[162:165], v[194:197], v[96:99]
	v_mfma_f32_16x16x32_bf16 v[96:99], v[166:169], v[198:201], v[96:99]
	v_mfma_f32_16x16x32_bf16 v[100:103], v[158:161], v[198:201], v[100:103]
	v_mfma_f32_16x16x32_bf16 v[100:103], v[154:157], v[194:197], v[100:103]
	s_barrier
	s_add_i32 s44, s39, s17
	s_add_i32 s45, s44, 0x100
	s_mov_b32 s10, s6
	s_mov_b32 s11, s7
	s_mov_b32 m0, s1
	ds_read_b128 v[202:205], v145
	ds_read_b128 v[206:209], v146
	ds_read_b128 v[210:213], v147
	ds_read_b128 v[214:217], v148
	buffer_load_dwordx4 v143, s[8:11], s45 offen lds
	s_mov_b32 m0, s3
	s_nop 0
	buffer_load_dwordx4 v144, s[8:11], s45 offen lds
	s_barrier
	s_waitcnt lgkmcnt(0)
	v_mfma_f32_16x16x32_bf16 v[92:95], v[202:205], v[170:173], v[92:95]
	v_mfma_f32_16x16x32_bf16 v[92:95], v[206:209], v[174:177], v[92:95]
	v_mfma_f32_16x16x32_bf16 v[88:91], v[214:217], v[174:177], v[88:91]
	v_mfma_f32_16x16x32_bf16 v[88:91], v[210:213], v[170:173], v[88:91]
	v_mfma_f32_16x16x32_bf16 v[80:83], v[210:213], v[178:181], v[80:83]
	v_mfma_f32_16x16x32_bf16 v[80:83], v[214:217], v[182:185], v[80:83]
	v_mfma_f32_16x16x32_bf16 v[84:87], v[206:209], v[182:185], v[84:87]
	v_mfma_f32_16x16x32_bf16 v[84:87], v[202:205], v[178:181], v[84:87]
	v_mfma_f32_16x16x32_bf16 v[76:79], v[202:205], v[186:189], v[76:79]
	v_mfma_f32_16x16x32_bf16 v[76:79], v[206:209], v[190:193], v[76:79]
	v_mfma_f32_16x16x32_bf16 v[72:75], v[214:217], v[190:193], v[72:75]
	v_mfma_f32_16x16x32_bf16 v[72:75], v[210:213], v[186:189], v[72:75]
	v_mfma_f32_16x16x32_bf16 v[64:67], v[210:213], v[194:197], v[64:67]
	v_mfma_f32_16x16x32_bf16 v[64:67], v[214:217], v[198:201], v[64:67]
	v_mfma_f32_16x16x32_bf16 v[68:71], v[206:209], v[198:201], v[68:71]
	v_mfma_f32_16x16x32_bf16 v[68:71], v[202:205], v[194:197], v[68:71]
	s_barrier
	s_add_i32 s45, s38, s17
	s_add_i32 s46, s45, 0x100
	s_mov_b32 m0, s0
	ds_read_b128 v[170:173], v131 offset:16384
	ds_read_b128 v[174:177], v131 offset:17408
	ds_read_b128 v[178:181], v134 offset:16384
	ds_read_b128 v[182:185], v134 offset:17408
	ds_read_b128 v[186:189], v133 offset:16384
	ds_read_b128 v[190:193], v133 offset:17408
	ds_read_b128 v[194:197], v132 offset:16384
	ds_read_b128 v[198:201], v132 offset:17408
	buffer_load_dwordx4 v143, s[4:7], s46 offen lds
	s_mov_b32 m0, s18
	s_nop 0
	buffer_load_dwordx4 v144, s[4:7], s46 offen lds
	s_barrier
	s_waitcnt lgkmcnt(0)
	v_mfma_f32_16x16x32_bf16 v[60:63], v[154:157], v[170:173], v[60:63]
	v_mfma_f32_16x16x32_bf16 v[60:63], v[158:161], v[174:177], v[60:63]
	v_mfma_f32_16x16x32_bf16 v[56:59], v[166:169], v[174:177], v[56:59]
	v_mfma_f32_16x16x32_bf16 v[56:59], v[162:165], v[170:173], v[56:59]
	v_mfma_f32_16x16x32_bf16 v[48:51], v[162:165], v[178:181], v[48:51]
	v_mfma_f32_16x16x32_bf16 v[48:51], v[166:169], v[182:185], v[48:51]
	v_mfma_f32_16x16x32_bf16 v[52:55], v[158:161], v[182:185], v[52:55]
	v_mfma_f32_16x16x32_bf16 v[52:55], v[154:157], v[178:181], v[52:55]
	v_mfma_f32_16x16x32_bf16 v[44:47], v[154:157], v[186:189], v[44:47]
	v_mfma_f32_16x16x32_bf16 v[44:47], v[158:161], v[190:193], v[44:47]
	v_mfma_f32_16x16x32_bf16 v[40:43], v[166:169], v[190:193], v[40:43]
	v_mfma_f32_16x16x32_bf16 v[40:43], v[162:165], v[186:189], v[40:43]
	v_mfma_f32_16x16x32_bf16 v[32:35], v[162:165], v[194:197], v[32:35]
	v_mfma_f32_16x16x32_bf16 v[32:35], v[166:169], v[198:201], v[32:35]
	v_mfma_f32_16x16x32_bf16 v[36:39], v[158:161], v[198:201], v[36:39]
	v_mfma_f32_16x16x32_bf16 v[36:39], v[154:157], v[194:197], v[36:39]
	s_barrier
	s_add_i32 s46, s40, s17
	s_add_i32 s47, s46, 0x100
	s_mov_b32 m0, s19
	s_nop 0
	buffer_load_dwordx4 v143, s[8:11], s47 offen lds
	s_mov_b32 m0, s20
	s_nop 0
	buffer_load_dwordx4 v144, s[8:11], s47 offen lds
	s_waitcnt vmcnt(6)
	s_barrier
; #define STAGE(P, RS, SOFF, OFF, kt) do { const int _so = (SOFF) + (kt) * (BK * 2); \
;     _Pragma("unroll") for (int _i = 0; _i < 2; ++_i) { \
;       __builtin_amdgcn_raw_ptr_buffer_load_lds(RS, (__attribute__((address_space(3))) void*)((P) + wave * 1024 + _i * 8192), 16, OFF[_i], _so, 0, 0); } } while (0)
; #define LDA(dst, b, h) _Pragma("unroll") for (int m = 0; m < 4; ++m) _Pragma("unroll") for (int k = 0; k < 2; ++k) \
;     dst[m][k] = *reinterpret_cast<const bf16x8*>(SA(b, h) + lds_byte(wr * 64 + m * 16 + fr, k * 32 + fq * 8))
; #define LDB(dst, b, h) _Pragma("unroll") for (int n = 0; n < 2; ++n) _Pragma("unroll") for (int k = 0; k < 2; ++k) \
;     dst[n][k] = *reinterpret_cast<const bf16x8*>(SB(b, h) + lds_byte(wc * 32 + n * 16 + fr, k * 32 + fq * 8))
; #define WAIT_V(n) asm volatile("s_waitcnt vmcnt(" #n ")" ::: "memory")
; #define WAIT_L(n) asm volatile("s_waitcnt lgkmcnt(" #n ")" ::: "memory")
; #define BAR __builtin_amdgcn_s_barrier()
; #define SCHED __builtin_amdgcn_sched_barrier(0)
;     ...
;       WAIT_V(6); BAR; MMA(1, 1, At, B1); BAR;
;       LDB(B0, 1, 0); SCHED; LDA(At, 1, 0); STAGE(SA(0, 1), rsA, sA1, offA, t + 2);
;       WAIT_L(8); BAR; WAIT_L(0); MMA(0, 0, At, B0); BAR; SCHED;
;       LDB(B1, 1, 1); STAGE(SB(1, 0), rsB, sB0, offB, t + 3);
;       BAR; WAIT_L(0); MMA(0, 1, At, B1); BAR;
;       LDA(At, 1, 1); STAGE(SA(1, 0), rsA, sA0, offA, t + 3);
;       BAR; WAIT_L(0); MMA(1, 0, At, B0); BAR; SCHED;
	v_mfma_f32_16x16x32_bf16 v[28:31], v[202:205], v[170:173], v[28:31]
	v_mfma_f32_16x16x32_bf16 v[28:31], v[206:209], v[174:177], v[28:31]
	v_mfma_f32_16x16x32_bf16 v[24:27], v[214:217], v[174:177], v[24:27]
	v_mfma_f32_16x16x32_bf16 v[24:27], v[210:213], v[170:173], v[24:27]
	v_mfma_f32_16x16x32_bf16 v[16:19], v[210:213], v[178:181], v[16:19]
	v_mfma_f32_16x16x32_bf16 v[16:19], v[214:217], v[182:185], v[16:19]
	v_mfma_f32_16x16x32_bf16 v[20:23], v[206:209], v[182:185], v[20:23]
	v_mfma_f32_16x16x32_bf16 v[20:23], v[202:205], v[178:181], v[20:23]
	v_mfma_f32_16x16x32_bf16 v[12:15], v[202:205], v[186:189], v[12:15]
	v_mfma_f32_16x16x32_bf16 v[12:15], v[206:209], v[190:193], v[12:15]
	v_mfma_f32_16x16x32_bf16 v[8:11], v[214:217], v[190:193], v[8:11]
	v_mfma_f32_16x16x32_bf16 v[8:11], v[210:213], v[186:189], v[8:11]
	v_mfma_f32_16x16x32_bf16 v[0:3], v[210:213], v[194:197], v[0:3]
	v_mfma_f32_16x16x32_bf16 v[0:3], v[214:217], v[198:201], v[0:3]
	v_mfma_f32_16x16x32_bf16 v[4:7], v[206:209], v[198:201], v[4:7]
	v_mfma_f32_16x16x32_bf16 v[4:7], v[202:205], v[194:197], v[4:7]
	s_barrier
	ds_read_b128 v[154:157], v139
	ds_read_b128 v[158:161], v140
	ds_read_b128 v[162:165], v141
	ds_read_b128 v[166:169], v142
	s_addk_i32 s43, 0x100
	s_mov_b32 m0, s21
	ds_read_b128 v[170:173], v131 offset:32768
	ds_read_b128 v[174:177], v131 offset:33792
	ds_read_b128 v[178:181], v134 offset:32768
	ds_read_b128 v[182:185], v134 offset:33792
	ds_read_b128 v[186:189], v133 offset:32768
	ds_read_b128 v[190:193], v133 offset:33792
	ds_read_b128 v[194:197], v132 offset:32768
	ds_read_b128 v[198:201], v132 offset:33792
	buffer_load_dwordx4 v143, s[4:7], s43 offen lds
	s_mov_b32 m0, s22
	s_nop 0
	buffer_load_dwordx4 v144, s[4:7], s43 offen lds
	s_waitcnt lgkmcnt(8)
	s_barrier
	s_waitcnt lgkmcnt(0)
	v_mfma_f32_16x16x32_bf16 v[124:127], v[154:157], v[170:173], v[124:127]
	v_mfma_f32_16x16x32_bf16 v[124:127], v[158:161], v[174:177], v[124:127]
	v_mfma_f32_16x16x32_bf16 v[120:123], v[166:169], v[174:177], v[120:123]
	v_mfma_f32_16x16x32_bf16 v[120:123], v[162:165], v[170:173], v[120:123]
	v_mfma_f32_16x16x32_bf16 v[112:115], v[162:165], v[178:181], v[112:115]
	v_mfma_f32_16x16x32_bf16 v[112:115], v[166:169], v[182:185], v[112:115]
	v_mfma_f32_16x16x32_bf16 v[116:119], v[158:161], v[182:185], v[116:119]
	v_mfma_f32_16x16x32_bf16 v[116:119], v[154:157], v[178:181], v[116:119]
	v_mfma_f32_16x16x32_bf16 v[108:111], v[154:157], v[186:189], v[108:111]
	v_mfma_f32_16x16x32_bf16 v[108:111], v[158:161], v[190:193], v[108:111]
	v_mfma_f32_16x16x32_bf16 v[104:107], v[166:169], v[190:193], v[104:107]
	v_mfma_f32_16x16x32_bf16 v[104:107], v[162:165], v[186:189], v[104:107]
	v_mfma_f32_16x16x32_bf16 v[96:99], v[162:165], v[194:197], v[96:99]
	v_mfma_f32_16x16x32_bf16 v[96:99], v[166:169], v[198:201], v[96:99]
	v_mfma_f32_16x16x32_bf16 v[100:103], v[158:161], v[198:201], v[100:103]
	v_mfma_f32_16x16x32_bf16 v[100:103], v[154:157], v[194:197], v[100:103]
	s_barrier
	s_addk_i32 s44, 0x180
	s_mov_b32 m0, s23
	ds_read_b128 v[202:205], v135
	ds_read_b128 v[206:209], v136
	ds_read_b128 v[210:213], v137
	ds_read_b128 v[214:217], v138
	buffer_load_dwordx4 v143, s[8:11], s44 offen lds
	s_mov_b32 m0, s24
	s_nop 0
	buffer_load_dwordx4 v144, s[8:11], s44 offen lds
	s_barrier
	s_waitcnt lgkmcnt(0)
	v_mfma_f32_16x16x32_bf16 v[92:95], v[202:205], v[170:173], v[92:95]
	v_mfma_f32_16x16x32_bf16 v[92:95], v[206:209], v[174:177], v[92:95]
	v_mfma_f32_16x16x32_bf16 v[88:91], v[214:217], v[174:177], v[88:91]
	v_mfma_f32_16x16x32_bf16 v[88:91], v[210:213], v[170:173], v[88:91]
	v_mfma_f32_16x16x32_bf16 v[80:83], v[210:213], v[178:181], v[80:83]
	v_mfma_f32_16x16x32_bf16 v[80:83], v[214:217], v[182:185], v[80:83]
	v_mfma_f32_16x16x32_bf16 v[84:87], v[206:209], v[182:185], v[84:87]
	v_mfma_f32_16x16x32_bf16 v[84:87], v[202:205], v[178:181], v[84:87]
	v_mfma_f32_16x16x32_bf16 v[76:79], v[202:205], v[186:189], v[76:79]
	v_mfma_f32_16x16x32_bf16 v[76:79], v[206:209], v[190:193], v[76:79]
	v_mfma_f32_16x16x32_bf16 v[72:75], v[214:217], v[190:193], v[72:75]
	v_mfma_f32_16x16x32_bf16 v[72:75], v[210:213], v[186:189], v[72:75]
	v_mfma_f32_16x16x32_bf16 v[64:67], v[210:213], v[194:197], v[64:67]
	v_mfma_f32_16x16x32_bf16 v[64:67], v[214:217], v[198:201], v[64:67]
	v_mfma_f32_16x16x32_bf16 v[68:71], v[206:209], v[198:201], v[68:71]
	v_mfma_f32_16x16x32_bf16 v[68:71], v[202:205], v[194:197], v[68:71]
	s_barrier
	s_addk_i32 s45, 0x180
	s_mov_b32 m0, s25
	ds_read_b128 v[170:173], v131 offset:49152
	ds_read_b128 v[174:177], v131 offset:50176
	ds_read_b128 v[178:181], v134 offset:49152
	ds_read_b128 v[182:185], v134 offset:50176
	ds_read_b128 v[186:189], v133 offset:49152
	ds_read_b128 v[190:193], v133 offset:50176
	ds_read_b128 v[194:197], v132 offset:49152
	ds_read_b128 v[198:201], v132 offset:50176
	buffer_load_dwordx4 v143, s[4:7], s45 offen lds
	s_mov_b32 m0, s26
	s_nop 0
	buffer_load_dwordx4 v144, s[4:7], s45 offen lds
	s_barrier
	s_waitcnt lgkmcnt(0)
	v_mfma_f32_16x16x32_bf16 v[60:63], v[154:157], v[170:173], v[60:63]
	v_mfma_f32_16x16x32_bf16 v[60:63], v[158:161], v[174:177], v[60:63]
	v_mfma_f32_16x16x32_bf16 v[56:59], v[166:169], v[174:177], v[56:59]
	v_mfma_f32_16x16x32_bf16 v[56:59], v[162:165], v[170:173], v[56:59]
	v_mfma_f32_16x16x32_bf16 v[48:51], v[162:165], v[178:181], v[48:51]
	v_mfma_f32_16x16x32_bf16 v[48:51], v[166:169], v[182:185], v[48:51]
	v_mfma_f32_16x16x32_bf16 v[52:55], v[158:161], v[182:185], v[52:55]
	v_mfma_f32_16x16x32_bf16 v[52:55], v[154:157], v[178:181], v[52:55]
	v_mfma_f32_16x16x32_bf16 v[44:47], v[154:157], v[186:189], v[44:47]
	v_mfma_f32_16x16x32_bf16 v[44:47], v[158:161], v[190:193], v[44:47]
	v_mfma_f32_16x16x32_bf16 v[40:43], v[166:169], v[190:193], v[40:43]
	v_mfma_f32_16x16x32_bf16 v[40:43], v[162:165], v[186:189], v[40:43]
	v_mfma_f32_16x16x32_bf16 v[32:35], v[162:165], v[194:197], v[32:35]
	v_mfma_f32_16x16x32_bf16 v[32:35], v[166:169], v[198:201], v[32:35]
	v_mfma_f32_16x16x32_bf16 v[36:39], v[158:161], v[198:201], v[36:39]
	v_mfma_f32_16x16x32_bf16 v[36:39], v[154:157], v[194:197], v[36:39]
	s_barrier
; #define STAGE(P, RS, SOFF, OFF, kt) do { const int _so = (SOFF) + (kt) * (BK * 2); \
;     _Pragma("unroll") for (int _i = 0; _i < 2; ++_i) { \
;       __builtin_amdgcn_raw_ptr_buffer_load_lds(RS, (__attribute__((address_space(3))) void*)((P) + wave * 1024 + _i * 8192), 16, OFF[_i], _so, 0, 0); } } while (0)
; #define LDA(dst, b, h) _Pragma("unroll") for (int m = 0; m < 4; ++m) _Pragma("unroll") for (int k = 0; k < 2; ++k) \
;     dst[m][k] = *reinterpret_cast<const bf16x8*>(SA(b, h) + lds_byte(wr * 64 + m * 16 + fr, k * 32 + fq * 8))
; #define LDB(dst, b, h) _Pragma("unroll") for (int n = 0; n < 2; ++n) _Pragma("unroll") for (int k = 0; k < 2; ++k) \
;     dst[n][k] = *reinterpret_cast<const bf16x8*>(SB(b, h) + lds_byte(wc * 32 + n * 16 + fr, k * 32 + fq * 8))
; #define WAIT_V(n) asm volatile("s_waitcnt vmcnt(" #n ")" ::: "memory")
; #define WAIT_L(n) asm volatile("s_waitcnt lgkmcnt(" #n ")" ::: "memory")
; #define BAR __builtin_amdgcn_s_barrier()
;     ...
;       STAGE(SB(1, 1), rsB, sB1, offB, t + 3);
;       WAIT_V(6); BAR; MMA(1, 1, At, B1); BAR;
;     }
;     { LDB(B0, 0, 0); LDA(At, 0, 0); STAGE(SA(1, 1), rsA, sA1, offA, nt - 1);
;       BAR; WAIT_L(0); MMA(0, 0, At, B0); BAR;
;       LDB(B1, 0, 1); BAR; WAIT_L(0); MMA(0, 1, At, B1); BAR;
;       LDA(At, 0, 1); WAIT_V(4); BAR; WAIT_L(0); MMA(1, 0, At, B0); MMA(1, 1, At, B1); BAR; }
	s_addk_i32 s46, 0x180
	s_mov_b32 m0, s27
	s_nop 0
	buffer_load_dwordx4 v143, s[8:11], s46 offen lds
	s_mov_b32 m0, s28
	s_nop 0
	buffer_load_dwordx4 v144, s[8:11], s46 offen lds
	s_add_i32 s16, s16, 2
	s_addk_i32 s17, 0x100
	s_cmp_gt_u32 s16, 27
	s_cbranch_scc0 .LBB0_556
	s_waitcnt vmcnt(6)
	s_barrier
	v_mfma_f32_16x16x32_bf16 v[28:31], v[202:205], v[170:173], v[28:31]
	v_mfma_f32_16x16x32_bf16 v[28:31], v[206:209], v[174:177], v[28:31]
	v_mfma_f32_16x16x32_bf16 v[24:27], v[214:217], v[174:177], v[24:27]
	v_mfma_f32_16x16x32_bf16 v[24:27], v[210:213], v[170:173], v[24:27]
	v_mfma_f32_16x16x32_bf16 v[16:19], v[210:213], v[178:181], v[16:19]
	v_mfma_f32_16x16x32_bf16 v[16:19], v[214:217], v[182:185], v[16:19]
	v_mfma_f32_16x16x32_bf16 v[20:23], v[206:209], v[182:185], v[20:23]
	v_mfma_f32_16x16x32_bf16 v[20:23], v[202:205], v[178:181], v[20:23]
	v_mfma_f32_16x16x32_bf16 v[12:15], v[202:205], v[186:189], v[12:15]
	v_mfma_f32_16x16x32_bf16 v[12:15], v[206:209], v[190:193], v[12:15]
	v_mfma_f32_16x16x32_bf16 v[8:11], v[214:217], v[190:193], v[8:11]
	v_mfma_f32_16x16x32_bf16 v[8:11], v[210:213], v[186:189], v[8:11]
	v_mfma_f32_16x16x32_bf16 v[0:3], v[210:213], v[194:197], v[0:3]
	v_mfma_f32_16x16x32_bf16 v[0:3], v[214:217], v[198:201], v[0:3]
	v_mfma_f32_16x16x32_bf16 v[4:7], v[206:209], v[198:201], v[4:7]
	v_mfma_f32_16x16x32_bf16 v[4:7], v[202:205], v[194:197], v[4:7]
	s_barrier
	s_add_i32 s10, s37, 0xf80
	s_mov_b32 m0, s30
	ds_read_b128 v[154:157], v149
	ds_read_b128 v[158:161], v150
	ds_read_b128 v[162:165], v151
	ds_read_b128 v[150:153], v152
	ds_read_b128 v[166:169], v131
	ds_read_b128 v[170:173], v131 offset:1024
	ds_read_b128 v[174:177], v134
	ds_read_b128 v[178:181], v134 offset:1024
	ds_read_b128 v[182:185], v133
	ds_read_b128 v[186:189], v133 offset:1024
	ds_read_b128 v[190:193], v132
	ds_read_b128 v[194:197], v132 offset:1024
	buffer_load_dwordx4 v143, s[4:7], s10 offen lds
	s_mov_b32 m0, s31
	s_nop 0
	buffer_load_dwordx4 v144, s[4:7], s10 offen lds
	s_barrier
	s_waitcnt lgkmcnt(0)
	v_mfma_f32_16x16x32_bf16 v[124:127], v[154:157], v[166:169], v[124:127]
	v_mfma_f32_16x16x32_bf16 v[124:127], v[158:161], v[170:173], v[124:127]
	v_mfma_f32_16x16x32_bf16 v[120:123], v[150:153], v[170:173], v[120:123]
	v_mfma_f32_16x16x32_bf16 v[120:123], v[162:165], v[166:169], v[120:123]
	v_mfma_f32_16x16x32_bf16 v[112:115], v[162:165], v[174:177], v[112:115]
	v_mfma_f32_16x16x32_bf16 v[112:115], v[150:153], v[178:181], v[112:115]
	v_mfma_f32_16x16x32_bf16 v[116:119], v[158:161], v[178:181], v[116:119]
	v_mfma_f32_16x16x32_bf16 v[116:119], v[154:157], v[174:177], v[116:119]
	v_mfma_f32_16x16x32_bf16 v[108:111], v[154:157], v[182:185], v[108:111]
	v_mfma_f32_16x16x32_bf16 v[108:111], v[158:161], v[186:189], v[108:111]
	v_mfma_f32_16x16x32_bf16 v[104:107], v[150:153], v[186:189], v[104:107]
	v_mfma_f32_16x16x32_bf16 v[104:107], v[162:165], v[182:185], v[104:107]
	v_mfma_f32_16x16x32_bf16 v[96:99], v[162:165], v[190:193], v[96:99]
	v_mfma_f32_16x16x32_bf16 v[96:99], v[150:153], v[194:197], v[96:99]
	v_mfma_f32_16x16x32_bf16 v[100:103], v[158:161], v[194:197], v[100:103]
	v_mfma_f32_16x16x32_bf16 v[100:103], v[154:157], v[190:193], v[100:103]
	s_barrier
	ds_read_b128 v[198:201], v145
	ds_read_b128 v[202:205], v146
	ds_read_b128 v[144:147], v147
	ds_read_b128 v[206:209], v148
	s_barrier
	s_waitcnt lgkmcnt(0)
	v_mfma_f32_16x16x32_bf16 v[92:95], v[198:201], v[166:169], v[92:95]
	v_mfma_f32_16x16x32_bf16 v[92:95], v[202:205], v[170:173], v[92:95]
	v_mfma_f32_16x16x32_bf16 v[88:91], v[206:209], v[170:173], v[88:91]
	v_mfma_f32_16x16x32_bf16 v[88:91], v[144:147], v[166:169], v[88:91]
	v_mfma_f32_16x16x32_bf16 v[80:83], v[144:147], v[174:177], v[80:83]
	v_mfma_f32_16x16x32_bf16 v[80:83], v[206:209], v[178:181], v[80:83]
	v_mfma_f32_16x16x32_bf16 v[84:87], v[202:205], v[178:181], v[84:87]
	v_mfma_f32_16x16x32_bf16 v[84:87], v[198:201], v[174:177], v[84:87]
	v_mfma_f32_16x16x32_bf16 v[76:79], v[198:201], v[182:185], v[76:79]
	v_mfma_f32_16x16x32_bf16 v[76:79], v[202:205], v[186:189], v[76:79]
	v_mfma_f32_16x16x32_bf16 v[72:75], v[206:209], v[186:189], v[72:75]
	v_mfma_f32_16x16x32_bf16 v[72:75], v[144:147], v[182:185], v[72:75]
	v_mfma_f32_16x16x32_bf16 v[64:67], v[144:147], v[190:193], v[64:67]
	v_mfma_f32_16x16x32_bf16 v[64:67], v[206:209], v[194:197], v[64:67]
	v_mfma_f32_16x16x32_bf16 v[68:71], v[202:205], v[194:197], v[68:71]
	v_mfma_f32_16x16x32_bf16 v[68:71], v[198:201], v[190:193], v[68:71]
	s_barrier
	ds_read_b128 v[166:169], v131 offset:16384
	ds_read_b128 v[170:173], v131 offset:17408
	ds_read_b128 v[174:177], v134 offset:16384
	ds_read_b128 v[178:181], v134 offset:17408
	ds_read_b128 v[182:185], v133 offset:16384
	ds_read_b128 v[186:189], v133 offset:17408
	ds_read_b128 v[190:193], v132 offset:16384
	ds_read_b128 v[194:197], v132 offset:17408
	s_waitcnt vmcnt(4)
	s_barrier
; #define LDA(dst, b, h) _Pragma("unroll") for (int m = 0; m < 4; ++m) _Pragma("unroll") for (int k = 0; k < 2; ++k) \
;     dst[m][k] = *reinterpret_cast<const bf16x8*>(SA(b, h) + lds_byte(wr * 64 + m * 16 + fr, k * 32 + fq * 8))
; #define LDB(dst, b, h) _Pragma("unroll") for (int n = 0; n < 2; ++n) _Pragma("unroll") for (int k = 0; k < 2; ++k) \
;     dst[n][k] = *reinterpret_cast<const bf16x8*>(SB(b, h) + lds_byte(wc * 32 + n * 16 + fr, k * 32 + fq * 8))
; #define WAIT_V(n) asm volatile("s_waitcnt vmcnt(" #n ")" ::: "memory")
; #define WAIT_L(n) asm volatile("s_waitcnt lgkmcnt(" #n ")" ::: "memory")
; #define BAR __builtin_amdgcn_s_barrier()
;     ...
;       LDA(At, 0, 1); WAIT_V(4); BAR; WAIT_L(0); MMA(1, 0, At, B0); MMA(1, 1, At, B1); BAR; }
;     { LDB(B0, 1, 0); LDA(At, 1, 0); WAIT_V(2); BAR; WAIT_L(0); MMA(0, 0, At, B0); BAR;
	s_waitcnt lgkmcnt(0)
	v_mfma_f32_16x16x32_bf16 v[60:63], v[154:157], v[166:169], v[60:63]
	v_mfma_f32_16x16x32_bf16 v[60:63], v[158:161], v[170:173], v[60:63]
	v_mfma_f32_16x16x32_bf16 v[56:59], v[150:153], v[170:173], v[56:59]
	v_mfma_f32_16x16x32_bf16 v[56:59], v[162:165], v[166:169], v[56:59]
	v_mfma_f32_16x16x32_bf16 v[48:51], v[162:165], v[174:177], v[48:51]
	v_mfma_f32_16x16x32_bf16 v[48:51], v[150:153], v[178:181], v[48:51]
	v_mfma_f32_16x16x32_bf16 v[52:55], v[158:161], v[178:181], v[52:55]
	v_mfma_f32_16x16x32_bf16 v[52:55], v[154:157], v[174:177], v[52:55]
	v_mfma_f32_16x16x32_bf16 v[44:47], v[154:157], v[182:185], v[44:47]
	v_mfma_f32_16x16x32_bf16 v[44:47], v[158:161], v[186:189], v[44:47]
	v_mfma_f32_16x16x32_bf16 v[40:43], v[150:153], v[186:189], v[40:43]
	v_mfma_f32_16x16x32_bf16 v[40:43], v[162:165], v[182:185], v[40:43]
	v_mfma_f32_16x16x32_bf16 v[32:35], v[162:165], v[190:193], v[32:35]
	v_mfma_f32_16x16x32_bf16 v[32:35], v[150:153], v[194:197], v[32:35]
	v_mfma_f32_16x16x32_bf16 v[36:39], v[158:161], v[194:197], v[36:39]
	v_mfma_f32_16x16x32_bf16 v[36:39], v[154:157], v[190:193], v[36:39]
	v_mfma_f32_16x16x32_bf16 v[4:7], v[198:201], v[190:193], v[4:7]
	v_mfma_f32_16x16x32_bf16 v[4:7], v[202:205], v[194:197], v[4:7]
	v_mfma_f32_16x16x32_bf16 v[28:31], v[202:205], v[170:173], v[28:31]
	v_mfma_f32_16x16x32_bf16 v[28:31], v[198:201], v[166:169], v[28:31]
	v_mfma_f32_16x16x32_bf16 v[24:27], v[144:147], v[166:169], v[24:27]
	v_mfma_f32_16x16x32_bf16 v[24:27], v[206:209], v[170:173], v[24:27]
	v_mfma_f32_16x16x32_bf16 v[16:19], v[206:209], v[178:181], v[16:19]
	v_mfma_f32_16x16x32_bf16 v[16:19], v[144:147], v[174:177], v[16:19]
	v_mfma_f32_16x16x32_bf16 v[20:23], v[198:201], v[174:177], v[20:23]
	v_mfma_f32_16x16x32_bf16 v[20:23], v[202:205], v[178:181], v[20:23]
	v_mfma_f32_16x16x32_bf16 v[12:15], v[202:205], v[186:189], v[12:15]
	v_mfma_f32_16x16x32_bf16 v[12:15], v[198:201], v[182:185], v[12:15]
	v_mfma_f32_16x16x32_bf16 v[8:11], v[144:147], v[182:185], v[8:11]
	v_mfma_f32_16x16x32_bf16 v[8:11], v[206:209], v[186:189], v[8:11]
	v_mfma_f32_16x16x32_bf16 v[0:3], v[206:209], v[194:197], v[0:3]
	v_mfma_f32_16x16x32_bf16 v[0:3], v[144:147], v[190:193], v[0:3]
	s_barrier
	ds_read_b128 v[144:147], v139
	ds_read_b128 v[148:151], v140
	ds_read_b128 v[152:155], v141
	ds_read_b128 v[140:143], v142
	ds_read_b128 v[156:159], v131 offset:32768
	ds_read_b128 v[160:163], v131 offset:33792
	ds_read_b128 v[164:167], v134 offset:32768
	ds_read_b128 v[168:171], v134 offset:33792
	ds_read_b128 v[172:175], v133 offset:32768
	ds_read_b128 v[176:179], v133 offset:33792
	ds_read_b128 v[180:183], v132 offset:32768
	ds_read_b128 v[184:187], v132 offset:33792
	s_waitcnt vmcnt(2)
	s_barrier
	s_waitcnt lgkmcnt(0)
	v_mfma_f32_16x16x32_bf16 v[124:127], v[144:147], v[156:159], v[124:127]
	v_mfma_f32_16x16x32_bf16 v[124:127], v[148:151], v[160:163], v[124:127]
	v_mfma_f32_16x16x32_bf16 v[120:123], v[140:143], v[160:163], v[120:123]
	v_mfma_f32_16x16x32_bf16 v[120:123], v[152:155], v[156:159], v[120:123]
	v_mfma_f32_16x16x32_bf16 v[112:115], v[152:155], v[164:167], v[112:115]
	v_mfma_f32_16x16x32_bf16 v[112:115], v[140:143], v[168:171], v[112:115]
	v_mfma_f32_16x16x32_bf16 v[116:119], v[148:151], v[168:171], v[116:119]
	v_mfma_f32_16x16x32_bf16 v[116:119], v[144:147], v[164:167], v[116:119]
	v_mfma_f32_16x16x32_bf16 v[108:111], v[144:147], v[172:175], v[108:111]
	v_mfma_f32_16x16x32_bf16 v[108:111], v[148:151], v[176:179], v[108:111]
	v_mfma_f32_16x16x32_bf16 v[104:107], v[140:143], v[176:179], v[104:107]
	v_mfma_f32_16x16x32_bf16 v[104:107], v[152:155], v[172:175], v[104:107]
	v_mfma_f32_16x16x32_bf16 v[96:99], v[152:155], v[180:183], v[96:99]
	v_mfma_f32_16x16x32_bf16 v[96:99], v[140:143], v[184:187], v[96:99]
	v_mfma_f32_16x16x32_bf16 v[100:103], v[148:151], v[184:187], v[100:103]
	v_mfma_f32_16x16x32_bf16 v[100:103], v[144:147], v[180:183], v[100:103]
	s_barrier
; #define LDA(dst, b, h) _Pragma("unroll") for (int m = 0; m < 4; ++m) _Pragma("unroll") for (int k = 0; k < 2; ++k) \
;     dst[m][k] = *reinterpret_cast<const bf16x8*>(SA(b, h) + lds_byte(wr * 64 + m * 16 + fr, k * 32 + fq * 8))
; #define LDB(dst, b, h) _Pragma("unroll") for (int n = 0; n < 2; ++n) _Pragma("unroll") for (int k = 0; k < 2; ++k) \
;     dst[n][k] = *reinterpret_cast<const bf16x8*>(SB(b, h) + lds_byte(wc * 32 + n * 16 + fr, k * 32 + fq * 8))
; #define WAIT_V(n) asm volatile("s_waitcnt vmcnt(" #n ")" ::: "memory")
; #define WAIT_L(n) asm volatile("s_waitcnt lgkmcnt(" #n ")" ::: "memory")
; #define BAR __builtin_amdgcn_s_barrier()
;     ...
;       LDB(B1, 1, 1); WAIT_V(0); BAR; WAIT_L(0); MMA(0, 1, At, B1); BAR;
;       LDA(At, 1, 1); BAR; WAIT_L(0); MMA(1, 0, At, B0); MMA(1, 1, At, B1); BAR; }
;     if (wr == 0) BAR;
	ds_read_b128 v[188:191], v135
	ds_read_b128 v[192:195], v136
	ds_read_b128 v[196:199], v137
	ds_read_b128 v[136:139], v138
	s_waitcnt vmcnt(0)
	s_barrier
	s_waitcnt lgkmcnt(0)
	v_mfma_f32_16x16x32_bf16 v[92:95], v[188:191], v[156:159], v[92:95]
	v_mfma_f32_16x16x32_bf16 v[92:95], v[192:195], v[160:163], v[92:95]
	v_mfma_f32_16x16x32_bf16 v[88:91], v[136:139], v[160:163], v[88:91]
	v_mfma_f32_16x16x32_bf16 v[88:91], v[196:199], v[156:159], v[88:91]
	v_mfma_f32_16x16x32_bf16 v[80:83], v[196:199], v[164:167], v[80:83]
	v_mfma_f32_16x16x32_bf16 v[80:83], v[136:139], v[168:171], v[80:83]
	v_mfma_f32_16x16x32_bf16 v[84:87], v[192:195], v[168:171], v[84:87]
	v_mfma_f32_16x16x32_bf16 v[84:87], v[188:191], v[164:167], v[84:87]
	v_mfma_f32_16x16x32_bf16 v[76:79], v[188:191], v[172:175], v[76:79]
	v_mfma_f32_16x16x32_bf16 v[76:79], v[192:195], v[176:179], v[76:79]
	v_mfma_f32_16x16x32_bf16 v[72:75], v[136:139], v[176:179], v[72:75]
	v_mfma_f32_16x16x32_bf16 v[72:75], v[196:199], v[172:175], v[72:75]
	v_mfma_f32_16x16x32_bf16 v[64:67], v[196:199], v[180:183], v[64:67]
	v_mfma_f32_16x16x32_bf16 v[64:67], v[136:139], v[184:187], v[64:67]
	v_mfma_f32_16x16x32_bf16 v[68:71], v[192:195], v[184:187], v[68:71]
	v_mfma_f32_16x16x32_bf16 v[68:71], v[188:191], v[180:183], v[68:71]
	s_barrier
	ds_read_b128 v[156:159], v131 offset:49152
	ds_read_b128 v[160:163], v131 offset:50176
	ds_read_b128 v[164:167], v134 offset:49152
	ds_read_b128 v[168:171], v134 offset:50176
	ds_read_b128 v[172:175], v133 offset:49152
	ds_read_b128 v[176:179], v133 offset:50176
	ds_read_b128 v[180:183], v132 offset:49152
	ds_read_b128 v[132:135], v132 offset:50176
	s_barrier
	s_waitcnt lgkmcnt(0)
	v_mfma_f32_16x16x32_bf16 v[60:63], v[144:147], v[156:159], v[60:63]
	v_mfma_f32_16x16x32_bf16 v[60:63], v[148:151], v[160:163], v[60:63]
	v_mfma_f32_16x16x32_bf16 v[56:59], v[140:143], v[160:163], v[56:59]
	v_mfma_f32_16x16x32_bf16 v[56:59], v[152:155], v[156:159], v[56:59]
	v_mfma_f32_16x16x32_bf16 v[48:51], v[152:155], v[164:167], v[48:51]
	v_mfma_f32_16x16x32_bf16 v[48:51], v[140:143], v[168:171], v[48:51]
	v_mfma_f32_16x16x32_bf16 v[52:55], v[148:151], v[168:171], v[52:55]
	v_mfma_f32_16x16x32_bf16 v[52:55], v[144:147], v[164:167], v[52:55]
	v_mfma_f32_16x16x32_bf16 v[44:47], v[144:147], v[172:175], v[44:47]
	v_mfma_f32_16x16x32_bf16 v[44:47], v[148:151], v[176:179], v[44:47]
	v_mfma_f32_16x16x32_bf16 v[40:43], v[140:143], v[176:179], v[40:43]
	v_mfma_f32_16x16x32_bf16 v[40:43], v[152:155], v[172:175], v[40:43]
	v_mfma_f32_16x16x32_bf16 v[32:35], v[152:155], v[180:183], v[32:35]
	v_mfma_f32_16x16x32_bf16 v[32:35], v[140:143], v[132:135], v[32:35]
	v_mfma_f32_16x16x32_bf16 v[36:39], v[148:151], v[132:135], v[36:39]
	v_mfma_f32_16x16x32_bf16 v[36:39], v[144:147], v[180:183], v[36:39]
	v_mfma_f32_16x16x32_bf16 v[4:7], v[188:191], v[180:183], v[4:7]
	v_mfma_f32_16x16x32_bf16 v[4:7], v[192:195], v[132:135], v[4:7]
	v_mfma_f32_16x16x32_bf16 v[28:31], v[192:195], v[160:163], v[28:31]
	v_mfma_f32_16x16x32_bf16 v[28:31], v[188:191], v[156:159], v[28:31]
	v_mfma_f32_16x16x32_bf16 v[24:27], v[196:199], v[156:159], v[24:27]
	v_mfma_f32_16x16x32_bf16 v[24:27], v[136:139], v[160:163], v[24:27]
	v_mfma_f32_16x16x32_bf16 v[16:19], v[136:139], v[168:171], v[16:19]
	v_mfma_f32_16x16x32_bf16 v[16:19], v[196:199], v[164:167], v[16:19]
	v_mfma_f32_16x16x32_bf16 v[20:23], v[188:191], v[164:167], v[20:23]
	v_mfma_f32_16x16x32_bf16 v[20:23], v[192:195], v[168:171], v[20:23]
	v_mfma_f32_16x16x32_bf16 v[12:15], v[192:195], v[176:179], v[12:15]
	v_mfma_f32_16x16x32_bf16 v[12:15], v[188:191], v[172:175], v[12:15]
	v_mfma_f32_16x16x32_bf16 v[8:11], v[196:199], v[172:175], v[8:11]
	v_mfma_f32_16x16x32_bf16 v[8:11], v[136:139], v[176:179], v[8:11]
	v_mfma_f32_16x16x32_bf16 v[0:3], v[136:139], v[132:135], v[0:3]
	v_mfma_f32_16x16x32_bf16 v[0:3], v[196:199], v[180:183], v[0:3]
	v_cmp_gt_u32_e32 vcc, s35, v130
	s_barrier
	s_and_saveexec_b64 s[10:11], vcc
	s_cbranch_execz .LBB0_559
	s_barrier

; #define STAGE(P, RS, SOFF, OFF, kt) do { const int _so = (SOFF) + (kt) * (BK * 2); \
;     _Pragma("unroll") for (int _i = 0; _i < 2; ++_i) { \
;       __builtin_amdgcn_raw_ptr_buffer_load_lds(RS, (__attribute__((address_space(3))) void*)((P) + wave * 1024 + _i * 8192), 16, OFF[_i], _so, 0, 0); } } while (0)
; #define LDA(dst, b, h) _Pragma("unroll") for (int m = 0; m < 4; ++m) _Pragma("unroll") for (int k = 0; k < 2; ++k) \
;     dst[m][k] = *reinterpret_cast<const bf16x8*>(SA(b, h) + lds_byte(wr * 64 + m * 16 + fr, k * 32 + fq * 8))
; #define LDB(dst, b, h) _Pragma("unroll") for (int n = 0; n < 2; ++n) _Pragma("unroll") for (int k = 0; k < 2; ++k) \
;     dst[n][k] = *reinterpret_cast<const bf16x8*>(SB(b, h) + lds_byte(wc * 32 + n * 16 + fr, k * 32 + fq * 8))
; #define WAIT_V(n) asm volatile("s_waitcnt vmcnt(" #n ")" ::: "memory")
; #define WAIT_L(n) asm volatile("s_waitcnt lgkmcnt(" #n ")" ::: "memory")
; #define BAR __builtin_amdgcn_s_barrier()
; #define SCHED __builtin_amdgcn_sched_barrier(0)
;     ...
;       LDB(B0, 0, 0); SCHED; LDA(At, 0, 0); STAGE(SA(1, 1), rsA, sA1, offA, t + 1);
;       WAIT_L(8); BAR; WAIT_L(0); MMA(0, 0, At, B0); BAR; SCHED;
;       LDB(B1, 0, 1); STAGE(SB(0, 0), rsB, sB0, offB, t + 2);
;       BAR; WAIT_L(0); MMA(0, 1, At, B1); BAR;
;       LDA(At, 0, 1); STAGE(SA(0, 0), rsA, sA0, offA, t + 2);
;       BAR; WAIT_L(0); MMA(1, 0, At, B0); BAR; SCHED;
;       STAGE(SB(0, 1), rsB, sB1, offB, t + 2);
;       WAIT_V(6); BAR; MMA(1, 1, At, B1); BAR;
.Lmy_rot_657:
	ds_read_b128 v[152:155], v147
	ds_read_b128 v[156:159], v148
	ds_read_b128 v[160:163], v149
	ds_read_b128 v[164:167], v150
	s_add_i32 s5, s81, s3
	s_add_i32 s6, s5, 0x80
	s_mov_b32 m0, s39
	ds_read_b128 v[168:171], v129
	ds_read_b128 v[172:175], v129 offset:1024
	ds_read_b128 v[176:179], v132
	ds_read_b128 v[180:183], v132 offset:1024
	ds_read_b128 v[184:187], v131
	ds_read_b128 v[188:191], v131 offset:1024
	ds_read_b128 v[192:195], v130
	ds_read_b128 v[196:199], v130 offset:1024
	buffer_load_dwordx4 v141, s[8:11], s6 offen lds
	s_mov_b32 m0, s58
	s_nop 0
	buffer_load_dwordx4 v142, s[8:11], s6 offen lds
	s_waitcnt lgkmcnt(8)
	s_barrier
	s_waitcnt lgkmcnt(0)
	v_mfma_f32_16x16x32_bf16 v[124:127], v[152:155], v[168:171], v[124:127]
	v_mfma_f32_16x16x32_bf16 v[124:127], v[156:159], v[172:175], v[124:127]
	v_mfma_f32_16x16x32_bf16 v[120:123], v[164:167], v[172:175], v[120:123]
	v_mfma_f32_16x16x32_bf16 v[120:123], v[160:163], v[168:171], v[120:123]
	v_mfma_f32_16x16x32_bf16 v[112:115], v[160:163], v[176:179], v[112:115]
	v_mfma_f32_16x16x32_bf16 v[112:115], v[164:167], v[180:183], v[112:115]
	v_mfma_f32_16x16x32_bf16 v[116:119], v[156:159], v[180:183], v[116:119]
	v_mfma_f32_16x16x32_bf16 v[116:119], v[152:155], v[176:179], v[116:119]
	v_mfma_f32_16x16x32_bf16 v[108:111], v[152:155], v[184:187], v[108:111]
	v_mfma_f32_16x16x32_bf16 v[108:111], v[156:159], v[188:191], v[108:111]
	v_mfma_f32_16x16x32_bf16 v[104:107], v[164:167], v[188:191], v[104:107]
	v_mfma_f32_16x16x32_bf16 v[104:107], v[160:163], v[184:187], v[104:107]
	v_mfma_f32_16x16x32_bf16 v[96:99], v[160:163], v[192:195], v[96:99]
	v_mfma_f32_16x16x32_bf16 v[96:99], v[164:167], v[196:199], v[96:99]
	v_mfma_f32_16x16x32_bf16 v[100:103], v[156:159], v[196:199], v[100:103]
	v_mfma_f32_16x16x32_bf16 v[100:103], v[152:155], v[192:195], v[100:103]
	s_barrier
	s_add_i32 s6, s83, s3
	s_add_i32 s7, s6, 0x100
	s_mov_b32 s14, s10
	s_mov_b32 s15, s11
	s_mov_b32 m0, s85
	ds_read_b128 v[200:203], v143
	ds_read_b128 v[204:207], v144
	ds_read_b128 v[208:211], v145
	ds_read_b128 v[212:215], v146
	buffer_load_dwordx4 v141, s[12:15], s7 offen lds
	s_mov_b32 m0, s75
	s_nop 0
	buffer_load_dwordx4 v142, s[12:15], s7 offen lds
	s_barrier
	s_waitcnt lgkmcnt(0)
	v_mfma_f32_16x16x32_bf16 v[92:95], v[200:203], v[168:171], v[92:95]
	v_mfma_f32_16x16x32_bf16 v[92:95], v[204:207], v[172:175], v[92:95]
	v_mfma_f32_16x16x32_bf16 v[88:91], v[212:215], v[172:175], v[88:91]
	v_mfma_f32_16x16x32_bf16 v[88:91], v[208:211], v[168:171], v[88:91]
	v_mfma_f32_16x16x32_bf16 v[68:71], v[208:211], v[176:179], v[68:71]
	v_mfma_f32_16x16x32_bf16 v[68:71], v[212:215], v[180:183], v[68:71]
	v_mfma_f32_16x16x32_bf16 v[80:83], v[204:207], v[180:183], v[80:83]
	v_mfma_f32_16x16x32_bf16 v[80:83], v[200:203], v[176:179], v[80:83]
	v_mfma_f32_16x16x32_bf16 v[60:63], v[200:203], v[184:187], v[60:63]
	v_mfma_f32_16x16x32_bf16 v[60:63], v[204:207], v[188:191], v[60:63]
	v_mfma_f32_16x16x32_bf16 v[56:59], v[212:215], v[188:191], v[56:59]
	v_mfma_f32_16x16x32_bf16 v[56:59], v[208:211], v[184:187], v[56:59]
	v_mfma_f32_16x16x32_bf16 v[48:51], v[208:211], v[192:195], v[48:51]
	v_mfma_f32_16x16x32_bf16 v[48:51], v[212:215], v[196:199], v[48:51]
	v_mfma_f32_16x16x32_bf16 v[52:55], v[204:207], v[196:199], v[52:55]
	v_mfma_f32_16x16x32_bf16 v[52:55], v[200:203], v[192:195], v[52:55]
	s_barrier
	s_add_i32 s7, s82, s3
	s_add_i32 s22, s7, 0x100
	s_mov_b32 m0, s38
	ds_read_b128 v[168:171], v129 offset:16384
	ds_read_b128 v[172:175], v129 offset:17408
	ds_read_b128 v[176:179], v132 offset:16384
	ds_read_b128 v[180:183], v132 offset:17408
	ds_read_b128 v[184:187], v131 offset:16384
	ds_read_b128 v[188:191], v131 offset:17408
	ds_read_b128 v[192:195], v130 offset:16384
	ds_read_b128 v[196:199], v130 offset:17408
	buffer_load_dwordx4 v141, s[8:11], s22 offen lds
	s_mov_b32 m0, s95
	s_nop 0
	buffer_load_dwordx4 v142, s[8:11], s22 offen lds
	s_barrier
	s_waitcnt lgkmcnt(0)
	v_mfma_f32_16x16x32_bf16 v[44:47], v[152:155], v[168:171], v[44:47]
	v_mfma_f32_16x16x32_bf16 v[44:47], v[156:159], v[172:175], v[44:47]
	v_mfma_f32_16x16x32_bf16 v[40:43], v[164:167], v[172:175], v[40:43]
	v_mfma_f32_16x16x32_bf16 v[40:43], v[160:163], v[168:171], v[40:43]
	v_mfma_f32_16x16x32_bf16 v[32:35], v[160:163], v[176:179], v[32:35]
	v_mfma_f32_16x16x32_bf16 v[32:35], v[164:167], v[180:183], v[32:35]
	v_mfma_f32_16x16x32_bf16 v[36:39], v[156:159], v[180:183], v[36:39]
	v_mfma_f32_16x16x32_bf16 v[36:39], v[152:155], v[176:179], v[36:39]
	v_mfma_f32_16x16x32_bf16 v[28:31], v[152:155], v[184:187], v[28:31]
	v_mfma_f32_16x16x32_bf16 v[28:31], v[156:159], v[188:191], v[28:31]
	v_mfma_f32_16x16x32_bf16 v[24:27], v[164:167], v[188:191], v[24:27]
	v_mfma_f32_16x16x32_bf16 v[24:27], v[160:163], v[184:187], v[24:27]
	v_mfma_f32_16x16x32_bf16 v[16:19], v[160:163], v[192:195], v[16:19]
	v_mfma_f32_16x16x32_bf16 v[16:19], v[164:167], v[196:199], v[16:19]
	v_mfma_f32_16x16x32_bf16 v[20:23], v[156:159], v[196:199], v[20:23]
	v_mfma_f32_16x16x32_bf16 v[20:23], v[152:155], v[192:195], v[20:23]
	s_barrier
	s_add_i32 s22, s84, s3
	s_add_i32 s23, s22, 0x100
	s_mov_b32 m0, s86
	s_nop 0
	buffer_load_dwordx4 v141, s[12:15], s23 offen lds
	s_mov_b32 m0, s28
	s_nop 0
	buffer_load_dwordx4 v142, s[12:15], s23 offen lds
	s_waitcnt vmcnt(6)
	s_barrier
; #define STAGE(P, RS, SOFF, OFF, kt) do { const int _so = (SOFF) + (kt) * (BK * 2); \
;     _Pragma("unroll") for (int _i = 0; _i < 2; ++_i) { \
;       __builtin_amdgcn_raw_ptr_buffer_load_lds(RS, (__attribute__((address_space(3))) void*)((P) + wave * 1024 + _i * 8192), 16, OFF[_i], _so, 0, 0); } } while (0)
; #define LDA(dst, b, h) _Pragma("unroll") for (int m = 0; m < 4; ++m) _Pragma("unroll") for (int k = 0; k < 2; ++k) \
;     dst[m][k] = *reinterpret_cast<const bf16x8*>(SA(b, h) + lds_byte(wr * 64 + m * 16 + fr, k * 32 + fq * 8))
; #define LDB(dst, b, h) _Pragma("unroll") for (int n = 0; n < 2; ++n) _Pragma("unroll") for (int k = 0; k < 2; ++k) \
;     dst[n][k] = *reinterpret_cast<const bf16x8*>(SB(b, h) + lds_byte(wc * 32 + n * 16 + fr, k * 32 + fq * 8))
; #define WAIT_V(n) asm volatile("s_waitcnt vmcnt(" #n ")" ::: "memory")
; #define WAIT_L(n) asm volatile("s_waitcnt lgkmcnt(" #n ")" ::: "memory")
; #define BAR __builtin_amdgcn_s_barrier()
; #define SCHED __builtin_amdgcn_sched_barrier(0)
;     ...
;       WAIT_V(6); BAR; MMA(1, 1, At, B1); BAR;
;       LDB(B0, 1, 0); SCHED; LDA(At, 1, 0); STAGE(SA(0, 1), rsA, sA1, offA, t + 2);
;       WAIT_L(8); BAR; WAIT_L(0); MMA(0, 0, At, B0); BAR; SCHED;
;       LDB(B1, 1, 1); STAGE(SB(1, 0), rsB, sB0, offB, t + 3);
;       BAR; WAIT_L(0); MMA(0, 1, At, B1); BAR;
;       LDA(At, 1, 1); STAGE(SA(1, 0), rsA, sA0, offA, t + 3);
;       BAR; WAIT_L(0); MMA(1, 0, At, B0); BAR; SCHED;
	v_mfma_f32_16x16x32_bf16 v[12:15], v[200:203], v[168:171], v[12:15]
	v_mfma_f32_16x16x32_bf16 v[12:15], v[204:207], v[172:175], v[12:15]
	v_mfma_f32_16x16x32_bf16 v[8:11], v[212:215], v[172:175], v[8:11]
	v_mfma_f32_16x16x32_bf16 v[8:11], v[208:211], v[168:171], v[8:11]
	v_mfma_f32_16x16x32_bf16 v[0:3], v[208:211], v[176:179], v[0:3]
	v_mfma_f32_16x16x32_bf16 v[0:3], v[212:215], v[180:183], v[0:3]
	v_mfma_f32_16x16x32_bf16 v[4:7], v[204:207], v[180:183], v[4:7]
	v_mfma_f32_16x16x32_bf16 v[4:7], v[200:203], v[176:179], v[4:7]
	v_mfma_f32_16x16x32_bf16 v[64:67], v[200:203], v[184:187], v[64:67]
	v_mfma_f32_16x16x32_bf16 v[64:67], v[204:207], v[188:191], v[64:67]
	v_mfma_f32_16x16x32_bf16 v[72:75], v[212:215], v[188:191], v[72:75]
	v_mfma_f32_16x16x32_bf16 v[72:75], v[208:211], v[184:187], v[72:75]
	v_mfma_f32_16x16x32_bf16 v[84:87], v[208:211], v[192:195], v[84:87]
	v_mfma_f32_16x16x32_bf16 v[84:87], v[212:215], v[196:199], v[84:87]
	v_mfma_f32_16x16x32_bf16 v[76:79], v[204:207], v[196:199], v[76:79]
	v_mfma_f32_16x16x32_bf16 v[76:79], v[200:203], v[192:195], v[76:79]
	s_barrier
	ds_read_b128 v[152:155], v137
	ds_read_b128 v[156:159], v138
	ds_read_b128 v[160:163], v139
	ds_read_b128 v[164:167], v140
	s_addk_i32 s5, 0x100
	s_mov_b32 m0, s87
	ds_read_b128 v[168:171], v129 offset:32768
	ds_read_b128 v[172:175], v129 offset:33792
	ds_read_b128 v[176:179], v132 offset:32768
	ds_read_b128 v[180:183], v132 offset:33792
	ds_read_b128 v[184:187], v131 offset:32768
	ds_read_b128 v[188:191], v131 offset:33792
	ds_read_b128 v[192:195], v130 offset:32768
	ds_read_b128 v[196:199], v130 offset:33792
	buffer_load_dwordx4 v141, s[8:11], s5 offen lds
	s_mov_b32 m0, s97
	s_nop 0
	buffer_load_dwordx4 v142, s[8:11], s5 offen lds
	s_waitcnt lgkmcnt(8)
	s_barrier
	s_waitcnt lgkmcnt(0)
	v_mfma_f32_16x16x32_bf16 v[124:127], v[152:155], v[168:171], v[124:127]
	v_mfma_f32_16x16x32_bf16 v[124:127], v[156:159], v[172:175], v[124:127]
	v_mfma_f32_16x16x32_bf16 v[120:123], v[164:167], v[172:175], v[120:123]
	v_mfma_f32_16x16x32_bf16 v[120:123], v[160:163], v[168:171], v[120:123]
	v_mfma_f32_16x16x32_bf16 v[112:115], v[160:163], v[176:179], v[112:115]
	v_mfma_f32_16x16x32_bf16 v[112:115], v[164:167], v[180:183], v[112:115]
	v_mfma_f32_16x16x32_bf16 v[116:119], v[156:159], v[180:183], v[116:119]
	v_mfma_f32_16x16x32_bf16 v[116:119], v[152:155], v[176:179], v[116:119]
	v_mfma_f32_16x16x32_bf16 v[108:111], v[152:155], v[184:187], v[108:111]
	v_mfma_f32_16x16x32_bf16 v[108:111], v[156:159], v[188:191], v[108:111]
	v_mfma_f32_16x16x32_bf16 v[104:107], v[164:167], v[188:191], v[104:107]
	v_mfma_f32_16x16x32_bf16 v[104:107], v[160:163], v[184:187], v[104:107]
	v_mfma_f32_16x16x32_bf16 v[96:99], v[160:163], v[192:195], v[96:99]
	v_mfma_f32_16x16x32_bf16 v[96:99], v[164:167], v[196:199], v[96:99]
	v_mfma_f32_16x16x32_bf16 v[100:103], v[156:159], v[196:199], v[100:103]
	v_mfma_f32_16x16x32_bf16 v[100:103], v[152:155], v[192:195], v[100:103]
	s_barrier
	s_addk_i32 s6, 0x180
	s_mov_b32 m0, s92
	ds_read_b128 v[200:203], v133
	ds_read_b128 v[204:207], v134
	ds_read_b128 v[208:211], v135
	ds_read_b128 v[212:215], v136
	buffer_load_dwordx4 v141, s[12:15], s6 offen lds
	s_mov_b32 m0, s29
	s_nop 0
	buffer_load_dwordx4 v142, s[12:15], s6 offen lds
	s_barrier
	s_waitcnt lgkmcnt(0)
	v_mfma_f32_16x16x32_bf16 v[92:95], v[200:203], v[168:171], v[92:95]
	v_mfma_f32_16x16x32_bf16 v[92:95], v[204:207], v[172:175], v[92:95]
	v_mfma_f32_16x16x32_bf16 v[88:91], v[212:215], v[172:175], v[88:91]
	v_mfma_f32_16x16x32_bf16 v[88:91], v[208:211], v[168:171], v[88:91]
	v_mfma_f32_16x16x32_bf16 v[68:71], v[208:211], v[176:179], v[68:71]
	v_mfma_f32_16x16x32_bf16 v[68:71], v[212:215], v[180:183], v[68:71]
	v_mfma_f32_16x16x32_bf16 v[80:83], v[204:207], v[180:183], v[80:83]
	v_mfma_f32_16x16x32_bf16 v[80:83], v[200:203], v[176:179], v[80:83]
	v_mfma_f32_16x16x32_bf16 v[60:63], v[200:203], v[184:187], v[60:63]
	v_mfma_f32_16x16x32_bf16 v[60:63], v[204:207], v[188:191], v[60:63]
	v_mfma_f32_16x16x32_bf16 v[56:59], v[212:215], v[188:191], v[56:59]
	v_mfma_f32_16x16x32_bf16 v[56:59], v[208:211], v[184:187], v[56:59]
	v_mfma_f32_16x16x32_bf16 v[48:51], v[208:211], v[192:195], v[48:51]
	v_mfma_f32_16x16x32_bf16 v[48:51], v[212:215], v[196:199], v[48:51]
	v_mfma_f32_16x16x32_bf16 v[52:55], v[204:207], v[196:199], v[52:55]
	v_mfma_f32_16x16x32_bf16 v[52:55], v[200:203], v[192:195], v[52:55]
	s_barrier
	s_addk_i32 s7, 0x180
	s_mov_b32 m0, s93
	ds_read_b128 v[168:171], v129 offset:49152
	ds_read_b128 v[172:175], v129 offset:50176
	ds_read_b128 v[176:179], v132 offset:49152
	ds_read_b128 v[180:183], v132 offset:50176
	ds_read_b128 v[184:187], v131 offset:49152
	ds_read_b128 v[188:191], v131 offset:50176
	ds_read_b128 v[192:195], v130 offset:49152
	ds_read_b128 v[196:199], v130 offset:50176
	buffer_load_dwordx4 v141, s[8:11], s7 offen lds
	s_mov_b32 m0, s56
	s_nop 0
	buffer_load_dwordx4 v142, s[8:11], s7 offen lds
	s_barrier
	s_waitcnt lgkmcnt(0)
	v_mfma_f32_16x16x32_bf16 v[44:47], v[152:155], v[168:171], v[44:47]
	v_mfma_f32_16x16x32_bf16 v[44:47], v[156:159], v[172:175], v[44:47]
	v_mfma_f32_16x16x32_bf16 v[40:43], v[164:167], v[172:175], v[40:43]
	v_mfma_f32_16x16x32_bf16 v[40:43], v[160:163], v[168:171], v[40:43]
	v_mfma_f32_16x16x32_bf16 v[32:35], v[160:163], v[176:179], v[32:35]
	v_mfma_f32_16x16x32_bf16 v[32:35], v[164:167], v[180:183], v[32:35]
	v_mfma_f32_16x16x32_bf16 v[36:39], v[156:159], v[180:183], v[36:39]
	v_mfma_f32_16x16x32_bf16 v[36:39], v[152:155], v[176:179], v[36:39]
	v_mfma_f32_16x16x32_bf16 v[28:31], v[152:155], v[184:187], v[28:31]
	v_mfma_f32_16x16x32_bf16 v[28:31], v[156:159], v[188:191], v[28:31]
	v_mfma_f32_16x16x32_bf16 v[24:27], v[164:167], v[188:191], v[24:27]
	v_mfma_f32_16x16x32_bf16 v[24:27], v[160:163], v[184:187], v[24:27]
	v_mfma_f32_16x16x32_bf16 v[16:19], v[160:163], v[192:195], v[16:19]
	v_mfma_f32_16x16x32_bf16 v[16:19], v[164:167], v[196:199], v[16:19]
	v_mfma_f32_16x16x32_bf16 v[20:23], v[156:159], v[196:199], v[20:23]
	v_mfma_f32_16x16x32_bf16 v[20:23], v[152:155], v[192:195], v[20:23]
	s_barrier
; #define STAGE(P, RS, SOFF, OFF, kt) do { const int _so = (SOFF) + (kt) * (BK * 2); \
;     _Pragma("unroll") for (int _i = 0; _i < 2; ++_i) { \
;       __builtin_amdgcn_raw_ptr_buffer_load_lds(RS, (__attribute__((address_space(3))) void*)((P) + wave * 1024 + _i * 8192), 16, OFF[_i], _so, 0, 0); } } while (0)
; #define LDA(dst, b, h) _Pragma("unroll") for (int m = 0; m < 4; ++m) _Pragma("unroll") for (int k = 0; k < 2; ++k) \
;     dst[m][k] = *reinterpret_cast<const bf16x8*>(SA(b, h) + lds_byte(wr * 64 + m * 16 + fr, k * 32 + fq * 8))
; #define LDB(dst, b, h) _Pragma("unroll") for (int n = 0; n < 2; ++n) _Pragma("unroll") for (int k = 0; k < 2; ++k) \
;     dst[n][k] = *reinterpret_cast<const bf16x8*>(SB(b, h) + lds_byte(wc * 32 + n * 16 + fr, k * 32 + fq * 8))
; #define WAIT_V(n) asm volatile("s_waitcnt vmcnt(" #n ")" ::: "memory")
; #define WAIT_L(n) asm volatile("s_waitcnt lgkmcnt(" #n ")" ::: "memory")
; #define BAR __builtin_amdgcn_s_barrier()
;     ...
;       STAGE(SB(1, 1), rsB, sB1, offB, t + 3);
;       WAIT_V(6); BAR; MMA(1, 1, At, B1); BAR;
;     }
;     { LDB(B0, 0, 0); LDA(At, 0, 0); STAGE(SA(1, 1), rsA, sA1, offA, nt - 1);
;       BAR; WAIT_L(0); MMA(0, 0, At, B0); BAR;
;       LDB(B1, 0, 1); BAR; WAIT_L(0); MMA(0, 1, At, B1); BAR;
;       LDA(At, 0, 1); WAIT_V(4); BAR; WAIT_L(0); MMA(1, 0, At, B0); MMA(1, 1, At, B1); BAR; }
	s_addk_i32 s22, 0x180
	s_mov_b32 m0, s94
	s_nop 0
	buffer_load_dwordx4 v141, s[12:15], s22 offen lds
	s_mov_b32 m0, s57
	s_nop 0
	buffer_load_dwordx4 v142, s[12:15], s22 offen lds
	s_add_i32 s1, s1, 2
	s_addk_i32 s3, 0x100
	s_cmp_gt_u32 s1, 27
	s_cbranch_scc0 .LBB0_657
	s_waitcnt vmcnt(6)
	s_barrier
	v_mfma_f32_16x16x32_bf16 v[12:15], v[200:203], v[168:171], v[12:15]
	v_mfma_f32_16x16x32_bf16 v[12:15], v[204:207], v[172:175], v[12:15]
	v_mfma_f32_16x16x32_bf16 v[8:11], v[212:215], v[172:175], v[8:11]
	v_mfma_f32_16x16x32_bf16 v[8:11], v[208:211], v[168:171], v[8:11]
	v_mfma_f32_16x16x32_bf16 v[0:3], v[208:211], v[176:179], v[0:3]
	v_mfma_f32_16x16x32_bf16 v[0:3], v[212:215], v[180:183], v[0:3]
	v_mfma_f32_16x16x32_bf16 v[4:7], v[204:207], v[180:183], v[4:7]
	v_mfma_f32_16x16x32_bf16 v[4:7], v[200:203], v[176:179], v[4:7]
	v_mfma_f32_16x16x32_bf16 v[64:67], v[200:203], v[184:187], v[64:67]
	v_mfma_f32_16x16x32_bf16 v[64:67], v[204:207], v[188:191], v[64:67]
	v_mfma_f32_16x16x32_bf16 v[72:75], v[212:215], v[188:191], v[72:75]
	v_mfma_f32_16x16x32_bf16 v[72:75], v[208:211], v[184:187], v[72:75]
	v_mfma_f32_16x16x32_bf16 v[84:87], v[208:211], v[192:195], v[84:87]
	v_mfma_f32_16x16x32_bf16 v[84:87], v[212:215], v[196:199], v[84:87]
	v_mfma_f32_16x16x32_bf16 v[76:79], v[204:207], v[196:199], v[76:79]
	v_mfma_f32_16x16x32_bf16 v[76:79], v[200:203], v[192:195], v[76:79]
	s_barrier
	s_add_i32 s1, s81, 0xf80
	s_mov_b32 m0, s39
	ds_read_b128 v[152:155], v147
	ds_read_b128 v[156:159], v148
	ds_read_b128 v[160:163], v149
	ds_read_b128 v[148:151], v150
	ds_read_b128 v[164:167], v129
	ds_read_b128 v[168:171], v129 offset:1024
	ds_read_b128 v[172:175], v132
	ds_read_b128 v[176:179], v132 offset:1024
	ds_read_b128 v[180:183], v131
	ds_read_b128 v[184:187], v131 offset:1024
	ds_read_b128 v[188:191], v130
	ds_read_b128 v[192:195], v130 offset:1024
	buffer_load_dwordx4 v141, s[8:11], s1 offen lds
	s_mov_b32 m0, s58
	s_nop 0
	buffer_load_dwordx4 v142, s[8:11], s1 offen lds
	s_barrier
	s_waitcnt lgkmcnt(0)
	v_mfma_f32_16x16x32_bf16 v[124:127], v[152:155], v[164:167], v[124:127]
	v_mfma_f32_16x16x32_bf16 v[124:127], v[156:159], v[168:171], v[124:127]
	v_mfma_f32_16x16x32_bf16 v[120:123], v[148:151], v[168:171], v[120:123]
	v_mfma_f32_16x16x32_bf16 v[120:123], v[160:163], v[164:167], v[120:123]
	v_mfma_f32_16x16x32_bf16 v[112:115], v[160:163], v[172:175], v[112:115]
	v_mfma_f32_16x16x32_bf16 v[112:115], v[148:151], v[176:179], v[112:115]
	v_mfma_f32_16x16x32_bf16 v[116:119], v[156:159], v[176:179], v[116:119]
	v_mfma_f32_16x16x32_bf16 v[116:119], v[152:155], v[172:175], v[116:119]
	v_mfma_f32_16x16x32_bf16 v[108:111], v[152:155], v[180:183], v[108:111]
	v_mfma_f32_16x16x32_bf16 v[108:111], v[156:159], v[184:187], v[108:111]
	v_mfma_f32_16x16x32_bf16 v[104:107], v[148:151], v[184:187], v[104:107]
	v_mfma_f32_16x16x32_bf16 v[104:107], v[160:163], v[180:183], v[104:107]
	v_mfma_f32_16x16x32_bf16 v[96:99], v[160:163], v[188:191], v[96:99]
	v_mfma_f32_16x16x32_bf16 v[96:99], v[148:151], v[192:195], v[96:99]
	v_mfma_f32_16x16x32_bf16 v[100:103], v[156:159], v[192:195], v[100:103]
	v_mfma_f32_16x16x32_bf16 v[100:103], v[152:155], v[188:191], v[100:103]
	s_barrier
	ds_read_b128 v[196:199], v143
	ds_read_b128 v[200:203], v144
	ds_read_b128 v[142:145], v145
	ds_read_b128 v[204:207], v146
	s_barrier
	s_waitcnt lgkmcnt(0)
	v_mfma_f32_16x16x32_bf16 v[88:91], v[142:145], v[164:167], v[88:91]
	v_mfma_f32_16x16x32_bf16 v[80:83], v[196:199], v[172:175], v[80:83]
	v_mfma_f32_16x16x32_bf16 v[60:63], v[196:199], v[180:183], v[60:63]
	v_mfma_f32_16x16x32_bf16 v[56:59], v[142:145], v[180:183], v[56:59]
	v_mfma_f32_16x16x32_bf16 v[52:55], v[196:199], v[188:191], v[52:55]
	v_mfma_f32_16x16x32_bf16 v[48:51], v[142:145], v[188:191], v[48:51]
	v_mfma_f32_16x16x32_bf16 v[92:95], v[196:199], v[164:167], v[92:95]
	v_mfma_f32_16x16x32_bf16 v[68:71], v[142:145], v[172:175], v[68:71]
	v_mfma_f32_16x16x32_bf16 v[88:91], v[204:207], v[168:171], v[88:91]
	v_mfma_f32_16x16x32_bf16 v[80:83], v[200:203], v[176:179], v[80:83]
	v_mfma_f32_16x16x32_bf16 v[60:63], v[200:203], v[184:187], v[60:63]
	v_mfma_f32_16x16x32_bf16 v[56:59], v[204:207], v[184:187], v[56:59]
	v_mfma_f32_16x16x32_bf16 v[52:55], v[200:203], v[192:195], v[52:55]
	v_mfma_f32_16x16x32_bf16 v[48:51], v[204:207], v[192:195], v[48:51]
	v_mfma_f32_16x16x32_bf16 v[164:167], v[200:203], v[168:171], v[92:95]
	v_mfma_f32_16x16x32_bf16 v[168:171], v[204:207], v[176:179], v[68:71]
	s_barrier
	s_nop 0
	ds_read_b128 v[68:71], v129 offset:16384
	ds_read_b128 v[92:95], v129 offset:17408
	ds_read_b128 v[172:175], v132 offset:16384
	ds_read_b128 v[176:179], v132 offset:17408
	ds_read_b128 v[180:183], v131 offset:16384
	ds_read_b128 v[184:187], v131 offset:17408
	ds_read_b128 v[188:191], v130 offset:16384
	ds_read_b128 v[192:195], v130 offset:17408
	s_waitcnt vmcnt(4)
	s_barrier
; #define LDA(dst, b, h) _Pragma("unroll") for (int m = 0; m < 4; ++m) _Pragma("unroll") for (int k = 0; k < 2; ++k) \
;     dst[m][k] = *reinterpret_cast<const bf16x8*>(SA(b, h) + lds_byte(wr * 64 + m * 16 + fr, k * 32 + fq * 8))
; #define LDB(dst, b, h) _Pragma("unroll") for (int n = 0; n < 2; ++n) _Pragma("unroll") for (int k = 0; k < 2; ++k) \
;     dst[n][k] = *reinterpret_cast<const bf16x8*>(SB(b, h) + lds_byte(wc * 32 + n * 16 + fr, k * 32 + fq * 8))
; #define WAIT_V(n) asm volatile("s_waitcnt vmcnt(" #n ")" ::: "memory")
; #define WAIT_L(n) asm volatile("s_waitcnt lgkmcnt(" #n ")" ::: "memory")
; #define BAR __builtin_amdgcn_s_barrier()
;     ...
;       LDA(At, 0, 1); WAIT_V(4); BAR; WAIT_L(0); MMA(1, 0, At, B0); MMA(1, 1, At, B1); BAR; }
;     { LDB(B0, 1, 0); LDA(At, 1, 0); WAIT_V(2); BAR; WAIT_L(0); MMA(0, 0, At, B0); BAR;
	s_waitcnt lgkmcnt(0)
	v_mfma_f32_16x16x32_bf16 v[44:47], v[152:155], v[68:71], v[44:47]
	v_mfma_f32_16x16x32_bf16 v[40:43], v[160:163], v[68:71], v[40:43]
	v_mfma_f32_16x16x32_bf16 v[36:39], v[152:155], v[172:175], v[36:39]
	v_mfma_f32_16x16x32_bf16 v[32:35], v[160:163], v[172:175], v[32:35]
	v_mfma_f32_16x16x32_bf16 v[28:31], v[152:155], v[180:183], v[28:31]
	v_mfma_f32_16x16x32_bf16 v[24:27], v[160:163], v[180:183], v[24:27]
	v_mfma_f32_16x16x32_bf16 v[20:23], v[152:155], v[188:191], v[20:23]
	v_mfma_f32_16x16x32_bf16 v[16:19], v[160:163], v[188:191], v[16:19]
	v_mfma_f32_16x16x32_bf16 v[44:47], v[156:159], v[92:95], v[44:47]
	v_mfma_f32_16x16x32_bf16 v[40:43], v[148:151], v[92:95], v[40:43]
	v_mfma_f32_16x16x32_bf16 v[36:39], v[156:159], v[176:179], v[36:39]
	v_mfma_f32_16x16x32_bf16 v[32:35], v[148:151], v[176:179], v[32:35]
	v_mfma_f32_16x16x32_bf16 v[28:31], v[156:159], v[184:187], v[28:31]
	v_mfma_f32_16x16x32_bf16 v[24:27], v[148:151], v[184:187], v[24:27]
	v_mfma_f32_16x16x32_bf16 v[20:23], v[156:159], v[192:195], v[20:23]
	v_mfma_f32_16x16x32_bf16 v[16:19], v[148:151], v[192:195], v[16:19]
	v_mfma_f32_16x16x32_bf16 v[4:7], v[196:199], v[172:175], v[4:7]
	v_mfma_f32_16x16x32_bf16 v[0:3], v[142:145], v[172:175], v[0:3]
	v_mfma_f32_16x16x32_bf16 v[12:15], v[196:199], v[68:71], v[12:15]
	v_mfma_f32_16x16x32_bf16 v[8:11], v[142:145], v[68:71], v[8:11]
	v_mfma_f32_16x16x32_bf16 v[64:67], v[196:199], v[180:183], v[64:67]
	v_mfma_f32_16x16x32_bf16 v[68:71], v[142:145], v[180:183], v[72:75]
	v_mfma_f32_16x16x32_bf16 v[72:75], v[196:199], v[188:191], v[76:79]
	v_mfma_f32_16x16x32_bf16 v[76:79], v[142:145], v[188:191], v[84:87]
	v_mfma_f32_16x16x32_bf16 v[4:7], v[200:203], v[176:179], v[4:7]
	v_mfma_f32_16x16x32_bf16 v[0:3], v[204:207], v[176:179], v[0:3]
	v_mfma_f32_16x16x32_bf16 v[142:145], v[200:203], v[92:95], v[12:15]
	v_mfma_f32_16x16x32_bf16 v[146:149], v[204:207], v[92:95], v[8:11]
	v_mfma_f32_16x16x32_bf16 v[150:153], v[200:203], v[184:187], v[64:67]
	v_mfma_f32_16x16x32_bf16 v[154:157], v[204:207], v[184:187], v[68:71]
	v_mfma_f32_16x16x32_bf16 v[158:161], v[200:203], v[192:195], v[72:75]
	v_mfma_f32_16x16x32_bf16 v[172:175], v[204:207], v[192:195], v[76:79]
	s_barrier
	ds_read_b128 v[8:11], v137
	ds_read_b128 v[12:15], v138
	ds_read_b128 v[176:179], v139
	ds_read_b128 v[138:141], v140
	ds_read_b128 v[64:67], v129 offset:32768
	ds_read_b128 v[72:75], v129 offset:33792
	ds_read_b128 v[180:183], v132 offset:32768
	ds_read_b128 v[184:187], v132 offset:33792
	ds_read_b128 v[188:191], v131 offset:32768
	ds_read_b128 v[192:195], v131 offset:33792
	ds_read_b128 v[196:199], v130 offset:32768
	ds_read_b128 v[200:203], v130 offset:33792
	s_waitcnt vmcnt(2)
	s_barrier
	s_waitcnt lgkmcnt(0)
	v_mfma_f32_16x16x32_bf16 v[68:71], v[8:11], v[64:67], v[124:127]
	v_mfma_f32_16x16x32_bf16 v[76:79], v[176:179], v[64:67], v[120:123]
	v_mfma_f32_16x16x32_bf16 v[84:87], v[8:11], v[180:183], v[116:119]
	v_mfma_f32_16x16x32_bf16 v[92:95], v[176:179], v[180:183], v[112:115]
	v_mfma_f32_16x16x32_bf16 v[112:115], v[8:11], v[188:191], v[108:111]
	v_mfma_f32_16x16x32_bf16 v[104:107], v[176:179], v[188:191], v[104:107]
	v_mfma_f32_16x16x32_bf16 v[120:123], v[8:11], v[196:199], v[100:103]
	v_mfma_f32_16x16x32_bf16 v[96:99], v[176:179], v[196:199], v[96:99]
	v_mfma_f32_16x16x32_bf16 v[124:127], v[12:15], v[72:75], v[68:71]
	v_mfma_f32_16x16x32_bf16 v[116:119], v[138:141], v[72:75], v[76:79]
	v_mfma_f32_16x16x32_bf16 v[108:111], v[12:15], v[184:187], v[84:87]
	v_mfma_f32_16x16x32_bf16 v[100:103], v[138:141], v[184:187], v[92:95]
	v_mfma_f32_16x16x32_bf16 v[92:95], v[12:15], v[192:195], v[112:115]
	v_mfma_f32_16x16x32_bf16 v[84:87], v[138:141], v[192:195], v[104:107]
	v_mfma_f32_16x16x32_bf16 v[76:79], v[12:15], v[200:203], v[120:123]
	v_mfma_f32_16x16x32_bf16 v[68:71], v[138:141], v[200:203], v[96:99]
	s_barrier
; #define LDA(dst, b, h) _Pragma("unroll") for (int m = 0; m < 4; ++m) _Pragma("unroll") for (int k = 0; k < 2; ++k) \
;     dst[m][k] = *reinterpret_cast<const bf16x8*>(SA(b, h) + lds_byte(wr * 64 + m * 16 + fr, k * 32 + fq * 8))
; #define LDB(dst, b, h) _Pragma("unroll") for (int n = 0; n < 2; ++n) _Pragma("unroll") for (int k = 0; k < 2; ++k) \
;     dst[n][k] = *reinterpret_cast<const bf16x8*>(SB(b, h) + lds_byte(wc * 32 + n * 16 + fr, k * 32 + fq * 8))
; #define WAIT_V(n) asm volatile("s_waitcnt vmcnt(" #n ")" ::: "memory")
; #define WAIT_L(n) asm volatile("s_waitcnt lgkmcnt(" #n ")" ::: "memory")
; #define BAR __builtin_amdgcn_s_barrier()
;     ...
;       LDB(B1, 1, 1); WAIT_V(0); BAR; WAIT_L(0); MMA(0, 1, At, B1); BAR;
;       LDA(At, 1, 1); BAR; WAIT_L(0); MMA(1, 0, At, B0); MMA(1, 1, At, B1); BAR; }
;     if (wr == 0) BAR;
	ds_read_b128 v[204:207], v133
	ds_read_b128 v[208:211], v134
	ds_read_b128 v[212:215], v135
	ds_read_b128 v[134:137], v136
	s_waitcnt vmcnt(0)
	s_barrier
	s_waitcnt lgkmcnt(0)
	v_mfma_f32_16x16x32_bf16 v[96:99], v[204:207], v[64:67], v[164:167]
	v_mfma_f32_16x16x32_bf16 v[64:67], v[212:215], v[64:67], v[88:91]
	v_mfma_f32_16x16x32_bf16 v[80:83], v[204:207], v[180:183], v[80:83]
	v_mfma_f32_16x16x32_bf16 v[88:91], v[212:215], v[180:183], v[168:171]
	v_mfma_f32_16x16x32_bf16 v[60:63], v[204:207], v[188:191], v[60:63]
	v_mfma_f32_16x16x32_bf16 v[56:59], v[212:215], v[188:191], v[56:59]
	v_mfma_f32_16x16x32_bf16 v[52:55], v[204:207], v[196:199], v[52:55]
	v_mfma_f32_16x16x32_bf16 v[48:51], v[212:215], v[196:199], v[48:51]
	v_mfma_f32_16x16x32_bf16 v[120:123], v[208:211], v[72:75], v[96:99]
	v_mfma_f32_16x16x32_bf16 v[112:115], v[134:137], v[72:75], v[64:67]
	v_mfma_f32_16x16x32_bf16 v[104:107], v[208:211], v[184:187], v[80:83]
	v_mfma_f32_16x16x32_bf16 v[96:99], v[134:137], v[184:187], v[88:91]
	v_mfma_f32_16x16x32_bf16 v[88:91], v[208:211], v[192:195], v[60:63]
	v_mfma_f32_16x16x32_bf16 v[80:83], v[134:137], v[192:195], v[56:59]
	v_mfma_f32_16x16x32_bf16 v[72:75], v[208:211], v[200:203], v[52:55]
	v_mfma_f32_16x16x32_bf16 v[64:67], v[134:137], v[200:203], v[48:51]
	s_barrier
	s_nop 0
	ds_read_b128 v[48:51], v129 offset:49152
	ds_read_b128 v[162:165], v129 offset:50176
	ds_read_b128 v[52:55], v132 offset:49152
	ds_read_b128 v[166:169], v132 offset:50176
	ds_read_b128 v[180:183], v131 offset:49152
	ds_read_b128 v[184:187], v131 offset:50176
	ds_read_b128 v[188:191], v130 offset:49152
	ds_read_b128 v[130:133], v130 offset:50176
	s_barrier
	s_waitcnt lgkmcnt(0)
	v_mfma_f32_16x16x32_bf16 v[44:47], v[8:11], v[48:51], v[44:47]
	v_mfma_f32_16x16x32_bf16 v[40:43], v[176:179], v[48:51], v[40:43]
	v_mfma_f32_16x16x32_bf16 v[36:39], v[8:11], v[52:55], v[36:39]
	v_mfma_f32_16x16x32_bf16 v[32:35], v[176:179], v[52:55], v[32:35]
	v_mfma_f32_16x16x32_bf16 v[28:31], v[8:11], v[180:183], v[28:31]
	v_mfma_f32_16x16x32_bf16 v[24:27], v[176:179], v[180:183], v[24:27]
	v_mfma_f32_16x16x32_bf16 v[8:11], v[8:11], v[188:191], v[20:23]
	v_mfma_f32_16x16x32_bf16 v[16:19], v[176:179], v[188:191], v[16:19]
	v_mfma_f32_16x16x32_bf16 v[60:63], v[12:15], v[162:165], v[44:47]
	v_mfma_f32_16x16x32_bf16 v[56:59], v[138:141], v[162:165], v[40:43]
	v_mfma_f32_16x16x32_bf16 v[44:47], v[12:15], v[166:169], v[36:39]
	v_mfma_f32_16x16x32_bf16 v[40:43], v[138:141], v[166:169], v[32:35]
	v_mfma_f32_16x16x32_bf16 v[28:31], v[12:15], v[184:187], v[28:31]
	v_mfma_f32_16x16x32_bf16 v[24:27], v[138:141], v[184:187], v[24:27]
	v_mfma_f32_16x16x32_bf16 v[12:15], v[12:15], v[130:133], v[8:11]
	v_mfma_f32_16x16x32_bf16 v[8:11], v[138:141], v[130:133], v[16:19]
	v_mfma_f32_16x16x32_bf16 v[16:19], v[204:207], v[48:51], v[142:145]
	v_mfma_f32_16x16x32_bf16 v[20:23], v[212:215], v[48:51], v[146:149]
	v_mfma_f32_16x16x32_bf16 v[4:7], v[204:207], v[52:55], v[4:7]
	v_mfma_f32_16x16x32_bf16 v[0:3], v[212:215], v[52:55], v[0:3]
	v_mfma_f32_16x16x32_bf16 v[138:141], v[204:207], v[180:183], v[150:153]
	v_mfma_f32_16x16x32_bf16 v[142:145], v[212:215], v[180:183], v[154:157]
	v_mfma_f32_16x16x32_bf16 v[146:149], v[204:207], v[188:191], v[158:161]
	v_mfma_f32_16x16x32_bf16 v[150:153], v[212:215], v[188:191], v[172:175]
	v_mfma_f32_16x16x32_bf16 v[52:55], v[208:211], v[162:165], v[16:19]
	v_mfma_f32_16x16x32_bf16 v[48:51], v[134:137], v[162:165], v[20:23]
	v_mfma_f32_16x16x32_bf16 v[36:39], v[208:211], v[166:169], v[4:7]
	v_mfma_f32_16x16x32_bf16 v[32:35], v[134:137], v[166:169], v[0:3]
	v_mfma_f32_16x16x32_bf16 v[20:23], v[208:211], v[184:187], v[138:141]
	v_mfma_f32_16x16x32_bf16 v[16:19], v[134:137], v[184:187], v[142:145]
	v_mfma_f32_16x16x32_bf16 v[4:7], v[208:211], v[130:133], v[146:149]
	v_mfma_f32_16x16x32_bf16 v[0:3], v[134:137], v[130:133], v[150:153]
	v_cmp_gt_u32_e32 vcc, s73, v128
	s_barrier
	s_and_saveexec_b64 s[6:7], vcc
	s_cbranch_execz .LBB0_660
	s_barrier

; #define STAGE(P, RS, SOFF, OFF, kt) do { const int _so = (SOFF) + (kt) * (BK * 2); \
;     _Pragma("unroll") for (int _i = 0; _i < 2; ++_i) { \
;       __builtin_amdgcn_raw_ptr_buffer_load_lds(RS, (__attribute__((address_space(3))) void*)((P) + wave * 1024 + _i * 8192), 16, OFF[_i], _so, 0, 0); } } while (0)
; #define LDA(dst, b, h) _Pragma("unroll") for (int m = 0; m < 4; ++m) _Pragma("unroll") for (int k = 0; k < 2; ++k) \
;     dst[m][k] = *reinterpret_cast<const bf16x8*>(SA(b, h) + lds_byte(wr * 64 + m * 16 + fr, k * 32 + fq * 8))
; #define LDB(dst, b, h) _Pragma("unroll") for (int n = 0; n < 2; ++n) _Pragma("unroll") for (int k = 0; k < 2; ++k) \
;     dst[n][k] = *reinterpret_cast<const bf16x8*>(SB(b, h) + lds_byte(wc * 32 + n * 16 + fr, k * 32 + fq * 8))
; #define WAIT_V(n) asm volatile("s_waitcnt vmcnt(" #n ")" ::: "memory")
; #define WAIT_L(n) asm volatile("s_waitcnt lgkmcnt(" #n ")" ::: "memory")
; #define BAR __builtin_amdgcn_s_barrier()
; #define SCHED __builtin_amdgcn_sched_barrier(0)
;     ...
;       LDB(B0, 0, 0); SCHED; LDA(At, 0, 0); STAGE(SA(1, 1), rsA, sA1, offA, t + 1);
;       WAIT_L(8); BAR; WAIT_L(0); MMA(0, 0, At, B0); BAR; SCHED;
;       LDB(B1, 0, 1); STAGE(SB(0, 0), rsB, sB0, offB, t + 2);
;       BAR; WAIT_L(0); MMA(0, 1, At, B1); BAR;
;       LDA(At, 0, 1); STAGE(SA(0, 0), rsA, sA0, offA, t + 2);
;       BAR; WAIT_L(0); MMA(1, 0, At, B0); BAR; SCHED;
;       STAGE(SB(0, 1), rsB, sB1, offB, t + 2);
;       WAIT_V(6); BAR; MMA(1, 1, At, B1); BAR;
.Lmy_rot_757:
	ds_read_b128 v[152:155], v147
	ds_read_b128 v[156:159], v148
	ds_read_b128 v[160:163], v149
	ds_read_b128 v[164:167], v150
	s_add_i32 s6, s85, s5
	s_add_i32 s7, s6, 0x80
	s_mov_b32 m0, s39
	ds_read_b128 v[168:171], v129
	ds_read_b128 v[172:175], v129 offset:1024
	ds_read_b128 v[176:179], v132
	ds_read_b128 v[180:183], v132 offset:1024
	ds_read_b128 v[184:187], v131
	ds_read_b128 v[188:191], v131 offset:1024
	ds_read_b128 v[192:195], v130
	ds_read_b128 v[196:199], v130 offset:1024
	buffer_load_dwordx4 v141, s[8:11], s7 offen lds
	s_mov_b32 m0, s56
	s_nop 0
	buffer_load_dwordx4 v142, s[8:11], s7 offen lds
	s_waitcnt lgkmcnt(8)
	s_barrier
	s_waitcnt lgkmcnt(0)
	v_mfma_f32_16x16x32_bf16 v[124:127], v[152:155], v[168:171], v[124:127]
	v_mfma_f32_16x16x32_bf16 v[124:127], v[156:159], v[172:175], v[124:127]
	v_mfma_f32_16x16x32_bf16 v[120:123], v[164:167], v[172:175], v[120:123]
	v_mfma_f32_16x16x32_bf16 v[120:123], v[160:163], v[168:171], v[120:123]
	v_mfma_f32_16x16x32_bf16 v[112:115], v[160:163], v[176:179], v[112:115]
	v_mfma_f32_16x16x32_bf16 v[112:115], v[164:167], v[180:183], v[112:115]
	v_mfma_f32_16x16x32_bf16 v[116:119], v[156:159], v[180:183], v[116:119]
	v_mfma_f32_16x16x32_bf16 v[116:119], v[152:155], v[176:179], v[116:119]
	v_mfma_f32_16x16x32_bf16 v[108:111], v[152:155], v[184:187], v[108:111]
	v_mfma_f32_16x16x32_bf16 v[108:111], v[156:159], v[188:191], v[108:111]
	v_mfma_f32_16x16x32_bf16 v[104:107], v[164:167], v[188:191], v[104:107]
	v_mfma_f32_16x16x32_bf16 v[104:107], v[160:163], v[184:187], v[104:107]
	v_mfma_f32_16x16x32_bf16 v[96:99], v[160:163], v[192:195], v[96:99]
	v_mfma_f32_16x16x32_bf16 v[96:99], v[164:167], v[196:199], v[96:99]
	v_mfma_f32_16x16x32_bf16 v[100:103], v[156:159], v[196:199], v[100:103]
	v_mfma_f32_16x16x32_bf16 v[100:103], v[152:155], v[192:195], v[100:103]
	s_barrier
	s_add_i32 s7, s87, s5
	s_add_i32 s23, s7, 0x100
	s_mov_b32 s14, s10
	s_mov_b32 s15, s11
	s_mov_b32 m0, s42
	ds_read_b128 v[200:203], v143
	ds_read_b128 v[204:207], v144
	ds_read_b128 v[208:211], v145
	ds_read_b128 v[212:215], v146
	buffer_load_dwordx4 v141, s[12:15], s23 offen lds
	s_mov_b32 m0, s49
	s_nop 0
	buffer_load_dwordx4 v142, s[12:15], s23 offen lds
	s_barrier
	s_waitcnt lgkmcnt(0)
	v_mfma_f32_16x16x32_bf16 v[92:95], v[200:203], v[168:171], v[92:95]
	v_mfma_f32_16x16x32_bf16 v[92:95], v[204:207], v[172:175], v[92:95]
	v_mfma_f32_16x16x32_bf16 v[88:91], v[212:215], v[172:175], v[88:91]
	v_mfma_f32_16x16x32_bf16 v[88:91], v[208:211], v[168:171], v[88:91]
	v_mfma_f32_16x16x32_bf16 v[68:71], v[208:211], v[176:179], v[68:71]
	v_mfma_f32_16x16x32_bf16 v[68:71], v[212:215], v[180:183], v[68:71]
	v_mfma_f32_16x16x32_bf16 v[80:83], v[204:207], v[180:183], v[80:83]
	v_mfma_f32_16x16x32_bf16 v[80:83], v[200:203], v[176:179], v[80:83]
	v_mfma_f32_16x16x32_bf16 v[60:63], v[200:203], v[184:187], v[60:63]
	v_mfma_f32_16x16x32_bf16 v[60:63], v[204:207], v[188:191], v[60:63]
	v_mfma_f32_16x16x32_bf16 v[56:59], v[212:215], v[188:191], v[56:59]
	v_mfma_f32_16x16x32_bf16 v[56:59], v[208:211], v[184:187], v[56:59]
	v_mfma_f32_16x16x32_bf16 v[48:51], v[208:211], v[192:195], v[48:51]
	v_mfma_f32_16x16x32_bf16 v[48:51], v[212:215], v[196:199], v[48:51]
	v_mfma_f32_16x16x32_bf16 v[52:55], v[204:207], v[196:199], v[52:55]
	v_mfma_f32_16x16x32_bf16 v[52:55], v[200:203], v[192:195], v[52:55]
	s_barrier
	s_add_i32 s23, s86, s5
	s_add_i32 s26, s23, 0x100
	s_mov_b32 m0, s33
	ds_read_b128 v[168:171], v129 offset:16384
	ds_read_b128 v[172:175], v129 offset:17408
	ds_read_b128 v[176:179], v132 offset:16384
	ds_read_b128 v[180:183], v132 offset:17408
	ds_read_b128 v[184:187], v131 offset:16384
	ds_read_b128 v[188:191], v131 offset:17408
	ds_read_b128 v[192:195], v130 offset:16384
	ds_read_b128 v[196:199], v130 offset:17408
	buffer_load_dwordx4 v141, s[8:11], s26 offen lds
	s_mov_b32 m0, s50
	s_nop 0
	buffer_load_dwordx4 v142, s[8:11], s26 offen lds
	s_barrier
	s_waitcnt lgkmcnt(0)
	v_mfma_f32_16x16x32_bf16 v[44:47], v[152:155], v[168:171], v[44:47]
	v_mfma_f32_16x16x32_bf16 v[44:47], v[156:159], v[172:175], v[44:47]
	v_mfma_f32_16x16x32_bf16 v[40:43], v[164:167], v[172:175], v[40:43]
	v_mfma_f32_16x16x32_bf16 v[40:43], v[160:163], v[168:171], v[40:43]
	v_mfma_f32_16x16x32_bf16 v[32:35], v[160:163], v[176:179], v[32:35]
	v_mfma_f32_16x16x32_bf16 v[32:35], v[164:167], v[180:183], v[32:35]
	v_mfma_f32_16x16x32_bf16 v[36:39], v[156:159], v[180:183], v[36:39]
	v_mfma_f32_16x16x32_bf16 v[36:39], v[152:155], v[176:179], v[36:39]
	v_mfma_f32_16x16x32_bf16 v[28:31], v[152:155], v[184:187], v[28:31]
	v_mfma_f32_16x16x32_bf16 v[28:31], v[156:159], v[188:191], v[28:31]
	v_mfma_f32_16x16x32_bf16 v[24:27], v[164:167], v[188:191], v[24:27]
	v_mfma_f32_16x16x32_bf16 v[24:27], v[160:163], v[184:187], v[24:27]
	v_mfma_f32_16x16x32_bf16 v[16:19], v[160:163], v[192:195], v[16:19]
	v_mfma_f32_16x16x32_bf16 v[16:19], v[164:167], v[196:199], v[16:19]
	v_mfma_f32_16x16x32_bf16 v[20:23], v[156:159], v[196:199], v[20:23]
	v_mfma_f32_16x16x32_bf16 v[20:23], v[152:155], v[192:195], v[20:23]
	s_barrier
	s_add_i32 s26, s90, s5
	s_add_i32 s27, s26, 0x100
	s_mov_b32 m0, s43
	s_nop 0
	buffer_load_dwordx4 v141, s[12:15], s27 offen lds
	s_mov_b32 m0, s51
	s_nop 0
	buffer_load_dwordx4 v142, s[12:15], s27 offen lds
	s_waitcnt vmcnt(6)
	s_barrier
; #define STAGE(P, RS, SOFF, OFF, kt) do { const int _so = (SOFF) + (kt) * (BK * 2); \
;     _Pragma("unroll") for (int _i = 0; _i < 2; ++_i) { \
;       __builtin_amdgcn_raw_ptr_buffer_load_lds(RS, (__attribute__((address_space(3))) void*)((P) + wave * 1024 + _i * 8192), 16, OFF[_i], _so, 0, 0); } } while (0)
; #define LDA(dst, b, h) _Pragma("unroll") for (int m = 0; m < 4; ++m) _Pragma("unroll") for (int k = 0; k < 2; ++k) \
;     dst[m][k] = *reinterpret_cast<const bf16x8*>(SA(b, h) + lds_byte(wr * 64 + m * 16 + fr, k * 32 + fq * 8))
; #define LDB(dst, b, h) _Pragma("unroll") for (int n = 0; n < 2; ++n) _Pragma("unroll") for (int k = 0; k < 2; ++k) \
;     dst[n][k] = *reinterpret_cast<const bf16x8*>(SB(b, h) + lds_byte(wc * 32 + n * 16 + fr, k * 32 + fq * 8))
; #define WAIT_V(n) asm volatile("s_waitcnt vmcnt(" #n ")" ::: "memory")
; #define WAIT_L(n) asm volatile("s_waitcnt lgkmcnt(" #n ")" ::: "memory")
; #define BAR __builtin_amdgcn_s_barrier()
; #define SCHED __builtin_amdgcn_sched_barrier(0)
;     ...
;       WAIT_V(6); BAR; MMA(1, 1, At, B1); BAR;
;       LDB(B0, 1, 0); SCHED; LDA(At, 1, 0); STAGE(SA(0, 1), rsA, sA1, offA, t + 2);
;       WAIT_L(8); BAR; WAIT_L(0); MMA(0, 0, At, B0); BAR; SCHED;
;       LDB(B1, 1, 1); STAGE(SB(1, 0), rsB, sB0, offB, t + 3);
;       BAR; WAIT_L(0); MMA(0, 1, At, B1); BAR;
;       LDA(At, 1, 1); STAGE(SA(1, 0), rsA, sA0, offA, t + 3);
;       BAR; WAIT_L(0); MMA(1, 0, At, B0); BAR; SCHED;
	v_mfma_f32_16x16x32_bf16 v[12:15], v[200:203], v[168:171], v[12:15]
	v_mfma_f32_16x16x32_bf16 v[12:15], v[204:207], v[172:175], v[12:15]
	v_mfma_f32_16x16x32_bf16 v[8:11], v[212:215], v[172:175], v[8:11]
	v_mfma_f32_16x16x32_bf16 v[8:11], v[208:211], v[168:171], v[8:11]
	v_mfma_f32_16x16x32_bf16 v[0:3], v[208:211], v[176:179], v[0:3]
	v_mfma_f32_16x16x32_bf16 v[0:3], v[212:215], v[180:183], v[0:3]
	v_mfma_f32_16x16x32_bf16 v[4:7], v[204:207], v[180:183], v[4:7]
	v_mfma_f32_16x16x32_bf16 v[4:7], v[200:203], v[176:179], v[4:7]
	v_mfma_f32_16x16x32_bf16 v[64:67], v[200:203], v[184:187], v[64:67]
	v_mfma_f32_16x16x32_bf16 v[64:67], v[204:207], v[188:191], v[64:67]
	v_mfma_f32_16x16x32_bf16 v[72:75], v[212:215], v[188:191], v[72:75]
	v_mfma_f32_16x16x32_bf16 v[72:75], v[208:211], v[184:187], v[72:75]
	v_mfma_f32_16x16x32_bf16 v[84:87], v[208:211], v[192:195], v[84:87]
	v_mfma_f32_16x16x32_bf16 v[84:87], v[212:215], v[196:199], v[84:87]
	v_mfma_f32_16x16x32_bf16 v[76:79], v[204:207], v[196:199], v[76:79]
	v_mfma_f32_16x16x32_bf16 v[76:79], v[200:203], v[192:195], v[76:79]
	s_barrier
	ds_read_b128 v[152:155], v137
	ds_read_b128 v[156:159], v138
	ds_read_b128 v[160:163], v139
	ds_read_b128 v[164:167], v140
	s_addk_i32 s6, 0x100
	s_mov_b32 m0, s44
	ds_read_b128 v[168:171], v129 offset:32768
	ds_read_b128 v[172:175], v129 offset:33792
	ds_read_b128 v[176:179], v132 offset:32768
	ds_read_b128 v[180:183], v132 offset:33792
	ds_read_b128 v[184:187], v131 offset:32768
	ds_read_b128 v[188:191], v131 offset:33792
	ds_read_b128 v[192:195], v130 offset:32768
	ds_read_b128 v[196:199], v130 offset:33792
	buffer_load_dwordx4 v141, s[8:11], s6 offen lds
	s_mov_b32 m0, s52
	s_nop 0
	buffer_load_dwordx4 v142, s[8:11], s6 offen lds
	s_waitcnt lgkmcnt(8)
	s_barrier
	s_waitcnt lgkmcnt(0)
	v_mfma_f32_16x16x32_bf16 v[124:127], v[152:155], v[168:171], v[124:127]
	v_mfma_f32_16x16x32_bf16 v[124:127], v[156:159], v[172:175], v[124:127]
	v_mfma_f32_16x16x32_bf16 v[120:123], v[164:167], v[172:175], v[120:123]
	v_mfma_f32_16x16x32_bf16 v[120:123], v[160:163], v[168:171], v[120:123]
	v_mfma_f32_16x16x32_bf16 v[112:115], v[160:163], v[176:179], v[112:115]
	v_mfma_f32_16x16x32_bf16 v[112:115], v[164:167], v[180:183], v[112:115]
	v_mfma_f32_16x16x32_bf16 v[116:119], v[156:159], v[180:183], v[116:119]
	v_mfma_f32_16x16x32_bf16 v[116:119], v[152:155], v[176:179], v[116:119]
	v_mfma_f32_16x16x32_bf16 v[108:111], v[152:155], v[184:187], v[108:111]
	v_mfma_f32_16x16x32_bf16 v[108:111], v[156:159], v[188:191], v[108:111]
	v_mfma_f32_16x16x32_bf16 v[104:107], v[164:167], v[188:191], v[104:107]
	v_mfma_f32_16x16x32_bf16 v[104:107], v[160:163], v[184:187], v[104:107]
	v_mfma_f32_16x16x32_bf16 v[96:99], v[160:163], v[192:195], v[96:99]
	v_mfma_f32_16x16x32_bf16 v[96:99], v[164:167], v[196:199], v[96:99]
	v_mfma_f32_16x16x32_bf16 v[100:103], v[156:159], v[196:199], v[100:103]
	v_mfma_f32_16x16x32_bf16 v[100:103], v[152:155], v[192:195], v[100:103]
	s_barrier
	s_addk_i32 s7, 0x180
	s_mov_b32 m0, s45
	ds_read_b128 v[200:203], v133
	ds_read_b128 v[204:207], v134
	ds_read_b128 v[208:211], v135
	ds_read_b128 v[212:215], v136
	buffer_load_dwordx4 v141, s[12:15], s7 offen lds
	s_mov_b32 m0, s53
	s_nop 0
	buffer_load_dwordx4 v142, s[12:15], s7 offen lds
	s_barrier
	s_waitcnt lgkmcnt(0)
	v_mfma_f32_16x16x32_bf16 v[92:95], v[200:203], v[168:171], v[92:95]
	v_mfma_f32_16x16x32_bf16 v[92:95], v[204:207], v[172:175], v[92:95]
	v_mfma_f32_16x16x32_bf16 v[88:91], v[212:215], v[172:175], v[88:91]
	v_mfma_f32_16x16x32_bf16 v[88:91], v[208:211], v[168:171], v[88:91]
	v_mfma_f32_16x16x32_bf16 v[68:71], v[208:211], v[176:179], v[68:71]
	v_mfma_f32_16x16x32_bf16 v[68:71], v[212:215], v[180:183], v[68:71]
	v_mfma_f32_16x16x32_bf16 v[80:83], v[204:207], v[180:183], v[80:83]
	v_mfma_f32_16x16x32_bf16 v[80:83], v[200:203], v[176:179], v[80:83]
	v_mfma_f32_16x16x32_bf16 v[60:63], v[200:203], v[184:187], v[60:63]
	v_mfma_f32_16x16x32_bf16 v[60:63], v[204:207], v[188:191], v[60:63]
	v_mfma_f32_16x16x32_bf16 v[56:59], v[212:215], v[188:191], v[56:59]
	v_mfma_f32_16x16x32_bf16 v[56:59], v[208:211], v[184:187], v[56:59]
	v_mfma_f32_16x16x32_bf16 v[48:51], v[208:211], v[192:195], v[48:51]
	v_mfma_f32_16x16x32_bf16 v[48:51], v[212:215], v[196:199], v[48:51]
	v_mfma_f32_16x16x32_bf16 v[52:55], v[204:207], v[196:199], v[52:55]
	v_mfma_f32_16x16x32_bf16 v[52:55], v[200:203], v[192:195], v[52:55]
	s_barrier
	s_addk_i32 s23, 0x180
	s_mov_b32 m0, s46
	ds_read_b128 v[168:171], v129 offset:49152
	ds_read_b128 v[172:175], v129 offset:50176
	ds_read_b128 v[176:179], v132 offset:49152
	ds_read_b128 v[180:183], v132 offset:50176
	ds_read_b128 v[184:187], v131 offset:49152
	ds_read_b128 v[188:191], v131 offset:50176
	ds_read_b128 v[192:195], v130 offset:49152
	ds_read_b128 v[196:199], v130 offset:50176
	buffer_load_dwordx4 v141, s[8:11], s23 offen lds
	s_mov_b32 m0, s54
	s_nop 0
	buffer_load_dwordx4 v142, s[8:11], s23 offen lds
	s_barrier
	s_waitcnt lgkmcnt(0)
	v_mfma_f32_16x16x32_bf16 v[44:47], v[152:155], v[168:171], v[44:47]
	v_mfma_f32_16x16x32_bf16 v[44:47], v[156:159], v[172:175], v[44:47]
	v_mfma_f32_16x16x32_bf16 v[40:43], v[164:167], v[172:175], v[40:43]
	v_mfma_f32_16x16x32_bf16 v[40:43], v[160:163], v[168:171], v[40:43]
	v_mfma_f32_16x16x32_bf16 v[32:35], v[160:163], v[176:179], v[32:35]
	v_mfma_f32_16x16x32_bf16 v[32:35], v[164:167], v[180:183], v[32:35]
	v_mfma_f32_16x16x32_bf16 v[36:39], v[156:159], v[180:183], v[36:39]
	v_mfma_f32_16x16x32_bf16 v[36:39], v[152:155], v[176:179], v[36:39]
	v_mfma_f32_16x16x32_bf16 v[28:31], v[152:155], v[184:187], v[28:31]
	v_mfma_f32_16x16x32_bf16 v[28:31], v[156:159], v[188:191], v[28:31]
	v_mfma_f32_16x16x32_bf16 v[24:27], v[164:167], v[188:191], v[24:27]
	v_mfma_f32_16x16x32_bf16 v[24:27], v[160:163], v[184:187], v[24:27]
	v_mfma_f32_16x16x32_bf16 v[16:19], v[160:163], v[192:195], v[16:19]
	v_mfma_f32_16x16x32_bf16 v[16:19], v[164:167], v[196:199], v[16:19]
	v_mfma_f32_16x16x32_bf16 v[20:23], v[156:159], v[196:199], v[20:23]
	v_mfma_f32_16x16x32_bf16 v[20:23], v[152:155], v[192:195], v[20:23]
	s_barrier
; #define STAGE(P, RS, SOFF, OFF, kt) do { const int _so = (SOFF) + (kt) * (BK * 2); \
;     _Pragma("unroll") for (int _i = 0; _i < 2; ++_i) { \
;       __builtin_amdgcn_raw_ptr_buffer_load_lds(RS, (__attribute__((address_space(3))) void*)((P) + wave * 1024 + _i * 8192), 16, OFF[_i], _so, 0, 0); } } while (0)
; #define LDA(dst, b, h) _Pragma("unroll") for (int m = 0; m < 4; ++m) _Pragma("unroll") for (int k = 0; k < 2; ++k) \
;     dst[m][k] = *reinterpret_cast<const bf16x8*>(SA(b, h) + lds_byte(wr * 64 + m * 16 + fr, k * 32 + fq * 8))
; #define LDB(dst, b, h) _Pragma("unroll") for (int n = 0; n < 2; ++n) _Pragma("unroll") for (int k = 0; k < 2; ++k) \
;     dst[n][k] = *reinterpret_cast<const bf16x8*>(SB(b, h) + lds_byte(wc * 32 + n * 16 + fr, k * 32 + fq * 8))
; #define WAIT_V(n) asm volatile("s_waitcnt vmcnt(" #n ")" ::: "memory")
; #define WAIT_L(n) asm volatile("s_waitcnt lgkmcnt(" #n ")" ::: "memory")
; #define BAR __builtin_amdgcn_s_barrier()
;     ...
;       STAGE(SB(1, 1), rsB, sB1, offB, t + 3);
;       WAIT_V(6); BAR; MMA(1, 1, At, B1); BAR;
;     }
;     { LDB(B0, 0, 0); LDA(At, 0, 0); STAGE(SA(1, 1), rsA, sA1, offA, nt - 1);
;       BAR; WAIT_L(0); MMA(0, 0, At, B0); BAR;
;       LDB(B1, 0, 1); BAR; WAIT_L(0); MMA(0, 1, At, B1); BAR;
;       LDA(At, 0, 1); WAIT_V(4); BAR; WAIT_L(0); MMA(1, 0, At, B0); MMA(1, 1, At, B1); BAR; }
	s_addk_i32 s26, 0x180
	s_mov_b32 m0, s47
	s_nop 0
	buffer_load_dwordx4 v141, s[12:15], s26 offen lds
	s_mov_b32 m0, s55
	s_nop 0
	buffer_load_dwordx4 v142, s[12:15], s26 offen lds
	s_add_i32 s4, s4, 2
	s_addk_i32 s5, 0x100
	s_cmp_gt_u32 s4, 59
	s_cbranch_scc0 .LBB0_757
	s_waitcnt vmcnt(6)
	s_barrier
	v_mfma_f32_16x16x32_bf16 v[12:15], v[200:203], v[168:171], v[12:15]
	v_mfma_f32_16x16x32_bf16 v[12:15], v[204:207], v[172:175], v[12:15]
	v_mfma_f32_16x16x32_bf16 v[8:11], v[212:215], v[172:175], v[8:11]
	v_mfma_f32_16x16x32_bf16 v[8:11], v[208:211], v[168:171], v[8:11]
	v_mfma_f32_16x16x32_bf16 v[0:3], v[208:211], v[176:179], v[0:3]
	v_mfma_f32_16x16x32_bf16 v[0:3], v[212:215], v[180:183], v[0:3]
	v_mfma_f32_16x16x32_bf16 v[4:7], v[204:207], v[180:183], v[4:7]
	v_mfma_f32_16x16x32_bf16 v[4:7], v[200:203], v[176:179], v[4:7]
	v_mfma_f32_16x16x32_bf16 v[64:67], v[200:203], v[184:187], v[64:67]
	v_mfma_f32_16x16x32_bf16 v[64:67], v[204:207], v[188:191], v[64:67]
	v_mfma_f32_16x16x32_bf16 v[72:75], v[212:215], v[188:191], v[72:75]
	v_mfma_f32_16x16x32_bf16 v[72:75], v[208:211], v[184:187], v[72:75]
	v_mfma_f32_16x16x32_bf16 v[84:87], v[208:211], v[192:195], v[84:87]
	v_mfma_f32_16x16x32_bf16 v[84:87], v[212:215], v[196:199], v[84:87]
	v_mfma_f32_16x16x32_bf16 v[76:79], v[204:207], v[196:199], v[76:79]
	v_mfma_f32_16x16x32_bf16 v[76:79], v[200:203], v[192:195], v[76:79]
	s_barrier
	s_add_i32 s4, s85, 0x1f80
	s_mov_b32 m0, s39
	ds_read_b128 v[152:155], v147
	ds_read_b128 v[156:159], v148
	ds_read_b128 v[160:163], v149
	ds_read_b128 v[148:151], v150
	ds_read_b128 v[164:167], v129
	ds_read_b128 v[168:171], v129 offset:1024
	ds_read_b128 v[172:175], v132
	ds_read_b128 v[176:179], v132 offset:1024
	ds_read_b128 v[180:183], v131
	ds_read_b128 v[184:187], v131 offset:1024
	ds_read_b128 v[188:191], v130
	ds_read_b128 v[192:195], v130 offset:1024
	buffer_load_dwordx4 v141, s[8:11], s4 offen lds
	s_mov_b32 m0, s56
	s_nop 0
	buffer_load_dwordx4 v142, s[8:11], s4 offen lds
	s_barrier
	s_waitcnt lgkmcnt(0)
	v_mfma_f32_16x16x32_bf16 v[124:127], v[152:155], v[164:167], v[124:127]
	v_mfma_f32_16x16x32_bf16 v[124:127], v[156:159], v[168:171], v[124:127]
	v_mfma_f32_16x16x32_bf16 v[120:123], v[148:151], v[168:171], v[120:123]
	v_mfma_f32_16x16x32_bf16 v[120:123], v[160:163], v[164:167], v[120:123]
	v_mfma_f32_16x16x32_bf16 v[112:115], v[160:163], v[172:175], v[112:115]
	v_mfma_f32_16x16x32_bf16 v[112:115], v[148:151], v[176:179], v[112:115]
	v_mfma_f32_16x16x32_bf16 v[116:119], v[156:159], v[176:179], v[116:119]
	v_mfma_f32_16x16x32_bf16 v[116:119], v[152:155], v[172:175], v[116:119]
	v_mfma_f32_16x16x32_bf16 v[108:111], v[152:155], v[180:183], v[108:111]
	v_mfma_f32_16x16x32_bf16 v[108:111], v[156:159], v[184:187], v[108:111]
	v_mfma_f32_16x16x32_bf16 v[104:107], v[148:151], v[184:187], v[104:107]
	v_mfma_f32_16x16x32_bf16 v[104:107], v[160:163], v[180:183], v[104:107]
	v_mfma_f32_16x16x32_bf16 v[96:99], v[160:163], v[188:191], v[96:99]
	v_mfma_f32_16x16x32_bf16 v[96:99], v[148:151], v[192:195], v[96:99]
	v_mfma_f32_16x16x32_bf16 v[100:103], v[156:159], v[192:195], v[100:103]
	v_mfma_f32_16x16x32_bf16 v[100:103], v[152:155], v[188:191], v[100:103]
	s_barrier
	ds_read_b128 v[196:199], v143
	ds_read_b128 v[200:203], v144
	ds_read_b128 v[142:145], v145
	ds_read_b128 v[204:207], v146
	s_barrier
	s_waitcnt lgkmcnt(0)
	v_mfma_f32_16x16x32_bf16 v[88:91], v[142:145], v[164:167], v[88:91]
	v_mfma_f32_16x16x32_bf16 v[80:83], v[196:199], v[172:175], v[80:83]
	v_mfma_f32_16x16x32_bf16 v[60:63], v[196:199], v[180:183], v[60:63]
	v_mfma_f32_16x16x32_bf16 v[56:59], v[142:145], v[180:183], v[56:59]
	v_mfma_f32_16x16x32_bf16 v[52:55], v[196:199], v[188:191], v[52:55]
	v_mfma_f32_16x16x32_bf16 v[48:51], v[142:145], v[188:191], v[48:51]
	v_mfma_f32_16x16x32_bf16 v[92:95], v[196:199], v[164:167], v[92:95]
	v_mfma_f32_16x16x32_bf16 v[68:71], v[142:145], v[172:175], v[68:71]
	v_mfma_f32_16x16x32_bf16 v[88:91], v[204:207], v[168:171], v[88:91]
	v_mfma_f32_16x16x32_bf16 v[80:83], v[200:203], v[176:179], v[80:83]
	v_mfma_f32_16x16x32_bf16 v[60:63], v[200:203], v[184:187], v[60:63]
	v_mfma_f32_16x16x32_bf16 v[56:59], v[204:207], v[184:187], v[56:59]
	v_mfma_f32_16x16x32_bf16 v[52:55], v[200:203], v[192:195], v[52:55]
	v_mfma_f32_16x16x32_bf16 v[48:51], v[204:207], v[192:195], v[48:51]
	v_mfma_f32_16x16x32_bf16 v[164:167], v[200:203], v[168:171], v[92:95]
	v_mfma_f32_16x16x32_bf16 v[168:171], v[204:207], v[176:179], v[68:71]
	s_barrier
	s_nop 0
	ds_read_b128 v[68:71], v129 offset:16384
	ds_read_b128 v[92:95], v129 offset:17408
	ds_read_b128 v[172:175], v132 offset:16384
	ds_read_b128 v[176:179], v132 offset:17408
	ds_read_b128 v[180:183], v131 offset:16384
	ds_read_b128 v[184:187], v131 offset:17408
	ds_read_b128 v[188:191], v130 offset:16384
	ds_read_b128 v[192:195], v130 offset:17408
	s_waitcnt vmcnt(4)
	s_barrier
; #define LDA(dst, b, h) _Pragma("unroll") for (int m = 0; m < 4; ++m) _Pragma("unroll") for (int k = 0; k < 2; ++k) \
;     dst[m][k] = *reinterpret_cast<const bf16x8*>(SA(b, h) + lds_byte(wr * 64 + m * 16 + fr, k * 32 + fq * 8))
; #define LDB(dst, b, h) _Pragma("unroll") for (int n = 0; n < 2; ++n) _Pragma("unroll") for (int k = 0; k < 2; ++k) \
;     dst[n][k] = *reinterpret_cast<const bf16x8*>(SB(b, h) + lds_byte(wc * 32 + n * 16 + fr, k * 32 + fq * 8))
; #define WAIT_V(n) asm volatile("s_waitcnt vmcnt(" #n ")" ::: "memory")
; #define WAIT_L(n) asm volatile("s_waitcnt lgkmcnt(" #n ")" ::: "memory")
; #define BAR __builtin_amdgcn_s_barrier()
;     ...
;       LDA(At, 0, 1); WAIT_V(4); BAR; WAIT_L(0); MMA(1, 0, At, B0); MMA(1, 1, At, B1); BAR; }
;     { LDB(B0, 1, 0); LDA(At, 1, 0); WAIT_V(2); BAR; WAIT_L(0); MMA(0, 0, At, B0); BAR;
	s_waitcnt lgkmcnt(0)
	v_mfma_f32_16x16x32_bf16 v[44:47], v[152:155], v[68:71], v[44:47]
	v_mfma_f32_16x16x32_bf16 v[40:43], v[160:163], v[68:71], v[40:43]
	v_mfma_f32_16x16x32_bf16 v[36:39], v[152:155], v[172:175], v[36:39]
	v_mfma_f32_16x16x32_bf16 v[32:35], v[160:163], v[172:175], v[32:35]
	v_mfma_f32_16x16x32_bf16 v[28:31], v[152:155], v[180:183], v[28:31]
	v_mfma_f32_16x16x32_bf16 v[24:27], v[160:163], v[180:183], v[24:27]
	v_mfma_f32_16x16x32_bf16 v[20:23], v[152:155], v[188:191], v[20:23]
	v_mfma_f32_16x16x32_bf16 v[16:19], v[160:163], v[188:191], v[16:19]
	v_mfma_f32_16x16x32_bf16 v[44:47], v[156:159], v[92:95], v[44:47]
	v_mfma_f32_16x16x32_bf16 v[40:43], v[148:151], v[92:95], v[40:43]
	v_mfma_f32_16x16x32_bf16 v[36:39], v[156:159], v[176:179], v[36:39]
	v_mfma_f32_16x16x32_bf16 v[32:35], v[148:151], v[176:179], v[32:35]
	v_mfma_f32_16x16x32_bf16 v[28:31], v[156:159], v[184:187], v[28:31]
	v_mfma_f32_16x16x32_bf16 v[24:27], v[148:151], v[184:187], v[24:27]
	v_mfma_f32_16x16x32_bf16 v[20:23], v[156:159], v[192:195], v[20:23]
	v_mfma_f32_16x16x32_bf16 v[16:19], v[148:151], v[192:195], v[16:19]
	v_mfma_f32_16x16x32_bf16 v[4:7], v[196:199], v[172:175], v[4:7]
	v_mfma_f32_16x16x32_bf16 v[0:3], v[142:145], v[172:175], v[0:3]
	v_mfma_f32_16x16x32_bf16 v[12:15], v[196:199], v[68:71], v[12:15]
	v_mfma_f32_16x16x32_bf16 v[8:11], v[142:145], v[68:71], v[8:11]
	v_mfma_f32_16x16x32_bf16 v[64:67], v[196:199], v[180:183], v[64:67]
	v_mfma_f32_16x16x32_bf16 v[68:71], v[142:145], v[180:183], v[72:75]
	v_mfma_f32_16x16x32_bf16 v[72:75], v[196:199], v[188:191], v[76:79]
	v_mfma_f32_16x16x32_bf16 v[76:79], v[142:145], v[188:191], v[84:87]
	v_mfma_f32_16x16x32_bf16 v[4:7], v[200:203], v[176:179], v[4:7]
	v_mfma_f32_16x16x32_bf16 v[0:3], v[204:207], v[176:179], v[0:3]
	v_mfma_f32_16x16x32_bf16 v[142:145], v[200:203], v[92:95], v[12:15]
	v_mfma_f32_16x16x32_bf16 v[146:149], v[204:207], v[92:95], v[8:11]
	v_mfma_f32_16x16x32_bf16 v[150:153], v[200:203], v[184:187], v[64:67]
	v_mfma_f32_16x16x32_bf16 v[154:157], v[204:207], v[184:187], v[68:71]
	v_mfma_f32_16x16x32_bf16 v[158:161], v[200:203], v[192:195], v[72:75]
	v_mfma_f32_16x16x32_bf16 v[172:175], v[204:207], v[192:195], v[76:79]
	s_barrier
	ds_read_b128 v[8:11], v137
	ds_read_b128 v[12:15], v138
	ds_read_b128 v[176:179], v139
	ds_read_b128 v[138:141], v140
	ds_read_b128 v[64:67], v129 offset:32768
	ds_read_b128 v[72:75], v129 offset:33792
	ds_read_b128 v[180:183], v132 offset:32768
	ds_read_b128 v[184:187], v132 offset:33792
	ds_read_b128 v[188:191], v131 offset:32768
	ds_read_b128 v[192:195], v131 offset:33792
	ds_read_b128 v[196:199], v130 offset:32768
	ds_read_b128 v[200:203], v130 offset:33792
	s_waitcnt vmcnt(2)
	s_barrier
	s_waitcnt lgkmcnt(0)
	v_mfma_f32_16x16x32_bf16 v[68:71], v[8:11], v[64:67], v[124:127]
	v_mfma_f32_16x16x32_bf16 v[76:79], v[176:179], v[64:67], v[120:123]
	v_mfma_f32_16x16x32_bf16 v[84:87], v[8:11], v[180:183], v[116:119]
	v_mfma_f32_16x16x32_bf16 v[92:95], v[176:179], v[180:183], v[112:115]
	v_mfma_f32_16x16x32_bf16 v[112:115], v[8:11], v[188:191], v[108:111]
	v_mfma_f32_16x16x32_bf16 v[104:107], v[176:179], v[188:191], v[104:107]
	v_mfma_f32_16x16x32_bf16 v[120:123], v[8:11], v[196:199], v[100:103]
	v_mfma_f32_16x16x32_bf16 v[96:99], v[176:179], v[196:199], v[96:99]
	v_mfma_f32_16x16x32_bf16 v[124:127], v[12:15], v[72:75], v[68:71]
	v_mfma_f32_16x16x32_bf16 v[116:119], v[138:141], v[72:75], v[76:79]
	v_mfma_f32_16x16x32_bf16 v[108:111], v[12:15], v[184:187], v[84:87]
	v_mfma_f32_16x16x32_bf16 v[100:103], v[138:141], v[184:187], v[92:95]
	v_mfma_f32_16x16x32_bf16 v[92:95], v[12:15], v[192:195], v[112:115]
	v_mfma_f32_16x16x32_bf16 v[84:87], v[138:141], v[192:195], v[104:107]
	v_mfma_f32_16x16x32_bf16 v[76:79], v[12:15], v[200:203], v[120:123]
	v_mfma_f32_16x16x32_bf16 v[68:71], v[138:141], v[200:203], v[96:99]
	s_barrier
; #define LDA(dst, b, h) _Pragma("unroll") for (int m = 0; m < 4; ++m) _Pragma("unroll") for (int k = 0; k < 2; ++k) \
;     dst[m][k] = *reinterpret_cast<const bf16x8*>(SA(b, h) + lds_byte(wr * 64 + m * 16 + fr, k * 32 + fq * 8))
; #define LDB(dst, b, h) _Pragma("unroll") for (int n = 0; n < 2; ++n) _Pragma("unroll") for (int k = 0; k < 2; ++k) \
;     dst[n][k] = *reinterpret_cast<const bf16x8*>(SB(b, h) + lds_byte(wc * 32 + n * 16 + fr, k * 32 + fq * 8))
; #define WAIT_V(n) asm volatile("s_waitcnt vmcnt(" #n ")" ::: "memory")
; #define WAIT_L(n) asm volatile("s_waitcnt lgkmcnt(" #n ")" ::: "memory")
; #define BAR __builtin_amdgcn_s_barrier()
;     ...
;       LDB(B1, 1, 1); WAIT_V(0); BAR; WAIT_L(0); MMA(0, 1, At, B1); BAR;
;       LDA(At, 1, 1); BAR; WAIT_L(0); MMA(1, 0, At, B0); MMA(1, 1, At, B1); BAR; }
;     if (wr == 0) BAR;
	ds_read_b128 v[204:207], v133
	ds_read_b128 v[208:211], v134
	ds_read_b128 v[212:215], v135
	ds_read_b128 v[134:137], v136
	s_waitcnt vmcnt(0)
	s_barrier
	s_waitcnt lgkmcnt(0)
	v_mfma_f32_16x16x32_bf16 v[96:99], v[204:207], v[64:67], v[164:167]
	v_mfma_f32_16x16x32_bf16 v[64:67], v[212:215], v[64:67], v[88:91]
	v_mfma_f32_16x16x32_bf16 v[80:83], v[204:207], v[180:183], v[80:83]
	v_mfma_f32_16x16x32_bf16 v[88:91], v[212:215], v[180:183], v[168:171]
	v_mfma_f32_16x16x32_bf16 v[60:63], v[204:207], v[188:191], v[60:63]
	v_mfma_f32_16x16x32_bf16 v[56:59], v[212:215], v[188:191], v[56:59]
	v_mfma_f32_16x16x32_bf16 v[52:55], v[204:207], v[196:199], v[52:55]
	v_mfma_f32_16x16x32_bf16 v[48:51], v[212:215], v[196:199], v[48:51]
	v_mfma_f32_16x16x32_bf16 v[120:123], v[208:211], v[72:75], v[96:99]
	v_mfma_f32_16x16x32_bf16 v[112:115], v[134:137], v[72:75], v[64:67]
	v_mfma_f32_16x16x32_bf16 v[104:107], v[208:211], v[184:187], v[80:83]
	v_mfma_f32_16x16x32_bf16 v[96:99], v[134:137], v[184:187], v[88:91]
	v_mfma_f32_16x16x32_bf16 v[88:91], v[208:211], v[192:195], v[60:63]
	v_mfma_f32_16x16x32_bf16 v[80:83], v[134:137], v[192:195], v[56:59]
	v_mfma_f32_16x16x32_bf16 v[72:75], v[208:211], v[200:203], v[52:55]
	v_mfma_f32_16x16x32_bf16 v[64:67], v[134:137], v[200:203], v[48:51]
	s_barrier
	s_nop 0
	ds_read_b128 v[48:51], v129 offset:49152
	ds_read_b128 v[162:165], v129 offset:50176
	ds_read_b128 v[52:55], v132 offset:49152
	ds_read_b128 v[166:169], v132 offset:50176
	ds_read_b128 v[180:183], v131 offset:49152
	ds_read_b128 v[184:187], v131 offset:50176
	ds_read_b128 v[188:191], v130 offset:49152
	ds_read_b128 v[130:133], v130 offset:50176
	s_barrier
	s_waitcnt lgkmcnt(0)
	v_mfma_f32_16x16x32_bf16 v[44:47], v[8:11], v[48:51], v[44:47]
	v_mfma_f32_16x16x32_bf16 v[40:43], v[176:179], v[48:51], v[40:43]
	v_mfma_f32_16x16x32_bf16 v[36:39], v[8:11], v[52:55], v[36:39]
	v_mfma_f32_16x16x32_bf16 v[32:35], v[176:179], v[52:55], v[32:35]
	v_mfma_f32_16x16x32_bf16 v[28:31], v[8:11], v[180:183], v[28:31]
	v_mfma_f32_16x16x32_bf16 v[24:27], v[176:179], v[180:183], v[24:27]
	v_mfma_f32_16x16x32_bf16 v[8:11], v[8:11], v[188:191], v[20:23]
	v_mfma_f32_16x16x32_bf16 v[16:19], v[176:179], v[188:191], v[16:19]
	v_mfma_f32_16x16x32_bf16 v[60:63], v[12:15], v[162:165], v[44:47]
	v_mfma_f32_16x16x32_bf16 v[56:59], v[138:141], v[162:165], v[40:43]
	v_mfma_f32_16x16x32_bf16 v[44:47], v[12:15], v[166:169], v[36:39]
	v_mfma_f32_16x16x32_bf16 v[40:43], v[138:141], v[166:169], v[32:35]
	v_mfma_f32_16x16x32_bf16 v[28:31], v[12:15], v[184:187], v[28:31]
	v_mfma_f32_16x16x32_bf16 v[24:27], v[138:141], v[184:187], v[24:27]
	v_mfma_f32_16x16x32_bf16 v[12:15], v[12:15], v[130:133], v[8:11]
	v_mfma_f32_16x16x32_bf16 v[8:11], v[138:141], v[130:133], v[16:19]
	v_mfma_f32_16x16x32_bf16 v[16:19], v[204:207], v[48:51], v[142:145]
	v_mfma_f32_16x16x32_bf16 v[20:23], v[212:215], v[48:51], v[146:149]
	v_mfma_f32_16x16x32_bf16 v[4:7], v[204:207], v[52:55], v[4:7]
	v_mfma_f32_16x16x32_bf16 v[0:3], v[212:215], v[52:55], v[0:3]
	v_mfma_f32_16x16x32_bf16 v[138:141], v[204:207], v[180:183], v[150:153]
	v_mfma_f32_16x16x32_bf16 v[142:145], v[212:215], v[180:183], v[154:157]
	v_mfma_f32_16x16x32_bf16 v[146:149], v[204:207], v[188:191], v[158:161]
	v_mfma_f32_16x16x32_bf16 v[150:153], v[212:215], v[188:191], v[172:175]
	v_mfma_f32_16x16x32_bf16 v[52:55], v[208:211], v[162:165], v[16:19]
	v_mfma_f32_16x16x32_bf16 v[48:51], v[134:137], v[162:165], v[20:23]
	v_mfma_f32_16x16x32_bf16 v[36:39], v[208:211], v[166:169], v[4:7]
	v_mfma_f32_16x16x32_bf16 v[32:35], v[134:137], v[166:169], v[0:3]
	v_mfma_f32_16x16x32_bf16 v[20:23], v[208:211], v[184:187], v[138:141]
	v_mfma_f32_16x16x32_bf16 v[16:19], v[134:137], v[184:187], v[142:145]
	v_mfma_f32_16x16x32_bf16 v[4:7], v[208:211], v[130:133], v[146:149]
	v_mfma_f32_16x16x32_bf16 v[0:3], v[134:137], v[130:133], v[150:153]
	v_cmp_gt_u32_e32 vcc, s74, v128
	s_barrier
	s_and_saveexec_b64 s[4:5], vcc
	s_cbranch_execz .LBB0_760
	s_barrier
